# v44 with every s_setprio removed (GEMM K-loops on age-based arbitration only)
# baseline (speedup 1.0000x reference)
; #define PG8_STAGE(bufoff, gbase, voff) do { _Pragma("unroll") for (int _i = 0; _i < 2; ++_i) \
;         __builtin_amdgcn_global_load_lds((const unsigned*)((const char*)(gbase) + (voff)[_i]), (PG8_LAS unsigned*)(lds + (bufoff) + ldsw + _i * 8192), 16, 0, 0); } while (0)
; #define PG8_LDA(dst, b, h) do { _Pragma("unroll") for (int m = 0; m < 4; ++m) _Pragma("unroll") for (int k = 0; k < 2; ++k) dst[m][k] = *(const PG8_LAS bf16x8*)(lds + PG8_SA(b, h) + aoff + m * 2048 + k * 1024); } while (0)
; #define PG8_LDB(dst, b, h) do { _Pragma("unroll") for (int n = 0; n < 2; ++n) _Pragma("unroll") for (int k = 0; k < 2; ++k) dst[n][k] = *(const PG8_LAS bf16x8*)(lds + PG8_SB(b, h) + boff + n * 2048 + k * 1024); } while (0)
; #define PG8_MMA(ai, bj, At, Bt) do { __builtin_amdgcn_s_setprio(1); _Pragma("unroll") for (int m = 0; m < 4; ++m) _Pragma("unroll") for (int n = 0; n < 2; ++n) _Pragma("unroll") for (int k = 0; k < 2; ++k) \
;         acc[ai][bj][m][n] = __builtin_amdgcn_mfma_f32_16x16x32_bf16(Bt[n][k], At[m][k], acc[ai][bj][m][n], 0, 0, 0); __builtin_amdgcn_s_setprio(0); } while (0)
; template <class Epi, class Sched, bool ALIGN_EPI = false, bool SP2 = false>
; __device__ __forceinline__ void gemm_phase(PG8_LAS unsigned char* lds, const Gemm g, const Sched& S, const Epi& E) {
;     ...
;             if constexpr (SP2) {
;             PG8_LDB(B0, 0, 0); PG8_LDB(B1, 0, 1); PG8_SCHED; PG8_LDA(At, 0, 0); PG8_STAGE(PG8_SA(1, 1), a1 + hstepA, voffA);
;             PG8_WAIT_V(8); PG8_WAIT_L(0); PG8_BAR; PG8_MMA(0, 0, At, B0); PG8_MMA(0, 1, At, B1); PG8_BAR; PG8_SCHED;
;             PG8_LDA(At, 0, 1); PG8_STAGE(PG8_SB(0, 0), b2, voffB); PG8_STAGE(PG8_SB(0, 1), b2 + hstepB, voffB); PG8_STAGE(PG8_SA(0, 0), a2, voffA);
;             PG8_WAIT_V(8); PG8_WAIT_L(0); PG8_BAR; PG8_MMA(1, 0, At, B0); PG8_MMA(1, 1, At, B1); PG8_BAR; PG8_SCHED;
;             PG8_LDB(B0, 1, 0); PG8_LDB(B1, 1, 1); PG8_SCHED; PG8_LDA(At, 1, 0); PG8_STAGE(PG8_SA(0, 1), a2 + hstepA, voffA);
;             PG8_WAIT_V(8); PG8_WAIT_L(0); PG8_BAR; PG8_MMA(0, 0, At, B0); PG8_MMA(0, 1, At, B1); PG8_BAR; PG8_SCHED;
;             PG8_LDA(At, 1, 1); PG8_STAGE(PG8_SB(1, 0), b3, voffB); PG8_STAGE(PG8_SB(1, 1), b3 + hstepB, voffB); PG8_STAGE(PG8_SA(1, 0), a3, voffA);
;             PG8_WAIT_V(8); PG8_WAIT_L(0); PG8_BAR; PG8_MMA(1, 0, At, B0); PG8_MMA(1, 1, At, B1); PG8_BAR; PG8_SCHED;
.LBB0_275:
	s_add_u32 s28, s26, 0xfffc0080
	s_addc_u32 s29, s27, -1
	s_add_i32 s51, 0, 0x10000
	s_cmp_eq_u32 s50, 12
	s_cselect_b32 s31, s9, s29
	s_cselect_b32 s30, s21, s28
	s_cselect_b32 s29, s19, s47
	s_cselect_b32 s28, s45, s46
	s_add_i32 s56, 0, 0x14000
	v_add_u32_e32 v44, s51, v163
	v_add_u32_e32 v158, s56, v163
	ds_read_b128 v[24:27], v44
	ds_read_b128 v[28:31], v44 offset:1024
	ds_read_b128 v[36:39], v44 offset:2048
	ds_read_b128 v[44:47], v44 offset:3072
	ds_read_b128 v[154:157], v158
	ds_read_b128 v[166:169], v158 offset:1024
	ds_read_b128 v[174:177], v158 offset:2048
	ds_read_b128 v[178:181], v158 offset:3072
	v_lshl_add_u64 v[160:161], s[26:27], 0, v[150:151]
	s_add_i32 m0, s3, 0xc000
	ds_read_b128 v[182:185], v165
	ds_read_b128 v[192:195], v165 offset:1024
	ds_read_b128 v[196:199], v165 offset:2048
	ds_read_b128 v[200:203], v165 offset:3072
	ds_read_b128 v[204:207], v165 offset:4096
	ds_read_b128 v[208:211], v165 offset:5120
	ds_read_b128 v[212:215], v165 offset:6144
	ds_read_b128 v[216:219], v165 offset:7168
	global_load_lds_dwordx4 v[160:161], off
	v_lshl_add_u64 v[160:161], s[26:27], 0, v[152:153]
	s_add_i32 m0, s3, 0xe000
	s_nop 0
	global_load_lds_dwordx4 v[160:161], off
	s_waitcnt vmcnt(8)
	s_waitcnt lgkmcnt(0)
	s_barrier
	s_waitcnt lgkmcnt(0)
	v_mfma_f32_16x16x32_bf16 v[140:143], v[24:27], v[182:185], v[140:143]
	v_mfma_f32_16x16x32_bf16 v[136:139], v[36:39], v[182:185], v[136:139]
	v_mfma_f32_16x16x32_bf16 v[124:127], v[24:27], v[196:199], v[124:127]
	v_mfma_f32_16x16x32_bf16 v[120:123], v[36:39], v[196:199], v[120:123]
	v_mfma_f32_16x16x32_bf16 v[108:111], v[24:27], v[204:207], v[108:111]
	v_mfma_f32_16x16x32_bf16 v[104:107], v[36:39], v[204:207], v[104:107]
	v_mfma_f32_16x16x32_bf16 v[92:95], v[24:27], v[212:215], v[92:95]
	v_mfma_f32_16x16x32_bf16 v[88:91], v[36:39], v[212:215], v[88:91]
	v_mfma_f32_16x16x32_bf16 v[140:143], v[28:31], v[192:195], v[140:143]
	v_mfma_f32_16x16x32_bf16 v[136:139], v[44:47], v[192:195], v[136:139]
	v_mfma_f32_16x16x32_bf16 v[124:127], v[28:31], v[200:203], v[124:127]
	v_mfma_f32_16x16x32_bf16 v[120:123], v[44:47], v[200:203], v[120:123]
	v_mfma_f32_16x16x32_bf16 v[108:111], v[28:31], v[208:211], v[108:111]
	v_mfma_f32_16x16x32_bf16 v[104:107], v[44:47], v[208:211], v[104:107]
	v_mfma_f32_16x16x32_bf16 v[92:95], v[28:31], v[216:219], v[92:95]
	v_mfma_f32_16x16x32_bf16 v[88:91], v[44:47], v[216:219], v[88:91]
	v_mfma_f32_16x16x32_bf16 v[132:135], v[154:157], v[182:185], v[132:135]
	v_mfma_f32_16x16x32_bf16 v[128:131], v[174:177], v[182:185], v[128:131]
	v_mfma_f32_16x16x32_bf16 v[116:119], v[154:157], v[196:199], v[116:119]
	v_mfma_f32_16x16x32_bf16 v[112:115], v[174:177], v[196:199], v[112:115]
	v_mfma_f32_16x16x32_bf16 v[100:103], v[154:157], v[204:207], v[100:103]
	v_mfma_f32_16x16x32_bf16 v[96:99], v[174:177], v[204:207], v[96:99]
	v_mfma_f32_16x16x32_bf16 v[84:87], v[154:157], v[212:215], v[84:87]
	v_mfma_f32_16x16x32_bf16 v[80:83], v[174:177], v[212:215], v[80:83]
	v_mfma_f32_16x16x32_bf16 v[132:135], v[166:169], v[192:195], v[132:135]
	v_mfma_f32_16x16x32_bf16 v[128:131], v[178:181], v[192:195], v[128:131]
	v_mfma_f32_16x16x32_bf16 v[116:119], v[166:169], v[200:203], v[116:119]
	v_mfma_f32_16x16x32_bf16 v[112:115], v[178:181], v[200:203], v[112:115]
	v_mfma_f32_16x16x32_bf16 v[100:103], v[166:169], v[208:211], v[100:103]
	v_mfma_f32_16x16x32_bf16 v[96:99], v[178:181], v[208:211], v[96:99]
	v_mfma_f32_16x16x32_bf16 v[84:87], v[166:169], v[216:219], v[84:87]
	v_mfma_f32_16x16x32_bf16 v[80:83], v[178:181], v[216:219], v[80:83]
	s_barrier
	s_add_i32 s51, s51, s2
	v_lshl_add_u64 v[160:161], s[28:29], 0, v[172:173]
	s_mov_b32 m0, s51
	ds_read_b128 v[182:185], v165 offset:16384
	ds_read_b128 v[192:195], v165 offset:17408
	ds_read_b128 v[196:199], v165 offset:18432
	ds_read_b128 v[200:203], v165 offset:19456
	ds_read_b128 v[204:207], v165 offset:20480
	ds_read_b128 v[208:211], v165 offset:21504
	ds_read_b128 v[212:215], v165 offset:22528
	ds_read_b128 v[216:219], v165 offset:23552
	global_load_lds_dwordx4 v[160:161], off
	s_add_i32 m0, s51, 0x2000
	s_add_u32 s52, s28, 0x10000
	v_lshl_add_u64 v[170:171], s[28:29], 0, v[148:149]
	s_addc_u32 s53, s29, 0
	s_add_i32 s51, s56, s2
	global_load_lds_dwordx4 v[170:171], off
	v_lshl_add_u64 v[186:187], s[52:53], 0, v[172:173]
	s_mov_b32 m0, s51
	v_lshl_add_u64 v[220:221], s[30:31], 0, v[146:147]
	global_load_lds_dwordx4 v[186:187], off
	v_lshl_add_u64 v[186:187], s[52:53], 0, v[148:149]
	s_add_i32 m0, s51, 0x2000
	s_nop 0
	global_load_lds_dwordx4 v[186:187], off
	v_lshl_add_u64 v[186:187], s[30:31], 0, v[144:145]
	s_mov_b32 m0, s3
	s_nop 0
	global_load_lds_dwordx4 v[186:187], off
	s_mov_b32 m0, s25
	s_nop 0
	global_load_lds_dwordx4 v[220:221], off
	s_waitcnt vmcnt(8)
	s_waitcnt lgkmcnt(0)
	s_barrier
; #define PG8_STAGE(bufoff, gbase, voff) do { _Pragma("unroll") for (int _i = 0; _i < 2; ++_i) \
;         __builtin_amdgcn_global_load_lds((const unsigned*)((const char*)(gbase) + (voff)[_i]), (PG8_LAS unsigned*)(lds + (bufoff) + ldsw + _i * 8192), 16, 0, 0); } while (0)
; #define PG8_LDA(dst, b, h) do { _Pragma("unroll") for (int m = 0; m < 4; ++m) _Pragma("unroll") for (int k = 0; k < 2; ++k) dst[m][k] = *(const PG8_LAS bf16x8*)(lds + PG8_SA(b, h) + aoff + m * 2048 + k * 1024); } while (0)
; #define PG8_LDB(dst, b, h) do { _Pragma("unroll") for (int n = 0; n < 2; ++n) _Pragma("unroll") for (int k = 0; k < 2; ++k) dst[n][k] = *(const PG8_LAS bf16x8*)(lds + PG8_SB(b, h) + boff + n * 2048 + k * 1024); } while (0)
; #define PG8_MMA(ai, bj, At, Bt) do { __builtin_amdgcn_s_setprio(1); _Pragma("unroll") for (int m = 0; m < 4; ++m) _Pragma("unroll") for (int n = 0; n < 2; ++n) _Pragma("unroll") for (int k = 0; k < 2; ++k) \
;         acc[ai][bj][m][n] = __builtin_amdgcn_mfma_f32_16x16x32_bf16(Bt[n][k], At[m][k], acc[ai][bj][m][n], 0, 0, 0); __builtin_amdgcn_s_setprio(0); } while (0)
; template <class Epi, class Sched, bool ALIGN_EPI = false, bool SP2 = false>
; __device__ __forceinline__ void gemm_phase(PG8_LAS unsigned char* lds, const Gemm g, const Sched& S, const Epi& E) {
;     ...
;             if constexpr (SP2) {
;             PG8_LDB(B0, 0, 0); PG8_LDB(B1, 0, 1); PG8_SCHED; PG8_LDA(At, 0, 0); PG8_STAGE(PG8_SA(1, 1), a1 + hstepA, voffA);
;             PG8_WAIT_V(8); PG8_WAIT_L(0); PG8_BAR; PG8_MMA(0, 0, At, B0); PG8_MMA(0, 1, At, B1); PG8_BAR; PG8_SCHED;
;             PG8_LDA(At, 0, 1); PG8_STAGE(PG8_SB(0, 0), b2, voffB); PG8_STAGE(PG8_SB(0, 1), b2 + hstepB, voffB); PG8_STAGE(PG8_SA(0, 0), a2, voffA);
;             PG8_WAIT_V(8); PG8_WAIT_L(0); PG8_BAR; PG8_MMA(1, 0, At, B0); PG8_MMA(1, 1, At, B1); PG8_BAR; PG8_SCHED;
;             PG8_LDB(B0, 1, 0); PG8_LDB(B1, 1, 1); PG8_SCHED; PG8_LDA(At, 1, 0); PG8_STAGE(PG8_SA(0, 1), a2 + hstepA, voffA);
;             PG8_WAIT_V(8); PG8_WAIT_L(0); PG8_BAR; PG8_MMA(0, 0, At, B0); PG8_MMA(0, 1, At, B1); PG8_BAR; PG8_SCHED;
;             PG8_LDA(At, 1, 1); PG8_STAGE(PG8_SB(1, 0), b3, voffB); PG8_STAGE(PG8_SB(1, 1), b3 + hstepB, voffB); PG8_STAGE(PG8_SA(1, 0), a3, voffA);
;             PG8_WAIT_V(8); PG8_WAIT_L(0); PG8_BAR; PG8_MMA(1, 0, At, B0); PG8_MMA(1, 1, At, B1); PG8_BAR; PG8_SCHED;
	s_waitcnt lgkmcnt(0)
	v_mfma_f32_16x16x32_bf16 v[76:79], v[24:27], v[182:185], v[76:79]
	v_mfma_f32_16x16x32_bf16 v[72:75], v[36:39], v[182:185], v[72:75]
	v_mfma_f32_16x16x32_bf16 v[60:63], v[24:27], v[196:199], v[60:63]
	v_mfma_f32_16x16x32_bf16 v[56:59], v[36:39], v[196:199], v[56:59]
	v_mfma_f32_16x16x32_bf16 v[40:43], v[24:27], v[204:207], v[40:43]
	v_mfma_f32_16x16x32_bf16 v[32:35], v[36:39], v[204:207], v[32:35]
	v_mfma_f32_16x16x32_bf16 v[12:15], v[24:27], v[212:215], v[12:15]
	v_mfma_f32_16x16x32_bf16 v[8:11], v[36:39], v[212:215], v[8:11]
	v_mfma_f32_16x16x32_bf16 v[76:79], v[28:31], v[192:195], v[76:79]
	v_mfma_f32_16x16x32_bf16 v[72:75], v[44:47], v[192:195], v[72:75]
	v_mfma_f32_16x16x32_bf16 v[60:63], v[28:31], v[200:203], v[60:63]
	v_mfma_f32_16x16x32_bf16 v[56:59], v[44:47], v[200:203], v[56:59]
	v_mfma_f32_16x16x32_bf16 v[40:43], v[28:31], v[208:211], v[40:43]
	v_mfma_f32_16x16x32_bf16 v[32:35], v[44:47], v[208:211], v[32:35]
	v_mfma_f32_16x16x32_bf16 v[12:15], v[28:31], v[216:219], v[12:15]
	v_mfma_f32_16x16x32_bf16 v[8:11], v[44:47], v[216:219], v[8:11]
	v_mfma_f32_16x16x32_bf16 v[20:23], v[154:157], v[204:207], v[20:23]
	v_mfma_f32_16x16x32_bf16 v[16:19], v[174:177], v[204:207], v[16:19]
	v_mfma_f32_16x16x32_bf16 v[4:7], v[154:157], v[212:215], v[4:7]
	v_mfma_f32_16x16x32_bf16 v[0:3], v[174:177], v[212:215], v[0:3]
	v_mfma_f32_16x16x32_bf16 v[24:27], v[154:157], v[182:185], v[68:71]
	v_mfma_f32_16x16x32_bf16 v[28:31], v[174:177], v[182:185], v[64:67]
	v_mfma_f32_16x16x32_bf16 v[36:39], v[154:157], v[196:199], v[52:55]
	v_mfma_f32_16x16x32_bf16 v[44:47], v[174:177], v[196:199], v[48:51]
	v_mfma_f32_16x16x32_bf16 v[20:23], v[166:169], v[208:211], v[20:23]
	v_mfma_f32_16x16x32_bf16 v[16:19], v[178:181], v[208:211], v[16:19]
	v_mfma_f32_16x16x32_bf16 v[4:7], v[166:169], v[216:219], v[4:7]
	v_mfma_f32_16x16x32_bf16 v[0:3], v[178:181], v[216:219], v[0:3]
	v_mfma_f32_16x16x32_bf16 v[24:27], v[166:169], v[192:195], v[24:27]
	v_mfma_f32_16x16x32_bf16 v[28:31], v[178:181], v[192:195], v[28:31]
	v_mfma_f32_16x16x32_bf16 v[36:39], v[166:169], v[200:203], v[36:39]
	v_mfma_f32_16x16x32_bf16 v[44:47], v[178:181], v[200:203], v[44:47]
	s_barrier
	s_add_i32 s51, 0, 0x18000
	s_add_i32 s52, 0, 0x1c000
	v_add_u32_e32 v68, s51, v163
	v_add_u32_e32 v158, s52, v163
	ds_read_b128 v[48:51], v68
	ds_read_b128 v[52:55], v68 offset:1024
	ds_read_b128 v[64:67], v68 offset:2048
	ds_read_b128 v[68:71], v68 offset:3072
	ds_read_b128 v[154:157], v158
	ds_read_b128 v[166:169], v158 offset:1024
	ds_read_b128 v[174:177], v158 offset:2048
	ds_read_b128 v[178:181], v158 offset:3072
	s_add_u32 s30, s30, 0x40000
	s_addc_u32 s31, s31, 0
	s_mov_b32 m0, s40
	v_lshl_add_u64 v[222:223], s[30:31], 0, v[144:145]
	ds_read_b128 v[182:185], v165 offset:32768
	ds_read_b128 v[192:195], v165 offset:33792
	ds_read_b128 v[196:199], v165 offset:34816
	ds_read_b128 v[200:203], v165 offset:35840
	ds_read_b128 v[204:207], v165 offset:36864
	ds_read_b128 v[208:211], v165 offset:37888
	ds_read_b128 v[212:215], v165 offset:38912
	ds_read_b128 v[216:219], v165 offset:39936
	global_load_lds_dwordx4 v[222:223], off
	v_lshl_add_u64 v[222:223], s[30:31], 0, v[146:147]
	s_mov_b32 m0, s41
	s_nop 0
	global_load_lds_dwordx4 v[222:223], off
	s_waitcnt vmcnt(8)
	s_waitcnt lgkmcnt(0)
	s_barrier
	s_waitcnt lgkmcnt(0)
	v_mfma_f32_16x16x32_bf16 v[140:143], v[48:51], v[182:185], v[140:143]
	v_mfma_f32_16x16x32_bf16 v[136:139], v[64:67], v[182:185], v[136:139]
	v_mfma_f32_16x16x32_bf16 v[124:127], v[48:51], v[196:199], v[124:127]
	v_mfma_f32_16x16x32_bf16 v[120:123], v[64:67], v[196:199], v[120:123]
	v_mfma_f32_16x16x32_bf16 v[108:111], v[48:51], v[204:207], v[108:111]
	v_mfma_f32_16x16x32_bf16 v[104:107], v[64:67], v[204:207], v[104:107]
	v_mfma_f32_16x16x32_bf16 v[92:95], v[48:51], v[212:215], v[92:95]
	v_mfma_f32_16x16x32_bf16 v[88:91], v[64:67], v[212:215], v[88:91]
	v_mfma_f32_16x16x32_bf16 v[140:143], v[52:55], v[192:195], v[140:143]
	v_mfma_f32_16x16x32_bf16 v[136:139], v[68:71], v[192:195], v[136:139]
	v_mfma_f32_16x16x32_bf16 v[124:127], v[52:55], v[200:203], v[124:127]
	v_mfma_f32_16x16x32_bf16 v[120:123], v[68:71], v[200:203], v[120:123]
	v_mfma_f32_16x16x32_bf16 v[108:111], v[52:55], v[208:211], v[108:111]
	v_mfma_f32_16x16x32_bf16 v[104:107], v[68:71], v[208:211], v[104:107]
	v_mfma_f32_16x16x32_bf16 v[92:95], v[52:55], v[216:219], v[92:95]
	v_mfma_f32_16x16x32_bf16 v[88:91], v[68:71], v[216:219], v[88:91]
	v_mfma_f32_16x16x32_bf16 v[132:135], v[154:157], v[182:185], v[132:135]
	v_mfma_f32_16x16x32_bf16 v[128:131], v[174:177], v[182:185], v[128:131]
	v_mfma_f32_16x16x32_bf16 v[116:119], v[154:157], v[196:199], v[116:119]
	v_mfma_f32_16x16x32_bf16 v[112:115], v[174:177], v[196:199], v[112:115]
	v_mfma_f32_16x16x32_bf16 v[100:103], v[154:157], v[204:207], v[100:103]
	v_mfma_f32_16x16x32_bf16 v[96:99], v[174:177], v[204:207], v[96:99]
	v_mfma_f32_16x16x32_bf16 v[84:87], v[154:157], v[212:215], v[84:87]
	v_mfma_f32_16x16x32_bf16 v[80:83], v[174:177], v[212:215], v[80:83]
	v_mfma_f32_16x16x32_bf16 v[132:135], v[166:169], v[192:195], v[132:135]
	v_mfma_f32_16x16x32_bf16 v[128:131], v[178:181], v[192:195], v[128:131]
	v_mfma_f32_16x16x32_bf16 v[116:119], v[166:169], v[200:203], v[116:119]
	v_mfma_f32_16x16x32_bf16 v[112:115], v[178:181], v[200:203], v[112:115]
	v_mfma_f32_16x16x32_bf16 v[100:103], v[166:169], v[208:211], v[100:103]
	v_mfma_f32_16x16x32_bf16 v[96:99], v[178:181], v[208:211], v[96:99]
	v_mfma_f32_16x16x32_bf16 v[84:87], v[166:169], v[216:219], v[84:87]
	v_mfma_f32_16x16x32_bf16 v[80:83], v[178:181], v[216:219], v[80:83]
	s_barrier
; template <class Epi, class Sched, bool ALIGN_EPI = false, bool SP2 = false>
; __device__ __forceinline__ void gemm_phase(PG8_LAS unsigned char* lds, const Gemm g, const Sched& S, const Epi& E) {
;     ...
;             if constexpr (SP2) {
;             PG8_LDB(B0, 0, 0); PG8_LDB(B1, 0, 1); PG8_SCHED; PG8_LDA(At, 0, 0); PG8_STAGE(PG8_SA(1, 1), a1 + hstepA, voffA);
;             PG8_WAIT_V(8); PG8_WAIT_L(0); PG8_BAR; PG8_MMA(0, 0, At, B0); PG8_MMA(0, 1, At, B1); PG8_BAR; PG8_SCHED;
;             PG8_LDA(At, 0, 1); PG8_STAGE(PG8_SB(0, 0), b2, voffB); PG8_STAGE(PG8_SB(0, 1), b2 + hstepB, voffB); PG8_STAGE(PG8_SA(0, 0), a2, voffA);
;             PG8_WAIT_V(8); PG8_WAIT_L(0); PG8_BAR; PG8_MMA(1, 0, At, B0); PG8_MMA(1, 1, At, B1); PG8_BAR; PG8_SCHED;
;             PG8_LDB(B0, 1, 0); PG8_LDB(B1, 1, 1); PG8_SCHED; PG8_LDA(At, 1, 0); PG8_STAGE(PG8_SA(0, 1), a2 + hstepA, voffA);
;             PG8_WAIT_V(8); PG8_WAIT_L(0); PG8_BAR; PG8_MMA(0, 0, At, B0); PG8_MMA(0, 1, At, B1); PG8_BAR; PG8_SCHED;
;             PG8_LDA(At, 1, 1); PG8_STAGE(PG8_SB(1, 0), b3, voffB); PG8_STAGE(PG8_SB(1, 1), b3 + hstepB, voffB); PG8_STAGE(PG8_SA(1, 0), a3, voffA);
;             PG8_WAIT_V(8); PG8_WAIT_L(0); PG8_BAR; PG8_MMA(1, 0, At, B0); PG8_MMA(1, 1, At, B1); PG8_BAR; PG8_SCHED;
;             } else {
;             PG8_LDB(B0, 0, 0); PG8_SCHED; PG8_LDA(At, 0, 0); PG8_STAGE(PG8_SA(1, 1), a1 + hstepA, voffA);
;             PG8_WAIT_L(8); PG8_BAR; PG8_WAIT_L(0); PG8_MMA(0, 0, At, B0); PG8_BAR; PG8_SCHED;
;             PG8_LDB(B1, 0, 1); PG8_STAGE(PG8_SB(0, 0), b2, voffB);
;             PG8_BAR; PG8_WAIT_L(0); PG8_MMA(0, 1, At, B1); PG8_BAR;
;             PG8_LDA(At, 0, 1); PG8_STAGE(PG8_SA(0, 0), a2, voffA);
;             PG8_BAR; PG8_WAIT_L(0); PG8_MMA(1, 0, At, B0); PG8_BAR; PG8_SCHED;
;             PG8_STAGE(PG8_SB(0, 1), b2 + hstepB, voffB);
;             PG8_WAIT_V(6); PG8_BAR; PG8_MMA(1, 1, At, B1); PG8_BAR;
;             PG8_LDB(B0, 1, 0); PG8_SCHED; PG8_LDA(At, 1, 0); PG8_STAGE(PG8_SA(0, 1), a2 + hstepA, voffA);
;             PG8_WAIT_L(8); PG8_BAR; PG8_WAIT_L(0); PG8_MMA(0, 0, At, B0); PG8_BAR; PG8_SCHED;
;             PG8_LDB(B1, 1, 1); PG8_STAGE(PG8_SB(1, 0), b3, voffB);
;             PG8_BAR; PG8_WAIT_L(0); PG8_MMA(0, 1, At, B1); PG8_BAR;
;             PG8_LDA(At, 1, 1); PG8_STAGE(PG8_SA(1, 0), a3, voffA);
;             PG8_BAR; PG8_WAIT_L(0); PG8_MMA(1, 0, At, B0); PG8_BAR; PG8_SCHED;
	s_add_i32 s30, s51, s2
	v_lshl_add_u64 v[160:161], v[160:161], 0, s[80:81]
	s_mov_b32 m0, s30
	ds_read_b128 v[182:185], v165 offset:49152
	ds_read_b128 v[192:195], v165 offset:50176
	ds_read_b128 v[196:199], v165 offset:51200
	ds_read_b128 v[200:203], v165 offset:52224
	ds_read_b128 v[204:207], v165 offset:53248
	ds_read_b128 v[208:211], v165 offset:54272
	ds_read_b128 v[212:215], v165 offset:55296
	ds_read_b128 v[216:219], v165 offset:56320
	global_load_lds_dwordx4 v[160:161], off
	s_add_i32 m0, s30, 0x2000
	s_add_u32 s28, s28, 0x10080
	v_lshl_add_u64 v[160:161], v[170:171], 0, s[80:81]
	s_addc_u32 s29, s29, 0
	s_add_i32 s30, s52, s2
	global_load_lds_dwordx4 v[160:161], off
	v_lshl_add_u64 v[160:161], s[28:29], 0, v[172:173]
	s_mov_b32 m0, s30
	s_nop 0
	global_load_lds_dwordx4 v[160:161], off
	v_lshl_add_u64 v[160:161], s[28:29], 0, v[148:149]
	s_add_i32 m0, s30, 0x2000
	s_nop 0
	global_load_lds_dwordx4 v[160:161], off
	v_lshl_add_u64 v[160:161], v[186:187], 0, s[80:81]
	s_mov_b32 m0, s42
	s_nop 0
	global_load_lds_dwordx4 v[160:161], off
	v_lshl_add_u64 v[160:161], v[220:221], 0, s[80:81]
	s_mov_b32 m0, s43
	s_nop 0
	global_load_lds_dwordx4 v[160:161], off
	s_waitcnt vmcnt(8)
	s_waitcnt lgkmcnt(0)
	s_barrier
	s_waitcnt lgkmcnt(0)
	v_mfma_f32_16x16x32_bf16 v[76:79], v[48:51], v[182:185], v[76:79]
	v_mfma_f32_16x16x32_bf16 v[72:75], v[64:67], v[182:185], v[72:75]
	v_mfma_f32_16x16x32_bf16 v[60:63], v[48:51], v[196:199], v[60:63]
	v_mfma_f32_16x16x32_bf16 v[56:59], v[64:67], v[196:199], v[56:59]
	v_mfma_f32_16x16x32_bf16 v[40:43], v[48:51], v[204:207], v[40:43]
	v_mfma_f32_16x16x32_bf16 v[32:35], v[64:67], v[204:207], v[32:35]
	v_mfma_f32_16x16x32_bf16 v[12:15], v[48:51], v[212:215], v[12:15]
	v_mfma_f32_16x16x32_bf16 v[8:11], v[64:67], v[212:215], v[8:11]
	v_mfma_f32_16x16x32_bf16 v[76:79], v[52:55], v[192:195], v[76:79]
	v_mfma_f32_16x16x32_bf16 v[72:75], v[68:71], v[192:195], v[72:75]
	v_mfma_f32_16x16x32_bf16 v[60:63], v[52:55], v[200:203], v[60:63]
	v_mfma_f32_16x16x32_bf16 v[56:59], v[68:71], v[200:203], v[56:59]
	v_mfma_f32_16x16x32_bf16 v[40:43], v[52:55], v[208:211], v[40:43]
	v_mfma_f32_16x16x32_bf16 v[32:35], v[68:71], v[208:211], v[32:35]
	v_mfma_f32_16x16x32_bf16 v[12:15], v[52:55], v[216:219], v[12:15]
	v_mfma_f32_16x16x32_bf16 v[8:11], v[68:71], v[216:219], v[8:11]
	v_mfma_f32_16x16x32_bf16 v[24:27], v[154:157], v[182:185], v[24:27]
	v_mfma_f32_16x16x32_bf16 v[68:71], v[166:169], v[192:195], v[24:27]
	v_mfma_f32_16x16x32_bf16 v[24:27], v[174:177], v[182:185], v[28:31]
	v_mfma_f32_16x16x32_bf16 v[64:67], v[178:181], v[192:195], v[24:27]
	v_mfma_f32_16x16x32_bf16 v[24:27], v[154:157], v[196:199], v[36:39]
	v_mfma_f32_16x16x32_bf16 v[52:55], v[166:169], v[200:203], v[24:27]
	v_mfma_f32_16x16x32_bf16 v[24:27], v[174:177], v[196:199], v[44:47]
	v_mfma_f32_16x16x32_bf16 v[20:23], v[154:157], v[204:207], v[20:23]
	v_mfma_f32_16x16x32_bf16 v[16:19], v[174:177], v[204:207], v[16:19]
	v_mfma_f32_16x16x32_bf16 v[4:7], v[154:157], v[212:215], v[4:7]
	v_mfma_f32_16x16x32_bf16 v[0:3], v[174:177], v[212:215], v[0:3]
	v_mfma_f32_16x16x32_bf16 v[48:51], v[178:181], v[200:203], v[24:27]
	v_mfma_f32_16x16x32_bf16 v[20:23], v[166:169], v[208:211], v[20:23]
	v_mfma_f32_16x16x32_bf16 v[16:19], v[178:181], v[208:211], v[16:19]
	v_mfma_f32_16x16x32_bf16 v[4:7], v[166:169], v[216:219], v[4:7]
	v_mfma_f32_16x16x32_bf16 v[0:3], v[178:181], v[216:219], v[0:3]
	s_barrier
	s_add_i32 s50, s50, 2
	s_add_u32 s26, s26, 0x100
	s_addc_u32 s27, s27, 0
	s_add_u32 s46, s46, 0x100
	s_addc_u32 s47, s47, 0
	s_cmp_gt_u32 s50, 13
	s_cbranch_scc0 .LBB0_275
	s_and_b64 vcc, exec, s[16:17]
	s_cbranch_vccz .LBB0_278
	s_barrier

; #define PG8_STAGE(bufoff, gbase, voff) do { _Pragma("unroll") for (int _i = 0; _i < 2; ++_i) \
;         __builtin_amdgcn_global_load_lds((const unsigned*)((const char*)(gbase) + (voff)[_i]), (PG8_LAS unsigned*)(lds + (bufoff) + ldsw + _i * 8192), 16, 0, 0); } while (0)
; #define PG8_LDA(dst, b, h) do { _Pragma("unroll") for (int m = 0; m < 4; ++m) _Pragma("unroll") for (int k = 0; k < 2; ++k) dst[m][k] = *(const PG8_LAS bf16x8*)(lds + PG8_SA(b, h) + aoff + m * 2048 + k * 1024); } while (0)
; #define PG8_LDB(dst, b, h) do { _Pragma("unroll") for (int n = 0; n < 2; ++n) _Pragma("unroll") for (int k = 0; k < 2; ++k) dst[n][k] = *(const PG8_LAS bf16x8*)(lds + PG8_SB(b, h) + boff + n * 2048 + k * 1024); } while (0)
; #define PG8_MMA(ai, bj, At, Bt) do { __builtin_amdgcn_s_setprio(1); _Pragma("unroll") for (int m = 0; m < 4; ++m) _Pragma("unroll") for (int n = 0; n < 2; ++n) _Pragma("unroll") for (int k = 0; k < 2; ++k) \
;         acc[ai][bj][m][n] = __builtin_amdgcn_mfma_f32_16x16x32_bf16(Bt[n][k], At[m][k], acc[ai][bj][m][n], 0, 0, 0); __builtin_amdgcn_s_setprio(0); } while (0)
; template <class Epi, class Sched, bool ALIGN_EPI = false, bool SP2 = false>
; __device__ __forceinline__ void gemm_phase(PG8_LAS unsigned char* lds, const Gemm g, const Sched& S, const Epi& E) {
;     ...
;             if constexpr (SP2) {
;             PG8_LDB(B0, 0, 0); PG8_LDB(B1, 0, 1); PG8_SCHED; PG8_LDA(At, 0, 0); PG8_STAGE(PG8_SA(1, 1), a1 + hstepA, voffA);
;             PG8_WAIT_V(8); PG8_WAIT_L(0); PG8_BAR; PG8_MMA(0, 0, At, B0); PG8_MMA(0, 1, At, B1); PG8_BAR; PG8_SCHED;
;             PG8_LDA(At, 0, 1); PG8_STAGE(PG8_SB(0, 0), b2, voffB); PG8_STAGE(PG8_SB(0, 1), b2 + hstepB, voffB); PG8_STAGE(PG8_SA(0, 0), a2, voffA);
;             PG8_WAIT_V(8); PG8_WAIT_L(0); PG8_BAR; PG8_MMA(1, 0, At, B0); PG8_MMA(1, 1, At, B1); PG8_BAR; PG8_SCHED;
;             PG8_LDB(B0, 1, 0); PG8_LDB(B1, 1, 1); PG8_SCHED; PG8_LDA(At, 1, 0); PG8_STAGE(PG8_SA(0, 1), a2 + hstepA, voffA);
;             PG8_WAIT_V(8); PG8_WAIT_L(0); PG8_BAR; PG8_MMA(0, 0, At, B0); PG8_MMA(0, 1, At, B1); PG8_BAR; PG8_SCHED;
;             PG8_LDA(At, 1, 1); PG8_STAGE(PG8_SB(1, 0), b3, voffB); PG8_STAGE(PG8_SB(1, 1), b3 + hstepB, voffB); PG8_STAGE(PG8_SA(1, 0), a3, voffA);
;             PG8_WAIT_V(8); PG8_WAIT_L(0); PG8_BAR; PG8_MMA(1, 0, At, B0); PG8_MMA(1, 1, At, B1); PG8_BAR; PG8_SCHED;
.LBB0_330:
	s_add_u32 s56, s42, 0xfffc0080
	s_addc_u32 s57, s43, -1
	s_add_i32 s64, 0, 0x10000
	s_cmp_eq_u32 s87, 12
	s_cselect_b32 vcc_hi, s73, s57
	s_cselect_b32 vcc_lo, s75, s56
	s_cselect_b32 s71, s47, s89
	s_cselect_b32 s70, s86, s85
	s_add_i32 s52, 0, 0x14000
	v_add_u32_e32 v150, s64, v171
	v_add_u32_e32 v166, s52, v171
	ds_read_b128 v[138:141], v150
	ds_read_b128 v[142:145], v150 offset:1024
	ds_read_b128 v[146:149], v150 offset:2048
	ds_read_b128 v[150:153], v150 offset:3072
	ds_read_b128 v[154:157], v166
	ds_read_b128 v[158:161], v166 offset:1024
	ds_read_b128 v[162:165], v166 offset:2048
	ds_read_b128 v[166:169], v166 offset:3072
	v_lshl_add_u64 v[186:187], s[42:43], 0, v[134:135]
	s_add_i32 m0, s45, 0xc000
	ds_read_b128 v[174:177], v180
	ds_read_b128 v[182:185], v180 offset:1024
	ds_read_b128 v[192:195], v180 offset:2048
	ds_read_b128 v[196:199], v180 offset:3072
	ds_read_b128 v[200:203], v180 offset:4096
	ds_read_b128 v[204:207], v180 offset:5120
	ds_read_b128 v[208:211], v180 offset:6144
	ds_read_b128 v[212:215], v180 offset:7168
	global_load_lds_dwordx4 v[186:187], off
	v_lshl_add_u64 v[186:187], s[42:43], 0, v[136:137]
	s_add_i32 m0, s45, 0xe000
	s_nop 0
	global_load_lds_dwordx4 v[186:187], off
	s_waitcnt vmcnt(8)
	s_waitcnt lgkmcnt(0)
	s_barrier
	s_waitcnt lgkmcnt(0)
	v_mfma_f32_16x16x32_bf16 v[124:127], v[138:141], v[174:177], v[124:127]
	v_mfma_f32_16x16x32_bf16 v[120:123], v[146:149], v[174:177], v[120:123]
	v_mfma_f32_16x16x32_bf16 v[108:111], v[138:141], v[192:195], v[108:111]
	v_mfma_f32_16x16x32_bf16 v[104:107], v[146:149], v[192:195], v[104:107]
	v_mfma_f32_16x16x32_bf16 v[92:95], v[138:141], v[200:203], v[92:95]
	v_mfma_f32_16x16x32_bf16 v[88:91], v[146:149], v[200:203], v[88:91]
	v_mfma_f32_16x16x32_bf16 v[76:79], v[138:141], v[208:211], v[76:79]
	v_mfma_f32_16x16x32_bf16 v[72:75], v[146:149], v[208:211], v[72:75]
	v_mfma_f32_16x16x32_bf16 v[124:127], v[142:145], v[182:185], v[124:127]
	v_mfma_f32_16x16x32_bf16 v[120:123], v[150:153], v[182:185], v[120:123]
	v_mfma_f32_16x16x32_bf16 v[108:111], v[142:145], v[196:199], v[108:111]
	v_mfma_f32_16x16x32_bf16 v[104:107], v[150:153], v[196:199], v[104:107]
	v_mfma_f32_16x16x32_bf16 v[92:95], v[142:145], v[204:207], v[92:95]
	v_mfma_f32_16x16x32_bf16 v[88:91], v[150:153], v[204:207], v[88:91]
	v_mfma_f32_16x16x32_bf16 v[76:79], v[142:145], v[212:215], v[76:79]
	v_mfma_f32_16x16x32_bf16 v[72:75], v[150:153], v[212:215], v[72:75]
	v_mfma_f32_16x16x32_bf16 v[116:119], v[154:157], v[174:177], v[116:119]
	v_mfma_f32_16x16x32_bf16 v[112:115], v[162:165], v[174:177], v[112:115]
	v_mfma_f32_16x16x32_bf16 v[100:103], v[154:157], v[192:195], v[100:103]
	v_mfma_f32_16x16x32_bf16 v[96:99], v[162:165], v[192:195], v[96:99]
	v_mfma_f32_16x16x32_bf16 v[84:87], v[154:157], v[200:203], v[84:87]
	v_mfma_f32_16x16x32_bf16 v[80:83], v[162:165], v[200:203], v[80:83]
	v_mfma_f32_16x16x32_bf16 v[68:71], v[154:157], v[208:211], v[68:71]
	v_mfma_f32_16x16x32_bf16 v[64:67], v[162:165], v[208:211], v[64:67]
	v_mfma_f32_16x16x32_bf16 v[116:119], v[158:161], v[182:185], v[116:119]
	v_mfma_f32_16x16x32_bf16 v[112:115], v[166:169], v[182:185], v[112:115]
	v_mfma_f32_16x16x32_bf16 v[100:103], v[158:161], v[196:199], v[100:103]
	v_mfma_f32_16x16x32_bf16 v[96:99], v[166:169], v[196:199], v[96:99]
	v_mfma_f32_16x16x32_bf16 v[84:87], v[158:161], v[204:207], v[84:87]
	v_mfma_f32_16x16x32_bf16 v[80:83], v[166:169], v[204:207], v[80:83]
	v_mfma_f32_16x16x32_bf16 v[68:71], v[158:161], v[212:215], v[68:71]
	v_mfma_f32_16x16x32_bf16 v[64:67], v[166:169], v[212:215], v[64:67]
	s_barrier
	s_add_i32 s56, s64, s66
	v_lshl_add_u64 v[186:187], s[70:71], 0, v[172:173]
	s_mov_b32 m0, s56
	ds_read_b128 v[174:177], v180 offset:16384
	ds_read_b128 v[182:185], v180 offset:17408
	ds_read_b128 v[192:195], v180 offset:18432
	ds_read_b128 v[196:199], v180 offset:19456
	ds_read_b128 v[200:203], v180 offset:20480
	ds_read_b128 v[204:207], v180 offset:21504
	ds_read_b128 v[208:211], v180 offset:22528
	ds_read_b128 v[212:215], v180 offset:23552
	global_load_lds_dwordx4 v[186:187], off
	s_add_i32 m0, s56, 0x2000
	s_add_u32 s56, s70, 0x40000
	v_lshl_add_u64 v[216:217], s[70:71], 0, v[132:133]
	s_addc_u32 s57, s71, 0
	s_add_i32 s52, s52, s66
	global_load_lds_dwordx4 v[216:217], off
	v_lshl_add_u64 v[218:219], s[56:57], 0, v[172:173]
	s_mov_b32 m0, s52
	v_lshl_add_u64 v[220:221], vcc, 0, v[130:131]
	global_load_lds_dwordx4 v[218:219], off
	v_lshl_add_u64 v[218:219], s[56:57], 0, v[132:133]
	s_add_i32 m0, s52, 0x2000
	s_nop 0
	global_load_lds_dwordx4 v[218:219], off
	v_lshl_add_u64 v[218:219], vcc, 0, v[128:129]
	s_mov_b32 m0, s45
	s_nop 0
	global_load_lds_dwordx4 v[218:219], off
	s_mov_b32 m0, s93
	s_nop 0
	global_load_lds_dwordx4 v[220:221], off
	s_waitcnt vmcnt(8)
	s_waitcnt lgkmcnt(0)
	s_barrier
; #define PG8_STAGE(bufoff, gbase, voff) do { _Pragma("unroll") for (int _i = 0; _i < 2; ++_i) \
;         __builtin_amdgcn_global_load_lds((const unsigned*)((const char*)(gbase) + (voff)[_i]), (PG8_LAS unsigned*)(lds + (bufoff) + ldsw + _i * 8192), 16, 0, 0); } while (0)
; #define PG8_LDA(dst, b, h) do { _Pragma("unroll") for (int m = 0; m < 4; ++m) _Pragma("unroll") for (int k = 0; k < 2; ++k) dst[m][k] = *(const PG8_LAS bf16x8*)(lds + PG8_SA(b, h) + aoff + m * 2048 + k * 1024); } while (0)
; #define PG8_LDB(dst, b, h) do { _Pragma("unroll") for (int n = 0; n < 2; ++n) _Pragma("unroll") for (int k = 0; k < 2; ++k) dst[n][k] = *(const PG8_LAS bf16x8*)(lds + PG8_SB(b, h) + boff + n * 2048 + k * 1024); } while (0)
; #define PG8_MMA(ai, bj, At, Bt) do { __builtin_amdgcn_s_setprio(1); _Pragma("unroll") for (int m = 0; m < 4; ++m) _Pragma("unroll") for (int n = 0; n < 2; ++n) _Pragma("unroll") for (int k = 0; k < 2; ++k) \
;         acc[ai][bj][m][n] = __builtin_amdgcn_mfma_f32_16x16x32_bf16(Bt[n][k], At[m][k], acc[ai][bj][m][n], 0, 0, 0); __builtin_amdgcn_s_setprio(0); } while (0)
; template <class Epi, class Sched, bool ALIGN_EPI = false, bool SP2 = false>
; __device__ __forceinline__ void gemm_phase(PG8_LAS unsigned char* lds, const Gemm g, const Sched& S, const Epi& E) {
;     ...
;             if constexpr (SP2) {
;             PG8_LDB(B0, 0, 0); PG8_LDB(B1, 0, 1); PG8_SCHED; PG8_LDA(At, 0, 0); PG8_STAGE(PG8_SA(1, 1), a1 + hstepA, voffA);
;             PG8_WAIT_V(8); PG8_WAIT_L(0); PG8_BAR; PG8_MMA(0, 0, At, B0); PG8_MMA(0, 1, At, B1); PG8_BAR; PG8_SCHED;
;             PG8_LDA(At, 0, 1); PG8_STAGE(PG8_SB(0, 0), b2, voffB); PG8_STAGE(PG8_SB(0, 1), b2 + hstepB, voffB); PG8_STAGE(PG8_SA(0, 0), a2, voffA);
;             PG8_WAIT_V(8); PG8_WAIT_L(0); PG8_BAR; PG8_MMA(1, 0, At, B0); PG8_MMA(1, 1, At, B1); PG8_BAR; PG8_SCHED;
;             PG8_LDB(B0, 1, 0); PG8_LDB(B1, 1, 1); PG8_SCHED; PG8_LDA(At, 1, 0); PG8_STAGE(PG8_SA(0, 1), a2 + hstepA, voffA);
;             PG8_WAIT_V(8); PG8_WAIT_L(0); PG8_BAR; PG8_MMA(0, 0, At, B0); PG8_MMA(0, 1, At, B1); PG8_BAR; PG8_SCHED;
;             PG8_LDA(At, 1, 1); PG8_STAGE(PG8_SB(1, 0), b3, voffB); PG8_STAGE(PG8_SB(1, 1), b3 + hstepB, voffB); PG8_STAGE(PG8_SA(1, 0), a3, voffA);
;             PG8_WAIT_V(8); PG8_WAIT_L(0); PG8_BAR; PG8_MMA(1, 0, At, B0); PG8_MMA(1, 1, At, B1); PG8_BAR; PG8_SCHED;
	s_waitcnt lgkmcnt(0)
	v_mfma_f32_16x16x32_bf16 v[60:63], v[138:141], v[174:177], v[60:63]
	v_mfma_f32_16x16x32_bf16 v[56:59], v[146:149], v[174:177], v[56:59]
	v_mfma_f32_16x16x32_bf16 v[44:47], v[138:141], v[192:195], v[44:47]
	v_mfma_f32_16x16x32_bf16 v[40:43], v[146:149], v[192:195], v[40:43]
	v_mfma_f32_16x16x32_bf16 v[28:31], v[138:141], v[200:203], v[28:31]
	v_mfma_f32_16x16x32_bf16 v[24:27], v[146:149], v[200:203], v[24:27]
	v_mfma_f32_16x16x32_bf16 v[12:15], v[138:141], v[208:211], v[12:15]
	v_mfma_f32_16x16x32_bf16 v[8:11], v[146:149], v[208:211], v[8:11]
	v_mfma_f32_16x16x32_bf16 v[60:63], v[142:145], v[182:185], v[60:63]
	v_mfma_f32_16x16x32_bf16 v[56:59], v[150:153], v[182:185], v[56:59]
	v_mfma_f32_16x16x32_bf16 v[44:47], v[142:145], v[196:199], v[44:47]
	v_mfma_f32_16x16x32_bf16 v[40:43], v[150:153], v[196:199], v[40:43]
	v_mfma_f32_16x16x32_bf16 v[28:31], v[142:145], v[204:207], v[28:31]
	v_mfma_f32_16x16x32_bf16 v[24:27], v[150:153], v[204:207], v[24:27]
	v_mfma_f32_16x16x32_bf16 v[12:15], v[142:145], v[212:215], v[12:15]
	v_mfma_f32_16x16x32_bf16 v[8:11], v[150:153], v[212:215], v[8:11]
	v_mfma_f32_16x16x32_bf16 v[52:55], v[154:157], v[174:177], v[52:55]
	v_mfma_f32_16x16x32_bf16 v[48:51], v[162:165], v[174:177], v[48:51]
	v_mfma_f32_16x16x32_bf16 v[36:39], v[154:157], v[192:195], v[36:39]
	v_mfma_f32_16x16x32_bf16 v[32:35], v[162:165], v[192:195], v[32:35]
	v_mfma_f32_16x16x32_bf16 v[20:23], v[154:157], v[200:203], v[20:23]
	v_mfma_f32_16x16x32_bf16 v[16:19], v[162:165], v[200:203], v[16:19]
	v_mfma_f32_16x16x32_bf16 v[4:7], v[154:157], v[208:211], v[4:7]
	v_mfma_f32_16x16x32_bf16 v[0:3], v[162:165], v[208:211], v[0:3]
	v_mfma_f32_16x16x32_bf16 v[52:55], v[158:161], v[182:185], v[52:55]
	v_mfma_f32_16x16x32_bf16 v[48:51], v[166:169], v[182:185], v[48:51]
	v_mfma_f32_16x16x32_bf16 v[36:39], v[158:161], v[196:199], v[36:39]
	v_mfma_f32_16x16x32_bf16 v[32:35], v[166:169], v[196:199], v[32:35]
	v_mfma_f32_16x16x32_bf16 v[20:23], v[158:161], v[204:207], v[20:23]
	v_mfma_f32_16x16x32_bf16 v[16:19], v[166:169], v[204:207], v[16:19]
	v_mfma_f32_16x16x32_bf16 v[4:7], v[158:161], v[212:215], v[4:7]
	v_mfma_f32_16x16x32_bf16 v[0:3], v[166:169], v[212:215], v[0:3]
	s_barrier
	s_add_i32 s52, 0, 0x18000
	s_add_i32 s64, 0, 0x1c000
	v_add_u32_e32 v150, s52, v171
	v_add_u32_e32 v166, s64, v171
	ds_read_b128 v[138:141], v150
	ds_read_b128 v[142:145], v150 offset:1024
	ds_read_b128 v[146:149], v150 offset:2048
	ds_read_b128 v[150:153], v150 offset:3072
	ds_read_b128 v[154:157], v166
	ds_read_b128 v[158:161], v166 offset:1024
	ds_read_b128 v[162:165], v166 offset:2048
	ds_read_b128 v[166:169], v166 offset:3072
	s_add_u32 s56, vcc_lo, 0x40000
	s_addc_u32 s57, vcc_hi, 0
	s_mov_b32 m0, s95
	v_lshl_add_u64 v[222:223], s[56:57], 0, v[128:129]
	ds_read_b128 v[174:177], v180 offset:32768
	ds_read_b128 v[182:185], v180 offset:33792
	ds_read_b128 v[192:195], v180 offset:34816
	ds_read_b128 v[196:199], v180 offset:35840
	ds_read_b128 v[200:203], v180 offset:36864
	ds_read_b128 v[204:207], v180 offset:37888
	ds_read_b128 v[208:211], v180 offset:38912
	ds_read_b128 v[212:215], v180 offset:39936
	global_load_lds_dwordx4 v[222:223], off
	v_lshl_add_u64 v[222:223], s[56:57], 0, v[130:131]
	s_mov_b32 m0, s96
	s_nop 0
	global_load_lds_dwordx4 v[222:223], off
	s_waitcnt vmcnt(8)
	s_waitcnt lgkmcnt(0)
	s_barrier
	s_waitcnt lgkmcnt(0)
	v_mfma_f32_16x16x32_bf16 v[124:127], v[138:141], v[174:177], v[124:127]
	v_mfma_f32_16x16x32_bf16 v[120:123], v[146:149], v[174:177], v[120:123]
	v_mfma_f32_16x16x32_bf16 v[108:111], v[138:141], v[192:195], v[108:111]
	v_mfma_f32_16x16x32_bf16 v[104:107], v[146:149], v[192:195], v[104:107]
	v_mfma_f32_16x16x32_bf16 v[92:95], v[138:141], v[200:203], v[92:95]
	v_mfma_f32_16x16x32_bf16 v[88:91], v[146:149], v[200:203], v[88:91]
	v_mfma_f32_16x16x32_bf16 v[76:79], v[138:141], v[208:211], v[76:79]
	v_mfma_f32_16x16x32_bf16 v[72:75], v[146:149], v[208:211], v[72:75]
	v_mfma_f32_16x16x32_bf16 v[124:127], v[142:145], v[182:185], v[124:127]
	v_mfma_f32_16x16x32_bf16 v[120:123], v[150:153], v[182:185], v[120:123]
	v_mfma_f32_16x16x32_bf16 v[108:111], v[142:145], v[196:199], v[108:111]
	v_mfma_f32_16x16x32_bf16 v[104:107], v[150:153], v[196:199], v[104:107]
	v_mfma_f32_16x16x32_bf16 v[92:95], v[142:145], v[204:207], v[92:95]
	v_mfma_f32_16x16x32_bf16 v[88:91], v[150:153], v[204:207], v[88:91]
	v_mfma_f32_16x16x32_bf16 v[76:79], v[142:145], v[212:215], v[76:79]
	v_mfma_f32_16x16x32_bf16 v[72:75], v[150:153], v[212:215], v[72:75]
	v_mfma_f32_16x16x32_bf16 v[116:119], v[154:157], v[174:177], v[116:119]
	v_mfma_f32_16x16x32_bf16 v[112:115], v[162:165], v[174:177], v[112:115]
	v_mfma_f32_16x16x32_bf16 v[100:103], v[154:157], v[192:195], v[100:103]
	v_mfma_f32_16x16x32_bf16 v[96:99], v[162:165], v[192:195], v[96:99]
	v_mfma_f32_16x16x32_bf16 v[84:87], v[154:157], v[200:203], v[84:87]
	v_mfma_f32_16x16x32_bf16 v[80:83], v[162:165], v[200:203], v[80:83]
	v_mfma_f32_16x16x32_bf16 v[68:71], v[154:157], v[208:211], v[68:71]
	v_mfma_f32_16x16x32_bf16 v[64:67], v[162:165], v[208:211], v[64:67]
	v_mfma_f32_16x16x32_bf16 v[116:119], v[158:161], v[182:185], v[116:119]
	v_mfma_f32_16x16x32_bf16 v[112:115], v[166:169], v[182:185], v[112:115]
	v_mfma_f32_16x16x32_bf16 v[100:103], v[158:161], v[196:199], v[100:103]
	v_mfma_f32_16x16x32_bf16 v[96:99], v[166:169], v[196:199], v[96:99]
	v_mfma_f32_16x16x32_bf16 v[84:87], v[158:161], v[204:207], v[84:87]
	v_mfma_f32_16x16x32_bf16 v[80:83], v[166:169], v[204:207], v[80:83]
	v_mfma_f32_16x16x32_bf16 v[68:71], v[158:161], v[212:215], v[68:71]
	v_mfma_f32_16x16x32_bf16 v[64:67], v[166:169], v[212:215], v[64:67]
	s_barrier
; template <class Epi, class Sched, bool ALIGN_EPI = false, bool SP2 = false>
; __device__ __forceinline__ void gemm_phase(PG8_LAS unsigned char* lds, const Gemm g, const Sched& S, const Epi& E) {
;     ...
;             if constexpr (SP2) {
;             PG8_LDB(B0, 0, 0); PG8_LDB(B1, 0, 1); PG8_SCHED; PG8_LDA(At, 0, 0); PG8_STAGE(PG8_SA(1, 1), a1 + hstepA, voffA);
;             PG8_WAIT_V(8); PG8_WAIT_L(0); PG8_BAR; PG8_MMA(0, 0, At, B0); PG8_MMA(0, 1, At, B1); PG8_BAR; PG8_SCHED;
;             PG8_LDA(At, 0, 1); PG8_STAGE(PG8_SB(0, 0), b2, voffB); PG8_STAGE(PG8_SB(0, 1), b2 + hstepB, voffB); PG8_STAGE(PG8_SA(0, 0), a2, voffA);
;             PG8_WAIT_V(8); PG8_WAIT_L(0); PG8_BAR; PG8_MMA(1, 0, At, B0); PG8_MMA(1, 1, At, B1); PG8_BAR; PG8_SCHED;
;             PG8_LDB(B0, 1, 0); PG8_LDB(B1, 1, 1); PG8_SCHED; PG8_LDA(At, 1, 0); PG8_STAGE(PG8_SA(0, 1), a2 + hstepA, voffA);
;             PG8_WAIT_V(8); PG8_WAIT_L(0); PG8_BAR; PG8_MMA(0, 0, At, B0); PG8_MMA(0, 1, At, B1); PG8_BAR; PG8_SCHED;
;             PG8_LDA(At, 1, 1); PG8_STAGE(PG8_SB(1, 0), b3, voffB); PG8_STAGE(PG8_SB(1, 1), b3 + hstepB, voffB); PG8_STAGE(PG8_SA(1, 0), a3, voffA);
;             PG8_WAIT_V(8); PG8_WAIT_L(0); PG8_BAR; PG8_MMA(1, 0, At, B0); PG8_MMA(1, 1, At, B1); PG8_BAR; PG8_SCHED;
;             } else {
;             PG8_LDB(B0, 0, 0); PG8_SCHED; PG8_LDA(At, 0, 0); PG8_STAGE(PG8_SA(1, 1), a1 + hstepA, voffA);
;             PG8_WAIT_L(8); PG8_BAR; PG8_WAIT_L(0); PG8_MMA(0, 0, At, B0); PG8_BAR; PG8_SCHED;
;             PG8_LDB(B1, 0, 1); PG8_STAGE(PG8_SB(0, 0), b2, voffB);
;             PG8_BAR; PG8_WAIT_L(0); PG8_MMA(0, 1, At, B1); PG8_BAR;
;             PG8_LDA(At, 0, 1); PG8_STAGE(PG8_SA(0, 0), a2, voffA);
;             PG8_BAR; PG8_WAIT_L(0); PG8_MMA(1, 0, At, B0); PG8_BAR; PG8_SCHED;
;             PG8_STAGE(PG8_SB(0, 1), b2 + hstepB, voffB);
;             PG8_WAIT_V(6); PG8_BAR; PG8_MMA(1, 1, At, B1); PG8_BAR;
;             PG8_LDB(B0, 1, 0); PG8_SCHED; PG8_LDA(At, 1, 0); PG8_STAGE(PG8_SA(0, 1), a2 + hstepA, voffA);
;             PG8_WAIT_L(8); PG8_BAR; PG8_WAIT_L(0); PG8_MMA(0, 0, At, B0); PG8_BAR; PG8_SCHED;
;             PG8_LDB(B1, 1, 1); PG8_STAGE(PG8_SB(1, 0), b3, voffB);
;             PG8_BAR; PG8_WAIT_L(0); PG8_MMA(0, 1, At, B1); PG8_BAR;
;             PG8_LDA(At, 1, 1); PG8_STAGE(PG8_SA(1, 0), a3, voffA);
;             PG8_BAR; PG8_WAIT_L(0); PG8_MMA(1, 0, At, B0); PG8_BAR; PG8_SCHED;
	s_add_i32 s52, s52, s66
	v_lshl_add_u64 v[186:187], v[186:187], 0, s[80:81]
	s_mov_b32 m0, s52
	ds_read_b128 v[174:177], v180 offset:49152
	ds_read_b128 v[182:185], v180 offset:50176
	ds_read_b128 v[192:195], v180 offset:51200
	ds_read_b128 v[196:199], v180 offset:52224
	ds_read_b128 v[200:203], v180 offset:53248
	ds_read_b128 v[204:207], v180 offset:54272
	ds_read_b128 v[208:211], v180 offset:55296
	ds_read_b128 v[212:215], v180 offset:56320
	global_load_lds_dwordx4 v[186:187], off
	s_add_i32 m0, s52, 0x2000
	s_add_u32 s56, s70, 0x40080
	v_lshl_add_u64 v[186:187], v[216:217], 0, s[80:81]
	s_addc_u32 s57, s71, 0
	s_add_i32 s52, s64, s66
	global_load_lds_dwordx4 v[186:187], off
	v_lshl_add_u64 v[186:187], s[56:57], 0, v[172:173]
	s_mov_b32 m0, s52
	s_nop 0
	global_load_lds_dwordx4 v[186:187], off
	v_lshl_add_u64 v[186:187], s[56:57], 0, v[132:133]
	s_add_i32 m0, s52, 0x2000
	s_nop 0
	global_load_lds_dwordx4 v[186:187], off
	v_lshl_add_u64 v[186:187], v[218:219], 0, s[80:81]
	s_mov_b32 m0, s53
	s_nop 0
	global_load_lds_dwordx4 v[186:187], off
	v_lshl_add_u64 v[186:187], v[220:221], 0, s[80:81]
	s_mov_b32 m0, s58
	s_nop 0
	global_load_lds_dwordx4 v[186:187], off
	s_waitcnt vmcnt(8)
	s_waitcnt lgkmcnt(0)
	s_barrier
	s_waitcnt lgkmcnt(0)
	v_mfma_f32_16x16x32_bf16 v[60:63], v[138:141], v[174:177], v[60:63]
	v_mfma_f32_16x16x32_bf16 v[56:59], v[146:149], v[174:177], v[56:59]
	v_mfma_f32_16x16x32_bf16 v[44:47], v[138:141], v[192:195], v[44:47]
	v_mfma_f32_16x16x32_bf16 v[40:43], v[146:149], v[192:195], v[40:43]
	v_mfma_f32_16x16x32_bf16 v[28:31], v[138:141], v[200:203], v[28:31]
	v_mfma_f32_16x16x32_bf16 v[24:27], v[146:149], v[200:203], v[24:27]
	v_mfma_f32_16x16x32_bf16 v[12:15], v[138:141], v[208:211], v[12:15]
	v_mfma_f32_16x16x32_bf16 v[8:11], v[146:149], v[208:211], v[8:11]
	v_mfma_f32_16x16x32_bf16 v[60:63], v[142:145], v[182:185], v[60:63]
	v_mfma_f32_16x16x32_bf16 v[56:59], v[150:153], v[182:185], v[56:59]
	v_mfma_f32_16x16x32_bf16 v[44:47], v[142:145], v[196:199], v[44:47]
	v_mfma_f32_16x16x32_bf16 v[40:43], v[150:153], v[196:199], v[40:43]
	v_mfma_f32_16x16x32_bf16 v[28:31], v[142:145], v[204:207], v[28:31]
	v_mfma_f32_16x16x32_bf16 v[24:27], v[150:153], v[204:207], v[24:27]
	v_mfma_f32_16x16x32_bf16 v[12:15], v[142:145], v[212:215], v[12:15]
	v_mfma_f32_16x16x32_bf16 v[8:11], v[150:153], v[212:215], v[8:11]
	v_mfma_f32_16x16x32_bf16 v[52:55], v[154:157], v[174:177], v[52:55]
	v_mfma_f32_16x16x32_bf16 v[48:51], v[162:165], v[174:177], v[48:51]
	v_mfma_f32_16x16x32_bf16 v[36:39], v[154:157], v[192:195], v[36:39]
	v_mfma_f32_16x16x32_bf16 v[32:35], v[162:165], v[192:195], v[32:35]
	v_mfma_f32_16x16x32_bf16 v[20:23], v[154:157], v[200:203], v[20:23]
	v_mfma_f32_16x16x32_bf16 v[16:19], v[162:165], v[200:203], v[16:19]
	v_mfma_f32_16x16x32_bf16 v[4:7], v[154:157], v[208:211], v[4:7]
	v_mfma_f32_16x16x32_bf16 v[0:3], v[162:165], v[208:211], v[0:3]
	v_mfma_f32_16x16x32_bf16 v[52:55], v[158:161], v[182:185], v[52:55]
	v_mfma_f32_16x16x32_bf16 v[48:51], v[166:169], v[182:185], v[48:51]
	v_mfma_f32_16x16x32_bf16 v[36:39], v[158:161], v[196:199], v[36:39]
	v_mfma_f32_16x16x32_bf16 v[32:35], v[166:169], v[196:199], v[32:35]
	v_mfma_f32_16x16x32_bf16 v[20:23], v[158:161], v[204:207], v[20:23]
	v_mfma_f32_16x16x32_bf16 v[16:19], v[166:169], v[204:207], v[16:19]
	v_mfma_f32_16x16x32_bf16 v[4:7], v[158:161], v[212:215], v[4:7]
	v_mfma_f32_16x16x32_bf16 v[0:3], v[166:169], v[212:215], v[0:3]
	s_barrier
	s_add_i32 s87, s87, 2
	s_add_u32 s42, s42, 0x100
	s_addc_u32 s43, s43, 0
	s_add_u32 s85, s85, 0x100
	s_addc_u32 s89, s89, 0
	s_cmp_gt_u32 s87, 13
	s_cbranch_scc0 .LBB0_330
	s_and_b64 vcc, exec, s[76:77]
	s_cbranch_vccz .LBB0_333
	s_barrier

; #define PG8_STAGE(bufoff, gbase, voff) do { _Pragma("unroll") for (int _i = 0; _i < 2; ++_i) \
;         __builtin_amdgcn_global_load_lds((const unsigned*)((const char*)(gbase) + (voff)[_i]), (PG8_LAS unsigned*)(lds + (bufoff) + ldsw + _i * 8192), 16, 0, 0); } while (0)
; #define PG8_LDA(dst, b, h) do { _Pragma("unroll") for (int m = 0; m < 4; ++m) _Pragma("unroll") for (int k = 0; k < 2; ++k) dst[m][k] = *(const PG8_LAS bf16x8*)(lds + PG8_SA(b, h) + aoff + m * 2048 + k * 1024); } while (0)
; #define PG8_LDB(dst, b, h) do { _Pragma("unroll") for (int n = 0; n < 2; ++n) _Pragma("unroll") for (int k = 0; k < 2; ++k) dst[n][k] = *(const PG8_LAS bf16x8*)(lds + PG8_SB(b, h) + boff + n * 2048 + k * 1024); } while (0)
; #define PG8_MMA(ai, bj, At, Bt) do { __builtin_amdgcn_s_setprio(1); _Pragma("unroll") for (int m = 0; m < 4; ++m) _Pragma("unroll") for (int n = 0; n < 2; ++n) _Pragma("unroll") for (int k = 0; k < 2; ++k) \
;         acc[ai][bj][m][n] = __builtin_amdgcn_mfma_f32_16x16x32_bf16(Bt[n][k], At[m][k], acc[ai][bj][m][n], 0, 0, 0); __builtin_amdgcn_s_setprio(0); } while (0)
; template <class Epi, class Sched, bool ALIGN_EPI = false, bool SP2 = false>
; __device__ __forceinline__ void gemm_phase(PG8_LAS unsigned char* lds, const Gemm g, const Sched& S, const Epi& E) {
;     ...
;             if constexpr (SP2) {
;             PG8_LDB(B0, 0, 0); PG8_LDB(B1, 0, 1); PG8_SCHED; PG8_LDA(At, 0, 0); PG8_STAGE(PG8_SA(1, 1), a1 + hstepA, voffA);
;             PG8_WAIT_V(8); PG8_WAIT_L(0); PG8_BAR; PG8_MMA(0, 0, At, B0); PG8_MMA(0, 1, At, B1); PG8_BAR; PG8_SCHED;
;             PG8_LDA(At, 0, 1); PG8_STAGE(PG8_SB(0, 0), b2, voffB); PG8_STAGE(PG8_SB(0, 1), b2 + hstepB, voffB); PG8_STAGE(PG8_SA(0, 0), a2, voffA);
;             PG8_WAIT_V(8); PG8_WAIT_L(0); PG8_BAR; PG8_MMA(1, 0, At, B0); PG8_MMA(1, 1, At, B1); PG8_BAR; PG8_SCHED;
;             PG8_LDB(B0, 1, 0); PG8_LDB(B1, 1, 1); PG8_SCHED; PG8_LDA(At, 1, 0); PG8_STAGE(PG8_SA(0, 1), a2 + hstepA, voffA);
;             PG8_WAIT_V(8); PG8_WAIT_L(0); PG8_BAR; PG8_MMA(0, 0, At, B0); PG8_MMA(0, 1, At, B1); PG8_BAR; PG8_SCHED;
;             PG8_LDA(At, 1, 1); PG8_STAGE(PG8_SB(1, 0), b3, voffB); PG8_STAGE(PG8_SB(1, 1), b3 + hstepB, voffB); PG8_STAGE(PG8_SA(1, 0), a3, voffA);
;             PG8_WAIT_V(8); PG8_WAIT_L(0); PG8_BAR; PG8_MMA(1, 0, At, B0); PG8_MMA(1, 1, At, B1); PG8_BAR; PG8_SCHED;
.LBB0_436:
	s_add_u32 s43, s38, s42
	s_addc_u32 s50, s39, 0
	s_add_u32 s46, s43, 0x100
	s_addc_u32 s47, s50, 0
	s_and_b64 s[44:45], s[40:41], exec
	s_cselect_b32 s45, s23, s47
	s_cselect_b32 s44, s25, s46
	s_add_u32 s42, s36, s42
	s_addc_u32 s46, s37, 0
	s_add_u32 s42, s42, 0x100
	s_addc_u32 s46, s46, 0
	s_add_i32 s74, 0, 0x10000
	s_and_b64 s[40:41], s[40:41], exec
	s_cselect_b32 s47, s27, s46
	s_cselect_b32 s46, s26, s42
	s_add_i32 s41, 0, 0x14000
	s_add_u32 s52, s43, 0x10080
	s_addc_u32 s53, s50, 0
	s_add_i32 s73, s74, s2
	s_add_i32 m0, s31, 0xc000
	s_add_i32 s76, s31, 0xe000
	s_add_i32 s70, s73, 0x2000
	v_add_u32_e32 v147, s74, v143
	s_add_u32 s50, s46, 0x440000
	ds_read_b128 v[134:137], v147
	ds_read_b128 v[138:141], v147 offset:1024
	ds_read_b128 v[148:151], v147 offset:2048
	ds_read_b128 v[152:155], v147 offset:3072
	v_add_u32_e32 v147, s41, v143
	s_addc_u32 s51, s47, 0
	s_add_i32 s72, s41, s2
	ds_read_b128 v[156:159], v147
	ds_read_b128 v[160:163], v147 offset:1024
	ds_read_b128 v[164:167], v147 offset:2048
	ds_read_b128 v[168:171], v147 offset:3072
	s_add_i32 s71, s72, 0x2000
	s_add_i32 s67, 0, 0x18000
	s_add_i32 s66, 0, 0x1c000
	s_add_u32 s42, s44, 0x10000
	s_addc_u32 s43, s45, 0
	s_add_i32 s65, s67, s2
	s_add_i32 s64, s65, 0x2000
	s_add_u32 s40, s46, 0x440080
	s_addc_u32 s41, s47, 0
	s_add_i32 s75, s66, s2
	s_add_i32 s74, s75, 0x2000
	v_lshl_add_u64 v[186:187], s[52:53], 0, v[132:133]
	ds_read_b128 v[174:177], v146
	ds_read_b128 v[178:181], v146 offset:1024
	ds_read_b128 v[182:185], v146 offset:2048
	ds_read_b128 v[192:195], v146 offset:3072
	ds_read_b128 v[196:199], v146 offset:4096
	ds_read_b128 v[200:203], v146 offset:5120
	ds_read_b128 v[204:207], v146 offset:6144
	ds_read_b128 v[208:211], v146 offset:7168
	global_load_lds_dwordx4 v[186:187], off
	v_lshl_add_u64 v[186:187], s[52:53], 0, v[130:131]
	s_mov_b32 m0, s76
	s_nop 0
	global_load_lds_dwordx4 v[186:187], off
	s_waitcnt vmcnt(8)
	s_waitcnt lgkmcnt(0)
	s_barrier
	s_waitcnt lgkmcnt(0)
	v_mfma_f32_16x16x32_bf16 v[124:127], v[134:137], v[174:177], v[124:127]
	v_mfma_f32_16x16x32_bf16 v[120:123], v[148:151], v[174:177], v[120:123]
	v_mfma_f32_16x16x32_bf16 v[108:111], v[134:137], v[182:185], v[108:111]
	v_mfma_f32_16x16x32_bf16 v[104:107], v[148:151], v[182:185], v[104:107]
	v_mfma_f32_16x16x32_bf16 v[92:95], v[134:137], v[196:199], v[92:95]
	v_mfma_f32_16x16x32_bf16 v[88:91], v[148:151], v[196:199], v[88:91]
	v_mfma_f32_16x16x32_bf16 v[76:79], v[134:137], v[204:207], v[76:79]
	v_mfma_f32_16x16x32_bf16 v[72:75], v[148:151], v[204:207], v[72:75]
	v_mfma_f32_16x16x32_bf16 v[124:127], v[138:141], v[178:181], v[124:127]
	v_mfma_f32_16x16x32_bf16 v[120:123], v[152:155], v[178:181], v[120:123]
	v_mfma_f32_16x16x32_bf16 v[108:111], v[138:141], v[192:195], v[108:111]
	v_mfma_f32_16x16x32_bf16 v[104:107], v[152:155], v[192:195], v[104:107]
	v_mfma_f32_16x16x32_bf16 v[92:95], v[138:141], v[200:203], v[92:95]
	v_mfma_f32_16x16x32_bf16 v[88:91], v[152:155], v[200:203], v[88:91]
	v_mfma_f32_16x16x32_bf16 v[76:79], v[138:141], v[208:211], v[76:79]
	v_mfma_f32_16x16x32_bf16 v[72:75], v[152:155], v[208:211], v[72:75]
	v_mfma_f32_16x16x32_bf16 v[116:119], v[156:159], v[174:177], v[116:119]
	v_mfma_f32_16x16x32_bf16 v[112:115], v[164:167], v[174:177], v[112:115]
	v_mfma_f32_16x16x32_bf16 v[100:103], v[156:159], v[182:185], v[100:103]
	v_mfma_f32_16x16x32_bf16 v[96:99], v[164:167], v[182:185], v[96:99]
	v_mfma_f32_16x16x32_bf16 v[84:87], v[156:159], v[196:199], v[84:87]
	v_mfma_f32_16x16x32_bf16 v[80:83], v[164:167], v[196:199], v[80:83]
	v_mfma_f32_16x16x32_bf16 v[68:71], v[156:159], v[204:207], v[68:71]
	v_mfma_f32_16x16x32_bf16 v[64:67], v[164:167], v[204:207], v[64:67]
	v_mfma_f32_16x16x32_bf16 v[116:119], v[160:163], v[178:181], v[116:119]
	v_mfma_f32_16x16x32_bf16 v[112:115], v[168:171], v[178:181], v[112:115]
	v_mfma_f32_16x16x32_bf16 v[100:103], v[160:163], v[192:195], v[100:103]
	v_mfma_f32_16x16x32_bf16 v[96:99], v[168:171], v[192:195], v[96:99]
	v_mfma_f32_16x16x32_bf16 v[84:87], v[160:163], v[200:203], v[84:87]
	v_mfma_f32_16x16x32_bf16 v[80:83], v[168:171], v[200:203], v[80:83]
	v_mfma_f32_16x16x32_bf16 v[68:71], v[160:163], v[208:211], v[68:71]
	v_mfma_f32_16x16x32_bf16 v[64:67], v[168:171], v[208:211], v[64:67]
	s_barrier
	s_mov_b32 m0, s73
	v_lshl_add_u64 v[186:187], s[46:47], 0, v[172:173]
	ds_read_b128 v[174:177], v146 offset:16384
	ds_read_b128 v[178:181], v146 offset:17408
	ds_read_b128 v[182:185], v146 offset:18432
	ds_read_b128 v[192:195], v146 offset:19456
	ds_read_b128 v[196:199], v146 offset:20480
	ds_read_b128 v[200:203], v146 offset:21504
	ds_read_b128 v[204:207], v146 offset:22528
	ds_read_b128 v[208:211], v146 offset:23552
	global_load_lds_dwordx4 v[186:187], off
	v_lshl_add_u64 v[212:213], s[46:47], 0, v[128:129]
	s_mov_b32 m0, s70
	v_lshl_add_u64 v[214:215], s[50:51], 0, v[172:173]
	global_load_lds_dwordx4 v[212:213], off
	s_mov_b32 m0, s72
	v_lshl_add_u64 v[216:217], s[44:45], 0, v[130:131]
	global_load_lds_dwordx4 v[214:215], off
	v_lshl_add_u64 v[214:215], s[50:51], 0, v[128:129]
	s_mov_b32 m0, s71
	s_nop 0
	global_load_lds_dwordx4 v[214:215], off
	v_lshl_add_u64 v[214:215], s[44:45], 0, v[132:133]
	s_mov_b32 m0, s31
	s_nop 0
	global_load_lds_dwordx4 v[214:215], off
	s_mov_b32 m0, s35
	s_nop 0
	global_load_lds_dwordx4 v[216:217], off
	s_waitcnt vmcnt(8)
	s_waitcnt lgkmcnt(0)
	s_barrier
; #define PG8_STAGE(bufoff, gbase, voff) do { _Pragma("unroll") for (int _i = 0; _i < 2; ++_i) \
;         __builtin_amdgcn_global_load_lds((const unsigned*)((const char*)(gbase) + (voff)[_i]), (PG8_LAS unsigned*)(lds + (bufoff) + ldsw + _i * 8192), 16, 0, 0); } while (0)
; #define PG8_LDA(dst, b, h) do { _Pragma("unroll") for (int m = 0; m < 4; ++m) _Pragma("unroll") for (int k = 0; k < 2; ++k) dst[m][k] = *(const PG8_LAS bf16x8*)(lds + PG8_SA(b, h) + aoff + m * 2048 + k * 1024); } while (0)
; #define PG8_LDB(dst, b, h) do { _Pragma("unroll") for (int n = 0; n < 2; ++n) _Pragma("unroll") for (int k = 0; k < 2; ++k) dst[n][k] = *(const PG8_LAS bf16x8*)(lds + PG8_SB(b, h) + boff + n * 2048 + k * 1024); } while (0)
; #define PG8_MMA(ai, bj, At, Bt) do { __builtin_amdgcn_s_setprio(1); _Pragma("unroll") for (int m = 0; m < 4; ++m) _Pragma("unroll") for (int n = 0; n < 2; ++n) _Pragma("unroll") for (int k = 0; k < 2; ++k) \
;         acc[ai][bj][m][n] = __builtin_amdgcn_mfma_f32_16x16x32_bf16(Bt[n][k], At[m][k], acc[ai][bj][m][n], 0, 0, 0); __builtin_amdgcn_s_setprio(0); } while (0)
; template <class Epi, class Sched, bool ALIGN_EPI = false, bool SP2 = false>
; __device__ __forceinline__ void gemm_phase(PG8_LAS unsigned char* lds, const Gemm g, const Sched& S, const Epi& E) {
;     ...
;             if constexpr (SP2) {
;             PG8_LDB(B0, 0, 0); PG8_LDB(B1, 0, 1); PG8_SCHED; PG8_LDA(At, 0, 0); PG8_STAGE(PG8_SA(1, 1), a1 + hstepA, voffA);
;             PG8_WAIT_V(8); PG8_WAIT_L(0); PG8_BAR; PG8_MMA(0, 0, At, B0); PG8_MMA(0, 1, At, B1); PG8_BAR; PG8_SCHED;
;             PG8_LDA(At, 0, 1); PG8_STAGE(PG8_SB(0, 0), b2, voffB); PG8_STAGE(PG8_SB(0, 1), b2 + hstepB, voffB); PG8_STAGE(PG8_SA(0, 0), a2, voffA);
;             PG8_WAIT_V(8); PG8_WAIT_L(0); PG8_BAR; PG8_MMA(1, 0, At, B0); PG8_MMA(1, 1, At, B1); PG8_BAR; PG8_SCHED;
;             PG8_LDB(B0, 1, 0); PG8_LDB(B1, 1, 1); PG8_SCHED; PG8_LDA(At, 1, 0); PG8_STAGE(PG8_SA(0, 1), a2 + hstepA, voffA);
;             PG8_WAIT_V(8); PG8_WAIT_L(0); PG8_BAR; PG8_MMA(0, 0, At, B0); PG8_MMA(0, 1, At, B1); PG8_BAR; PG8_SCHED;
;             PG8_LDA(At, 1, 1); PG8_STAGE(PG8_SB(1, 0), b3, voffB); PG8_STAGE(PG8_SB(1, 1), b3 + hstepB, voffB); PG8_STAGE(PG8_SA(1, 0), a3, voffA);
;             PG8_WAIT_V(8); PG8_WAIT_L(0); PG8_BAR; PG8_MMA(1, 0, At, B0); PG8_MMA(1, 1, At, B1); PG8_BAR; PG8_SCHED;
	s_waitcnt lgkmcnt(0)
	v_mfma_f32_16x16x32_bf16 v[60:63], v[134:137], v[174:177], v[60:63]
	v_mfma_f32_16x16x32_bf16 v[56:59], v[148:151], v[174:177], v[56:59]
	v_mfma_f32_16x16x32_bf16 v[44:47], v[134:137], v[182:185], v[44:47]
	v_mfma_f32_16x16x32_bf16 v[40:43], v[148:151], v[182:185], v[40:43]
	v_mfma_f32_16x16x32_bf16 v[28:31], v[134:137], v[196:199], v[28:31]
	v_mfma_f32_16x16x32_bf16 v[24:27], v[148:151], v[196:199], v[24:27]
	v_mfma_f32_16x16x32_bf16 v[12:15], v[134:137], v[204:207], v[12:15]
	v_mfma_f32_16x16x32_bf16 v[8:11], v[148:151], v[204:207], v[8:11]
	v_mfma_f32_16x16x32_bf16 v[60:63], v[138:141], v[178:181], v[60:63]
	v_mfma_f32_16x16x32_bf16 v[56:59], v[152:155], v[178:181], v[56:59]
	v_mfma_f32_16x16x32_bf16 v[44:47], v[138:141], v[192:195], v[44:47]
	v_mfma_f32_16x16x32_bf16 v[40:43], v[152:155], v[192:195], v[40:43]
	v_mfma_f32_16x16x32_bf16 v[28:31], v[138:141], v[200:203], v[28:31]
	v_mfma_f32_16x16x32_bf16 v[24:27], v[152:155], v[200:203], v[24:27]
	v_mfma_f32_16x16x32_bf16 v[12:15], v[138:141], v[208:211], v[12:15]
	v_mfma_f32_16x16x32_bf16 v[8:11], v[152:155], v[208:211], v[8:11]
	v_mfma_f32_16x16x32_bf16 v[52:55], v[156:159], v[174:177], v[52:55]
	v_mfma_f32_16x16x32_bf16 v[48:51], v[164:167], v[174:177], v[48:51]
	v_mfma_f32_16x16x32_bf16 v[36:39], v[156:159], v[182:185], v[36:39]
	v_mfma_f32_16x16x32_bf16 v[32:35], v[164:167], v[182:185], v[32:35]
	v_mfma_f32_16x16x32_bf16 v[20:23], v[156:159], v[196:199], v[20:23]
	v_mfma_f32_16x16x32_bf16 v[16:19], v[164:167], v[196:199], v[16:19]
	v_mfma_f32_16x16x32_bf16 v[4:7], v[156:159], v[204:207], v[4:7]
	v_mfma_f32_16x16x32_bf16 v[0:3], v[164:167], v[204:207], v[0:3]
	v_mfma_f32_16x16x32_bf16 v[52:55], v[160:163], v[178:181], v[52:55]
	v_mfma_f32_16x16x32_bf16 v[48:51], v[168:171], v[178:181], v[48:51]
	v_mfma_f32_16x16x32_bf16 v[36:39], v[160:163], v[192:195], v[36:39]
	v_mfma_f32_16x16x32_bf16 v[32:35], v[168:171], v[192:195], v[32:35]
	v_mfma_f32_16x16x32_bf16 v[20:23], v[160:163], v[200:203], v[20:23]
	v_mfma_f32_16x16x32_bf16 v[16:19], v[168:171], v[200:203], v[16:19]
	v_mfma_f32_16x16x32_bf16 v[4:7], v[160:163], v[208:211], v[4:7]
	v_mfma_f32_16x16x32_bf16 v[0:3], v[168:171], v[208:211], v[0:3]
	s_barrier
	v_add_u32_e32 v147, s67, v143
	ds_read_b128 v[134:137], v147
	ds_read_b128 v[138:141], v147 offset:1024
	ds_read_b128 v[148:151], v147 offset:2048
	ds_read_b128 v[152:155], v147 offset:3072
	v_add_u32_e32 v147, s66, v143
	ds_read_b128 v[156:159], v147
	ds_read_b128 v[160:163], v147 offset:1024
	ds_read_b128 v[164:167], v147 offset:2048
	ds_read_b128 v[168:171], v147 offset:3072
	s_mov_b32 m0, s59
	v_lshl_add_u64 v[218:219], s[42:43], 0, v[132:133]
	ds_read_b128 v[174:177], v146 offset:32768
	ds_read_b128 v[178:181], v146 offset:33792
	ds_read_b128 v[182:185], v146 offset:34816
	ds_read_b128 v[192:195], v146 offset:35840
	ds_read_b128 v[196:199], v146 offset:36864
	ds_read_b128 v[200:203], v146 offset:37888
	ds_read_b128 v[204:207], v146 offset:38912
	ds_read_b128 v[208:211], v146 offset:39936
	global_load_lds_dwordx4 v[218:219], off
	v_lshl_add_u64 v[218:219], s[42:43], 0, v[130:131]
	s_mov_b32 m0, s60
	s_nop 0
	global_load_lds_dwordx4 v[218:219], off
	s_waitcnt vmcnt(8)
	s_waitcnt lgkmcnt(0)
	s_barrier
	s_waitcnt lgkmcnt(0)
	v_mfma_f32_16x16x32_bf16 v[124:127], v[134:137], v[174:177], v[124:127]
	v_mfma_f32_16x16x32_bf16 v[120:123], v[148:151], v[174:177], v[120:123]
	v_mfma_f32_16x16x32_bf16 v[108:111], v[134:137], v[182:185], v[108:111]
	v_mfma_f32_16x16x32_bf16 v[104:107], v[148:151], v[182:185], v[104:107]
	v_mfma_f32_16x16x32_bf16 v[92:95], v[134:137], v[196:199], v[92:95]
	v_mfma_f32_16x16x32_bf16 v[88:91], v[148:151], v[196:199], v[88:91]
	v_mfma_f32_16x16x32_bf16 v[76:79], v[134:137], v[204:207], v[76:79]
	v_mfma_f32_16x16x32_bf16 v[72:75], v[148:151], v[204:207], v[72:75]
	v_mfma_f32_16x16x32_bf16 v[124:127], v[138:141], v[178:181], v[124:127]
	v_mfma_f32_16x16x32_bf16 v[120:123], v[152:155], v[178:181], v[120:123]
	v_mfma_f32_16x16x32_bf16 v[108:111], v[138:141], v[192:195], v[108:111]
	v_mfma_f32_16x16x32_bf16 v[104:107], v[152:155], v[192:195], v[104:107]
	v_mfma_f32_16x16x32_bf16 v[92:95], v[138:141], v[200:203], v[92:95]
	v_mfma_f32_16x16x32_bf16 v[88:91], v[152:155], v[200:203], v[88:91]
	v_mfma_f32_16x16x32_bf16 v[76:79], v[138:141], v[208:211], v[76:79]
	v_mfma_f32_16x16x32_bf16 v[72:75], v[152:155], v[208:211], v[72:75]
	v_mfma_f32_16x16x32_bf16 v[116:119], v[156:159], v[174:177], v[116:119]
	v_mfma_f32_16x16x32_bf16 v[112:115], v[164:167], v[174:177], v[112:115]
	v_mfma_f32_16x16x32_bf16 v[100:103], v[156:159], v[182:185], v[100:103]
	v_mfma_f32_16x16x32_bf16 v[96:99], v[164:167], v[182:185], v[96:99]
	v_mfma_f32_16x16x32_bf16 v[84:87], v[156:159], v[196:199], v[84:87]
	v_mfma_f32_16x16x32_bf16 v[80:83], v[164:167], v[196:199], v[80:83]
	v_mfma_f32_16x16x32_bf16 v[68:71], v[156:159], v[204:207], v[68:71]
	v_mfma_f32_16x16x32_bf16 v[64:67], v[164:167], v[204:207], v[64:67]
	v_mfma_f32_16x16x32_bf16 v[116:119], v[160:163], v[178:181], v[116:119]
	v_mfma_f32_16x16x32_bf16 v[112:115], v[168:171], v[178:181], v[112:115]
	v_mfma_f32_16x16x32_bf16 v[100:103], v[160:163], v[192:195], v[100:103]
	v_mfma_f32_16x16x32_bf16 v[96:99], v[168:171], v[192:195], v[96:99]
	v_mfma_f32_16x16x32_bf16 v[84:87], v[160:163], v[200:203], v[84:87]
	v_mfma_f32_16x16x32_bf16 v[80:83], v[168:171], v[200:203], v[80:83]
	v_mfma_f32_16x16x32_bf16 v[68:71], v[160:163], v[208:211], v[68:71]
	v_mfma_f32_16x16x32_bf16 v[64:67], v[168:171], v[208:211], v[64:67]
	s_barrier
; template <class Epi, class Sched, bool ALIGN_EPI = false, bool SP2 = false>
; __device__ __forceinline__ void gemm_phase(PG8_LAS unsigned char* lds, const Gemm g, const Sched& S, const Epi& E) {
;     ...
;             if constexpr (SP2) {
;             PG8_LDB(B0, 0, 0); PG8_LDB(B1, 0, 1); PG8_SCHED; PG8_LDA(At, 0, 0); PG8_STAGE(PG8_SA(1, 1), a1 + hstepA, voffA);
;             PG8_WAIT_V(8); PG8_WAIT_L(0); PG8_BAR; PG8_MMA(0, 0, At, B0); PG8_MMA(0, 1, At, B1); PG8_BAR; PG8_SCHED;
;             PG8_LDA(At, 0, 1); PG8_STAGE(PG8_SB(0, 0), b2, voffB); PG8_STAGE(PG8_SB(0, 1), b2 + hstepB, voffB); PG8_STAGE(PG8_SA(0, 0), a2, voffA);
;             PG8_WAIT_V(8); PG8_WAIT_L(0); PG8_BAR; PG8_MMA(1, 0, At, B0); PG8_MMA(1, 1, At, B1); PG8_BAR; PG8_SCHED;
;             PG8_LDB(B0, 1, 0); PG8_LDB(B1, 1, 1); PG8_SCHED; PG8_LDA(At, 1, 0); PG8_STAGE(PG8_SA(0, 1), a2 + hstepA, voffA);
;             PG8_WAIT_V(8); PG8_WAIT_L(0); PG8_BAR; PG8_MMA(0, 0, At, B0); PG8_MMA(0, 1, At, B1); PG8_BAR; PG8_SCHED;
;             PG8_LDA(At, 1, 1); PG8_STAGE(PG8_SB(1, 0), b3, voffB); PG8_STAGE(PG8_SB(1, 1), b3 + hstepB, voffB); PG8_STAGE(PG8_SA(1, 0), a3, voffA);
;             PG8_WAIT_V(8); PG8_WAIT_L(0); PG8_BAR; PG8_MMA(1, 0, At, B0); PG8_MMA(1, 1, At, B1); PG8_BAR; PG8_SCHED;
;             } else {
;             PG8_LDB(B0, 0, 0); PG8_SCHED; PG8_LDA(At, 0, 0); PG8_STAGE(PG8_SA(1, 1), a1 + hstepA, voffA);
;             PG8_WAIT_L(8); PG8_BAR; PG8_WAIT_L(0); PG8_MMA(0, 0, At, B0); PG8_BAR; PG8_SCHED;
;             PG8_LDB(B1, 0, 1); PG8_STAGE(PG8_SB(0, 0), b2, voffB);
;             PG8_BAR; PG8_WAIT_L(0); PG8_MMA(0, 1, At, B1); PG8_BAR;
;             PG8_LDA(At, 0, 1); PG8_STAGE(PG8_SA(0, 0), a2, voffA);
;             PG8_BAR; PG8_WAIT_L(0); PG8_MMA(1, 0, At, B0); PG8_BAR; PG8_SCHED;
;             PG8_STAGE(PG8_SB(0, 1), b2 + hstepB, voffB);
;             PG8_WAIT_V(6); PG8_BAR; PG8_MMA(1, 1, At, B1); PG8_BAR;
;             PG8_LDB(B0, 1, 0); PG8_SCHED; PG8_LDA(At, 1, 0); PG8_STAGE(PG8_SA(0, 1), a2 + hstepA, voffA);
;             PG8_WAIT_L(8); PG8_BAR; PG8_WAIT_L(0); PG8_MMA(0, 0, At, B0); PG8_BAR; PG8_SCHED;
;             PG8_LDB(B1, 1, 1); PG8_STAGE(PG8_SB(1, 0), b3, voffB);
;             PG8_BAR; PG8_WAIT_L(0); PG8_MMA(0, 1, At, B1); PG8_BAR;
;             PG8_LDA(At, 1, 1); PG8_STAGE(PG8_SA(1, 0), a3, voffA);
;             PG8_BAR; PG8_WAIT_L(0); PG8_MMA(1, 0, At, B0); PG8_BAR; PG8_SCHED;
	s_mov_b32 m0, s65
	v_lshl_add_u64 v[186:187], v[186:187], 0, s[80:81]
	ds_read_b128 v[174:177], v146 offset:49152
	ds_read_b128 v[178:181], v146 offset:50176
	ds_read_b128 v[182:185], v146 offset:51200
	ds_read_b128 v[192:195], v146 offset:52224
	ds_read_b128 v[196:199], v146 offset:53248
	ds_read_b128 v[200:203], v146 offset:54272
	ds_read_b128 v[204:207], v146 offset:55296
	ds_read_b128 v[208:211], v146 offset:56320
	global_load_lds_dwordx4 v[186:187], off
	v_lshl_add_u64 v[186:187], v[212:213], 0, s[80:81]
	s_mov_b32 m0, s64
	s_nop 0
	global_load_lds_dwordx4 v[186:187], off
	v_lshl_add_u64 v[186:187], s[40:41], 0, v[172:173]
	s_mov_b32 m0, s75
	s_nop 0
	global_load_lds_dwordx4 v[186:187], off
	v_lshl_add_u64 v[186:187], s[40:41], 0, v[128:129]
	s_mov_b32 m0, s74
	s_nop 0
	global_load_lds_dwordx4 v[186:187], off
	v_lshl_add_u64 v[186:187], v[214:215], 0, s[80:81]
	s_mov_b32 m0, s61
	s_nop 0
	global_load_lds_dwordx4 v[186:187], off
	v_lshl_add_u64 v[186:187], v[216:217], 0, s[80:81]
	s_mov_b32 m0, s62
	s_nop 0
	global_load_lds_dwordx4 v[186:187], off
	s_waitcnt vmcnt(8)
	s_waitcnt lgkmcnt(0)
	s_barrier
	s_waitcnt lgkmcnt(0)
	v_mfma_f32_16x16x32_bf16 v[60:63], v[134:137], v[174:177], v[60:63]
	v_mfma_f32_16x16x32_bf16 v[56:59], v[148:151], v[174:177], v[56:59]
	v_mfma_f32_16x16x32_bf16 v[44:47], v[134:137], v[182:185], v[44:47]
	v_mfma_f32_16x16x32_bf16 v[40:43], v[148:151], v[182:185], v[40:43]
	v_mfma_f32_16x16x32_bf16 v[28:31], v[134:137], v[196:199], v[28:31]
	v_mfma_f32_16x16x32_bf16 v[24:27], v[148:151], v[196:199], v[24:27]
	v_mfma_f32_16x16x32_bf16 v[12:15], v[134:137], v[204:207], v[12:15]
	v_mfma_f32_16x16x32_bf16 v[8:11], v[148:151], v[204:207], v[8:11]
	v_mfma_f32_16x16x32_bf16 v[60:63], v[138:141], v[178:181], v[60:63]
	v_mfma_f32_16x16x32_bf16 v[56:59], v[152:155], v[178:181], v[56:59]
	v_mfma_f32_16x16x32_bf16 v[44:47], v[138:141], v[192:195], v[44:47]
	v_mfma_f32_16x16x32_bf16 v[40:43], v[152:155], v[192:195], v[40:43]
	v_mfma_f32_16x16x32_bf16 v[28:31], v[138:141], v[200:203], v[28:31]
	v_mfma_f32_16x16x32_bf16 v[24:27], v[152:155], v[200:203], v[24:27]
	v_mfma_f32_16x16x32_bf16 v[12:15], v[138:141], v[208:211], v[12:15]
	v_mfma_f32_16x16x32_bf16 v[8:11], v[152:155], v[208:211], v[8:11]
	v_mfma_f32_16x16x32_bf16 v[52:55], v[156:159], v[174:177], v[52:55]
	v_mfma_f32_16x16x32_bf16 v[48:51], v[164:167], v[174:177], v[48:51]
	v_mfma_f32_16x16x32_bf16 v[36:39], v[156:159], v[182:185], v[36:39]
	v_mfma_f32_16x16x32_bf16 v[32:35], v[164:167], v[182:185], v[32:35]
	v_mfma_f32_16x16x32_bf16 v[20:23], v[156:159], v[196:199], v[20:23]
	v_mfma_f32_16x16x32_bf16 v[16:19], v[164:167], v[196:199], v[16:19]
	v_mfma_f32_16x16x32_bf16 v[4:7], v[156:159], v[204:207], v[4:7]
	v_mfma_f32_16x16x32_bf16 v[0:3], v[164:167], v[204:207], v[0:3]
	v_mfma_f32_16x16x32_bf16 v[52:55], v[160:163], v[178:181], v[52:55]
	v_mfma_f32_16x16x32_bf16 v[48:51], v[168:171], v[178:181], v[48:51]
	v_mfma_f32_16x16x32_bf16 v[36:39], v[160:163], v[192:195], v[36:39]
	v_mfma_f32_16x16x32_bf16 v[32:35], v[168:171], v[192:195], v[32:35]
	v_mfma_f32_16x16x32_bf16 v[20:23], v[160:163], v[200:203], v[20:23]
	v_mfma_f32_16x16x32_bf16 v[16:19], v[168:171], v[200:203], v[16:19]
	v_mfma_f32_16x16x32_bf16 v[4:7], v[160:163], v[208:211], v[4:7]
	v_mfma_f32_16x16x32_bf16 v[0:3], v[168:171], v[208:211], v[0:3]
	s_barrier
	s_movk_i32 s42, 0x100
	s_andn2_b64 vcc, exec, s[8:9]
	s_mov_b64 s[40:41], -1
	s_mov_b64 s[8:9], 0
	s_cbranch_vccz .LBB0_436
	s_and_b64 vcc, exec, s[20:21]
	s_cbranch_vccz .LBB0_439
	s_barrier

; #define PG8_STAGE(bufoff, gbase, voff) do { _Pragma("unroll") for (int _i = 0; _i < 2; ++_i) \
;         __builtin_amdgcn_global_load_lds((const unsigned*)((const char*)(gbase) + (voff)[_i]), (PG8_LAS unsigned*)(lds + (bufoff) + ldsw + _i * 8192), 16, 0, 0); } while (0)
; #define PG8_LDA(dst, b, h) do { _Pragma("unroll") for (int m = 0; m < 4; ++m) _Pragma("unroll") for (int k = 0; k < 2; ++k) dst[m][k] = *(const PG8_LAS bf16x8*)(lds + PG8_SA(b, h) + aoff + m * 2048 + k * 1024); } while (0)
; #define PG8_LDB(dst, b, h) do { _Pragma("unroll") for (int n = 0; n < 2; ++n) _Pragma("unroll") for (int k = 0; k < 2; ++k) dst[n][k] = *(const PG8_LAS bf16x8*)(lds + PG8_SB(b, h) + boff + n * 2048 + k * 1024); } while (0)
; #define PG8_MMA(ai, bj, At, Bt) do { __builtin_amdgcn_s_setprio(1); _Pragma("unroll") for (int m = 0; m < 4; ++m) _Pragma("unroll") for (int n = 0; n < 2; ++n) _Pragma("unroll") for (int k = 0; k < 2; ++k) \
;         acc[ai][bj][m][n] = __builtin_amdgcn_mfma_f32_16x16x32_bf16(Bt[n][k], At[m][k], acc[ai][bj][m][n], 0, 0, 0); __builtin_amdgcn_s_setprio(0); } while (0)
; template <class Epi, class Sched, bool ALIGN_EPI = false, bool SP2 = false>
; __device__ __forceinline__ void gemm_phase(PG8_LAS unsigned char* lds, const Gemm g, const Sched& S, const Epi& E) {
;     ...
;             if constexpr (SP2) {
;             PG8_LDB(B0, 0, 0); PG8_LDB(B1, 0, 1); PG8_SCHED; PG8_LDA(At, 0, 0); PG8_STAGE(PG8_SA(1, 1), a1 + hstepA, voffA);
;             PG8_WAIT_V(8); PG8_WAIT_L(0); PG8_BAR; PG8_MMA(0, 0, At, B0); PG8_MMA(0, 1, At, B1); PG8_BAR; PG8_SCHED;
;             PG8_LDA(At, 0, 1); PG8_STAGE(PG8_SB(0, 0), b2, voffB); PG8_STAGE(PG8_SB(0, 1), b2 + hstepB, voffB); PG8_STAGE(PG8_SA(0, 0), a2, voffA);
;             PG8_WAIT_V(8); PG8_WAIT_L(0); PG8_BAR; PG8_MMA(1, 0, At, B0); PG8_MMA(1, 1, At, B1); PG8_BAR; PG8_SCHED;
;             PG8_LDB(B0, 1, 0); PG8_LDB(B1, 1, 1); PG8_SCHED; PG8_LDA(At, 1, 0); PG8_STAGE(PG8_SA(0, 1), a2 + hstepA, voffA);
;             PG8_WAIT_V(8); PG8_WAIT_L(0); PG8_BAR; PG8_MMA(0, 0, At, B0); PG8_MMA(0, 1, At, B1); PG8_BAR; PG8_SCHED;
;             PG8_LDA(At, 1, 1); PG8_STAGE(PG8_SB(1, 0), b3, voffB); PG8_STAGE(PG8_SB(1, 1), b3 + hstepB, voffB); PG8_STAGE(PG8_SA(1, 0), a3, voffA);
;             PG8_WAIT_V(8); PG8_WAIT_L(0); PG8_BAR; PG8_MMA(1, 0, At, B0); PG8_MMA(1, 1, At, B1); PG8_BAR; PG8_SCHED;
.LBB0_533:
	s_add_u32 s40, s38, 0xfff80080
	s_addc_u32 s41, s39, -1
	s_add_i32 s70, 0, 0x10000
	s_cmp_eq_u32 s68, 28
	s_cselect_b32 s43, s27, s41
	s_cselect_b32 s42, s35, s40
	s_cselect_b32 s41, s25, s67
	s_cselect_b32 s40, s37, s66
	s_add_i32 s72, 0, 0x14000
	v_add_u32_e32 v92, s70, v181
	v_add_u32_e32 v164, s72, v181
	ds_read_b128 v[72:75], v92
	ds_read_b128 v[76:79], v92 offset:1024
	ds_read_b128 v[88:91], v92 offset:2048
	ds_read_b128 v[92:95], v92 offset:3072
	ds_read_b128 v[152:155], v164
	ds_read_b128 v[156:159], v164 offset:1024
	ds_read_b128 v[160:163], v164 offset:2048
	ds_read_b128 v[164:167], v164 offset:3072
	v_lshl_add_u64 v[178:179], s[38:39], 0, v[148:149]
	s_add_i32 m0, s51, 0xc000
	ds_read_b128 v[168:171], v186
	ds_read_b128 v[174:177], v186 offset:1024
	ds_read_b128 v[192:195], v186 offset:2048
	ds_read_b128 v[196:199], v186 offset:3072
	ds_read_b128 v[200:203], v186 offset:4096
	ds_read_b128 v[204:207], v186 offset:5120
	ds_read_b128 v[208:211], v186 offset:6144
	ds_read_b128 v[212:215], v186 offset:7168
	global_load_lds_dwordx4 v[178:179], off
	v_lshl_add_u64 v[178:179], s[38:39], 0, v[150:151]
	s_add_i32 m0, s51, 0xe000
	s_nop 0
	global_load_lds_dwordx4 v[178:179], off
	s_waitcnt vmcnt(8)
	s_waitcnt lgkmcnt(0)
	s_barrier
	s_waitcnt lgkmcnt(0)
	v_mfma_f32_16x16x32_bf16 v[140:143], v[72:75], v[168:171], v[140:143]
	v_mfma_f32_16x16x32_bf16 v[136:139], v[88:91], v[168:171], v[136:139]
	v_mfma_f32_16x16x32_bf16 v[124:127], v[72:75], v[192:195], v[124:127]
	v_mfma_f32_16x16x32_bf16 v[120:123], v[88:91], v[192:195], v[120:123]
	v_mfma_f32_16x16x32_bf16 v[108:111], v[72:75], v[200:203], v[108:111]
	v_mfma_f32_16x16x32_bf16 v[104:107], v[88:91], v[200:203], v[104:107]
	v_mfma_f32_16x16x32_bf16 v[84:87], v[72:75], v[208:211], v[84:87]
	v_mfma_f32_16x16x32_bf16 v[80:83], v[88:91], v[208:211], v[80:83]
	v_mfma_f32_16x16x32_bf16 v[140:143], v[76:79], v[174:177], v[140:143]
	v_mfma_f32_16x16x32_bf16 v[136:139], v[92:95], v[174:177], v[136:139]
	v_mfma_f32_16x16x32_bf16 v[124:127], v[76:79], v[196:199], v[124:127]
	v_mfma_f32_16x16x32_bf16 v[120:123], v[92:95], v[196:199], v[120:123]
	v_mfma_f32_16x16x32_bf16 v[108:111], v[76:79], v[204:207], v[108:111]
	v_mfma_f32_16x16x32_bf16 v[104:107], v[92:95], v[204:207], v[104:107]
	v_mfma_f32_16x16x32_bf16 v[84:87], v[76:79], v[212:215], v[84:87]
	v_mfma_f32_16x16x32_bf16 v[80:83], v[92:95], v[212:215], v[80:83]
	v_mfma_f32_16x16x32_bf16 v[132:135], v[152:155], v[168:171], v[132:135]
	v_mfma_f32_16x16x32_bf16 v[128:131], v[160:163], v[168:171], v[128:131]
	v_mfma_f32_16x16x32_bf16 v[116:119], v[152:155], v[192:195], v[116:119]
	v_mfma_f32_16x16x32_bf16 v[112:115], v[160:163], v[192:195], v[112:115]
	v_mfma_f32_16x16x32_bf16 v[100:103], v[152:155], v[200:203], v[100:103]
	v_mfma_f32_16x16x32_bf16 v[96:99], v[160:163], v[200:203], v[96:99]
	v_mfma_f32_16x16x32_bf16 v[68:71], v[152:155], v[208:211], v[68:71]
	v_mfma_f32_16x16x32_bf16 v[64:67], v[160:163], v[208:211], v[64:67]
	v_mfma_f32_16x16x32_bf16 v[132:135], v[156:159], v[174:177], v[132:135]
	v_mfma_f32_16x16x32_bf16 v[128:131], v[164:167], v[174:177], v[128:131]
	v_mfma_f32_16x16x32_bf16 v[116:119], v[156:159], v[196:199], v[116:119]
	v_mfma_f32_16x16x32_bf16 v[112:115], v[164:167], v[196:199], v[112:115]
	v_mfma_f32_16x16x32_bf16 v[100:103], v[156:159], v[204:207], v[100:103]
	v_mfma_f32_16x16x32_bf16 v[96:99], v[164:167], v[204:207], v[96:99]
	v_mfma_f32_16x16x32_bf16 v[68:71], v[156:159], v[212:215], v[68:71]
	v_mfma_f32_16x16x32_bf16 v[64:67], v[164:167], v[212:215], v[64:67]
	s_barrier
	s_add_i32 s70, s70, s50
	v_lshl_add_u64 v[178:179], s[40:41], 0, v[172:173]
	s_mov_b32 m0, s70
	ds_read_b128 v[168:171], v186 offset:16384
	ds_read_b128 v[174:177], v186 offset:17408
	ds_read_b128 v[192:195], v186 offset:18432
	ds_read_b128 v[196:199], v186 offset:19456
	ds_read_b128 v[200:203], v186 offset:20480
	ds_read_b128 v[204:207], v186 offset:21504
	ds_read_b128 v[208:211], v186 offset:22528
	ds_read_b128 v[212:215], v186 offset:23552
	global_load_lds_dwordx4 v[178:179], off
	s_add_i32 m0, s70, 0x2000
	s_add_u32 s70, s40, 0x80000
	v_lshl_add_u64 v[216:217], s[40:41], 0, v[144:145]
	s_addc_u32 s71, s41, 0
	s_add_i32 s72, s72, s50
	global_load_lds_dwordx4 v[216:217], off
	v_lshl_add_u64 v[218:219], s[70:71], 0, v[172:173]
	s_mov_b32 m0, s72
	v_lshl_add_u64 v[220:221], s[42:43], 0, v[144:145]
	global_load_lds_dwordx4 v[218:219], off
	v_lshl_add_u64 v[218:219], s[70:71], 0, v[144:145]
	s_add_i32 m0, s72, 0x2000
	s_nop 0
	global_load_lds_dwordx4 v[218:219], off
	v_lshl_add_u64 v[218:219], s[42:43], 0, v[172:173]
	s_mov_b32 m0, s51
	s_nop 0
	global_load_lds_dwordx4 v[218:219], off
	s_mov_b32 m0, s52
	s_nop 0
	global_load_lds_dwordx4 v[220:221], off
	s_waitcnt vmcnt(8)
	s_waitcnt lgkmcnt(0)
	s_barrier
; #define PG8_STAGE(bufoff, gbase, voff) do { _Pragma("unroll") for (int _i = 0; _i < 2; ++_i) \
;         __builtin_amdgcn_global_load_lds((const unsigned*)((const char*)(gbase) + (voff)[_i]), (PG8_LAS unsigned*)(lds + (bufoff) + ldsw + _i * 8192), 16, 0, 0); } while (0)
; #define PG8_LDA(dst, b, h) do { _Pragma("unroll") for (int m = 0; m < 4; ++m) _Pragma("unroll") for (int k = 0; k < 2; ++k) dst[m][k] = *(const PG8_LAS bf16x8*)(lds + PG8_SA(b, h) + aoff + m * 2048 + k * 1024); } while (0)
; #define PG8_LDB(dst, b, h) do { _Pragma("unroll") for (int n = 0; n < 2; ++n) _Pragma("unroll") for (int k = 0; k < 2; ++k) dst[n][k] = *(const PG8_LAS bf16x8*)(lds + PG8_SB(b, h) + boff + n * 2048 + k * 1024); } while (0)
; #define PG8_MMA(ai, bj, At, Bt) do { __builtin_amdgcn_s_setprio(1); _Pragma("unroll") for (int m = 0; m < 4; ++m) _Pragma("unroll") for (int n = 0; n < 2; ++n) _Pragma("unroll") for (int k = 0; k < 2; ++k) \
;         acc[ai][bj][m][n] = __builtin_amdgcn_mfma_f32_16x16x32_bf16(Bt[n][k], At[m][k], acc[ai][bj][m][n], 0, 0, 0); __builtin_amdgcn_s_setprio(0); } while (0)
; template <class Epi, class Sched, bool ALIGN_EPI = false, bool SP2 = false>
; __device__ __forceinline__ void gemm_phase(PG8_LAS unsigned char* lds, const Gemm g, const Sched& S, const Epi& E) {
;     ...
;             if constexpr (SP2) {
;             PG8_LDB(B0, 0, 0); PG8_LDB(B1, 0, 1); PG8_SCHED; PG8_LDA(At, 0, 0); PG8_STAGE(PG8_SA(1, 1), a1 + hstepA, voffA);
;             PG8_WAIT_V(8); PG8_WAIT_L(0); PG8_BAR; PG8_MMA(0, 0, At, B0); PG8_MMA(0, 1, At, B1); PG8_BAR; PG8_SCHED;
;             PG8_LDA(At, 0, 1); PG8_STAGE(PG8_SB(0, 0), b2, voffB); PG8_STAGE(PG8_SB(0, 1), b2 + hstepB, voffB); PG8_STAGE(PG8_SA(0, 0), a2, voffA);
;             PG8_WAIT_V(8); PG8_WAIT_L(0); PG8_BAR; PG8_MMA(1, 0, At, B0); PG8_MMA(1, 1, At, B1); PG8_BAR; PG8_SCHED;
;             PG8_LDB(B0, 1, 0); PG8_LDB(B1, 1, 1); PG8_SCHED; PG8_LDA(At, 1, 0); PG8_STAGE(PG8_SA(0, 1), a2 + hstepA, voffA);
;             PG8_WAIT_V(8); PG8_WAIT_L(0); PG8_BAR; PG8_MMA(0, 0, At, B0); PG8_MMA(0, 1, At, B1); PG8_BAR; PG8_SCHED;
;             PG8_LDA(At, 1, 1); PG8_STAGE(PG8_SB(1, 0), b3, voffB); PG8_STAGE(PG8_SB(1, 1), b3 + hstepB, voffB); PG8_STAGE(PG8_SA(1, 0), a3, voffA);
;             PG8_WAIT_V(8); PG8_WAIT_L(0); PG8_BAR; PG8_MMA(1, 0, At, B0); PG8_MMA(1, 1, At, B1); PG8_BAR; PG8_SCHED;
	s_waitcnt lgkmcnt(0)
	v_mfma_f32_16x16x32_bf16 v[60:63], v[72:75], v[168:171], v[60:63]
	v_mfma_f32_16x16x32_bf16 v[56:59], v[88:91], v[168:171], v[56:59]
	v_mfma_f32_16x16x32_bf16 v[44:47], v[72:75], v[192:195], v[44:47]
	v_mfma_f32_16x16x32_bf16 v[40:43], v[88:91], v[192:195], v[40:43]
	v_mfma_f32_16x16x32_bf16 v[28:31], v[72:75], v[200:203], v[28:31]
	v_mfma_f32_16x16x32_bf16 v[24:27], v[88:91], v[200:203], v[24:27]
	v_mfma_f32_16x16x32_bf16 v[12:15], v[72:75], v[208:211], v[12:15]
	v_mfma_f32_16x16x32_bf16 v[8:11], v[88:91], v[208:211], v[8:11]
	v_mfma_f32_16x16x32_bf16 v[60:63], v[76:79], v[174:177], v[60:63]
	v_mfma_f32_16x16x32_bf16 v[56:59], v[92:95], v[174:177], v[56:59]
	v_mfma_f32_16x16x32_bf16 v[44:47], v[76:79], v[196:199], v[44:47]
	v_mfma_f32_16x16x32_bf16 v[40:43], v[92:95], v[196:199], v[40:43]
	v_mfma_f32_16x16x32_bf16 v[28:31], v[76:79], v[204:207], v[28:31]
	v_mfma_f32_16x16x32_bf16 v[24:27], v[92:95], v[204:207], v[24:27]
	v_mfma_f32_16x16x32_bf16 v[12:15], v[76:79], v[212:215], v[12:15]
	v_mfma_f32_16x16x32_bf16 v[8:11], v[92:95], v[212:215], v[8:11]
	v_mfma_f32_16x16x32_bf16 v[52:55], v[152:155], v[168:171], v[52:55]
	v_mfma_f32_16x16x32_bf16 v[48:51], v[160:163], v[168:171], v[48:51]
	v_mfma_f32_16x16x32_bf16 v[36:39], v[152:155], v[192:195], v[36:39]
	v_mfma_f32_16x16x32_bf16 v[32:35], v[160:163], v[192:195], v[32:35]
	v_mfma_f32_16x16x32_bf16 v[20:23], v[152:155], v[200:203], v[20:23]
	v_mfma_f32_16x16x32_bf16 v[16:19], v[160:163], v[200:203], v[16:19]
	v_mfma_f32_16x16x32_bf16 v[4:7], v[152:155], v[208:211], v[4:7]
	v_mfma_f32_16x16x32_bf16 v[0:3], v[160:163], v[208:211], v[0:3]
	v_mfma_f32_16x16x32_bf16 v[52:55], v[156:159], v[174:177], v[52:55]
	v_mfma_f32_16x16x32_bf16 v[48:51], v[164:167], v[174:177], v[48:51]
	v_mfma_f32_16x16x32_bf16 v[36:39], v[156:159], v[196:199], v[36:39]
	v_mfma_f32_16x16x32_bf16 v[32:35], v[164:167], v[196:199], v[32:35]
	v_mfma_f32_16x16x32_bf16 v[20:23], v[156:159], v[204:207], v[20:23]
	v_mfma_f32_16x16x32_bf16 v[16:19], v[164:167], v[204:207], v[16:19]
	v_mfma_f32_16x16x32_bf16 v[4:7], v[156:159], v[212:215], v[4:7]
	v_mfma_f32_16x16x32_bf16 v[0:3], v[164:167], v[212:215], v[0:3]
	s_barrier
	s_add_i32 s70, 0, 0x18000
	s_add_i32 s71, 0, 0x1c000
	v_add_u32_e32 v92, s70, v181
	v_add_u32_e32 v164, s71, v181
	ds_read_b128 v[72:75], v92
	ds_read_b128 v[76:79], v92 offset:1024
	ds_read_b128 v[88:91], v92 offset:2048
	ds_read_b128 v[92:95], v92 offset:3072
	ds_read_b128 v[152:155], v164
	ds_read_b128 v[156:159], v164 offset:1024
	ds_read_b128 v[160:163], v164 offset:2048
	ds_read_b128 v[164:167], v164 offset:3072
	s_add_u32 s42, s42, 0x80000
	s_addc_u32 s43, s43, 0
	s_mov_b32 m0, s53
	v_lshl_add_u64 v[222:223], s[42:43], 0, v[172:173]
	ds_read_b128 v[168:171], v186 offset:32768
	ds_read_b128 v[174:177], v186 offset:33792
	ds_read_b128 v[192:195], v186 offset:34816
	ds_read_b128 v[196:199], v186 offset:35840
	ds_read_b128 v[200:203], v186 offset:36864
	ds_read_b128 v[204:207], v186 offset:37888
	ds_read_b128 v[208:211], v186 offset:38912
	ds_read_b128 v[212:215], v186 offset:39936
	global_load_lds_dwordx4 v[222:223], off
	v_lshl_add_u64 v[222:223], s[42:43], 0, v[144:145]
	s_mov_b32 m0, s56
	s_nop 0
	global_load_lds_dwordx4 v[222:223], off
	s_waitcnt vmcnt(8)
	s_waitcnt lgkmcnt(0)
	s_barrier
	s_waitcnt lgkmcnt(0)
	v_mfma_f32_16x16x32_bf16 v[140:143], v[72:75], v[168:171], v[140:143]
	v_mfma_f32_16x16x32_bf16 v[136:139], v[88:91], v[168:171], v[136:139]
	v_mfma_f32_16x16x32_bf16 v[124:127], v[72:75], v[192:195], v[124:127]
	v_mfma_f32_16x16x32_bf16 v[120:123], v[88:91], v[192:195], v[120:123]
	v_mfma_f32_16x16x32_bf16 v[108:111], v[72:75], v[200:203], v[108:111]
	v_mfma_f32_16x16x32_bf16 v[104:107], v[88:91], v[200:203], v[104:107]
	v_mfma_f32_16x16x32_bf16 v[84:87], v[72:75], v[208:211], v[84:87]
	v_mfma_f32_16x16x32_bf16 v[80:83], v[88:91], v[208:211], v[80:83]
	v_mfma_f32_16x16x32_bf16 v[140:143], v[76:79], v[174:177], v[140:143]
	v_mfma_f32_16x16x32_bf16 v[136:139], v[92:95], v[174:177], v[136:139]
	v_mfma_f32_16x16x32_bf16 v[124:127], v[76:79], v[196:199], v[124:127]
	v_mfma_f32_16x16x32_bf16 v[120:123], v[92:95], v[196:199], v[120:123]
	v_mfma_f32_16x16x32_bf16 v[108:111], v[76:79], v[204:207], v[108:111]
	v_mfma_f32_16x16x32_bf16 v[104:107], v[92:95], v[204:207], v[104:107]
	v_mfma_f32_16x16x32_bf16 v[84:87], v[76:79], v[212:215], v[84:87]
	v_mfma_f32_16x16x32_bf16 v[80:83], v[92:95], v[212:215], v[80:83]
	v_mfma_f32_16x16x32_bf16 v[132:135], v[152:155], v[168:171], v[132:135]
	v_mfma_f32_16x16x32_bf16 v[128:131], v[160:163], v[168:171], v[128:131]
	v_mfma_f32_16x16x32_bf16 v[116:119], v[152:155], v[192:195], v[116:119]
	v_mfma_f32_16x16x32_bf16 v[112:115], v[160:163], v[192:195], v[112:115]
	v_mfma_f32_16x16x32_bf16 v[100:103], v[152:155], v[200:203], v[100:103]
	v_mfma_f32_16x16x32_bf16 v[96:99], v[160:163], v[200:203], v[96:99]
	v_mfma_f32_16x16x32_bf16 v[68:71], v[152:155], v[208:211], v[68:71]
	v_mfma_f32_16x16x32_bf16 v[64:67], v[160:163], v[208:211], v[64:67]
	v_mfma_f32_16x16x32_bf16 v[132:135], v[156:159], v[174:177], v[132:135]
	v_mfma_f32_16x16x32_bf16 v[128:131], v[164:167], v[174:177], v[128:131]
	v_mfma_f32_16x16x32_bf16 v[116:119], v[156:159], v[196:199], v[116:119]
	v_mfma_f32_16x16x32_bf16 v[112:115], v[164:167], v[196:199], v[112:115]
	v_mfma_f32_16x16x32_bf16 v[100:103], v[156:159], v[204:207], v[100:103]
	v_mfma_f32_16x16x32_bf16 v[96:99], v[164:167], v[204:207], v[96:99]
	v_mfma_f32_16x16x32_bf16 v[68:71], v[156:159], v[212:215], v[68:71]
	v_mfma_f32_16x16x32_bf16 v[64:67], v[164:167], v[212:215], v[64:67]
	s_barrier
; template <class Epi, class Sched, bool ALIGN_EPI = false, bool SP2 = false>
; __device__ __forceinline__ void gemm_phase(PG8_LAS unsigned char* lds, const Gemm g, const Sched& S, const Epi& E) {
;     ...
;             if constexpr (SP2) {
;             PG8_LDB(B0, 0, 0); PG8_LDB(B1, 0, 1); PG8_SCHED; PG8_LDA(At, 0, 0); PG8_STAGE(PG8_SA(1, 1), a1 + hstepA, voffA);
;             PG8_WAIT_V(8); PG8_WAIT_L(0); PG8_BAR; PG8_MMA(0, 0, At, B0); PG8_MMA(0, 1, At, B1); PG8_BAR; PG8_SCHED;
;             PG8_LDA(At, 0, 1); PG8_STAGE(PG8_SB(0, 0), b2, voffB); PG8_STAGE(PG8_SB(0, 1), b2 + hstepB, voffB); PG8_STAGE(PG8_SA(0, 0), a2, voffA);
;             PG8_WAIT_V(8); PG8_WAIT_L(0); PG8_BAR; PG8_MMA(1, 0, At, B0); PG8_MMA(1, 1, At, B1); PG8_BAR; PG8_SCHED;
;             PG8_LDB(B0, 1, 0); PG8_LDB(B1, 1, 1); PG8_SCHED; PG8_LDA(At, 1, 0); PG8_STAGE(PG8_SA(0, 1), a2 + hstepA, voffA);
;             PG8_WAIT_V(8); PG8_WAIT_L(0); PG8_BAR; PG8_MMA(0, 0, At, B0); PG8_MMA(0, 1, At, B1); PG8_BAR; PG8_SCHED;
;             PG8_LDA(At, 1, 1); PG8_STAGE(PG8_SB(1, 0), b3, voffB); PG8_STAGE(PG8_SB(1, 1), b3 + hstepB, voffB); PG8_STAGE(PG8_SA(1, 0), a3, voffA);
;             PG8_WAIT_V(8); PG8_WAIT_L(0); PG8_BAR; PG8_MMA(1, 0, At, B0); PG8_MMA(1, 1, At, B1); PG8_BAR; PG8_SCHED;
;             } else {
;             PG8_LDB(B0, 0, 0); PG8_SCHED; PG8_LDA(At, 0, 0); PG8_STAGE(PG8_SA(1, 1), a1 + hstepA, voffA);
;             PG8_WAIT_L(8); PG8_BAR; PG8_WAIT_L(0); PG8_MMA(0, 0, At, B0); PG8_BAR; PG8_SCHED;
;             PG8_LDB(B1, 0, 1); PG8_STAGE(PG8_SB(0, 0), b2, voffB);
;             PG8_BAR; PG8_WAIT_L(0); PG8_MMA(0, 1, At, B1); PG8_BAR;
;             PG8_LDA(At, 0, 1); PG8_STAGE(PG8_SA(0, 0), a2, voffA);
;             PG8_BAR; PG8_WAIT_L(0); PG8_MMA(1, 0, At, B0); PG8_BAR; PG8_SCHED;
;             PG8_STAGE(PG8_SB(0, 1), b2 + hstepB, voffB);
;             PG8_WAIT_V(6); PG8_BAR; PG8_MMA(1, 1, At, B1); PG8_BAR;
;             PG8_LDB(B0, 1, 0); PG8_SCHED; PG8_LDA(At, 1, 0); PG8_STAGE(PG8_SA(0, 1), a2 + hstepA, voffA);
;             PG8_WAIT_L(8); PG8_BAR; PG8_WAIT_L(0); PG8_MMA(0, 0, At, B0); PG8_BAR; PG8_SCHED;
;             PG8_LDB(B1, 1, 1); PG8_STAGE(PG8_SB(1, 0), b3, voffB);
;             PG8_BAR; PG8_WAIT_L(0); PG8_MMA(0, 1, At, B1); PG8_BAR;
;             PG8_LDA(At, 1, 1); PG8_STAGE(PG8_SA(1, 0), a3, voffA);
;             PG8_BAR; PG8_WAIT_L(0); PG8_MMA(1, 0, At, B0); PG8_BAR; PG8_SCHED;
	s_add_i32 s42, s70, s50
	v_lshl_add_u64 v[178:179], v[178:179], 0, s[80:81]
	s_mov_b32 m0, s42
	ds_read_b128 v[168:171], v186 offset:49152
	ds_read_b128 v[174:177], v186 offset:50176
	ds_read_b128 v[192:195], v186 offset:51200
	ds_read_b128 v[196:199], v186 offset:52224
	ds_read_b128 v[200:203], v186 offset:53248
	ds_read_b128 v[204:207], v186 offset:54272
	ds_read_b128 v[208:211], v186 offset:55296
	ds_read_b128 v[212:215], v186 offset:56320
	global_load_lds_dwordx4 v[178:179], off
	s_add_i32 m0, s42, 0x2000
	s_add_u32 s40, s40, 0x80080
	v_lshl_add_u64 v[178:179], v[216:217], 0, s[80:81]
	s_addc_u32 s41, s41, 0
	s_add_i32 s42, s71, s50
	global_load_lds_dwordx4 v[178:179], off
	v_lshl_add_u64 v[178:179], s[40:41], 0, v[172:173]
	s_mov_b32 m0, s42
	s_nop 0
	global_load_lds_dwordx4 v[178:179], off
	v_lshl_add_u64 v[178:179], s[40:41], 0, v[144:145]
	s_add_i32 m0, s42, 0x2000
	s_nop 0
	global_load_lds_dwordx4 v[178:179], off
	v_lshl_add_u64 v[178:179], v[218:219], 0, s[80:81]
	s_mov_b32 m0, s61
	s_nop 0
	global_load_lds_dwordx4 v[178:179], off
	v_lshl_add_u64 v[178:179], v[220:221], 0, s[80:81]
	s_mov_b32 m0, s62
	s_nop 0
	global_load_lds_dwordx4 v[178:179], off
	s_waitcnt vmcnt(8)
	s_waitcnt lgkmcnt(0)
	s_barrier
	s_waitcnt lgkmcnt(0)
	v_mfma_f32_16x16x32_bf16 v[60:63], v[72:75], v[168:171], v[60:63]
	v_mfma_f32_16x16x32_bf16 v[56:59], v[88:91], v[168:171], v[56:59]
	v_mfma_f32_16x16x32_bf16 v[44:47], v[72:75], v[192:195], v[44:47]
	v_mfma_f32_16x16x32_bf16 v[40:43], v[88:91], v[192:195], v[40:43]
	v_mfma_f32_16x16x32_bf16 v[28:31], v[72:75], v[200:203], v[28:31]
	v_mfma_f32_16x16x32_bf16 v[24:27], v[88:91], v[200:203], v[24:27]
	v_mfma_f32_16x16x32_bf16 v[12:15], v[72:75], v[208:211], v[12:15]
	v_mfma_f32_16x16x32_bf16 v[8:11], v[88:91], v[208:211], v[8:11]
	v_mfma_f32_16x16x32_bf16 v[60:63], v[76:79], v[174:177], v[60:63]
	v_mfma_f32_16x16x32_bf16 v[56:59], v[92:95], v[174:177], v[56:59]
	v_mfma_f32_16x16x32_bf16 v[44:47], v[76:79], v[196:199], v[44:47]
	v_mfma_f32_16x16x32_bf16 v[40:43], v[92:95], v[196:199], v[40:43]
	v_mfma_f32_16x16x32_bf16 v[28:31], v[76:79], v[204:207], v[28:31]
	v_mfma_f32_16x16x32_bf16 v[24:27], v[92:95], v[204:207], v[24:27]
	v_mfma_f32_16x16x32_bf16 v[12:15], v[76:79], v[212:215], v[12:15]
	v_mfma_f32_16x16x32_bf16 v[8:11], v[92:95], v[212:215], v[8:11]
	v_mfma_f32_16x16x32_bf16 v[52:55], v[152:155], v[168:171], v[52:55]
	v_mfma_f32_16x16x32_bf16 v[48:51], v[160:163], v[168:171], v[48:51]
	v_mfma_f32_16x16x32_bf16 v[36:39], v[152:155], v[192:195], v[36:39]
	v_mfma_f32_16x16x32_bf16 v[32:35], v[160:163], v[192:195], v[32:35]
	v_mfma_f32_16x16x32_bf16 v[20:23], v[152:155], v[200:203], v[20:23]
	v_mfma_f32_16x16x32_bf16 v[16:19], v[160:163], v[200:203], v[16:19]
	v_mfma_f32_16x16x32_bf16 v[4:7], v[152:155], v[208:211], v[4:7]
	v_mfma_f32_16x16x32_bf16 v[0:3], v[160:163], v[208:211], v[0:3]
	v_mfma_f32_16x16x32_bf16 v[52:55], v[156:159], v[174:177], v[52:55]
	v_mfma_f32_16x16x32_bf16 v[48:51], v[164:167], v[174:177], v[48:51]
	v_mfma_f32_16x16x32_bf16 v[36:39], v[156:159], v[196:199], v[36:39]
	v_mfma_f32_16x16x32_bf16 v[32:35], v[164:167], v[196:199], v[32:35]
	v_mfma_f32_16x16x32_bf16 v[20:23], v[156:159], v[204:207], v[20:23]
	v_mfma_f32_16x16x32_bf16 v[16:19], v[164:167], v[204:207], v[16:19]
	v_mfma_f32_16x16x32_bf16 v[4:7], v[156:159], v[212:215], v[4:7]
	v_mfma_f32_16x16x32_bf16 v[0:3], v[164:167], v[212:215], v[0:3]
	s_barrier
	s_add_i32 s68, s68, 2
	s_add_u32 s38, s38, 0x100
	s_addc_u32 s39, s39, 0
	s_add_u32 s66, s66, 0x100
	s_addc_u32 s67, s67, 0
	s_cmp_gt_u32 s68, 29
	s_cbranch_scc0 .LBB0_533
	s_and_b64 vcc, exec, s[22:23]
	s_cbranch_vccz .LBB0_536
	s_barrier

; #define PG8_STAGE(bufoff, gbase, voff) do { _Pragma("unroll") for (int _i = 0; _i < 2; ++_i) \
;         __builtin_amdgcn_global_load_lds((const unsigned*)((const char*)(gbase) + (voff)[_i]), (PG8_LAS unsigned*)(lds + (bufoff) + ldsw + _i * 8192), 16, 0, 0); } while (0)
; #define PG8_LDA(dst, b, h) do { _Pragma("unroll") for (int m = 0; m < 4; ++m) _Pragma("unroll") for (int k = 0; k < 2; ++k) dst[m][k] = *(const PG8_LAS bf16x8*)(lds + PG8_SA(b, h) + aoff + m * 2048 + k * 1024); } while (0)
; #define PG8_LDB(dst, b, h) do { _Pragma("unroll") for (int n = 0; n < 2; ++n) _Pragma("unroll") for (int k = 0; k < 2; ++k) dst[n][k] = *(const PG8_LAS bf16x8*)(lds + PG8_SB(b, h) + boff + n * 2048 + k * 1024); } while (0)
; #define PG8_MMA(ai, bj, At, Bt) do { __builtin_amdgcn_s_setprio(1); _Pragma("unroll") for (int m = 0; m < 4; ++m) _Pragma("unroll") for (int n = 0; n < 2; ++n) _Pragma("unroll") for (int k = 0; k < 2; ++k) \
;         acc[ai][bj][m][n] = __builtin_amdgcn_mfma_f32_16x16x32_bf16(Bt[n][k], At[m][k], acc[ai][bj][m][n], 0, 0, 0); __builtin_amdgcn_s_setprio(0); } while (0)
; template <class Epi, class Sched, bool ALIGN_EPI = false, bool SP2 = false>
; __device__ __forceinline__ void gemm_phase(PG8_LAS unsigned char* lds, const Gemm g, const Sched& S, const Epi& E) {
;     ...
;             if constexpr (SP2) {
;             PG8_LDB(B0, 0, 0); PG8_LDB(B1, 0, 1); PG8_SCHED; PG8_LDA(At, 0, 0); PG8_STAGE(PG8_SA(1, 1), a1 + hstepA, voffA);
;             PG8_WAIT_V(8); PG8_WAIT_L(0); PG8_BAR; PG8_MMA(0, 0, At, B0); PG8_MMA(0, 1, At, B1); PG8_BAR; PG8_SCHED;
;             PG8_LDA(At, 0, 1); PG8_STAGE(PG8_SB(0, 0), b2, voffB); PG8_STAGE(PG8_SB(0, 1), b2 + hstepB, voffB); PG8_STAGE(PG8_SA(0, 0), a2, voffA);
;             PG8_WAIT_V(8); PG8_WAIT_L(0); PG8_BAR; PG8_MMA(1, 0, At, B0); PG8_MMA(1, 1, At, B1); PG8_BAR; PG8_SCHED;
;             PG8_LDB(B0, 1, 0); PG8_LDB(B1, 1, 1); PG8_SCHED; PG8_LDA(At, 1, 0); PG8_STAGE(PG8_SA(0, 1), a2 + hstepA, voffA);
;             PG8_WAIT_V(8); PG8_WAIT_L(0); PG8_BAR; PG8_MMA(0, 0, At, B0); PG8_MMA(0, 1, At, B1); PG8_BAR; PG8_SCHED;
;             PG8_LDA(At, 1, 1); PG8_STAGE(PG8_SB(1, 0), b3, voffB); PG8_STAGE(PG8_SB(1, 1), b3 + hstepB, voffB); PG8_STAGE(PG8_SA(1, 0), a3, voffA);
;             PG8_WAIT_V(8); PG8_WAIT_L(0); PG8_BAR; PG8_MMA(1, 0, At, B0); PG8_MMA(1, 1, At, B1); PG8_BAR; PG8_SCHED;
.LBB0_570:
	s_add_u32 s23, s26, s19
	s_addc_u32 s40, s27, 0
	s_add_u32 s36, s23, 0x100
	s_addc_u32 s37, s40, 0
	s_and_b64 s[34:35], s[30:31], exec
	s_cselect_b32 s37, s17, s37
	s_cselect_b32 s36, s16, s36
	s_add_u32 s19, s24, s19
	s_addc_u32 s34, s25, 0
	s_add_u32 s19, s19, 0x100
	s_addc_u32 s34, s34, 0
	s_add_i32 s68, 0, 0x10000
	s_and_b64 s[30:31], s[30:31], exec
	s_cselect_b32 s39, s21, s34
	s_cselect_b32 s38, s20, s19
	s_add_i32 s31, 0, 0x14000
	s_add_u32 s42, s23, 0x80080
	s_addc_u32 s43, s40, 0
	s_add_i32 s67, s68, s50
	s_add_i32 m0, s51, 0xc000
	s_add_i32 s71, s51, 0xe000
	s_add_i32 s64, s67, 0x2000
	s_add_u32 s40, s38, 0x80000
	v_add_u32_e32 v124, s68, v154
	v_add_u32_e32 v152, s31, v154
	s_addc_u32 s41, s39, 0
	s_add_i32 s66, s31, s50
	ds_read_b128 v[112:115], v124
	ds_read_b128 v[116:119], v124 offset:1024
	ds_read_b128 v[120:123], v124 offset:2048
	ds_read_b128 v[124:127], v124 offset:3072
	ds_read_b128 v[148:151], v152
	ds_read_b128 v[158:161], v152 offset:1024
	ds_read_b128 v[162:165], v152 offset:2048
	ds_read_b128 v[166:169], v152 offset:3072
	s_add_i32 s65, s66, 0x2000
	s_add_i32 s63, 0, 0x18000
	s_add_i32 s62, 0, 0x1c000
	s_add_u32 s34, s36, 0x80000
	s_addc_u32 s35, s37, 0
	s_add_i32 s23, s63, s50
	s_add_i32 s19, s23, 0x2000
	s_add_u32 s30, s38, 0x80080
	s_addc_u32 s31, s39, 0
	s_add_i32 s70, s62, s50
	s_add_i32 s68, s70, 0x2000
	v_lshl_add_u64 v[152:153], s[42:43], 0, v[146:147]
	ds_read_b128 v[174:177], v157
	ds_read_b128 v[178:181], v157 offset:1024
	ds_read_b128 v[182:185], v157 offset:2048
	ds_read_b128 v[192:195], v157 offset:3072
	ds_read_b128 v[196:199], v157 offset:4096
	ds_read_b128 v[200:203], v157 offset:5120
	ds_read_b128 v[204:207], v157 offset:6144
	ds_read_b128 v[208:211], v157 offset:7168
	global_load_lds_dwordx4 v[152:153], off
	v_lshl_add_u64 v[152:153], s[42:43], 0, v[144:145]
	s_mov_b32 m0, s71
	s_nop 0
	global_load_lds_dwordx4 v[152:153], off
	s_waitcnt vmcnt(8)
	s_waitcnt lgkmcnt(0)
	s_barrier
	s_waitcnt lgkmcnt(0)
	v_mfma_f32_16x16x32_bf16 v[140:143], v[112:115], v[174:177], v[140:143]
	v_mfma_f32_16x16x32_bf16 v[136:139], v[120:123], v[174:177], v[136:139]
	v_mfma_f32_16x16x32_bf16 v[108:111], v[112:115], v[182:185], v[108:111]
	v_mfma_f32_16x16x32_bf16 v[104:107], v[120:123], v[182:185], v[104:107]
	v_mfma_f32_16x16x32_bf16 v[92:95], v[112:115], v[196:199], v[92:95]
	v_mfma_f32_16x16x32_bf16 v[88:91], v[120:123], v[196:199], v[88:91]
	v_mfma_f32_16x16x32_bf16 v[76:79], v[112:115], v[204:207], v[76:79]
	v_mfma_f32_16x16x32_bf16 v[72:75], v[120:123], v[204:207], v[72:75]
	v_mfma_f32_16x16x32_bf16 v[140:143], v[116:119], v[178:181], v[140:143]
	v_mfma_f32_16x16x32_bf16 v[136:139], v[124:127], v[178:181], v[136:139]
	v_mfma_f32_16x16x32_bf16 v[108:111], v[116:119], v[192:195], v[108:111]
	v_mfma_f32_16x16x32_bf16 v[104:107], v[124:127], v[192:195], v[104:107]
	v_mfma_f32_16x16x32_bf16 v[92:95], v[116:119], v[200:203], v[92:95]
	v_mfma_f32_16x16x32_bf16 v[88:91], v[124:127], v[200:203], v[88:91]
	v_mfma_f32_16x16x32_bf16 v[76:79], v[116:119], v[208:211], v[76:79]
	v_mfma_f32_16x16x32_bf16 v[72:75], v[124:127], v[208:211], v[72:75]
	v_mfma_f32_16x16x32_bf16 v[132:135], v[148:151], v[174:177], v[132:135]
	v_mfma_f32_16x16x32_bf16 v[128:131], v[162:165], v[174:177], v[128:131]
	v_mfma_f32_16x16x32_bf16 v[100:103], v[148:151], v[182:185], v[100:103]
	v_mfma_f32_16x16x32_bf16 v[96:99], v[162:165], v[182:185], v[96:99]
	v_mfma_f32_16x16x32_bf16 v[84:87], v[148:151], v[196:199], v[84:87]
	v_mfma_f32_16x16x32_bf16 v[80:83], v[162:165], v[196:199], v[80:83]
	v_mfma_f32_16x16x32_bf16 v[68:71], v[148:151], v[204:207], v[68:71]
	v_mfma_f32_16x16x32_bf16 v[64:67], v[162:165], v[204:207], v[64:67]
	v_mfma_f32_16x16x32_bf16 v[132:135], v[158:161], v[178:181], v[132:135]
	v_mfma_f32_16x16x32_bf16 v[128:131], v[166:169], v[178:181], v[128:131]
	v_mfma_f32_16x16x32_bf16 v[100:103], v[158:161], v[192:195], v[100:103]
	v_mfma_f32_16x16x32_bf16 v[96:99], v[166:169], v[192:195], v[96:99]
	v_mfma_f32_16x16x32_bf16 v[84:87], v[158:161], v[200:203], v[84:87]
	v_mfma_f32_16x16x32_bf16 v[80:83], v[166:169], v[200:203], v[80:83]
	v_mfma_f32_16x16x32_bf16 v[68:71], v[158:161], v[208:211], v[68:71]
	v_mfma_f32_16x16x32_bf16 v[64:67], v[166:169], v[208:211], v[64:67]
	s_barrier
	s_mov_b32 m0, s67
	v_lshl_add_u64 v[152:153], s[38:39], 0, v[146:147]
	ds_read_b128 v[174:177], v157 offset:16384
	ds_read_b128 v[178:181], v157 offset:17408
	ds_read_b128 v[182:185], v157 offset:18432
	ds_read_b128 v[192:195], v157 offset:19456
	ds_read_b128 v[196:199], v157 offset:20480
	ds_read_b128 v[200:203], v157 offset:21504
	ds_read_b128 v[204:207], v157 offset:22528
	ds_read_b128 v[208:211], v157 offset:23552
	global_load_lds_dwordx4 v[152:153], off
	v_lshl_add_u64 v[170:171], s[38:39], 0, v[144:145]
	s_mov_b32 m0, s64
	v_lshl_add_u64 v[186:187], s[40:41], 0, v[146:147]
	global_load_lds_dwordx4 v[170:171], off
	s_mov_b32 m0, s66
	v_lshl_add_u64 v[212:213], s[36:37], 0, v[144:145]
	global_load_lds_dwordx4 v[186:187], off
	v_lshl_add_u64 v[186:187], s[40:41], 0, v[144:145]
	s_mov_b32 m0, s65
	s_nop 0
	global_load_lds_dwordx4 v[186:187], off
	v_lshl_add_u64 v[186:187], s[36:37], 0, v[146:147]
	s_mov_b32 m0, s51
	s_nop 0
	global_load_lds_dwordx4 v[186:187], off
	s_mov_b32 m0, s52
	s_nop 0
	global_load_lds_dwordx4 v[212:213], off
	s_waitcnt vmcnt(8)
	s_waitcnt lgkmcnt(0)
	s_barrier
; #define PG8_STAGE(bufoff, gbase, voff) do { _Pragma("unroll") for (int _i = 0; _i < 2; ++_i) \
;         __builtin_amdgcn_global_load_lds((const unsigned*)((const char*)(gbase) + (voff)[_i]), (PG8_LAS unsigned*)(lds + (bufoff) + ldsw + _i * 8192), 16, 0, 0); } while (0)
; #define PG8_LDA(dst, b, h) do { _Pragma("unroll") for (int m = 0; m < 4; ++m) _Pragma("unroll") for (int k = 0; k < 2; ++k) dst[m][k] = *(const PG8_LAS bf16x8*)(lds + PG8_SA(b, h) + aoff + m * 2048 + k * 1024); } while (0)
; #define PG8_LDB(dst, b, h) do { _Pragma("unroll") for (int n = 0; n < 2; ++n) _Pragma("unroll") for (int k = 0; k < 2; ++k) dst[n][k] = *(const PG8_LAS bf16x8*)(lds + PG8_SB(b, h) + boff + n * 2048 + k * 1024); } while (0)
; #define PG8_MMA(ai, bj, At, Bt) do { __builtin_amdgcn_s_setprio(1); _Pragma("unroll") for (int m = 0; m < 4; ++m) _Pragma("unroll") for (int n = 0; n < 2; ++n) _Pragma("unroll") for (int k = 0; k < 2; ++k) \
;         acc[ai][bj][m][n] = __builtin_amdgcn_mfma_f32_16x16x32_bf16(Bt[n][k], At[m][k], acc[ai][bj][m][n], 0, 0, 0); __builtin_amdgcn_s_setprio(0); } while (0)
; template <class Epi, class Sched, bool ALIGN_EPI = false, bool SP2 = false>
; __device__ __forceinline__ void gemm_phase(PG8_LAS unsigned char* lds, const Gemm g, const Sched& S, const Epi& E) {
;     ...
;             if constexpr (SP2) {
;             PG8_LDB(B0, 0, 0); PG8_LDB(B1, 0, 1); PG8_SCHED; PG8_LDA(At, 0, 0); PG8_STAGE(PG8_SA(1, 1), a1 + hstepA, voffA);
;             PG8_WAIT_V(8); PG8_WAIT_L(0); PG8_BAR; PG8_MMA(0, 0, At, B0); PG8_MMA(0, 1, At, B1); PG8_BAR; PG8_SCHED;
;             PG8_LDA(At, 0, 1); PG8_STAGE(PG8_SB(0, 0), b2, voffB); PG8_STAGE(PG8_SB(0, 1), b2 + hstepB, voffB); PG8_STAGE(PG8_SA(0, 0), a2, voffA);
;             PG8_WAIT_V(8); PG8_WAIT_L(0); PG8_BAR; PG8_MMA(1, 0, At, B0); PG8_MMA(1, 1, At, B1); PG8_BAR; PG8_SCHED;
;             PG8_LDB(B0, 1, 0); PG8_LDB(B1, 1, 1); PG8_SCHED; PG8_LDA(At, 1, 0); PG8_STAGE(PG8_SA(0, 1), a2 + hstepA, voffA);
;             PG8_WAIT_V(8); PG8_WAIT_L(0); PG8_BAR; PG8_MMA(0, 0, At, B0); PG8_MMA(0, 1, At, B1); PG8_BAR; PG8_SCHED;
;             PG8_LDA(At, 1, 1); PG8_STAGE(PG8_SB(1, 0), b3, voffB); PG8_STAGE(PG8_SB(1, 1), b3 + hstepB, voffB); PG8_STAGE(PG8_SA(1, 0), a3, voffA);
;             PG8_WAIT_V(8); PG8_WAIT_L(0); PG8_BAR; PG8_MMA(1, 0, At, B0); PG8_MMA(1, 1, At, B1); PG8_BAR; PG8_SCHED;
	s_waitcnt lgkmcnt(0)
	v_mfma_f32_16x16x32_bf16 v[60:63], v[112:115], v[174:177], v[60:63]
	v_mfma_f32_16x16x32_bf16 v[56:59], v[120:123], v[174:177], v[56:59]
	v_mfma_f32_16x16x32_bf16 v[52:55], v[112:115], v[182:185], v[52:55]
	v_mfma_f32_16x16x32_bf16 v[40:43], v[120:123], v[182:185], v[40:43]
	v_mfma_f32_16x16x32_bf16 v[36:39], v[112:115], v[196:199], v[36:39]
	v_mfma_f32_16x16x32_bf16 v[24:27], v[120:123], v[196:199], v[24:27]
	v_mfma_f32_16x16x32_bf16 v[20:23], v[112:115], v[204:207], v[20:23]
	v_mfma_f32_16x16x32_bf16 v[8:11], v[120:123], v[204:207], v[8:11]
	v_mfma_f32_16x16x32_bf16 v[60:63], v[116:119], v[178:181], v[60:63]
	v_mfma_f32_16x16x32_bf16 v[56:59], v[124:127], v[178:181], v[56:59]
	v_mfma_f32_16x16x32_bf16 v[52:55], v[116:119], v[192:195], v[52:55]
	v_mfma_f32_16x16x32_bf16 v[40:43], v[124:127], v[192:195], v[40:43]
	v_mfma_f32_16x16x32_bf16 v[36:39], v[116:119], v[200:203], v[36:39]
	v_mfma_f32_16x16x32_bf16 v[24:27], v[124:127], v[200:203], v[24:27]
	v_mfma_f32_16x16x32_bf16 v[20:23], v[116:119], v[208:211], v[20:23]
	v_mfma_f32_16x16x32_bf16 v[8:11], v[124:127], v[208:211], v[8:11]
	v_mfma_f32_16x16x32_bf16 v[48:51], v[148:151], v[174:177], v[48:51]
	v_mfma_f32_16x16x32_bf16 v[44:47], v[162:165], v[174:177], v[44:47]
	v_mfma_f32_16x16x32_bf16 v[32:35], v[148:151], v[182:185], v[32:35]
	v_mfma_f32_16x16x32_bf16 v[28:31], v[162:165], v[182:185], v[28:31]
	v_mfma_f32_16x16x32_bf16 v[16:19], v[148:151], v[196:199], v[16:19]
	v_mfma_f32_16x16x32_bf16 v[12:15], v[162:165], v[196:199], v[12:15]
	v_mfma_f32_16x16x32_bf16 v[4:7], v[148:151], v[204:207], v[4:7]
	v_mfma_f32_16x16x32_bf16 v[0:3], v[162:165], v[204:207], v[0:3]
	v_mfma_f32_16x16x32_bf16 v[48:51], v[158:161], v[178:181], v[48:51]
	v_mfma_f32_16x16x32_bf16 v[44:47], v[166:169], v[178:181], v[44:47]
	v_mfma_f32_16x16x32_bf16 v[32:35], v[158:161], v[192:195], v[32:35]
	v_mfma_f32_16x16x32_bf16 v[28:31], v[166:169], v[192:195], v[28:31]
	v_mfma_f32_16x16x32_bf16 v[16:19], v[158:161], v[200:203], v[16:19]
	v_mfma_f32_16x16x32_bf16 v[12:15], v[166:169], v[200:203], v[12:15]
	v_mfma_f32_16x16x32_bf16 v[4:7], v[158:161], v[208:211], v[4:7]
	v_mfma_f32_16x16x32_bf16 v[0:3], v[166:169], v[208:211], v[0:3]
	s_barrier
	v_add_u32_e32 v124, s63, v154
	v_add_u32_e32 v166, s62, v154
	ds_read_b128 v[112:115], v124
	ds_read_b128 v[116:119], v124 offset:1024
	ds_read_b128 v[120:123], v124 offset:2048
	ds_read_b128 v[124:127], v124 offset:3072
	ds_read_b128 v[148:151], v166
	ds_read_b128 v[158:161], v166 offset:1024
	ds_read_b128 v[162:165], v166 offset:2048
	ds_read_b128 v[166:169], v166 offset:3072
	s_mov_b32 m0, s53
	v_lshl_add_u64 v[214:215], s[34:35], 0, v[146:147]
	ds_read_b128 v[174:177], v157 offset:32768
	ds_read_b128 v[178:181], v157 offset:33792
	ds_read_b128 v[182:185], v157 offset:34816
	ds_read_b128 v[192:195], v157 offset:35840
	ds_read_b128 v[196:199], v157 offset:36864
	ds_read_b128 v[200:203], v157 offset:37888
	ds_read_b128 v[204:207], v157 offset:38912
	ds_read_b128 v[208:211], v157 offset:39936
	global_load_lds_dwordx4 v[214:215], off
	v_lshl_add_u64 v[214:215], s[34:35], 0, v[144:145]
	s_mov_b32 m0, s56
	s_nop 0
	global_load_lds_dwordx4 v[214:215], off
	s_waitcnt vmcnt(8)
	s_waitcnt lgkmcnt(0)
	s_barrier
	s_waitcnt lgkmcnt(0)
	v_mfma_f32_16x16x32_bf16 v[140:143], v[112:115], v[174:177], v[140:143]
	v_mfma_f32_16x16x32_bf16 v[136:139], v[120:123], v[174:177], v[136:139]
	v_mfma_f32_16x16x32_bf16 v[108:111], v[112:115], v[182:185], v[108:111]
	v_mfma_f32_16x16x32_bf16 v[104:107], v[120:123], v[182:185], v[104:107]
	v_mfma_f32_16x16x32_bf16 v[92:95], v[112:115], v[196:199], v[92:95]
	v_mfma_f32_16x16x32_bf16 v[88:91], v[120:123], v[196:199], v[88:91]
	v_mfma_f32_16x16x32_bf16 v[76:79], v[112:115], v[204:207], v[76:79]
	v_mfma_f32_16x16x32_bf16 v[72:75], v[120:123], v[204:207], v[72:75]
	v_mfma_f32_16x16x32_bf16 v[140:143], v[116:119], v[178:181], v[140:143]
	v_mfma_f32_16x16x32_bf16 v[136:139], v[124:127], v[178:181], v[136:139]
	v_mfma_f32_16x16x32_bf16 v[108:111], v[116:119], v[192:195], v[108:111]
	v_mfma_f32_16x16x32_bf16 v[104:107], v[124:127], v[192:195], v[104:107]
	v_mfma_f32_16x16x32_bf16 v[92:95], v[116:119], v[200:203], v[92:95]
	v_mfma_f32_16x16x32_bf16 v[88:91], v[124:127], v[200:203], v[88:91]
	v_mfma_f32_16x16x32_bf16 v[76:79], v[116:119], v[208:211], v[76:79]
	v_mfma_f32_16x16x32_bf16 v[72:75], v[124:127], v[208:211], v[72:75]
	v_mfma_f32_16x16x32_bf16 v[132:135], v[148:151], v[174:177], v[132:135]
	v_mfma_f32_16x16x32_bf16 v[128:131], v[162:165], v[174:177], v[128:131]
	v_mfma_f32_16x16x32_bf16 v[100:103], v[148:151], v[182:185], v[100:103]
	v_mfma_f32_16x16x32_bf16 v[96:99], v[162:165], v[182:185], v[96:99]
	v_mfma_f32_16x16x32_bf16 v[84:87], v[148:151], v[196:199], v[84:87]
	v_mfma_f32_16x16x32_bf16 v[80:83], v[162:165], v[196:199], v[80:83]
	v_mfma_f32_16x16x32_bf16 v[68:71], v[148:151], v[204:207], v[68:71]
	v_mfma_f32_16x16x32_bf16 v[64:67], v[162:165], v[204:207], v[64:67]
	v_mfma_f32_16x16x32_bf16 v[132:135], v[158:161], v[178:181], v[132:135]
	v_mfma_f32_16x16x32_bf16 v[128:131], v[166:169], v[178:181], v[128:131]
	v_mfma_f32_16x16x32_bf16 v[100:103], v[158:161], v[192:195], v[100:103]
	v_mfma_f32_16x16x32_bf16 v[96:99], v[166:169], v[192:195], v[96:99]
	v_mfma_f32_16x16x32_bf16 v[84:87], v[158:161], v[200:203], v[84:87]
	v_mfma_f32_16x16x32_bf16 v[80:83], v[166:169], v[200:203], v[80:83]
	v_mfma_f32_16x16x32_bf16 v[68:71], v[158:161], v[208:211], v[68:71]
	v_mfma_f32_16x16x32_bf16 v[64:67], v[166:169], v[208:211], v[64:67]
	s_barrier
; template <class Epi, class Sched, bool ALIGN_EPI = false, bool SP2 = false>
; __device__ __forceinline__ void gemm_phase(PG8_LAS unsigned char* lds, const Gemm g, const Sched& S, const Epi& E) {
;     ...
;             if constexpr (SP2) {
;             PG8_LDB(B0, 0, 0); PG8_LDB(B1, 0, 1); PG8_SCHED; PG8_LDA(At, 0, 0); PG8_STAGE(PG8_SA(1, 1), a1 + hstepA, voffA);
;             PG8_WAIT_V(8); PG8_WAIT_L(0); PG8_BAR; PG8_MMA(0, 0, At, B0); PG8_MMA(0, 1, At, B1); PG8_BAR; PG8_SCHED;
;             PG8_LDA(At, 0, 1); PG8_STAGE(PG8_SB(0, 0), b2, voffB); PG8_STAGE(PG8_SB(0, 1), b2 + hstepB, voffB); PG8_STAGE(PG8_SA(0, 0), a2, voffA);
;             PG8_WAIT_V(8); PG8_WAIT_L(0); PG8_BAR; PG8_MMA(1, 0, At, B0); PG8_MMA(1, 1, At, B1); PG8_BAR; PG8_SCHED;
;             PG8_LDB(B0, 1, 0); PG8_LDB(B1, 1, 1); PG8_SCHED; PG8_LDA(At, 1, 0); PG8_STAGE(PG8_SA(0, 1), a2 + hstepA, voffA);
;             PG8_WAIT_V(8); PG8_WAIT_L(0); PG8_BAR; PG8_MMA(0, 0, At, B0); PG8_MMA(0, 1, At, B1); PG8_BAR; PG8_SCHED;
;             PG8_LDA(At, 1, 1); PG8_STAGE(PG8_SB(1, 0), b3, voffB); PG8_STAGE(PG8_SB(1, 1), b3 + hstepB, voffB); PG8_STAGE(PG8_SA(1, 0), a3, voffA);
;             PG8_WAIT_V(8); PG8_WAIT_L(0); PG8_BAR; PG8_MMA(1, 0, At, B0); PG8_MMA(1, 1, At, B1); PG8_BAR; PG8_SCHED;
;             } else {
;             PG8_LDB(B0, 0, 0); PG8_SCHED; PG8_LDA(At, 0, 0); PG8_STAGE(PG8_SA(1, 1), a1 + hstepA, voffA);
;             PG8_WAIT_L(8); PG8_BAR; PG8_WAIT_L(0); PG8_MMA(0, 0, At, B0); PG8_BAR; PG8_SCHED;
;             PG8_LDB(B1, 0, 1); PG8_STAGE(PG8_SB(0, 0), b2, voffB);
;             PG8_BAR; PG8_WAIT_L(0); PG8_MMA(0, 1, At, B1); PG8_BAR;
;             PG8_LDA(At, 0, 1); PG8_STAGE(PG8_SA(0, 0), a2, voffA);
;             PG8_BAR; PG8_WAIT_L(0); PG8_MMA(1, 0, At, B0); PG8_BAR; PG8_SCHED;
;             PG8_STAGE(PG8_SB(0, 1), b2 + hstepB, voffB);
;             PG8_WAIT_V(6); PG8_BAR; PG8_MMA(1, 1, At, B1); PG8_BAR;
;             PG8_LDB(B0, 1, 0); PG8_SCHED; PG8_LDA(At, 1, 0); PG8_STAGE(PG8_SA(0, 1), a2 + hstepA, voffA);
;             PG8_WAIT_L(8); PG8_BAR; PG8_WAIT_L(0); PG8_MMA(0, 0, At, B0); PG8_BAR; PG8_SCHED;
;             PG8_LDB(B1, 1, 1); PG8_STAGE(PG8_SB(1, 0), b3, voffB);
;             PG8_BAR; PG8_WAIT_L(0); PG8_MMA(0, 1, At, B1); PG8_BAR;
;             PG8_LDA(At, 1, 1); PG8_STAGE(PG8_SA(1, 0), a3, voffA);
;             PG8_BAR; PG8_WAIT_L(0); PG8_MMA(1, 0, At, B0); PG8_BAR; PG8_SCHED;
	s_mov_b32 m0, s23
	v_lshl_add_u64 v[152:153], v[152:153], 0, s[80:81]
	ds_read_b128 v[174:177], v157 offset:49152
	ds_read_b128 v[178:181], v157 offset:50176
	ds_read_b128 v[182:185], v157 offset:51200
	ds_read_b128 v[192:195], v157 offset:52224
	ds_read_b128 v[196:199], v157 offset:53248
	ds_read_b128 v[200:203], v157 offset:54272
	ds_read_b128 v[204:207], v157 offset:55296
	ds_read_b128 v[208:211], v157 offset:56320
	global_load_lds_dwordx4 v[152:153], off
	v_lshl_add_u64 v[152:153], v[170:171], 0, s[80:81]
	s_mov_b32 m0, s19
	s_nop 0
	global_load_lds_dwordx4 v[152:153], off
	v_lshl_add_u64 v[152:153], s[30:31], 0, v[146:147]
	s_mov_b32 m0, s70
	s_nop 0
	global_load_lds_dwordx4 v[152:153], off
	v_lshl_add_u64 v[152:153], s[30:31], 0, v[144:145]
	s_mov_b32 m0, s68
	s_nop 0
	global_load_lds_dwordx4 v[152:153], off
	v_lshl_add_u64 v[152:153], v[186:187], 0, s[80:81]
	s_mov_b32 m0, s57
	s_nop 0
	global_load_lds_dwordx4 v[152:153], off
	v_lshl_add_u64 v[152:153], v[212:213], 0, s[80:81]
	s_mov_b32 m0, s58
	s_nop 0
	global_load_lds_dwordx4 v[152:153], off
	s_waitcnt vmcnt(8)
	s_waitcnt lgkmcnt(0)
	s_barrier
	s_waitcnt lgkmcnt(0)
	v_mfma_f32_16x16x32_bf16 v[60:63], v[112:115], v[174:177], v[60:63]
	v_mfma_f32_16x16x32_bf16 v[56:59], v[120:123], v[174:177], v[56:59]
	v_mfma_f32_16x16x32_bf16 v[52:55], v[112:115], v[182:185], v[52:55]
	v_mfma_f32_16x16x32_bf16 v[40:43], v[120:123], v[182:185], v[40:43]
	v_mfma_f32_16x16x32_bf16 v[36:39], v[112:115], v[196:199], v[36:39]
	v_mfma_f32_16x16x32_bf16 v[24:27], v[120:123], v[196:199], v[24:27]
	v_mfma_f32_16x16x32_bf16 v[20:23], v[112:115], v[204:207], v[20:23]
	v_mfma_f32_16x16x32_bf16 v[8:11], v[120:123], v[204:207], v[8:11]
	v_mfma_f32_16x16x32_bf16 v[60:63], v[116:119], v[178:181], v[60:63]
	v_mfma_f32_16x16x32_bf16 v[56:59], v[124:127], v[178:181], v[56:59]
	v_mfma_f32_16x16x32_bf16 v[52:55], v[116:119], v[192:195], v[52:55]
	v_mfma_f32_16x16x32_bf16 v[40:43], v[124:127], v[192:195], v[40:43]
	v_mfma_f32_16x16x32_bf16 v[36:39], v[116:119], v[200:203], v[36:39]
	v_mfma_f32_16x16x32_bf16 v[24:27], v[124:127], v[200:203], v[24:27]
	v_mfma_f32_16x16x32_bf16 v[20:23], v[116:119], v[208:211], v[20:23]
	v_mfma_f32_16x16x32_bf16 v[8:11], v[124:127], v[208:211], v[8:11]
	v_mfma_f32_16x16x32_bf16 v[48:51], v[148:151], v[174:177], v[48:51]
	v_mfma_f32_16x16x32_bf16 v[44:47], v[162:165], v[174:177], v[44:47]
	v_mfma_f32_16x16x32_bf16 v[32:35], v[148:151], v[182:185], v[32:35]
	v_mfma_f32_16x16x32_bf16 v[28:31], v[162:165], v[182:185], v[28:31]
	v_mfma_f32_16x16x32_bf16 v[16:19], v[148:151], v[196:199], v[16:19]
	v_mfma_f32_16x16x32_bf16 v[12:15], v[162:165], v[196:199], v[12:15]
	v_mfma_f32_16x16x32_bf16 v[4:7], v[148:151], v[204:207], v[4:7]
	v_mfma_f32_16x16x32_bf16 v[0:3], v[162:165], v[204:207], v[0:3]
	v_mfma_f32_16x16x32_bf16 v[48:51], v[158:161], v[178:181], v[48:51]
	v_mfma_f32_16x16x32_bf16 v[44:47], v[166:169], v[178:181], v[44:47]
	v_mfma_f32_16x16x32_bf16 v[32:35], v[158:161], v[192:195], v[32:35]
	v_mfma_f32_16x16x32_bf16 v[28:31], v[166:169], v[192:195], v[28:31]
	v_mfma_f32_16x16x32_bf16 v[16:19], v[158:161], v[200:203], v[16:19]
	v_mfma_f32_16x16x32_bf16 v[12:15], v[166:169], v[200:203], v[12:15]
	v_mfma_f32_16x16x32_bf16 v[4:7], v[158:161], v[208:211], v[4:7]
	v_mfma_f32_16x16x32_bf16 v[0:3], v[166:169], v[208:211], v[0:3]
	s_barrier
	s_movk_i32 s19, 0x100
	s_andn2_b64 vcc, exec, s[28:29]
	s_mov_b64 s[30:31], -1
	s_mov_b64 s[28:29], 0
	s_cbranch_vccz .LBB0_570
	s_and_b64 vcc, exec, s[10:11]
	s_cbranch_vccz .LBB0_573
	s_barrier

; #define PG8_STAGE(bufoff, gbase, voff) do { _Pragma("unroll") for (int _i = 0; _i < 2; ++_i) \
;         __builtin_amdgcn_global_load_lds((const unsigned*)((const char*)(gbase) + (voff)[_i]), (PG8_LAS unsigned*)(lds + (bufoff) + ldsw + _i * 8192), 16, 0, 0); } while (0)
; #define PG8_LDA(dst, b, h) do { _Pragma("unroll") for (int m = 0; m < 4; ++m) _Pragma("unroll") for (int k = 0; k < 2; ++k) dst[m][k] = *(const PG8_LAS bf16x8*)(lds + PG8_SA(b, h) + aoff + m * 2048 + k * 1024); } while (0)
; #define PG8_LDB(dst, b, h) do { _Pragma("unroll") for (int n = 0; n < 2; ++n) _Pragma("unroll") for (int k = 0; k < 2; ++k) dst[n][k] = *(const PG8_LAS bf16x8*)(lds + PG8_SB(b, h) + boff + n * 2048 + k * 1024); } while (0)
; #define PG8_MMA(ai, bj, At, Bt) do { __builtin_amdgcn_s_setprio(1); _Pragma("unroll") for (int m = 0; m < 4; ++m) _Pragma("unroll") for (int n = 0; n < 2; ++n) _Pragma("unroll") for (int k = 0; k < 2; ++k) \
;         acc[ai][bj][m][n] = __builtin_amdgcn_mfma_f32_16x16x32_bf16(Bt[n][k], At[m][k], acc[ai][bj][m][n], 0, 0, 0); __builtin_amdgcn_s_setprio(0); } while (0)
; template <class Epi, class Sched, bool ALIGN_EPI = false, bool SP2 = false>
; __device__ __forceinline__ void gemm_phase(PG8_LAS unsigned char* lds, const Gemm g, const Sched& S, const Epi& E) {
;     ...
;             if constexpr (SP2) {
;             PG8_LDB(B0, 0, 0); PG8_LDB(B1, 0, 1); PG8_SCHED; PG8_LDA(At, 0, 0); PG8_STAGE(PG8_SA(1, 1), a1 + hstepA, voffA);
;             PG8_WAIT_V(8); PG8_WAIT_L(0); PG8_BAR; PG8_MMA(0, 0, At, B0); PG8_MMA(0, 1, At, B1); PG8_BAR; PG8_SCHED;
;             PG8_LDA(At, 0, 1); PG8_STAGE(PG8_SB(0, 0), b2, voffB); PG8_STAGE(PG8_SB(0, 1), b2 + hstepB, voffB); PG8_STAGE(PG8_SA(0, 0), a2, voffA);
;             PG8_WAIT_V(8); PG8_WAIT_L(0); PG8_BAR; PG8_MMA(1, 0, At, B0); PG8_MMA(1, 1, At, B1); PG8_BAR; PG8_SCHED;
;             PG8_LDB(B0, 1, 0); PG8_LDB(B1, 1, 1); PG8_SCHED; PG8_LDA(At, 1, 0); PG8_STAGE(PG8_SA(0, 1), a2 + hstepA, voffA);
;             PG8_WAIT_V(8); PG8_WAIT_L(0); PG8_BAR; PG8_MMA(0, 0, At, B0); PG8_MMA(0, 1, At, B1); PG8_BAR; PG8_SCHED;
;             PG8_LDA(At, 1, 1); PG8_STAGE(PG8_SB(1, 0), b3, voffB); PG8_STAGE(PG8_SB(1, 1), b3 + hstepB, voffB); PG8_STAGE(PG8_SA(1, 0), a3, voffA);
;             PG8_WAIT_V(8); PG8_WAIT_L(0); PG8_BAR; PG8_MMA(1, 0, At, B0); PG8_MMA(1, 1, At, B1); PG8_BAR; PG8_SCHED;
.LBB0_780:
	s_add_u32 s12, s10, 0xfffc0080
	s_addc_u32 s13, s11, -1
	s_add_i32 s61, 0, 0x10000
	s_cmp_eq_u32 s21, 12
	s_cselect_b32 s15, s5, s13
	s_cselect_b32 s14, s16, s12
	s_cselect_b32 s13, s17, s20
	s_cselect_b32 s12, s18, s19
	s_add_i32 s63, 0, 0x14000
	v_add_u32_e32 v44, s61, v197
	v_add_u32_e32 v60, s63, v197
	ds_read_b128 v[32:35], v44
	ds_read_b128 v[36:39], v44 offset:1024
	ds_read_b128 v[40:43], v44 offset:2048
	ds_read_b128 v[44:47], v44 offset:3072
	ds_read_b128 v[48:51], v60
	ds_read_b128 v[52:55], v60 offset:1024
	ds_read_b128 v[56:59], v60 offset:2048
	ds_read_b128 v[60:63], v60 offset:3072
	v_lshl_add_u64 v[174:175], s[10:11], 0, v[164:165]
	s_add_i32 m0, s27, 0xc000
	ds_read_b128 v[168:171], v201
	ds_read_b128 v[178:181], v201 offset:1024
	ds_read_b128 v[182:185], v201 offset:2048
	ds_read_b128 v[202:205], v201 offset:3072
	ds_read_b128 v[206:209], v201 offset:4096
	ds_read_b128 v[210:213], v201 offset:5120
	ds_read_b128 v[214:217], v201 offset:6144
	ds_read_b128 v[218:221], v201 offset:7168
	global_load_lds_dwordx4 v[174:175], off
	v_lshl_add_u64 v[174:175], s[10:11], 0, v[166:167]
	s_add_i32 m0, s27, 0xe000
	s_nop 0
	global_load_lds_dwordx4 v[174:175], off
	s_waitcnt vmcnt(8)
	s_waitcnt lgkmcnt(0)
	s_barrier
	s_waitcnt lgkmcnt(0)
	v_mfma_f32_16x16x32_bf16 v[156:159], v[32:35], v[168:171], v[156:159]
	v_mfma_f32_16x16x32_bf16 v[152:155], v[40:43], v[168:171], v[152:155]
	v_mfma_f32_16x16x32_bf16 v[140:143], v[32:35], v[182:185], v[140:143]
	v_mfma_f32_16x16x32_bf16 v[136:139], v[40:43], v[182:185], v[136:139]
	v_mfma_f32_16x16x32_bf16 v[124:127], v[32:35], v[206:209], v[124:127]
	v_mfma_f32_16x16x32_bf16 v[120:123], v[40:43], v[206:209], v[120:123]
	v_mfma_f32_16x16x32_bf16 v[108:111], v[32:35], v[214:217], v[108:111]
	v_mfma_f32_16x16x32_bf16 v[104:107], v[40:43], v[214:217], v[104:107]
	v_mfma_f32_16x16x32_bf16 v[156:159], v[36:39], v[178:181], v[156:159]
	v_mfma_f32_16x16x32_bf16 v[152:155], v[44:47], v[178:181], v[152:155]
	v_mfma_f32_16x16x32_bf16 v[140:143], v[36:39], v[202:205], v[140:143]
	v_mfma_f32_16x16x32_bf16 v[136:139], v[44:47], v[202:205], v[136:139]
	v_mfma_f32_16x16x32_bf16 v[124:127], v[36:39], v[210:213], v[124:127]
	v_mfma_f32_16x16x32_bf16 v[120:123], v[44:47], v[210:213], v[120:123]
	v_mfma_f32_16x16x32_bf16 v[108:111], v[36:39], v[218:221], v[108:111]
	v_mfma_f32_16x16x32_bf16 v[104:107], v[44:47], v[218:221], v[104:107]
	v_mfma_f32_16x16x32_bf16 v[148:151], v[48:51], v[168:171], v[148:151]
	v_mfma_f32_16x16x32_bf16 v[144:147], v[56:59], v[168:171], v[144:147]
	v_mfma_f32_16x16x32_bf16 v[132:135], v[48:51], v[182:185], v[132:135]
	v_mfma_f32_16x16x32_bf16 v[128:131], v[56:59], v[182:185], v[128:131]
	v_mfma_f32_16x16x32_bf16 v[116:119], v[48:51], v[206:209], v[116:119]
	v_mfma_f32_16x16x32_bf16 v[112:115], v[56:59], v[206:209], v[112:115]
	v_mfma_f32_16x16x32_bf16 v[100:103], v[48:51], v[214:217], v[100:103]
	v_mfma_f32_16x16x32_bf16 v[96:99], v[56:59], v[214:217], v[96:99]
	v_mfma_f32_16x16x32_bf16 v[148:151], v[52:55], v[178:181], v[148:151]
	v_mfma_f32_16x16x32_bf16 v[144:147], v[60:63], v[178:181], v[144:147]
	v_mfma_f32_16x16x32_bf16 v[132:135], v[52:55], v[202:205], v[132:135]
	v_mfma_f32_16x16x32_bf16 v[128:131], v[60:63], v[202:205], v[128:131]
	v_mfma_f32_16x16x32_bf16 v[116:119], v[52:55], v[210:213], v[116:119]
	v_mfma_f32_16x16x32_bf16 v[112:115], v[60:63], v[210:213], v[112:115]
	v_mfma_f32_16x16x32_bf16 v[100:103], v[52:55], v[218:221], v[100:103]
	v_mfma_f32_16x16x32_bf16 v[96:99], v[60:63], v[218:221], v[96:99]
	s_barrier
	s_add_i32 s61, s61, s91
	v_lshl_add_u64 v[174:175], s[12:13], 0, v[160:161]
	s_mov_b32 m0, s61
	ds_read_b128 v[168:171], v201 offset:16384
	ds_read_b128 v[178:181], v201 offset:17408
	ds_read_b128 v[182:185], v201 offset:18432
	ds_read_b128 v[202:205], v201 offset:19456
	ds_read_b128 v[206:209], v201 offset:20480
	ds_read_b128 v[210:213], v201 offset:21504
	ds_read_b128 v[214:217], v201 offset:22528
	ds_read_b128 v[218:221], v201 offset:23552
	global_load_lds_dwordx4 v[174:175], off
	s_add_i32 m0, s61, 0x2000
	s_add_u32 s70, s12, 0x40000
	v_lshl_add_u64 v[176:177], s[12:13], 0, v[162:163]
	s_addc_u32 s71, s13, 0
	s_add_i32 s61, s63, s91
	global_load_lds_dwordx4 v[176:177], off
	v_lshl_add_u64 v[186:187], s[70:71], 0, v[160:161]
	s_mov_b32 m0, s61
	v_lshl_add_u64 v[192:193], s[14:15], 0, v[162:163]
	global_load_lds_dwordx4 v[186:187], off
	v_lshl_add_u64 v[186:187], s[70:71], 0, v[162:163]
	s_add_i32 m0, s61, 0x2000
	s_nop 0
	global_load_lds_dwordx4 v[186:187], off
	v_lshl_add_u64 v[186:187], s[14:15], 0, v[160:161]
	s_mov_b32 m0, s27
	s_nop 0
	global_load_lds_dwordx4 v[186:187], off
	s_mov_b32 m0, s93
	s_nop 0
	global_load_lds_dwordx4 v[192:193], off
	s_waitcnt vmcnt(8)
	s_waitcnt lgkmcnt(0)
	s_barrier
; #define PG8_STAGE(bufoff, gbase, voff) do { _Pragma("unroll") for (int _i = 0; _i < 2; ++_i) \
;         __builtin_amdgcn_global_load_lds((const unsigned*)((const char*)(gbase) + (voff)[_i]), (PG8_LAS unsigned*)(lds + (bufoff) + ldsw + _i * 8192), 16, 0, 0); } while (0)
; #define PG8_LDA(dst, b, h) do { _Pragma("unroll") for (int m = 0; m < 4; ++m) _Pragma("unroll") for (int k = 0; k < 2; ++k) dst[m][k] = *(const PG8_LAS bf16x8*)(lds + PG8_SA(b, h) + aoff + m * 2048 + k * 1024); } while (0)
; #define PG8_LDB(dst, b, h) do { _Pragma("unroll") for (int n = 0; n < 2; ++n) _Pragma("unroll") for (int k = 0; k < 2; ++k) dst[n][k] = *(const PG8_LAS bf16x8*)(lds + PG8_SB(b, h) + boff + n * 2048 + k * 1024); } while (0)
; #define PG8_MMA(ai, bj, At, Bt) do { __builtin_amdgcn_s_setprio(1); _Pragma("unroll") for (int m = 0; m < 4; ++m) _Pragma("unroll") for (int n = 0; n < 2; ++n) _Pragma("unroll") for (int k = 0; k < 2; ++k) \
;         acc[ai][bj][m][n] = __builtin_amdgcn_mfma_f32_16x16x32_bf16(Bt[n][k], At[m][k], acc[ai][bj][m][n], 0, 0, 0); __builtin_amdgcn_s_setprio(0); } while (0)
; #define PG8_WAIT_V(n) asm volatile("s_waitcnt vmcnt(" #n ")" ::: "memory")
; #define PG8_WAIT_L(n) asm volatile("s_waitcnt lgkmcnt(" #n ")" ::: "memory")
; #define PG8_BAR __builtin_amdgcn_s_barrier()
; #define PG8_SCHED __builtin_amdgcn_sched_barrier(0)
; template <class Epi, class Sched, bool ALIGN_EPI = false, bool SP2 = false>
; __device__ __forceinline__ void gemm_phase(PG8_LAS unsigned char* lds, const Gemm g, const Sched& S, const Epi& E) {
;     ...
;             PG8_WAIT_V(8); PG8_WAIT_L(0); PG8_BAR; PG8_MMA(1, 0, At, B0); PG8_MMA(1, 1, At, B1); PG8_BAR; PG8_SCHED;
;             PG8_LDB(B0, 1, 0); PG8_LDB(B1, 1, 1); PG8_SCHED; PG8_LDA(At, 1, 0); PG8_STAGE(PG8_SA(0, 1), a2 + hstepA, voffA);
;             PG8_WAIT_V(8); PG8_WAIT_L(0); PG8_BAR; PG8_MMA(0, 0, At, B0); PG8_MMA(0, 1, At, B1); PG8_BAR; PG8_SCHED;
	s_waitcnt lgkmcnt(0)
	v_mfma_f32_16x16x32_bf16 v[92:95], v[32:35], v[168:171], v[92:95]
	v_mfma_f32_16x16x32_bf16 v[88:91], v[40:43], v[168:171], v[88:91]
	v_mfma_f32_16x16x32_bf16 v[76:79], v[32:35], v[182:185], v[76:79]
	v_mfma_f32_16x16x32_bf16 v[72:75], v[40:43], v[182:185], v[72:75]
	v_mfma_f32_16x16x32_bf16 v[28:31], v[32:35], v[206:209], v[28:31]
	v_mfma_f32_16x16x32_bf16 v[24:27], v[40:43], v[206:209], v[24:27]
	v_mfma_f32_16x16x32_bf16 v[12:15], v[32:35], v[214:217], v[12:15]
	v_mfma_f32_16x16x32_bf16 v[8:11], v[40:43], v[214:217], v[8:11]
	v_mfma_f32_16x16x32_bf16 v[92:95], v[36:39], v[178:181], v[92:95]
	v_mfma_f32_16x16x32_bf16 v[88:91], v[44:47], v[178:181], v[88:91]
	v_mfma_f32_16x16x32_bf16 v[76:79], v[36:39], v[202:205], v[76:79]
	v_mfma_f32_16x16x32_bf16 v[72:75], v[44:47], v[202:205], v[72:75]
	v_mfma_f32_16x16x32_bf16 v[28:31], v[36:39], v[210:213], v[28:31]
	v_mfma_f32_16x16x32_bf16 v[24:27], v[44:47], v[210:213], v[24:27]
	v_mfma_f32_16x16x32_bf16 v[12:15], v[36:39], v[218:221], v[12:15]
	v_mfma_f32_16x16x32_bf16 v[8:11], v[44:47], v[218:221], v[8:11]
	v_mfma_f32_16x16x32_bf16 v[20:23], v[48:51], v[206:209], v[20:23]
	v_mfma_f32_16x16x32_bf16 v[16:19], v[56:59], v[206:209], v[16:19]
	v_mfma_f32_16x16x32_bf16 v[4:7], v[48:51], v[214:217], v[4:7]
	v_mfma_f32_16x16x32_bf16 v[0:3], v[56:59], v[214:217], v[0:3]
	v_mfma_f32_16x16x32_bf16 v[32:35], v[48:51], v[168:171], v[84:87]
	v_mfma_f32_16x16x32_bf16 v[36:39], v[56:59], v[168:171], v[80:83]
	v_mfma_f32_16x16x32_bf16 v[40:43], v[48:51], v[182:185], v[68:71]
	v_mfma_f32_16x16x32_bf16 v[44:47], v[56:59], v[182:185], v[64:67]
	v_mfma_f32_16x16x32_bf16 v[20:23], v[52:55], v[210:213], v[20:23]
	v_mfma_f32_16x16x32_bf16 v[16:19], v[60:63], v[210:213], v[16:19]
	v_mfma_f32_16x16x32_bf16 v[4:7], v[52:55], v[218:221], v[4:7]
	v_mfma_f32_16x16x32_bf16 v[0:3], v[60:63], v[218:221], v[0:3]
	v_mfma_f32_16x16x32_bf16 v[32:35], v[52:55], v[178:181], v[32:35]
	v_mfma_f32_16x16x32_bf16 v[36:39], v[60:63], v[178:181], v[36:39]
	v_mfma_f32_16x16x32_bf16 v[40:43], v[52:55], v[202:205], v[40:43]
	v_mfma_f32_16x16x32_bf16 v[44:47], v[60:63], v[202:205], v[44:47]
	s_barrier
	s_add_i32 s61, 0, 0x18000
	s_add_i32 s63, 0, 0x1c000
	v_add_u32_e32 v60, s61, v197
	v_add_u32_e32 v64, s63, v197
	ds_read_b128 v[48:51], v60
	ds_read_b128 v[52:55], v60 offset:1024
	ds_read_b128 v[56:59], v60 offset:2048
	ds_read_b128 v[60:63], v60 offset:3072
	ds_read_b128 v[168:171], v64
	ds_read_b128 v[178:181], v64 offset:1024
	ds_read_b128 v[182:185], v64 offset:2048
	ds_read_b128 v[202:205], v64 offset:3072
	s_add_u32 s14, s14, 0x40000
	s_addc_u32 s15, s15, 0
	s_mov_b32 m0, s95
	v_lshl_add_u64 v[194:195], s[14:15], 0, v[160:161]
	ds_read_b128 v[64:67], v201 offset:32768
	ds_read_b128 v[68:71], v201 offset:33792
	ds_read_b128 v[80:83], v201 offset:34816
	ds_read_b128 v[84:87], v201 offset:35840
	ds_read_b128 v[206:209], v201 offset:36864
	ds_read_b128 v[210:213], v201 offset:37888
	ds_read_b128 v[214:217], v201 offset:38912
	ds_read_b128 v[218:221], v201 offset:39936
	global_load_lds_dwordx4 v[194:195], off
	v_lshl_add_u64 v[194:195], s[14:15], 0, v[162:163]
	s_mov_b32 m0, s96
	s_nop 0
	global_load_lds_dwordx4 v[194:195], off
	s_waitcnt vmcnt(8)
	s_waitcnt lgkmcnt(0)
	s_barrier
	s_waitcnt lgkmcnt(0)
	v_mfma_f32_16x16x32_bf16 v[156:159], v[48:51], v[64:67], v[156:159]
	v_mfma_f32_16x16x32_bf16 v[152:155], v[56:59], v[64:67], v[152:155]
	v_mfma_f32_16x16x32_bf16 v[140:143], v[48:51], v[80:83], v[140:143]
	v_mfma_f32_16x16x32_bf16 v[136:139], v[56:59], v[80:83], v[136:139]
	v_mfma_f32_16x16x32_bf16 v[124:127], v[48:51], v[206:209], v[124:127]
	v_mfma_f32_16x16x32_bf16 v[120:123], v[56:59], v[206:209], v[120:123]
	v_mfma_f32_16x16x32_bf16 v[108:111], v[48:51], v[214:217], v[108:111]
	v_mfma_f32_16x16x32_bf16 v[104:107], v[56:59], v[214:217], v[104:107]
	v_mfma_f32_16x16x32_bf16 v[156:159], v[52:55], v[68:71], v[156:159]
	v_mfma_f32_16x16x32_bf16 v[152:155], v[60:63], v[68:71], v[152:155]
	v_mfma_f32_16x16x32_bf16 v[140:143], v[52:55], v[84:87], v[140:143]
	v_mfma_f32_16x16x32_bf16 v[136:139], v[60:63], v[84:87], v[136:139]
	v_mfma_f32_16x16x32_bf16 v[124:127], v[52:55], v[210:213], v[124:127]
	v_mfma_f32_16x16x32_bf16 v[120:123], v[60:63], v[210:213], v[120:123]
	v_mfma_f32_16x16x32_bf16 v[108:111], v[52:55], v[218:221], v[108:111]
	v_mfma_f32_16x16x32_bf16 v[104:107], v[60:63], v[218:221], v[104:107]
	v_mfma_f32_16x16x32_bf16 v[148:151], v[168:171], v[64:67], v[148:151]
	v_mfma_f32_16x16x32_bf16 v[64:67], v[182:185], v[64:67], v[144:147]
	v_mfma_f32_16x16x32_bf16 v[144:147], v[202:205], v[68:71], v[64:67]
	v_mfma_f32_16x16x32_bf16 v[64:67], v[168:171], v[80:83], v[132:135]
	v_mfma_f32_16x16x32_bf16 v[132:135], v[178:181], v[84:87], v[64:67]
	v_mfma_f32_16x16x32_bf16 v[64:67], v[182:185], v[80:83], v[128:131]
	v_mfma_f32_16x16x32_bf16 v[128:131], v[202:205], v[84:87], v[64:67]
	v_mfma_f32_16x16x32_bf16 v[64:67], v[168:171], v[206:209], v[116:119]
	v_mfma_f32_16x16x32_bf16 v[116:119], v[178:181], v[210:213], v[64:67]
	v_mfma_f32_16x16x32_bf16 v[64:67], v[182:185], v[206:209], v[112:115]
	v_mfma_f32_16x16x32_bf16 v[112:115], v[202:205], v[210:213], v[64:67]
	v_mfma_f32_16x16x32_bf16 v[64:67], v[168:171], v[214:217], v[100:103]
	v_mfma_f32_16x16x32_bf16 v[100:103], v[178:181], v[218:221], v[64:67]
	v_mfma_f32_16x16x32_bf16 v[64:67], v[182:185], v[214:217], v[96:99]
	v_mfma_f32_16x16x32_bf16 v[148:151], v[178:181], v[68:71], v[148:151]
	v_mfma_f32_16x16x32_bf16 v[96:99], v[202:205], v[218:221], v[64:67]
	s_barrier
; #define PG8_STAGE(bufoff, gbase, voff) do { _Pragma("unroll") for (int _i = 0; _i < 2; ++_i) \
;         __builtin_amdgcn_global_load_lds((const unsigned*)((const char*)(gbase) + (voff)[_i]), (PG8_LAS unsigned*)(lds + (bufoff) + ldsw + _i * 8192), 16, 0, 0); } while (0)
; #define PG8_LDA(dst, b, h) do { _Pragma("unroll") for (int m = 0; m < 4; ++m) _Pragma("unroll") for (int k = 0; k < 2; ++k) dst[m][k] = *(const PG8_LAS bf16x8*)(lds + PG8_SA(b, h) + aoff + m * 2048 + k * 1024); } while (0)
; #define PG8_MMA(ai, bj, At, Bt) do { __builtin_amdgcn_s_setprio(1); _Pragma("unroll") for (int m = 0; m < 4; ++m) _Pragma("unroll") for (int n = 0; n < 2; ++n) _Pragma("unroll") for (int k = 0; k < 2; ++k) \
;         acc[ai][bj][m][n] = __builtin_amdgcn_mfma_f32_16x16x32_bf16(Bt[n][k], At[m][k], acc[ai][bj][m][n], 0, 0, 0); __builtin_amdgcn_s_setprio(0); } while (0)
; #define PG8_WAIT_V(n) asm volatile("s_waitcnt vmcnt(" #n ")" ::: "memory")
; #define PG8_WAIT_L(n) asm volatile("s_waitcnt lgkmcnt(" #n ")" ::: "memory")
; #define PG8_BAR __builtin_amdgcn_s_barrier()
; #define PG8_SCHED __builtin_amdgcn_sched_barrier(0)
; template <class Epi, class Sched, bool ALIGN_EPI = false, bool SP2 = false>
; __device__ __forceinline__ void gemm_phase(PG8_LAS unsigned char* lds, const Gemm g, const Sched& S, const Epi& E) {
;     ...
;             PG8_LDA(At, 1, 1); PG8_STAGE(PG8_SB(1, 0), b3, voffB); PG8_STAGE(PG8_SB(1, 1), b3 + hstepB, voffB); PG8_STAGE(PG8_SA(1, 0), a3, voffA);
;             PG8_WAIT_V(8); PG8_WAIT_L(0); PG8_BAR; PG8_MMA(1, 0, At, B0); PG8_MMA(1, 1, At, B1); PG8_BAR; PG8_SCHED;
;     ...
;         if constexpr (ALIGN_EPI) { if (wr == 0) PG8_BAR; }
	s_add_i32 s14, s61, s91
	v_lshl_add_u64 v[80:81], v[174:175], 0, s[80:81]
	s_mov_b32 m0, s14
	s_nop 0
	ds_read_b128 v[64:67], v201 offset:49152
	ds_read_b128 v[68:71], v201 offset:50176
	ds_read_b128 v[206:209], v201 offset:51200
	ds_read_b128 v[210:213], v201 offset:52224
	ds_read_b128 v[214:217], v201 offset:53248
	ds_read_b128 v[218:221], v201 offset:54272
	ds_read_b128 v[222:225], v201 offset:55296
	ds_read_b128 v[226:229], v201 offset:56320
	global_load_lds_dwordx4 v[80:81], off
	s_add_i32 m0, s14, 0x2000
	s_add_u32 s12, s12, 0x40080
	v_lshl_add_u64 v[80:81], v[176:177], 0, s[80:81]
	s_addc_u32 s13, s13, 0
	s_add_i32 s14, s63, s91
	global_load_lds_dwordx4 v[80:81], off
	v_lshl_add_u64 v[80:81], s[12:13], 0, v[160:161]
	s_mov_b32 m0, s14
	s_nop 0
	global_load_lds_dwordx4 v[80:81], off
	v_lshl_add_u64 v[80:81], s[12:13], 0, v[162:163]
	s_add_i32 m0, s14, 0x2000
	s_nop 0
	global_load_lds_dwordx4 v[80:81], off
	v_lshl_add_u64 v[80:81], v[186:187], 0, s[80:81]
	s_mov_b32 m0, s77
	s_nop 0
	global_load_lds_dwordx4 v[80:81], off
	v_lshl_add_u64 v[80:81], v[192:193], 0, s[80:81]
	s_mov_b32 m0, s1
	s_nop 0
	global_load_lds_dwordx4 v[80:81], off
	s_waitcnt vmcnt(8)
	s_waitcnt lgkmcnt(0)
	s_barrier
	s_waitcnt lgkmcnt(0)
	v_mfma_f32_16x16x32_bf16 v[80:83], v[48:51], v[64:67], v[92:95]
	v_mfma_f32_16x16x32_bf16 v[92:95], v[52:55], v[68:71], v[80:83]
	v_mfma_f32_16x16x32_bf16 v[80:83], v[56:59], v[64:67], v[88:91]
	v_mfma_f32_16x16x32_bf16 v[76:79], v[48:51], v[206:209], v[76:79]
	v_mfma_f32_16x16x32_bf16 v[72:75], v[56:59], v[206:209], v[72:75]
	v_mfma_f32_16x16x32_bf16 v[28:31], v[48:51], v[214:217], v[28:31]
	v_mfma_f32_16x16x32_bf16 v[24:27], v[56:59], v[214:217], v[24:27]
	v_mfma_f32_16x16x32_bf16 v[12:15], v[48:51], v[222:225], v[12:15]
	v_mfma_f32_16x16x32_bf16 v[8:11], v[56:59], v[222:225], v[8:11]
	v_mfma_f32_16x16x32_bf16 v[88:91], v[60:63], v[68:71], v[80:83]
	v_mfma_f32_16x16x32_bf16 v[76:79], v[52:55], v[210:213], v[76:79]
	v_mfma_f32_16x16x32_bf16 v[72:75], v[60:63], v[210:213], v[72:75]
	v_mfma_f32_16x16x32_bf16 v[28:31], v[52:55], v[218:221], v[28:31]
	v_mfma_f32_16x16x32_bf16 v[24:27], v[60:63], v[218:221], v[24:27]
	v_mfma_f32_16x16x32_bf16 v[12:15], v[52:55], v[226:229], v[12:15]
	v_mfma_f32_16x16x32_bf16 v[8:11], v[60:63], v[226:229], v[8:11]
	v_mfma_f32_16x16x32_bf16 v[32:35], v[168:171], v[64:67], v[32:35]
	v_mfma_f32_16x16x32_bf16 v[84:87], v[178:181], v[68:71], v[32:35]
	v_mfma_f32_16x16x32_bf16 v[32:35], v[182:185], v[64:67], v[36:39]
	v_mfma_f32_16x16x32_bf16 v[80:83], v[202:205], v[68:71], v[32:35]
	v_mfma_f32_16x16x32_bf16 v[32:35], v[168:171], v[206:209], v[40:43]
	v_mfma_f32_16x16x32_bf16 v[68:71], v[178:181], v[210:213], v[32:35]
	v_mfma_f32_16x16x32_bf16 v[32:35], v[182:185], v[206:209], v[44:47]
	v_mfma_f32_16x16x32_bf16 v[20:23], v[168:171], v[214:217], v[20:23]
	v_mfma_f32_16x16x32_bf16 v[16:19], v[182:185], v[214:217], v[16:19]
	v_mfma_f32_16x16x32_bf16 v[4:7], v[168:171], v[222:225], v[4:7]
	v_mfma_f32_16x16x32_bf16 v[0:3], v[182:185], v[222:225], v[0:3]
	v_mfma_f32_16x16x32_bf16 v[64:67], v[202:205], v[210:213], v[32:35]
	v_mfma_f32_16x16x32_bf16 v[20:23], v[178:181], v[218:221], v[20:23]
	v_mfma_f32_16x16x32_bf16 v[16:19], v[202:205], v[218:221], v[16:19]
	v_mfma_f32_16x16x32_bf16 v[4:7], v[178:181], v[226:229], v[4:7]
	v_mfma_f32_16x16x32_bf16 v[0:3], v[202:205], v[226:229], v[0:3]
	s_barrier
	s_add_i32 s21, s21, 2
	s_add_u32 s10, s10, 0x100
	s_addc_u32 s11, s11, 0
	s_add_u32 s19, s19, 0x100
	s_addc_u32 s20, s20, 0
	s_cmp_gt_u32 s21, 13
	s_cbranch_scc0 .LBB0_780
	s_and_b64 vcc, exec, s[56:57]
	s_cbranch_vccz .LBB0_783
	s_barrier

;     __device__ __forceinline__ bool next(int i, Unit& u) const { const int L = i * G + c; if (L >= nsub) return false; u.pk = L >> 4; u.pm = MLAT / BM + (L & 3); u.pn = (L >> 2) & 3; return true; }
; #define PG8_STAGE(bufoff, gbase, voff) do { _Pragma("unroll") for (int _i = 0; _i < 2; ++_i) \
;         __builtin_amdgcn_global_load_lds((const unsigned*)((const char*)(gbase) + (voff)[_i]), (PG8_LAS unsigned*)(lds + (bufoff) + ldsw + _i * 8192), 16, 0, 0); } while (0)
; #define PG8_LDA(dst, b, h) do { _Pragma("unroll") for (int m = 0; m < 4; ++m) _Pragma("unroll") for (int k = 0; k < 2; ++k) dst[m][k] = *(const PG8_LAS bf16x8*)(lds + PG8_SA(b, h) + aoff + m * 2048 + k * 1024); } while (0)
; #define PG8_LDB(dst, b, h) do { _Pragma("unroll") for (int n = 0; n < 2; ++n) _Pragma("unroll") for (int k = 0; k < 2; ++k) dst[n][k] = *(const PG8_LAS bf16x8*)(lds + PG8_SB(b, h) + boff + n * 2048 + k * 1024); } while (0)
; #define PG8_WAIT_V(n) asm volatile("s_waitcnt vmcnt(" #n ")" ::: "memory")
; #define PG8_WAIT_L(n) asm volatile("s_waitcnt lgkmcnt(" #n ")" ::: "memory")
; template <class Epi, class Sched, bool ALIGN_EPI = false, bool SP2 = false>
; __device__ __forceinline__ void gemm_phase(PG8_LAS unsigned char* lds, const Gemm g, const Sched& S, const Epi& E) {
;     ...
;         const bool has_next = S.next(ui + 1, nxt);
;         const char* nA = has_next ? g.a_of(nxt) : cA; const char* nB = has_next ? g.b_of(nxt) : cB;
;         for (int t = 0; t < nt; t += 2) {
;             const bool last = (t == nt - 2);
;             const char* a1 = cA + (size_t)(t + 1) * kstep;
;             const char* a2 = last ? nA : cA + (size_t)(t + 2) * kstep; const char* b2 = last ? nB : cB + (size_t)(t + 2) * kstep;
;             const char* a3 = a2 + kstep; const char* b3 = b2 + kstep;
;             if (last && has_next) S.a_ready(nxt);
;             if constexpr (SP2) {
;             PG8_LDB(B0, 0, 0); PG8_LDB(B1, 0, 1); PG8_SCHED; PG8_LDA(At, 0, 0); PG8_STAGE(PG8_SA(1, 1), a1 + hstepA, voffA);
;             PG8_WAIT_V(8); PG8_WAIT_L(0); PG8_BAR; PG8_MMA(0, 0, At, B0); PG8_MMA(0, 1, At, B1); PG8_BAR; PG8_SCHED;
;             PG8_LDA(At, 0, 1); PG8_STAGE(PG8_SB(0, 0), b2, voffB); PG8_STAGE(PG8_SB(0, 1), b2 + hstepB, voffB); PG8_STAGE(PG8_SA(0, 0), a2, voffA);
;             PG8_WAIT_V(8); PG8_WAIT_L(0); PG8_BAR; PG8_MMA(1, 0, At, B0); PG8_MMA(1, 1, At, B1); PG8_BAR; PG8_SCHED;
.LBB0_1303:
	s_add_u32 s8, s28, 0x100
	s_addc_u32 s9, s29, 0
	s_add_i32 s63, 0, 0x10000
	s_cmp_eq_u32 s62, 2
	s_cselect_b32 s35, s25, s9
	s_cselect_b32 s34, s24, s8
	v_add_u32_e32 v142, s63, v147
	s_cselect_b32 s31, s27, s61
	s_cselect_b32 s30, s26, s59
	s_add_i32 s64, 0, 0x14000
	ds_read_b128 v[138:141], v142
	ds_read_b128 v[150:153], v142 offset:1024
	ds_read_b128 v[154:157], v142 offset:2048
	ds_read_b128 v[158:161], v142 offset:3072
	v_add_u32_e32 v142, s64, v147
	ds_read_b128 v[162:165], v142
	ds_read_b128 v[166:169], v142 offset:1024
	ds_read_b128 v[178:181], v142 offset:2048
	ds_read_b128 v[182:185], v142 offset:3072
	v_lshl_add_u64 v[142:143], s[28:29], 0, v[134:135]
	s_add_i32 m0, s46, 0xc000
	ds_read_b128 v[196:199], v149
	ds_read_b128 v[200:203], v149 offset:1024
	ds_read_b128 v[204:207], v149 offset:2048
	ds_read_b128 v[208:211], v149 offset:3072
	ds_read_b128 v[212:215], v149 offset:4096
	ds_read_b128 v[216:219], v149 offset:5120
	ds_read_b128 v[220:223], v149 offset:6144
	ds_read_b128 v[224:227], v149 offset:7168
	global_load_lds_dwordx4 v[142:143], off
	v_lshl_add_u64 v[142:143], s[28:29], 0, v[136:137]
	s_add_i32 m0, s46, 0xe000
	s_nop 0
	global_load_lds_dwordx4 v[142:143], off
	s_waitcnt vmcnt(8)
	s_waitcnt lgkmcnt(0)
	s_barrier
	s_waitcnt lgkmcnt(0)
	v_mfma_f32_16x16x32_bf16 v[124:127], v[138:141], v[196:199], v[124:127]
	v_mfma_f32_16x16x32_bf16 v[120:123], v[154:157], v[196:199], v[120:123]
	v_mfma_f32_16x16x32_bf16 v[108:111], v[138:141], v[204:207], v[108:111]
	v_mfma_f32_16x16x32_bf16 v[104:107], v[154:157], v[204:207], v[104:107]
	v_mfma_f32_16x16x32_bf16 v[92:95], v[138:141], v[212:215], v[92:95]
	v_mfma_f32_16x16x32_bf16 v[88:91], v[154:157], v[212:215], v[88:91]
	v_mfma_f32_16x16x32_bf16 v[76:79], v[138:141], v[220:223], v[76:79]
	v_mfma_f32_16x16x32_bf16 v[72:75], v[154:157], v[220:223], v[72:75]
	v_mfma_f32_16x16x32_bf16 v[124:127], v[150:153], v[200:203], v[124:127]
	v_mfma_f32_16x16x32_bf16 v[120:123], v[158:161], v[200:203], v[120:123]
	v_mfma_f32_16x16x32_bf16 v[108:111], v[150:153], v[208:211], v[108:111]
	v_mfma_f32_16x16x32_bf16 v[104:107], v[158:161], v[208:211], v[104:107]
	v_mfma_f32_16x16x32_bf16 v[92:95], v[150:153], v[216:219], v[92:95]
	v_mfma_f32_16x16x32_bf16 v[88:91], v[158:161], v[216:219], v[88:91]
	v_mfma_f32_16x16x32_bf16 v[76:79], v[150:153], v[224:227], v[76:79]
	v_mfma_f32_16x16x32_bf16 v[72:75], v[158:161], v[224:227], v[72:75]
	v_mfma_f32_16x16x32_bf16 v[116:119], v[162:165], v[196:199], v[116:119]
	v_mfma_f32_16x16x32_bf16 v[112:115], v[178:181], v[196:199], v[112:115]
	v_mfma_f32_16x16x32_bf16 v[100:103], v[162:165], v[204:207], v[100:103]
	v_mfma_f32_16x16x32_bf16 v[96:99], v[178:181], v[204:207], v[96:99]
	v_mfma_f32_16x16x32_bf16 v[84:87], v[162:165], v[212:215], v[84:87]
	v_mfma_f32_16x16x32_bf16 v[80:83], v[178:181], v[212:215], v[80:83]
	v_mfma_f32_16x16x32_bf16 v[68:71], v[162:165], v[220:223], v[68:71]
	v_mfma_f32_16x16x32_bf16 v[64:67], v[178:181], v[220:223], v[64:67]
	v_mfma_f32_16x16x32_bf16 v[116:119], v[166:169], v[200:203], v[116:119]
	v_mfma_f32_16x16x32_bf16 v[112:115], v[182:185], v[200:203], v[112:115]
	v_mfma_f32_16x16x32_bf16 v[100:103], v[166:169], v[208:211], v[100:103]
	v_mfma_f32_16x16x32_bf16 v[96:99], v[182:185], v[208:211], v[96:99]
	v_mfma_f32_16x16x32_bf16 v[84:87], v[166:169], v[216:219], v[84:87]
	v_mfma_f32_16x16x32_bf16 v[80:83], v[182:185], v[216:219], v[80:83]
	v_mfma_f32_16x16x32_bf16 v[68:71], v[166:169], v[224:227], v[68:71]
	v_mfma_f32_16x16x32_bf16 v[64:67], v[182:185], v[224:227], v[64:67]
	s_barrier
	s_add_i32 s28, s63, s43
	v_lshl_add_u64 v[142:143], s[30:31], 0, v[172:173]
	s_mov_b32 m0, s28
	ds_read_b128 v[196:199], v149 offset:16384
	ds_read_b128 v[200:203], v149 offset:17408
	ds_read_b128 v[204:207], v149 offset:18432
	ds_read_b128 v[208:211], v149 offset:19456
	ds_read_b128 v[212:215], v149 offset:20480
	ds_read_b128 v[216:219], v149 offset:21504
	ds_read_b128 v[220:223], v149 offset:22528
	ds_read_b128 v[224:227], v149 offset:23552
	global_load_lds_dwordx4 v[142:143], off
	s_add_i32 m0, s28, 0x2000
	s_add_u32 s28, s30, 0x6000
	v_lshl_add_u64 v[170:171], s[30:31], 0, v[132:133]
	s_addc_u32 s29, s31, 0
	s_add_i32 s63, s64, s43
	global_load_lds_dwordx4 v[170:171], off
	v_lshl_add_u64 v[174:175], s[28:29], 0, v[172:173]
	s_mov_b32 m0, s63
	v_lshl_add_u64 v[176:177], s[34:35], 0, v[130:131]
	global_load_lds_dwordx4 v[174:175], off
	v_lshl_add_u64 v[174:175], s[28:29], 0, v[132:133]
	s_add_i32 m0, s63, 0x2000
	s_nop 0
	global_load_lds_dwordx4 v[174:175], off
	v_lshl_add_u64 v[174:175], s[34:35], 0, v[128:129]
	s_mov_b32 m0, s46
	s_nop 0
	global_load_lds_dwordx4 v[174:175], off
	s_mov_b32 m0, s47
	s_nop 0
	global_load_lds_dwordx4 v[176:177], off
	s_waitcnt vmcnt(8)
	s_waitcnt lgkmcnt(0)
	s_barrier
; #define PG8_STAGE(bufoff, gbase, voff) do { _Pragma("unroll") for (int _i = 0; _i < 2; ++_i) \
;         __builtin_amdgcn_global_load_lds((const unsigned*)((const char*)(gbase) + (voff)[_i]), (PG8_LAS unsigned*)(lds + (bufoff) + ldsw + _i * 8192), 16, 0, 0); } while (0)
; #define PG8_LDA(dst, b, h) do { _Pragma("unroll") for (int m = 0; m < 4; ++m) _Pragma("unroll") for (int k = 0; k < 2; ++k) dst[m][k] = *(const PG8_LAS bf16x8*)(lds + PG8_SA(b, h) + aoff + m * 2048 + k * 1024); } while (0)
; #define PG8_LDB(dst, b, h) do { _Pragma("unroll") for (int n = 0; n < 2; ++n) _Pragma("unroll") for (int k = 0; k < 2; ++k) dst[n][k] = *(const PG8_LAS bf16x8*)(lds + PG8_SB(b, h) + boff + n * 2048 + k * 1024); } while (0)
; #define PG8_MMA(ai, bj, At, Bt) do { __builtin_amdgcn_s_setprio(1); _Pragma("unroll") for (int m = 0; m < 4; ++m) _Pragma("unroll") for (int n = 0; n < 2; ++n) _Pragma("unroll") for (int k = 0; k < 2; ++k) \
;         acc[ai][bj][m][n] = __builtin_amdgcn_mfma_f32_16x16x32_bf16(Bt[n][k], At[m][k], acc[ai][bj][m][n], 0, 0, 0); __builtin_amdgcn_s_setprio(0); } while (0)
; #define PG8_WAIT_V(n) asm volatile("s_waitcnt vmcnt(" #n ")" ::: "memory")
; #define PG8_WAIT_L(n) asm volatile("s_waitcnt lgkmcnt(" #n ")" ::: "memory")
; #define PG8_BAR __builtin_amdgcn_s_barrier()
; #define PG8_SCHED __builtin_amdgcn_sched_barrier(0)
; template <class Epi, class Sched, bool ALIGN_EPI = false, bool SP2 = false>
; __device__ __forceinline__ void gemm_phase(PG8_LAS unsigned char* lds, const Gemm g, const Sched& S, const Epi& E) {
;     ...
;             PG8_WAIT_V(8); PG8_WAIT_L(0); PG8_BAR; PG8_MMA(1, 0, At, B0); PG8_MMA(1, 1, At, B1); PG8_BAR; PG8_SCHED;
;             PG8_LDB(B0, 1, 0); PG8_LDB(B1, 1, 1); PG8_SCHED; PG8_LDA(At, 1, 0); PG8_STAGE(PG8_SA(0, 1), a2 + hstepA, voffA);
;             PG8_WAIT_V(8); PG8_WAIT_L(0); PG8_BAR; PG8_MMA(0, 0, At, B0); PG8_MMA(0, 1, At, B1); PG8_BAR; PG8_SCHED;
	s_waitcnt lgkmcnt(0)
	v_mfma_f32_16x16x32_bf16 v[60:63], v[138:141], v[196:199], v[60:63]
	v_mfma_f32_16x16x32_bf16 v[56:59], v[154:157], v[196:199], v[56:59]
	v_mfma_f32_16x16x32_bf16 v[44:47], v[138:141], v[204:207], v[44:47]
	v_mfma_f32_16x16x32_bf16 v[40:43], v[154:157], v[204:207], v[40:43]
	v_mfma_f32_16x16x32_bf16 v[28:31], v[138:141], v[212:215], v[28:31]
	v_mfma_f32_16x16x32_bf16 v[24:27], v[154:157], v[212:215], v[24:27]
	v_mfma_f32_16x16x32_bf16 v[12:15], v[138:141], v[220:223], v[12:15]
	v_mfma_f32_16x16x32_bf16 v[8:11], v[154:157], v[220:223], v[8:11]
	v_mfma_f32_16x16x32_bf16 v[60:63], v[150:153], v[200:203], v[60:63]
	v_mfma_f32_16x16x32_bf16 v[56:59], v[158:161], v[200:203], v[56:59]
	v_mfma_f32_16x16x32_bf16 v[44:47], v[150:153], v[208:211], v[44:47]
	v_mfma_f32_16x16x32_bf16 v[40:43], v[158:161], v[208:211], v[40:43]
	v_mfma_f32_16x16x32_bf16 v[28:31], v[150:153], v[216:219], v[28:31]
	v_mfma_f32_16x16x32_bf16 v[24:27], v[158:161], v[216:219], v[24:27]
	v_mfma_f32_16x16x32_bf16 v[12:15], v[150:153], v[224:227], v[12:15]
	v_mfma_f32_16x16x32_bf16 v[8:11], v[158:161], v[224:227], v[8:11]
	v_mfma_f32_16x16x32_bf16 v[52:55], v[162:165], v[196:199], v[52:55]
	v_mfma_f32_16x16x32_bf16 v[48:51], v[178:181], v[196:199], v[48:51]
	v_mfma_f32_16x16x32_bf16 v[36:39], v[162:165], v[204:207], v[36:39]
	v_mfma_f32_16x16x32_bf16 v[32:35], v[178:181], v[204:207], v[32:35]
	v_mfma_f32_16x16x32_bf16 v[20:23], v[162:165], v[212:215], v[20:23]
	v_mfma_f32_16x16x32_bf16 v[16:19], v[178:181], v[212:215], v[16:19]
	v_mfma_f32_16x16x32_bf16 v[4:7], v[162:165], v[220:223], v[4:7]
	v_mfma_f32_16x16x32_bf16 v[0:3], v[178:181], v[220:223], v[0:3]
	v_mfma_f32_16x16x32_bf16 v[52:55], v[166:169], v[200:203], v[52:55]
	v_mfma_f32_16x16x32_bf16 v[48:51], v[182:185], v[200:203], v[48:51]
	v_mfma_f32_16x16x32_bf16 v[36:39], v[166:169], v[208:211], v[36:39]
	v_mfma_f32_16x16x32_bf16 v[32:35], v[182:185], v[208:211], v[32:35]
	v_mfma_f32_16x16x32_bf16 v[20:23], v[166:169], v[216:219], v[20:23]
	v_mfma_f32_16x16x32_bf16 v[16:19], v[182:185], v[216:219], v[16:19]
	v_mfma_f32_16x16x32_bf16 v[4:7], v[166:169], v[224:227], v[4:7]
	v_mfma_f32_16x16x32_bf16 v[0:3], v[182:185], v[224:227], v[0:3]
	s_barrier
	s_add_i32 s63, 0, 0x18000
	v_add_u32_e32 v144, s63, v147
	s_add_i32 s64, 0, 0x1c000
	ds_read_b128 v[138:141], v144
	ds_read_b128 v[150:153], v144 offset:1024
	ds_read_b128 v[154:157], v144 offset:2048
	ds_read_b128 v[158:161], v144 offset:3072
	v_add_u32_e32 v144, s64, v147
	ds_read_b128 v[162:165], v144
	ds_read_b128 v[166:169], v144 offset:1024
	ds_read_b128 v[178:181], v144 offset:2048
	ds_read_b128 v[182:185], v144 offset:3072
	s_add_u32 s28, s34, 0x18000
	s_addc_u32 s29, s35, 0
	s_mov_b32 m0, s50
	v_lshl_add_u64 v[186:187], s[28:29], 0, v[128:129]
	ds_read_b128 v[196:199], v149 offset:32768
	ds_read_b128 v[200:203], v149 offset:33792
	ds_read_b128 v[204:207], v149 offset:34816
	ds_read_b128 v[208:211], v149 offset:35840
	ds_read_b128 v[212:215], v149 offset:36864
	ds_read_b128 v[216:219], v149 offset:37888
	ds_read_b128 v[220:223], v149 offset:38912
	ds_read_b128 v[224:227], v149 offset:39936
	global_load_lds_dwordx4 v[186:187], off
	v_lshl_add_u64 v[186:187], s[28:29], 0, v[130:131]
	s_mov_b32 m0, s51
	s_nop 0
	global_load_lds_dwordx4 v[186:187], off
	s_waitcnt vmcnt(8)
	s_waitcnt lgkmcnt(0)
	s_barrier
	s_waitcnt lgkmcnt(0)
	v_mfma_f32_16x16x32_bf16 v[124:127], v[138:141], v[196:199], v[124:127]
	v_mfma_f32_16x16x32_bf16 v[120:123], v[154:157], v[196:199], v[120:123]
	v_mfma_f32_16x16x32_bf16 v[108:111], v[138:141], v[204:207], v[108:111]
	v_mfma_f32_16x16x32_bf16 v[104:107], v[154:157], v[204:207], v[104:107]
	v_mfma_f32_16x16x32_bf16 v[92:95], v[138:141], v[212:215], v[92:95]
	v_mfma_f32_16x16x32_bf16 v[88:91], v[154:157], v[212:215], v[88:91]
	v_mfma_f32_16x16x32_bf16 v[76:79], v[138:141], v[220:223], v[76:79]
	v_mfma_f32_16x16x32_bf16 v[72:75], v[154:157], v[220:223], v[72:75]
	v_mfma_f32_16x16x32_bf16 v[124:127], v[150:153], v[200:203], v[124:127]
	v_mfma_f32_16x16x32_bf16 v[120:123], v[158:161], v[200:203], v[120:123]
	v_mfma_f32_16x16x32_bf16 v[108:111], v[150:153], v[208:211], v[108:111]
	v_mfma_f32_16x16x32_bf16 v[104:107], v[158:161], v[208:211], v[104:107]
	v_mfma_f32_16x16x32_bf16 v[92:95], v[150:153], v[216:219], v[92:95]
	v_mfma_f32_16x16x32_bf16 v[88:91], v[158:161], v[216:219], v[88:91]
	v_mfma_f32_16x16x32_bf16 v[76:79], v[150:153], v[224:227], v[76:79]
	v_mfma_f32_16x16x32_bf16 v[72:75], v[158:161], v[224:227], v[72:75]
	v_mfma_f32_16x16x32_bf16 v[116:119], v[162:165], v[196:199], v[116:119]
	v_mfma_f32_16x16x32_bf16 v[112:115], v[178:181], v[196:199], v[112:115]
	v_mfma_f32_16x16x32_bf16 v[100:103], v[162:165], v[204:207], v[100:103]
	v_mfma_f32_16x16x32_bf16 v[96:99], v[178:181], v[204:207], v[96:99]
	v_mfma_f32_16x16x32_bf16 v[84:87], v[162:165], v[212:215], v[84:87]
	v_mfma_f32_16x16x32_bf16 v[80:83], v[178:181], v[212:215], v[80:83]
	v_mfma_f32_16x16x32_bf16 v[68:71], v[162:165], v[220:223], v[68:71]
	v_mfma_f32_16x16x32_bf16 v[64:67], v[178:181], v[220:223], v[64:67]
	v_mfma_f32_16x16x32_bf16 v[116:119], v[166:169], v[200:203], v[116:119]
	v_mfma_f32_16x16x32_bf16 v[112:115], v[182:185], v[200:203], v[112:115]
	v_mfma_f32_16x16x32_bf16 v[100:103], v[166:169], v[208:211], v[100:103]
	v_mfma_f32_16x16x32_bf16 v[96:99], v[182:185], v[208:211], v[96:99]
	v_mfma_f32_16x16x32_bf16 v[84:87], v[166:169], v[216:219], v[84:87]
	v_mfma_f32_16x16x32_bf16 v[80:83], v[182:185], v[216:219], v[80:83]
	v_mfma_f32_16x16x32_bf16 v[68:71], v[166:169], v[224:227], v[68:71]
	v_mfma_f32_16x16x32_bf16 v[64:67], v[182:185], v[224:227], v[64:67]
	s_barrier
; #define PG8_STAGE(bufoff, gbase, voff) do { _Pragma("unroll") for (int _i = 0; _i < 2; ++_i) \
;         __builtin_amdgcn_global_load_lds((const unsigned*)((const char*)(gbase) + (voff)[_i]), (PG8_LAS unsigned*)(lds + (bufoff) + ldsw + _i * 8192), 16, 0, 0); } while (0)
; #define PG8_LDA(dst, b, h) do { _Pragma("unroll") for (int m = 0; m < 4; ++m) _Pragma("unroll") for (int k = 0; k < 2; ++k) dst[m][k] = *(const PG8_LAS bf16x8*)(lds + PG8_SA(b, h) + aoff + m * 2048 + k * 1024); } while (0)
; #define PG8_MMA(ai, bj, At, Bt) do { __builtin_amdgcn_s_setprio(1); _Pragma("unroll") for (int m = 0; m < 4; ++m) _Pragma("unroll") for (int n = 0; n < 2; ++n) _Pragma("unroll") for (int k = 0; k < 2; ++k) \
;         acc[ai][bj][m][n] = __builtin_amdgcn_mfma_f32_16x16x32_bf16(Bt[n][k], At[m][k], acc[ai][bj][m][n], 0, 0, 0); __builtin_amdgcn_s_setprio(0); } while (0)
; #define PG8_WAIT_V(n) asm volatile("s_waitcnt vmcnt(" #n ")" ::: "memory")
; #define PG8_WAIT_L(n) asm volatile("s_waitcnt lgkmcnt(" #n ")" ::: "memory")
; #define PG8_BAR __builtin_amdgcn_s_barrier()
; #define PG8_SCHED __builtin_amdgcn_sched_barrier(0)
; template <class Epi, class Sched, bool ALIGN_EPI = false, bool SP2 = false>
; __device__ __forceinline__ void gemm_phase(PG8_LAS unsigned char* lds, const Gemm g, const Sched& S, const Epi& E) {
;     ...
;             PG8_LDA(At, 1, 1); PG8_STAGE(PG8_SB(1, 0), b3, voffB); PG8_STAGE(PG8_SB(1, 1), b3 + hstepB, voffB); PG8_STAGE(PG8_SA(1, 0), a3, voffA);
;             PG8_WAIT_V(8); PG8_WAIT_L(0); PG8_BAR; PG8_MMA(1, 0, At, B0); PG8_MMA(1, 1, At, B1); PG8_BAR; PG8_SCHED;
;     ...
;         if constexpr (ALIGN_EPI) { if (wr == 0) PG8_BAR; }
	s_add_i32 s28, s63, s43
	v_lshl_add_u64 v[142:143], v[142:143], 0, s[80:81]
	s_mov_b32 m0, s28
	ds_read_b128 v[196:199], v149 offset:49152
	ds_read_b128 v[200:203], v149 offset:50176
	ds_read_b128 v[204:207], v149 offset:51200
	ds_read_b128 v[208:211], v149 offset:52224
	ds_read_b128 v[212:215], v149 offset:53248
	ds_read_b128 v[216:219], v149 offset:54272
	ds_read_b128 v[220:223], v149 offset:55296
	ds_read_b128 v[224:227], v149 offset:56320
	global_load_lds_dwordx4 v[142:143], off
	s_add_i32 m0, s28, 0x2000
	s_add_u32 s28, s30, 0x6080
	v_lshl_add_u64 v[142:143], v[170:171], 0, s[80:81]
	s_addc_u32 s29, s31, 0
	s_add_i32 s30, s64, s43
	global_load_lds_dwordx4 v[142:143], off
	v_lshl_add_u64 v[142:143], s[28:29], 0, v[172:173]
	s_mov_b32 m0, s30
	s_nop 0
	global_load_lds_dwordx4 v[142:143], off
	v_lshl_add_u64 v[142:143], s[28:29], 0, v[132:133]
	s_add_i32 m0, s30, 0x2000
	s_nop 0
	global_load_lds_dwordx4 v[142:143], off
	v_lshl_add_u64 v[142:143], v[174:175], 0, s[80:81]
	s_mov_b32 m0, s52
	s_nop 0
	global_load_lds_dwordx4 v[142:143], off
	v_lshl_add_u64 v[142:143], v[176:177], 0, s[80:81]
	s_mov_b32 m0, s53
	s_nop 0
	global_load_lds_dwordx4 v[142:143], off
	s_waitcnt vmcnt(8)
	s_waitcnt lgkmcnt(0)
	s_barrier
	s_waitcnt lgkmcnt(0)
	v_mfma_f32_16x16x32_bf16 v[60:63], v[138:141], v[196:199], v[60:63]
	v_mfma_f32_16x16x32_bf16 v[56:59], v[154:157], v[196:199], v[56:59]
	v_mfma_f32_16x16x32_bf16 v[44:47], v[138:141], v[204:207], v[44:47]
	v_mfma_f32_16x16x32_bf16 v[40:43], v[154:157], v[204:207], v[40:43]
	v_mfma_f32_16x16x32_bf16 v[28:31], v[138:141], v[212:215], v[28:31]
	v_mfma_f32_16x16x32_bf16 v[24:27], v[154:157], v[212:215], v[24:27]
	v_mfma_f32_16x16x32_bf16 v[12:15], v[138:141], v[220:223], v[12:15]
	v_mfma_f32_16x16x32_bf16 v[8:11], v[154:157], v[220:223], v[8:11]
	v_mfma_f32_16x16x32_bf16 v[60:63], v[150:153], v[200:203], v[60:63]
	v_mfma_f32_16x16x32_bf16 v[56:59], v[158:161], v[200:203], v[56:59]
	v_mfma_f32_16x16x32_bf16 v[44:47], v[150:153], v[208:211], v[44:47]
	v_mfma_f32_16x16x32_bf16 v[40:43], v[158:161], v[208:211], v[40:43]
	v_mfma_f32_16x16x32_bf16 v[28:31], v[150:153], v[216:219], v[28:31]
	v_mfma_f32_16x16x32_bf16 v[24:27], v[158:161], v[216:219], v[24:27]
	v_mfma_f32_16x16x32_bf16 v[12:15], v[150:153], v[224:227], v[12:15]
	v_mfma_f32_16x16x32_bf16 v[8:11], v[158:161], v[224:227], v[8:11]
	v_mfma_f32_16x16x32_bf16 v[52:55], v[162:165], v[196:199], v[52:55]
	v_mfma_f32_16x16x32_bf16 v[48:51], v[178:181], v[196:199], v[48:51]
	v_mfma_f32_16x16x32_bf16 v[36:39], v[162:165], v[204:207], v[36:39]
	v_mfma_f32_16x16x32_bf16 v[32:35], v[178:181], v[204:207], v[32:35]
	v_mfma_f32_16x16x32_bf16 v[20:23], v[162:165], v[212:215], v[20:23]
	v_mfma_f32_16x16x32_bf16 v[16:19], v[178:181], v[212:215], v[16:19]
	v_mfma_f32_16x16x32_bf16 v[4:7], v[162:165], v[220:223], v[4:7]
	v_mfma_f32_16x16x32_bf16 v[0:3], v[178:181], v[220:223], v[0:3]
	v_mfma_f32_16x16x32_bf16 v[52:55], v[166:169], v[200:203], v[52:55]
	v_mfma_f32_16x16x32_bf16 v[48:51], v[182:185], v[200:203], v[48:51]
	v_mfma_f32_16x16x32_bf16 v[36:39], v[166:169], v[208:211], v[36:39]
	v_mfma_f32_16x16x32_bf16 v[32:35], v[182:185], v[208:211], v[32:35]
	v_mfma_f32_16x16x32_bf16 v[20:23], v[166:169], v[216:219], v[20:23]
	v_mfma_f32_16x16x32_bf16 v[16:19], v[182:185], v[216:219], v[16:19]
	v_mfma_f32_16x16x32_bf16 v[4:7], v[166:169], v[224:227], v[4:7]
	v_mfma_f32_16x16x32_bf16 v[0:3], v[182:185], v[224:227], v[0:3]
	s_barrier
	s_add_i32 s62, s62, 2
	s_add_u32 s59, s59, 0x100
	s_addc_u32 s61, s61, 0
	s_cmp_gt_u32 s62, 3
	s_mov_b64 s[28:29], s[8:9]
	s_cbranch_scc0 .LBB0_1303
	s_and_b64 vcc, exec, s[20:21]
	s_cbranch_vccz .LBB0_1306
	s_barrier

;     __device__ __forceinline__ bool next(int i, Unit& u) const { const int L = i * G + c; if (L >= nsub) return false; u.pk = L >> 4; u.pm = MLAT / BM + (L & 3); u.pn = (L >> 2) & 3; return true; }
; #define PG8_STAGE(bufoff, gbase, voff) do { _Pragma("unroll") for (int _i = 0; _i < 2; ++_i) \
;         __builtin_amdgcn_global_load_lds((const unsigned*)((const char*)(gbase) + (voff)[_i]), (PG8_LAS unsigned*)(lds + (bufoff) + ldsw + _i * 8192), 16, 0, 0); } while (0)
; #define PG8_LDA(dst, b, h) do { _Pragma("unroll") for (int m = 0; m < 4; ++m) _Pragma("unroll") for (int k = 0; k < 2; ++k) dst[m][k] = *(const PG8_LAS bf16x8*)(lds + PG8_SA(b, h) + aoff + m * 2048 + k * 1024); } while (0)
; #define PG8_LDB(dst, b, h) do { _Pragma("unroll") for (int n = 0; n < 2; ++n) _Pragma("unroll") for (int k = 0; k < 2; ++k) dst[n][k] = *(const PG8_LAS bf16x8*)(lds + PG8_SB(b, h) + boff + n * 2048 + k * 1024); } while (0)
; #define PG8_WAIT_V(n) asm volatile("s_waitcnt vmcnt(" #n ")" ::: "memory")
; #define PG8_WAIT_L(n) asm volatile("s_waitcnt lgkmcnt(" #n ")" ::: "memory")
; template <class Epi, class Sched, bool ALIGN_EPI = false, bool SP2 = false>
; __device__ __forceinline__ void gemm_phase(PG8_LAS unsigned char* lds, const Gemm g, const Sched& S, const Epi& E) {
;     ...
;         const bool has_next = S.next(ui + 1, nxt);
;         const char* nA = has_next ? g.a_of(nxt) : cA; const char* nB = has_next ? g.b_of(nxt) : cB;
;         for (int t = 0; t < nt; t += 2) {
;             const bool last = (t == nt - 2);
;             const char* a1 = cA + (size_t)(t + 1) * kstep;
;             const char* a2 = last ? nA : cA + (size_t)(t + 2) * kstep; const char* b2 = last ? nB : cB + (size_t)(t + 2) * kstep;
;             const char* a3 = a2 + kstep; const char* b3 = b2 + kstep;
;             if (last && has_next) S.a_ready(nxt);
;             if constexpr (SP2) {
;             PG8_LDB(B0, 0, 0); PG8_LDB(B1, 0, 1); PG8_SCHED; PG8_LDA(At, 0, 0); PG8_STAGE(PG8_SA(1, 1), a1 + hstepA, voffA);
;             PG8_WAIT_V(8); PG8_WAIT_L(0); PG8_BAR; PG8_MMA(0, 0, At, B0); PG8_MMA(0, 1, At, B1); PG8_BAR; PG8_SCHED;
;             PG8_LDA(At, 0, 1); PG8_STAGE(PG8_SB(0, 0), b2, voffB); PG8_STAGE(PG8_SB(0, 1), b2 + hstepB, voffB); PG8_STAGE(PG8_SA(0, 0), a2, voffA);
;             PG8_WAIT_V(8); PG8_WAIT_L(0); PG8_BAR; PG8_MMA(1, 0, At, B0); PG8_MMA(1, 1, At, B1); PG8_BAR; PG8_SCHED;
.LBB0_1337:
	s_add_u32 s51, s42, s50
	s_addc_u32 s56, s43, 0
	s_add_u32 s54, s51, 0x100
	s_addc_u32 s55, s56, 0
	s_and_b64 s[52:53], s[46:47], exec
	s_cselect_b32 s53, s29, s55
	s_cselect_b32 s52, s37, s54
	s_add_u32 s50, s40, s50
	s_addc_u32 s54, s41, 0
	s_add_u32 s50, s50, 0x100
	s_addc_u32 s54, s54, 0
	s_add_i32 s89, 0, 0x10000
	s_and_b64 s[46:47], s[46:47], exec
	s_cselect_b32 s55, s27, s54
	s_cselect_b32 s54, s39, s50
	s_add_i32 s47, 0, 0x14000
	s_add_u32 s58, s51, 0x10080
	s_addc_u32 s59, s56, 0
	s_add_i32 s87, s89, s3
	s_add_i32 m0, s65, 0xc000
	s_add_i32 s93, s65, 0xe000
	s_add_i32 s83, s87, 0x2000
	s_add_u32 s56, s54, 0x10000
	v_add_u32_e32 v160, s89, v196
	v_add_u32_e32 v174, s47, v196
	s_addc_u32 s57, s55, 0
	s_add_i32 s86, s47, s3
	ds_read_b128 v[64:67], v160
	ds_read_b128 v[68:71], v160 offset:1024
	ds_read_b128 v[156:159], v160 offset:2048
	ds_read_b128 v[160:163], v160 offset:3072
	ds_read_b128 v[164:167], v174
	ds_read_b128 v[168:171], v174 offset:1024
	ds_read_b128 v[178:181], v174 offset:2048
	ds_read_b128 v[182:185], v174 offset:3072
	s_add_i32 s85, s86, 0x2000
	s_add_i32 s79, 0, 0x18000
	s_add_i32 s78, 0, 0x1c000
	s_add_u32 s50, s52, 0x10000
	s_addc_u32 s51, s53, 0
	s_add_i32 s77, s79, s3
	s_add_i32 s76, s77, 0x2000
	s_add_u32 s46, s54, 0x10080
	s_addc_u32 s47, s55, 0
	s_add_i32 s91, s78, s3
	s_add_i32 s89, s91, 0x2000
	v_lshl_add_u64 v[174:175], s[58:59], 0, v[136:137]
	ds_read_b128 v[202:205], v200
	ds_read_b128 v[206:209], v200 offset:1024
	ds_read_b128 v[210:213], v200 offset:2048
	ds_read_b128 v[214:217], v200 offset:3072
	ds_read_b128 v[218:221], v200 offset:4096
	ds_read_b128 v[222:225], v200 offset:5120
	ds_read_b128 v[226:229], v200 offset:6144
	ds_read_b128 v[230:233], v200 offset:7168
	global_load_lds_dwordx4 v[174:175], off
	v_lshl_add_u64 v[174:175], s[58:59], 0, v[140:141]
	s_mov_b32 m0, s93
	s_nop 0
	global_load_lds_dwordx4 v[174:175], off
	s_waitcnt vmcnt(8)
	s_waitcnt lgkmcnt(0)
	s_barrier
	s_waitcnt lgkmcnt(0)
	v_mfma_f32_16x16x32_bf16 v[132:135], v[64:67], v[202:205], v[132:135]
	v_mfma_f32_16x16x32_bf16 v[128:131], v[156:159], v[202:205], v[128:131]
	v_mfma_f32_16x16x32_bf16 v[116:119], v[64:67], v[210:213], v[116:119]
	v_mfma_f32_16x16x32_bf16 v[112:115], v[156:159], v[210:213], v[112:115]
	v_mfma_f32_16x16x32_bf16 v[100:103], v[64:67], v[218:221], v[100:103]
	v_mfma_f32_16x16x32_bf16 v[96:99], v[156:159], v[218:221], v[96:99]
	v_mfma_f32_16x16x32_bf16 v[84:87], v[64:67], v[226:229], v[84:87]
	v_mfma_f32_16x16x32_bf16 v[80:83], v[156:159], v[226:229], v[80:83]
	v_mfma_f32_16x16x32_bf16 v[132:135], v[68:71], v[206:209], v[132:135]
	v_mfma_f32_16x16x32_bf16 v[128:131], v[160:163], v[206:209], v[128:131]
	v_mfma_f32_16x16x32_bf16 v[116:119], v[68:71], v[214:217], v[116:119]
	v_mfma_f32_16x16x32_bf16 v[112:115], v[160:163], v[214:217], v[112:115]
	v_mfma_f32_16x16x32_bf16 v[100:103], v[68:71], v[222:225], v[100:103]
	v_mfma_f32_16x16x32_bf16 v[96:99], v[160:163], v[222:225], v[96:99]
	v_mfma_f32_16x16x32_bf16 v[84:87], v[68:71], v[230:233], v[84:87]
	v_mfma_f32_16x16x32_bf16 v[80:83], v[160:163], v[230:233], v[80:83]
	v_mfma_f32_16x16x32_bf16 v[124:127], v[164:167], v[202:205], v[124:127]
	v_mfma_f32_16x16x32_bf16 v[120:123], v[178:181], v[202:205], v[120:123]
	v_mfma_f32_16x16x32_bf16 v[108:111], v[164:167], v[210:213], v[108:111]
	v_mfma_f32_16x16x32_bf16 v[104:107], v[178:181], v[210:213], v[104:107]
	v_mfma_f32_16x16x32_bf16 v[92:95], v[164:167], v[218:221], v[92:95]
	v_mfma_f32_16x16x32_bf16 v[88:91], v[178:181], v[218:221], v[88:91]
	v_mfma_f32_16x16x32_bf16 v[76:79], v[164:167], v[226:229], v[76:79]
	v_mfma_f32_16x16x32_bf16 v[72:75], v[178:181], v[226:229], v[72:75]
	v_mfma_f32_16x16x32_bf16 v[124:127], v[168:171], v[206:209], v[124:127]
	v_mfma_f32_16x16x32_bf16 v[120:123], v[182:185], v[206:209], v[120:123]
	v_mfma_f32_16x16x32_bf16 v[108:111], v[168:171], v[214:217], v[108:111]
	v_mfma_f32_16x16x32_bf16 v[104:107], v[182:185], v[214:217], v[104:107]
	v_mfma_f32_16x16x32_bf16 v[92:95], v[168:171], v[222:225], v[92:95]
	v_mfma_f32_16x16x32_bf16 v[88:91], v[182:185], v[222:225], v[88:91]
	v_mfma_f32_16x16x32_bf16 v[76:79], v[168:171], v[230:233], v[76:79]
	v_mfma_f32_16x16x32_bf16 v[72:75], v[182:185], v[230:233], v[72:75]
	s_barrier
	s_mov_b32 m0, s87
	v_lshl_add_u64 v[174:175], s[54:55], 0, v[138:139]
	ds_read_b128 v[202:205], v200 offset:16384
	ds_read_b128 v[206:209], v200 offset:17408
	ds_read_b128 v[210:213], v200 offset:18432
	ds_read_b128 v[214:217], v200 offset:19456
	ds_read_b128 v[218:221], v200 offset:20480
	ds_read_b128 v[222:225], v200 offset:21504
	ds_read_b128 v[226:229], v200 offset:22528
	ds_read_b128 v[230:233], v200 offset:23552
	global_load_lds_dwordx4 v[174:175], off
	v_lshl_add_u64 v[176:177], s[54:55], 0, v[142:143]
	s_mov_b32 m0, s83
	v_lshl_add_u64 v[192:193], s[56:57], 0, v[138:139]
	global_load_lds_dwordx4 v[176:177], off
	s_mov_b32 m0, s86
	v_lshl_add_u64 v[194:195], s[52:53], 0, v[140:141]
	global_load_lds_dwordx4 v[192:193], off
	v_lshl_add_u64 v[192:193], s[56:57], 0, v[142:143]
	s_mov_b32 m0, s85
	s_nop 0
	global_load_lds_dwordx4 v[192:193], off
	v_lshl_add_u64 v[192:193], s[52:53], 0, v[136:137]
	s_mov_b32 m0, s65
	s_nop 0
	global_load_lds_dwordx4 v[192:193], off
	s_mov_b32 m0, s66
	s_nop 0
	global_load_lds_dwordx4 v[194:195], off
	s_waitcnt vmcnt(8)
	s_waitcnt lgkmcnt(0)
	s_barrier
; #define PG8_STAGE(bufoff, gbase, voff) do { _Pragma("unroll") for (int _i = 0; _i < 2; ++_i) \
;         __builtin_amdgcn_global_load_lds((const unsigned*)((const char*)(gbase) + (voff)[_i]), (PG8_LAS unsigned*)(lds + (bufoff) + ldsw + _i * 8192), 16, 0, 0); } while (0)
; #define PG8_LDA(dst, b, h) do { _Pragma("unroll") for (int m = 0; m < 4; ++m) _Pragma("unroll") for (int k = 0; k < 2; ++k) dst[m][k] = *(const PG8_LAS bf16x8*)(lds + PG8_SA(b, h) + aoff + m * 2048 + k * 1024); } while (0)
; #define PG8_LDB(dst, b, h) do { _Pragma("unroll") for (int n = 0; n < 2; ++n) _Pragma("unroll") for (int k = 0; k < 2; ++k) dst[n][k] = *(const PG8_LAS bf16x8*)(lds + PG8_SB(b, h) + boff + n * 2048 + k * 1024); } while (0)
; #define PG8_MMA(ai, bj, At, Bt) do { __builtin_amdgcn_s_setprio(1); _Pragma("unroll") for (int m = 0; m < 4; ++m) _Pragma("unroll") for (int n = 0; n < 2; ++n) _Pragma("unroll") for (int k = 0; k < 2; ++k) \
;         acc[ai][bj][m][n] = __builtin_amdgcn_mfma_f32_16x16x32_bf16(Bt[n][k], At[m][k], acc[ai][bj][m][n], 0, 0, 0); __builtin_amdgcn_s_setprio(0); } while (0)
; #define PG8_WAIT_V(n) asm volatile("s_waitcnt vmcnt(" #n ")" ::: "memory")
; #define PG8_WAIT_L(n) asm volatile("s_waitcnt lgkmcnt(" #n ")" ::: "memory")
; #define PG8_BAR __builtin_amdgcn_s_barrier()
; #define PG8_SCHED __builtin_amdgcn_sched_barrier(0)
; template <class Epi, class Sched, bool ALIGN_EPI = false, bool SP2 = false>
; __device__ __forceinline__ void gemm_phase(PG8_LAS unsigned char* lds, const Gemm g, const Sched& S, const Epi& E) {
;     ...
;             PG8_WAIT_V(8); PG8_WAIT_L(0); PG8_BAR; PG8_MMA(1, 0, At, B0); PG8_MMA(1, 1, At, B1); PG8_BAR; PG8_SCHED;
;             PG8_LDB(B0, 1, 0); PG8_LDB(B1, 1, 1); PG8_SCHED; PG8_LDA(At, 1, 0); PG8_STAGE(PG8_SA(0, 1), a2 + hstepA, voffA);
;             PG8_WAIT_V(8); PG8_WAIT_L(0); PG8_BAR; PG8_MMA(0, 0, At, B0); PG8_MMA(0, 1, At, B1); PG8_BAR; PG8_SCHED;
	s_waitcnt lgkmcnt(0)
	v_mfma_f32_16x16x32_bf16 v[56:59], v[64:67], v[202:205], v[56:59]
	v_mfma_f32_16x16x32_bf16 v[48:51], v[156:159], v[202:205], v[48:51]
	v_mfma_f32_16x16x32_bf16 v[44:47], v[64:67], v[210:213], v[44:47]
	v_mfma_f32_16x16x32_bf16 v[40:43], v[156:159], v[210:213], v[40:43]
	v_mfma_f32_16x16x32_bf16 v[28:31], v[64:67], v[218:221], v[28:31]
	v_mfma_f32_16x16x32_bf16 v[24:27], v[156:159], v[218:221], v[24:27]
	v_mfma_f32_16x16x32_bf16 v[12:15], v[64:67], v[226:229], v[12:15]
	v_mfma_f32_16x16x32_bf16 v[8:11], v[156:159], v[226:229], v[8:11]
	v_mfma_f32_16x16x32_bf16 v[56:59], v[68:71], v[206:209], v[56:59]
	v_mfma_f32_16x16x32_bf16 v[48:51], v[160:163], v[206:209], v[48:51]
	v_mfma_f32_16x16x32_bf16 v[44:47], v[68:71], v[214:217], v[44:47]
	v_mfma_f32_16x16x32_bf16 v[40:43], v[160:163], v[214:217], v[40:43]
	v_mfma_f32_16x16x32_bf16 v[28:31], v[68:71], v[222:225], v[28:31]
	v_mfma_f32_16x16x32_bf16 v[24:27], v[160:163], v[222:225], v[24:27]
	v_mfma_f32_16x16x32_bf16 v[12:15], v[68:71], v[230:233], v[12:15]
	v_mfma_f32_16x16x32_bf16 v[8:11], v[160:163], v[230:233], v[8:11]
	v_mfma_f32_16x16x32_bf16 v[60:63], v[164:167], v[202:205], v[60:63]
	v_mfma_f32_16x16x32_bf16 v[52:55], v[178:181], v[202:205], v[52:55]
	v_mfma_f32_16x16x32_bf16 v[36:39], v[164:167], v[210:213], v[36:39]
	v_mfma_f32_16x16x32_bf16 v[32:35], v[178:181], v[210:213], v[32:35]
	v_mfma_f32_16x16x32_bf16 v[20:23], v[164:167], v[218:221], v[20:23]
	v_mfma_f32_16x16x32_bf16 v[16:19], v[178:181], v[218:221], v[16:19]
	v_mfma_f32_16x16x32_bf16 v[4:7], v[164:167], v[226:229], v[4:7]
	v_mfma_f32_16x16x32_bf16 v[0:3], v[178:181], v[226:229], v[0:3]
	v_mfma_f32_16x16x32_bf16 v[60:63], v[168:171], v[206:209], v[60:63]
	v_mfma_f32_16x16x32_bf16 v[52:55], v[182:185], v[206:209], v[52:55]
	v_mfma_f32_16x16x32_bf16 v[36:39], v[168:171], v[214:217], v[36:39]
	v_mfma_f32_16x16x32_bf16 v[32:35], v[182:185], v[214:217], v[32:35]
	v_mfma_f32_16x16x32_bf16 v[20:23], v[168:171], v[222:225], v[20:23]
	v_mfma_f32_16x16x32_bf16 v[16:19], v[182:185], v[222:225], v[16:19]
	v_mfma_f32_16x16x32_bf16 v[4:7], v[168:171], v[230:233], v[4:7]
	v_mfma_f32_16x16x32_bf16 v[0:3], v[182:185], v[230:233], v[0:3]
	s_barrier
	v_add_u32_e32 v160, s79, v196
	v_add_u32_e32 v182, s78, v196
	ds_read_b128 v[64:67], v160
	ds_read_b128 v[68:71], v160 offset:1024
	ds_read_b128 v[156:159], v160 offset:2048
	ds_read_b128 v[160:163], v160 offset:3072
	ds_read_b128 v[164:167], v182
	ds_read_b128 v[168:171], v182 offset:1024
	ds_read_b128 v[178:181], v182 offset:2048
	ds_read_b128 v[182:185], v182 offset:3072
	s_mov_b32 m0, s67
	v_lshl_add_u64 v[234:235], s[50:51], 0, v[136:137]
	ds_read_b128 v[202:205], v200 offset:32768
	ds_read_b128 v[206:209], v200 offset:33792
	ds_read_b128 v[210:213], v200 offset:34816
	ds_read_b128 v[214:217], v200 offset:35840
	ds_read_b128 v[218:221], v200 offset:36864
	ds_read_b128 v[222:225], v200 offset:37888
	ds_read_b128 v[226:229], v200 offset:38912
	ds_read_b128 v[230:233], v200 offset:39936
	global_load_lds_dwordx4 v[234:235], off
	v_lshl_add_u64 v[234:235], s[50:51], 0, v[140:141]
	s_mov_b32 m0, s70
	s_nop 0
	global_load_lds_dwordx4 v[234:235], off
	s_waitcnt vmcnt(8)
	s_waitcnt lgkmcnt(0)
	s_barrier
	s_waitcnt lgkmcnt(0)
	v_mfma_f32_16x16x32_bf16 v[132:135], v[64:67], v[202:205], v[132:135]
	v_mfma_f32_16x16x32_bf16 v[128:131], v[156:159], v[202:205], v[128:131]
	v_mfma_f32_16x16x32_bf16 v[116:119], v[64:67], v[210:213], v[116:119]
	v_mfma_f32_16x16x32_bf16 v[112:115], v[156:159], v[210:213], v[112:115]
	v_mfma_f32_16x16x32_bf16 v[100:103], v[64:67], v[218:221], v[100:103]
	v_mfma_f32_16x16x32_bf16 v[96:99], v[156:159], v[218:221], v[96:99]
	v_mfma_f32_16x16x32_bf16 v[84:87], v[64:67], v[226:229], v[84:87]
	v_mfma_f32_16x16x32_bf16 v[80:83], v[156:159], v[226:229], v[80:83]
	v_mfma_f32_16x16x32_bf16 v[132:135], v[68:71], v[206:209], v[132:135]
	v_mfma_f32_16x16x32_bf16 v[128:131], v[160:163], v[206:209], v[128:131]
	v_mfma_f32_16x16x32_bf16 v[116:119], v[68:71], v[214:217], v[116:119]
	v_mfma_f32_16x16x32_bf16 v[112:115], v[160:163], v[214:217], v[112:115]
	v_mfma_f32_16x16x32_bf16 v[100:103], v[68:71], v[222:225], v[100:103]
	v_mfma_f32_16x16x32_bf16 v[96:99], v[160:163], v[222:225], v[96:99]
	v_mfma_f32_16x16x32_bf16 v[84:87], v[68:71], v[230:233], v[84:87]
	v_mfma_f32_16x16x32_bf16 v[80:83], v[160:163], v[230:233], v[80:83]
	v_mfma_f32_16x16x32_bf16 v[124:127], v[164:167], v[202:205], v[124:127]
	v_mfma_f32_16x16x32_bf16 v[120:123], v[178:181], v[202:205], v[120:123]
	v_mfma_f32_16x16x32_bf16 v[108:111], v[164:167], v[210:213], v[108:111]
	v_mfma_f32_16x16x32_bf16 v[104:107], v[178:181], v[210:213], v[104:107]
	v_mfma_f32_16x16x32_bf16 v[92:95], v[164:167], v[218:221], v[92:95]
	v_mfma_f32_16x16x32_bf16 v[88:91], v[178:181], v[218:221], v[88:91]
	v_mfma_f32_16x16x32_bf16 v[76:79], v[164:167], v[226:229], v[76:79]
	v_mfma_f32_16x16x32_bf16 v[72:75], v[178:181], v[226:229], v[72:75]
	v_mfma_f32_16x16x32_bf16 v[124:127], v[168:171], v[206:209], v[124:127]
	v_mfma_f32_16x16x32_bf16 v[120:123], v[182:185], v[206:209], v[120:123]
	v_mfma_f32_16x16x32_bf16 v[108:111], v[168:171], v[214:217], v[108:111]
	v_mfma_f32_16x16x32_bf16 v[104:107], v[182:185], v[214:217], v[104:107]
	v_mfma_f32_16x16x32_bf16 v[92:95], v[168:171], v[222:225], v[92:95]
	v_mfma_f32_16x16x32_bf16 v[88:91], v[182:185], v[222:225], v[88:91]
	v_mfma_f32_16x16x32_bf16 v[76:79], v[168:171], v[230:233], v[76:79]
	v_mfma_f32_16x16x32_bf16 v[72:75], v[182:185], v[230:233], v[72:75]
	s_barrier
; #define PG8_STAGE(bufoff, gbase, voff) do { _Pragma("unroll") for (int _i = 0; _i < 2; ++_i) \
;         __builtin_amdgcn_global_load_lds((const unsigned*)((const char*)(gbase) + (voff)[_i]), (PG8_LAS unsigned*)(lds + (bufoff) + ldsw + _i * 8192), 16, 0, 0); } while (0)
; #define PG8_LDA(dst, b, h) do { _Pragma("unroll") for (int m = 0; m < 4; ++m) _Pragma("unroll") for (int k = 0; k < 2; ++k) dst[m][k] = *(const PG8_LAS bf16x8*)(lds + PG8_SA(b, h) + aoff + m * 2048 + k * 1024); } while (0)
; #define PG8_MMA(ai, bj, At, Bt) do { __builtin_amdgcn_s_setprio(1); _Pragma("unroll") for (int m = 0; m < 4; ++m) _Pragma("unroll") for (int n = 0; n < 2; ++n) _Pragma("unroll") for (int k = 0; k < 2; ++k) \
;         acc[ai][bj][m][n] = __builtin_amdgcn_mfma_f32_16x16x32_bf16(Bt[n][k], At[m][k], acc[ai][bj][m][n], 0, 0, 0); __builtin_amdgcn_s_setprio(0); } while (0)
; #define PG8_WAIT_V(n) asm volatile("s_waitcnt vmcnt(" #n ")" ::: "memory")
; #define PG8_WAIT_L(n) asm volatile("s_waitcnt lgkmcnt(" #n ")" ::: "memory")
; #define PG8_BAR __builtin_amdgcn_s_barrier()
; #define PG8_SCHED __builtin_amdgcn_sched_barrier(0)
; template <class Epi, class Sched, bool ALIGN_EPI = false, bool SP2 = false>
; __device__ __forceinline__ void gemm_phase(PG8_LAS unsigned char* lds, const Gemm g, const Sched& S, const Epi& E) {
;     ...
;             PG8_LDA(At, 1, 1); PG8_STAGE(PG8_SB(1, 0), b3, voffB); PG8_STAGE(PG8_SB(1, 1), b3 + hstepB, voffB); PG8_STAGE(PG8_SA(1, 0), a3, voffA);
;             PG8_WAIT_V(8); PG8_WAIT_L(0); PG8_BAR; PG8_MMA(1, 0, At, B0); PG8_MMA(1, 1, At, B1); PG8_BAR; PG8_SCHED;
;     ...
;         if constexpr (ALIGN_EPI) { if (wr == 0) PG8_BAR; }
	s_mov_b32 m0, s77
	v_lshl_add_u64 v[174:175], v[174:175], 0, s[80:81]
	ds_read_b128 v[202:205], v200 offset:49152
	ds_read_b128 v[206:209], v200 offset:50176
	ds_read_b128 v[210:213], v200 offset:51200
	ds_read_b128 v[214:217], v200 offset:52224
	ds_read_b128 v[218:221], v200 offset:53248
	ds_read_b128 v[222:225], v200 offset:54272
	ds_read_b128 v[226:229], v200 offset:55296
	ds_read_b128 v[230:233], v200 offset:56320
	global_load_lds_dwordx4 v[174:175], off
	v_lshl_add_u64 v[174:175], v[176:177], 0, s[80:81]
	s_mov_b32 m0, s76
	s_nop 0
	global_load_lds_dwordx4 v[174:175], off
	v_lshl_add_u64 v[174:175], s[46:47], 0, v[138:139]
	s_mov_b32 m0, s91
	s_nop 0
	global_load_lds_dwordx4 v[174:175], off
	v_lshl_add_u64 v[174:175], s[46:47], 0, v[142:143]
	s_mov_b32 m0, s89
	s_nop 0
	global_load_lds_dwordx4 v[174:175], off
	v_lshl_add_u64 v[174:175], v[192:193], 0, s[80:81]
	s_mov_b32 m0, s72
	s_nop 0
	global_load_lds_dwordx4 v[174:175], off
	v_lshl_add_u64 v[174:175], v[194:195], 0, s[80:81]
	s_mov_b32 m0, s73
	s_nop 0
	global_load_lds_dwordx4 v[174:175], off
	s_waitcnt vmcnt(8)
	s_waitcnt lgkmcnt(0)
	s_barrier
	s_waitcnt lgkmcnt(0)
	v_mfma_f32_16x16x32_bf16 v[56:59], v[64:67], v[202:205], v[56:59]
	v_mfma_f32_16x16x32_bf16 v[48:51], v[156:159], v[202:205], v[48:51]
	v_mfma_f32_16x16x32_bf16 v[44:47], v[64:67], v[210:213], v[44:47]
	v_mfma_f32_16x16x32_bf16 v[40:43], v[156:159], v[210:213], v[40:43]
	v_mfma_f32_16x16x32_bf16 v[28:31], v[64:67], v[218:221], v[28:31]
	v_mfma_f32_16x16x32_bf16 v[24:27], v[156:159], v[218:221], v[24:27]
	v_mfma_f32_16x16x32_bf16 v[12:15], v[64:67], v[226:229], v[12:15]
	v_mfma_f32_16x16x32_bf16 v[8:11], v[156:159], v[226:229], v[8:11]
	v_mfma_f32_16x16x32_bf16 v[56:59], v[68:71], v[206:209], v[56:59]
	v_mfma_f32_16x16x32_bf16 v[48:51], v[160:163], v[206:209], v[48:51]
	v_mfma_f32_16x16x32_bf16 v[44:47], v[68:71], v[214:217], v[44:47]
	v_mfma_f32_16x16x32_bf16 v[40:43], v[160:163], v[214:217], v[40:43]
	v_mfma_f32_16x16x32_bf16 v[28:31], v[68:71], v[222:225], v[28:31]
	v_mfma_f32_16x16x32_bf16 v[24:27], v[160:163], v[222:225], v[24:27]
	v_mfma_f32_16x16x32_bf16 v[12:15], v[68:71], v[230:233], v[12:15]
	v_mfma_f32_16x16x32_bf16 v[8:11], v[160:163], v[230:233], v[8:11]
	v_mfma_f32_16x16x32_bf16 v[60:63], v[164:167], v[202:205], v[60:63]
	v_mfma_f32_16x16x32_bf16 v[52:55], v[178:181], v[202:205], v[52:55]
	v_mfma_f32_16x16x32_bf16 v[36:39], v[164:167], v[210:213], v[36:39]
	v_mfma_f32_16x16x32_bf16 v[32:35], v[178:181], v[210:213], v[32:35]
	v_mfma_f32_16x16x32_bf16 v[20:23], v[164:167], v[218:221], v[20:23]
	v_mfma_f32_16x16x32_bf16 v[16:19], v[178:181], v[218:221], v[16:19]
	v_mfma_f32_16x16x32_bf16 v[4:7], v[164:167], v[226:229], v[4:7]
	v_mfma_f32_16x16x32_bf16 v[0:3], v[178:181], v[226:229], v[0:3]
	v_mfma_f32_16x16x32_bf16 v[60:63], v[168:171], v[206:209], v[60:63]
	v_mfma_f32_16x16x32_bf16 v[52:55], v[182:185], v[206:209], v[52:55]
	v_mfma_f32_16x16x32_bf16 v[36:39], v[168:171], v[214:217], v[36:39]
	v_mfma_f32_16x16x32_bf16 v[32:35], v[182:185], v[214:217], v[32:35]
	v_mfma_f32_16x16x32_bf16 v[20:23], v[168:171], v[222:225], v[20:23]
	v_mfma_f32_16x16x32_bf16 v[16:19], v[182:185], v[222:225], v[16:19]
	v_mfma_f32_16x16x32_bf16 v[4:7], v[168:171], v[230:233], v[4:7]
	v_mfma_f32_16x16x32_bf16 v[0:3], v[182:185], v[230:233], v[0:3]
	s_barrier
	s_movk_i32 s50, 0x100
	s_andn2_b64 vcc, exec, s[44:45]
	s_mov_b64 s[46:47], -1
	s_mov_b64 s[44:45], 0
	s_cbranch_vccz .LBB0_1337
	s_and_b64 vcc, exec, s[24:25]
	s_cbranch_vccz .LBB0_1340
	s_barrier

;     __device__ __forceinline__ bool next(int i, Unit& u) const { const int L = i * G + c; if (L >= nsub) return false; u.pk = L >> 4; u.pm = MLAT / BM + (L & 3); u.pn = (L >> 2) & 3; return true; }
; #define PG8_STAGE(bufoff, gbase, voff) do { _Pragma("unroll") for (int _i = 0; _i < 2; ++_i) \
;         __builtin_amdgcn_global_load_lds((const unsigned*)((const char*)(gbase) + (voff)[_i]), (PG8_LAS unsigned*)(lds + (bufoff) + ldsw + _i * 8192), 16, 0, 0); } while (0)
; #define PG8_LDA(dst, b, h) do { _Pragma("unroll") for (int m = 0; m < 4; ++m) _Pragma("unroll") for (int k = 0; k < 2; ++k) dst[m][k] = *(const PG8_LAS bf16x8*)(lds + PG8_SA(b, h) + aoff + m * 2048 + k * 1024); } while (0)
; #define PG8_LDB(dst, b, h) do { _Pragma("unroll") for (int n = 0; n < 2; ++n) _Pragma("unroll") for (int k = 0; k < 2; ++k) dst[n][k] = *(const PG8_LAS bf16x8*)(lds + PG8_SB(b, h) + boff + n * 2048 + k * 1024); } while (0)
; #define PG8_WAIT_V(n) asm volatile("s_waitcnt vmcnt(" #n ")" ::: "memory")
; #define PG8_WAIT_L(n) asm volatile("s_waitcnt lgkmcnt(" #n ")" ::: "memory")
; template <class Epi, class Sched, bool ALIGN_EPI = false, bool SP2 = false>
; __device__ __forceinline__ void gemm_phase(PG8_LAS unsigned char* lds, const Gemm g, const Sched& S, const Epi& E) {
;     ...
;         const bool has_next = S.next(ui + 1, nxt);
;         const char* nA = has_next ? g.a_of(nxt) : cA; const char* nB = has_next ? g.b_of(nxt) : cB;
;         for (int t = 0; t < nt; t += 2) {
;             const bool last = (t == nt - 2);
;             const char* a1 = cA + (size_t)(t + 1) * kstep;
;             const char* a2 = last ? nA : cA + (size_t)(t + 2) * kstep; const char* b2 = last ? nB : cB + (size_t)(t + 2) * kstep;
;             const char* a3 = a2 + kstep; const char* b3 = b2 + kstep;
;             if (last && has_next) S.a_ready(nxt);
;             if constexpr (SP2) {
;             PG8_LDB(B0, 0, 0); PG8_LDB(B1, 0, 1); PG8_SCHED; PG8_LDA(At, 0, 0); PG8_STAGE(PG8_SA(1, 1), a1 + hstepA, voffA);
;             PG8_WAIT_V(8); PG8_WAIT_L(0); PG8_BAR; PG8_MMA(0, 0, At, B0); PG8_MMA(0, 1, At, B1); PG8_BAR; PG8_SCHED;
;             PG8_LDA(At, 0, 1); PG8_STAGE(PG8_SB(0, 0), b2, voffB); PG8_STAGE(PG8_SB(0, 1), b2 + hstepB, voffB); PG8_STAGE(PG8_SA(0, 0), a2, voffA);
;             PG8_WAIT_V(8); PG8_WAIT_L(0); PG8_BAR; PG8_MMA(1, 0, At, B0); PG8_MMA(1, 1, At, B1); PG8_BAR; PG8_SCHED;
.LBB0_1575:
	s_add_u32 s40, s38, 0xfffc0080
	s_addc_u32 s41, s39, -1
	s_add_i32 s67, 0, 0x10000
	s_cmp_eq_u32 s66, 12
	s_cselect_b32 s43, s27, s41
	s_cselect_b32 s42, s35, s40
	s_cselect_b32 s41, s25, s65
	s_cselect_b32 s40, s37, s64
	s_add_i32 s68, 0, 0x14000
	v_add_u32_e32 v92, s67, v181
	v_add_u32_e32 v164, s68, v181
	ds_read_b128 v[72:75], v92
	ds_read_b128 v[76:79], v92 offset:1024
	ds_read_b128 v[88:91], v92 offset:2048
	ds_read_b128 v[92:95], v92 offset:3072
	ds_read_b128 v[152:155], v164
	ds_read_b128 v[156:159], v164 offset:1024
	ds_read_b128 v[160:163], v164 offset:2048
	ds_read_b128 v[164:167], v164 offset:3072
	v_lshl_add_u64 v[178:179], s[38:39], 0, v[148:149]
	s_add_i32 m0, s51, 0xc000
	ds_read_b128 v[168:171], v186
	ds_read_b128 v[174:177], v186 offset:1024
	ds_read_b128 v[192:195], v186 offset:2048
	ds_read_b128 v[196:199], v186 offset:3072
	ds_read_b128 v[200:203], v186 offset:4096
	ds_read_b128 v[204:207], v186 offset:5120
	ds_read_b128 v[208:211], v186 offset:6144
	ds_read_b128 v[212:215], v186 offset:7168
	global_load_lds_dwordx4 v[178:179], off
	v_lshl_add_u64 v[178:179], s[38:39], 0, v[150:151]
	s_add_i32 m0, s51, 0xe000
	s_nop 0
	global_load_lds_dwordx4 v[178:179], off
	s_waitcnt vmcnt(8)
	s_waitcnt lgkmcnt(0)
	s_barrier
	s_waitcnt lgkmcnt(0)
	v_mfma_f32_16x16x32_bf16 v[140:143], v[72:75], v[168:171], v[140:143]
	v_mfma_f32_16x16x32_bf16 v[136:139], v[88:91], v[168:171], v[136:139]
	v_mfma_f32_16x16x32_bf16 v[124:127], v[72:75], v[192:195], v[124:127]
	v_mfma_f32_16x16x32_bf16 v[120:123], v[88:91], v[192:195], v[120:123]
	v_mfma_f32_16x16x32_bf16 v[108:111], v[72:75], v[200:203], v[108:111]
	v_mfma_f32_16x16x32_bf16 v[104:107], v[88:91], v[200:203], v[104:107]
	v_mfma_f32_16x16x32_bf16 v[84:87], v[72:75], v[208:211], v[84:87]
	v_mfma_f32_16x16x32_bf16 v[80:83], v[88:91], v[208:211], v[80:83]
	v_mfma_f32_16x16x32_bf16 v[140:143], v[76:79], v[174:177], v[140:143]
	v_mfma_f32_16x16x32_bf16 v[136:139], v[92:95], v[174:177], v[136:139]
	v_mfma_f32_16x16x32_bf16 v[124:127], v[76:79], v[196:199], v[124:127]
	v_mfma_f32_16x16x32_bf16 v[120:123], v[92:95], v[196:199], v[120:123]
	v_mfma_f32_16x16x32_bf16 v[108:111], v[76:79], v[204:207], v[108:111]
	v_mfma_f32_16x16x32_bf16 v[104:107], v[92:95], v[204:207], v[104:107]
	v_mfma_f32_16x16x32_bf16 v[84:87], v[76:79], v[212:215], v[84:87]
	v_mfma_f32_16x16x32_bf16 v[80:83], v[92:95], v[212:215], v[80:83]
	v_mfma_f32_16x16x32_bf16 v[132:135], v[152:155], v[168:171], v[132:135]
	v_mfma_f32_16x16x32_bf16 v[128:131], v[160:163], v[168:171], v[128:131]
	v_mfma_f32_16x16x32_bf16 v[116:119], v[152:155], v[192:195], v[116:119]
	v_mfma_f32_16x16x32_bf16 v[112:115], v[160:163], v[192:195], v[112:115]
	v_mfma_f32_16x16x32_bf16 v[100:103], v[152:155], v[200:203], v[100:103]
	v_mfma_f32_16x16x32_bf16 v[96:99], v[160:163], v[200:203], v[96:99]
	v_mfma_f32_16x16x32_bf16 v[68:71], v[152:155], v[208:211], v[68:71]
	v_mfma_f32_16x16x32_bf16 v[64:67], v[160:163], v[208:211], v[64:67]
	v_mfma_f32_16x16x32_bf16 v[132:135], v[156:159], v[174:177], v[132:135]
	v_mfma_f32_16x16x32_bf16 v[128:131], v[164:167], v[174:177], v[128:131]
	v_mfma_f32_16x16x32_bf16 v[116:119], v[156:159], v[196:199], v[116:119]
	v_mfma_f32_16x16x32_bf16 v[112:115], v[164:167], v[196:199], v[112:115]
	v_mfma_f32_16x16x32_bf16 v[100:103], v[156:159], v[204:207], v[100:103]
	v_mfma_f32_16x16x32_bf16 v[96:99], v[164:167], v[204:207], v[96:99]
	v_mfma_f32_16x16x32_bf16 v[68:71], v[156:159], v[212:215], v[68:71]
	v_mfma_f32_16x16x32_bf16 v[64:67], v[164:167], v[212:215], v[64:67]
	s_barrier
	s_add_i32 s67, s67, s50
	v_lshl_add_u64 v[178:179], s[40:41], 0, v[172:173]
	s_mov_b32 m0, s67
	ds_read_b128 v[168:171], v186 offset:16384
	ds_read_b128 v[174:177], v186 offset:17408
	ds_read_b128 v[192:195], v186 offset:18432
	ds_read_b128 v[196:199], v186 offset:19456
	ds_read_b128 v[200:203], v186 offset:20480
	ds_read_b128 v[204:207], v186 offset:21504
	ds_read_b128 v[208:211], v186 offset:22528
	ds_read_b128 v[212:215], v186 offset:23552
	global_load_lds_dwordx4 v[178:179], off
	s_add_i32 m0, s67, 0x2000
	s_add_u32 s70, s40, 0x40000
	v_lshl_add_u64 v[216:217], s[40:41], 0, v[144:145]
	s_addc_u32 s71, s41, 0
	s_add_i32 s67, s68, s50
	global_load_lds_dwordx4 v[216:217], off
	v_lshl_add_u64 v[218:219], s[70:71], 0, v[172:173]
	s_mov_b32 m0, s67
	v_lshl_add_u64 v[220:221], s[42:43], 0, v[144:145]
	global_load_lds_dwordx4 v[218:219], off
	v_lshl_add_u64 v[218:219], s[70:71], 0, v[144:145]
	s_add_i32 m0, s67, 0x2000
	s_nop 0
	global_load_lds_dwordx4 v[218:219], off
	v_lshl_add_u64 v[218:219], s[42:43], 0, v[172:173]
	s_mov_b32 m0, s51
	s_nop 0
	global_load_lds_dwordx4 v[218:219], off
	s_mov_b32 m0, s52
	s_nop 0
	global_load_lds_dwordx4 v[220:221], off
	s_waitcnt vmcnt(8)
	s_waitcnt lgkmcnt(0)
	s_barrier
; #define PG8_STAGE(bufoff, gbase, voff) do { _Pragma("unroll") for (int _i = 0; _i < 2; ++_i) \
;         __builtin_amdgcn_global_load_lds((const unsigned*)((const char*)(gbase) + (voff)[_i]), (PG8_LAS unsigned*)(lds + (bufoff) + ldsw + _i * 8192), 16, 0, 0); } while (0)
; #define PG8_LDA(dst, b, h) do { _Pragma("unroll") for (int m = 0; m < 4; ++m) _Pragma("unroll") for (int k = 0; k < 2; ++k) dst[m][k] = *(const PG8_LAS bf16x8*)(lds + PG8_SA(b, h) + aoff + m * 2048 + k * 1024); } while (0)
; #define PG8_LDB(dst, b, h) do { _Pragma("unroll") for (int n = 0; n < 2; ++n) _Pragma("unroll") for (int k = 0; k < 2; ++k) dst[n][k] = *(const PG8_LAS bf16x8*)(lds + PG8_SB(b, h) + boff + n * 2048 + k * 1024); } while (0)
; #define PG8_MMA(ai, bj, At, Bt) do { __builtin_amdgcn_s_setprio(1); _Pragma("unroll") for (int m = 0; m < 4; ++m) _Pragma("unroll") for (int n = 0; n < 2; ++n) _Pragma("unroll") for (int k = 0; k < 2; ++k) \
;         acc[ai][bj][m][n] = __builtin_amdgcn_mfma_f32_16x16x32_bf16(Bt[n][k], At[m][k], acc[ai][bj][m][n], 0, 0, 0); __builtin_amdgcn_s_setprio(0); } while (0)
; #define PG8_WAIT_V(n) asm volatile("s_waitcnt vmcnt(" #n ")" ::: "memory")
; #define PG8_WAIT_L(n) asm volatile("s_waitcnt lgkmcnt(" #n ")" ::: "memory")
; #define PG8_BAR __builtin_amdgcn_s_barrier()
; #define PG8_SCHED __builtin_amdgcn_sched_barrier(0)
; template <class Epi, class Sched, bool ALIGN_EPI = false, bool SP2 = false>
; __device__ __forceinline__ void gemm_phase(PG8_LAS unsigned char* lds, const Gemm g, const Sched& S, const Epi& E) {
;     ...
;             PG8_WAIT_V(8); PG8_WAIT_L(0); PG8_BAR; PG8_MMA(1, 0, At, B0); PG8_MMA(1, 1, At, B1); PG8_BAR; PG8_SCHED;
;             PG8_LDB(B0, 1, 0); PG8_LDB(B1, 1, 1); PG8_SCHED; PG8_LDA(At, 1, 0); PG8_STAGE(PG8_SA(0, 1), a2 + hstepA, voffA);
;             PG8_WAIT_V(8); PG8_WAIT_L(0); PG8_BAR; PG8_MMA(0, 0, At, B0); PG8_MMA(0, 1, At, B1); PG8_BAR; PG8_SCHED;
	s_waitcnt lgkmcnt(0)
	v_mfma_f32_16x16x32_bf16 v[60:63], v[72:75], v[168:171], v[60:63]
	v_mfma_f32_16x16x32_bf16 v[56:59], v[88:91], v[168:171], v[56:59]
	v_mfma_f32_16x16x32_bf16 v[44:47], v[72:75], v[192:195], v[44:47]
	v_mfma_f32_16x16x32_bf16 v[40:43], v[88:91], v[192:195], v[40:43]
	v_mfma_f32_16x16x32_bf16 v[28:31], v[72:75], v[200:203], v[28:31]
	v_mfma_f32_16x16x32_bf16 v[24:27], v[88:91], v[200:203], v[24:27]
	v_mfma_f32_16x16x32_bf16 v[12:15], v[72:75], v[208:211], v[12:15]
	v_mfma_f32_16x16x32_bf16 v[8:11], v[88:91], v[208:211], v[8:11]
	v_mfma_f32_16x16x32_bf16 v[60:63], v[76:79], v[174:177], v[60:63]
	v_mfma_f32_16x16x32_bf16 v[56:59], v[92:95], v[174:177], v[56:59]
	v_mfma_f32_16x16x32_bf16 v[44:47], v[76:79], v[196:199], v[44:47]
	v_mfma_f32_16x16x32_bf16 v[40:43], v[92:95], v[196:199], v[40:43]
	v_mfma_f32_16x16x32_bf16 v[28:31], v[76:79], v[204:207], v[28:31]
	v_mfma_f32_16x16x32_bf16 v[24:27], v[92:95], v[204:207], v[24:27]
	v_mfma_f32_16x16x32_bf16 v[12:15], v[76:79], v[212:215], v[12:15]
	v_mfma_f32_16x16x32_bf16 v[8:11], v[92:95], v[212:215], v[8:11]
	v_mfma_f32_16x16x32_bf16 v[52:55], v[152:155], v[168:171], v[52:55]
	v_mfma_f32_16x16x32_bf16 v[48:51], v[160:163], v[168:171], v[48:51]
	v_mfma_f32_16x16x32_bf16 v[36:39], v[152:155], v[192:195], v[36:39]
	v_mfma_f32_16x16x32_bf16 v[32:35], v[160:163], v[192:195], v[32:35]
	v_mfma_f32_16x16x32_bf16 v[20:23], v[152:155], v[200:203], v[20:23]
	v_mfma_f32_16x16x32_bf16 v[16:19], v[160:163], v[200:203], v[16:19]
	v_mfma_f32_16x16x32_bf16 v[4:7], v[152:155], v[208:211], v[4:7]
	v_mfma_f32_16x16x32_bf16 v[0:3], v[160:163], v[208:211], v[0:3]
	v_mfma_f32_16x16x32_bf16 v[52:55], v[156:159], v[174:177], v[52:55]
	v_mfma_f32_16x16x32_bf16 v[48:51], v[164:167], v[174:177], v[48:51]
	v_mfma_f32_16x16x32_bf16 v[36:39], v[156:159], v[196:199], v[36:39]
	v_mfma_f32_16x16x32_bf16 v[32:35], v[164:167], v[196:199], v[32:35]
	v_mfma_f32_16x16x32_bf16 v[20:23], v[156:159], v[204:207], v[20:23]
	v_mfma_f32_16x16x32_bf16 v[16:19], v[164:167], v[204:207], v[16:19]
	v_mfma_f32_16x16x32_bf16 v[4:7], v[156:159], v[212:215], v[4:7]
	v_mfma_f32_16x16x32_bf16 v[0:3], v[164:167], v[212:215], v[0:3]
	s_barrier
	s_add_i32 s67, 0, 0x18000
	s_add_i32 s68, 0, 0x1c000
	v_add_u32_e32 v92, s67, v181
	v_add_u32_e32 v164, s68, v181
	ds_read_b128 v[72:75], v92
	ds_read_b128 v[76:79], v92 offset:1024
	ds_read_b128 v[88:91], v92 offset:2048
	ds_read_b128 v[92:95], v92 offset:3072
	ds_read_b128 v[152:155], v164
	ds_read_b128 v[156:159], v164 offset:1024
	ds_read_b128 v[160:163], v164 offset:2048
	ds_read_b128 v[164:167], v164 offset:3072
	s_add_u32 s42, s42, 0x40000
	s_addc_u32 s43, s43, 0
	s_mov_b32 m0, s53
	v_lshl_add_u64 v[222:223], s[42:43], 0, v[172:173]
	ds_read_b128 v[168:171], v186 offset:32768
	ds_read_b128 v[174:177], v186 offset:33792
	ds_read_b128 v[192:195], v186 offset:34816
	ds_read_b128 v[196:199], v186 offset:35840
	ds_read_b128 v[200:203], v186 offset:36864
	ds_read_b128 v[204:207], v186 offset:37888
	ds_read_b128 v[208:211], v186 offset:38912
	ds_read_b128 v[212:215], v186 offset:39936
	global_load_lds_dwordx4 v[222:223], off
	v_lshl_add_u64 v[222:223], s[42:43], 0, v[144:145]
	s_mov_b32 m0, s54
	s_nop 0
	global_load_lds_dwordx4 v[222:223], off
	s_waitcnt vmcnt(8)
	s_waitcnt lgkmcnt(0)
	s_barrier
	s_waitcnt lgkmcnt(0)
	v_mfma_f32_16x16x32_bf16 v[140:143], v[72:75], v[168:171], v[140:143]
	v_mfma_f32_16x16x32_bf16 v[136:139], v[88:91], v[168:171], v[136:139]
	v_mfma_f32_16x16x32_bf16 v[124:127], v[72:75], v[192:195], v[124:127]
	v_mfma_f32_16x16x32_bf16 v[120:123], v[88:91], v[192:195], v[120:123]
	v_mfma_f32_16x16x32_bf16 v[108:111], v[72:75], v[200:203], v[108:111]
	v_mfma_f32_16x16x32_bf16 v[104:107], v[88:91], v[200:203], v[104:107]
	v_mfma_f32_16x16x32_bf16 v[84:87], v[72:75], v[208:211], v[84:87]
	v_mfma_f32_16x16x32_bf16 v[80:83], v[88:91], v[208:211], v[80:83]
	v_mfma_f32_16x16x32_bf16 v[140:143], v[76:79], v[174:177], v[140:143]
	v_mfma_f32_16x16x32_bf16 v[136:139], v[92:95], v[174:177], v[136:139]
	v_mfma_f32_16x16x32_bf16 v[124:127], v[76:79], v[196:199], v[124:127]
	v_mfma_f32_16x16x32_bf16 v[120:123], v[92:95], v[196:199], v[120:123]
	v_mfma_f32_16x16x32_bf16 v[108:111], v[76:79], v[204:207], v[108:111]
	v_mfma_f32_16x16x32_bf16 v[104:107], v[92:95], v[204:207], v[104:107]
	v_mfma_f32_16x16x32_bf16 v[84:87], v[76:79], v[212:215], v[84:87]
	v_mfma_f32_16x16x32_bf16 v[80:83], v[92:95], v[212:215], v[80:83]
	v_mfma_f32_16x16x32_bf16 v[132:135], v[152:155], v[168:171], v[132:135]
	v_mfma_f32_16x16x32_bf16 v[128:131], v[160:163], v[168:171], v[128:131]
	v_mfma_f32_16x16x32_bf16 v[116:119], v[152:155], v[192:195], v[116:119]
	v_mfma_f32_16x16x32_bf16 v[112:115], v[160:163], v[192:195], v[112:115]
	v_mfma_f32_16x16x32_bf16 v[100:103], v[152:155], v[200:203], v[100:103]
	v_mfma_f32_16x16x32_bf16 v[96:99], v[160:163], v[200:203], v[96:99]
	v_mfma_f32_16x16x32_bf16 v[68:71], v[152:155], v[208:211], v[68:71]
	v_mfma_f32_16x16x32_bf16 v[64:67], v[160:163], v[208:211], v[64:67]
	v_mfma_f32_16x16x32_bf16 v[132:135], v[156:159], v[174:177], v[132:135]
	v_mfma_f32_16x16x32_bf16 v[128:131], v[164:167], v[174:177], v[128:131]
	v_mfma_f32_16x16x32_bf16 v[116:119], v[156:159], v[196:199], v[116:119]
	v_mfma_f32_16x16x32_bf16 v[112:115], v[164:167], v[196:199], v[112:115]
	v_mfma_f32_16x16x32_bf16 v[100:103], v[156:159], v[204:207], v[100:103]
	v_mfma_f32_16x16x32_bf16 v[96:99], v[164:167], v[204:207], v[96:99]
	v_mfma_f32_16x16x32_bf16 v[68:71], v[156:159], v[212:215], v[68:71]
	v_mfma_f32_16x16x32_bf16 v[64:67], v[164:167], v[212:215], v[64:67]
	s_barrier
; #define PG8_STAGE(bufoff, gbase, voff) do { _Pragma("unroll") for (int _i = 0; _i < 2; ++_i) \
;         __builtin_amdgcn_global_load_lds((const unsigned*)((const char*)(gbase) + (voff)[_i]), (PG8_LAS unsigned*)(lds + (bufoff) + ldsw + _i * 8192), 16, 0, 0); } while (0)
; #define PG8_LDA(dst, b, h) do { _Pragma("unroll") for (int m = 0; m < 4; ++m) _Pragma("unroll") for (int k = 0; k < 2; ++k) dst[m][k] = *(const PG8_LAS bf16x8*)(lds + PG8_SA(b, h) + aoff + m * 2048 + k * 1024); } while (0)
; #define PG8_MMA(ai, bj, At, Bt) do { __builtin_amdgcn_s_setprio(1); _Pragma("unroll") for (int m = 0; m < 4; ++m) _Pragma("unroll") for (int n = 0; n < 2; ++n) _Pragma("unroll") for (int k = 0; k < 2; ++k) \
;         acc[ai][bj][m][n] = __builtin_amdgcn_mfma_f32_16x16x32_bf16(Bt[n][k], At[m][k], acc[ai][bj][m][n], 0, 0, 0); __builtin_amdgcn_s_setprio(0); } while (0)
; #define PG8_WAIT_V(n) asm volatile("s_waitcnt vmcnt(" #n ")" ::: "memory")
; #define PG8_WAIT_L(n) asm volatile("s_waitcnt lgkmcnt(" #n ")" ::: "memory")
; #define PG8_BAR __builtin_amdgcn_s_barrier()
; #define PG8_SCHED __builtin_amdgcn_sched_barrier(0)
; template <class Epi, class Sched, bool ALIGN_EPI = false, bool SP2 = false>
; __device__ __forceinline__ void gemm_phase(PG8_LAS unsigned char* lds, const Gemm g, const Sched& S, const Epi& E) {
;     ...
;             PG8_LDA(At, 1, 1); PG8_STAGE(PG8_SB(1, 0), b3, voffB); PG8_STAGE(PG8_SB(1, 1), b3 + hstepB, voffB); PG8_STAGE(PG8_SA(1, 0), a3, voffA);
;             PG8_WAIT_V(8); PG8_WAIT_L(0); PG8_BAR; PG8_MMA(1, 0, At, B0); PG8_MMA(1, 1, At, B1); PG8_BAR; PG8_SCHED;
;     ...
;         if constexpr (ALIGN_EPI) { if (wr == 0) PG8_BAR; }
	s_add_i32 s42, s67, s50
	v_lshl_add_u64 v[178:179], v[178:179], 0, s[80:81]
	s_mov_b32 m0, s42
	ds_read_b128 v[168:171], v186 offset:49152
	ds_read_b128 v[174:177], v186 offset:50176
	ds_read_b128 v[192:195], v186 offset:51200
	ds_read_b128 v[196:199], v186 offset:52224
	ds_read_b128 v[200:203], v186 offset:53248
	ds_read_b128 v[204:207], v186 offset:54272
	ds_read_b128 v[208:211], v186 offset:55296
	ds_read_b128 v[212:215], v186 offset:56320
	global_load_lds_dwordx4 v[178:179], off
	s_add_i32 m0, s42, 0x2000
	s_add_u32 s40, s40, 0x40080
	v_lshl_add_u64 v[178:179], v[216:217], 0, s[80:81]
	s_addc_u32 s41, s41, 0
	s_add_i32 s42, s68, s50
	global_load_lds_dwordx4 v[178:179], off
	v_lshl_add_u64 v[178:179], s[40:41], 0, v[172:173]
	s_mov_b32 m0, s42
	s_nop 0
	global_load_lds_dwordx4 v[178:179], off
	v_lshl_add_u64 v[178:179], s[40:41], 0, v[144:145]
	s_add_i32 m0, s42, 0x2000
	s_nop 0
	global_load_lds_dwordx4 v[178:179], off
	v_lshl_add_u64 v[178:179], v[218:219], 0, s[80:81]
	s_mov_b32 m0, s59
	s_nop 0
	global_load_lds_dwordx4 v[178:179], off
	v_lshl_add_u64 v[178:179], v[220:221], 0, s[80:81]
	s_mov_b32 m0, s60
	s_nop 0
	global_load_lds_dwordx4 v[178:179], off
	s_waitcnt vmcnt(8)
	s_waitcnt lgkmcnt(0)
	s_barrier
	s_waitcnt lgkmcnt(0)
	v_mfma_f32_16x16x32_bf16 v[60:63], v[72:75], v[168:171], v[60:63]
	v_mfma_f32_16x16x32_bf16 v[56:59], v[88:91], v[168:171], v[56:59]
	v_mfma_f32_16x16x32_bf16 v[44:47], v[72:75], v[192:195], v[44:47]
	v_mfma_f32_16x16x32_bf16 v[40:43], v[88:91], v[192:195], v[40:43]
	v_mfma_f32_16x16x32_bf16 v[28:31], v[72:75], v[200:203], v[28:31]
	v_mfma_f32_16x16x32_bf16 v[24:27], v[88:91], v[200:203], v[24:27]
	v_mfma_f32_16x16x32_bf16 v[12:15], v[72:75], v[208:211], v[12:15]
	v_mfma_f32_16x16x32_bf16 v[8:11], v[88:91], v[208:211], v[8:11]
	v_mfma_f32_16x16x32_bf16 v[60:63], v[76:79], v[174:177], v[60:63]
	v_mfma_f32_16x16x32_bf16 v[56:59], v[92:95], v[174:177], v[56:59]
	v_mfma_f32_16x16x32_bf16 v[44:47], v[76:79], v[196:199], v[44:47]
	v_mfma_f32_16x16x32_bf16 v[40:43], v[92:95], v[196:199], v[40:43]
	v_mfma_f32_16x16x32_bf16 v[28:31], v[76:79], v[204:207], v[28:31]
	v_mfma_f32_16x16x32_bf16 v[24:27], v[92:95], v[204:207], v[24:27]
	v_mfma_f32_16x16x32_bf16 v[12:15], v[76:79], v[212:215], v[12:15]
	v_mfma_f32_16x16x32_bf16 v[8:11], v[92:95], v[212:215], v[8:11]
	v_mfma_f32_16x16x32_bf16 v[52:55], v[152:155], v[168:171], v[52:55]
	v_mfma_f32_16x16x32_bf16 v[48:51], v[160:163], v[168:171], v[48:51]
	v_mfma_f32_16x16x32_bf16 v[36:39], v[152:155], v[192:195], v[36:39]
	v_mfma_f32_16x16x32_bf16 v[32:35], v[160:163], v[192:195], v[32:35]
	v_mfma_f32_16x16x32_bf16 v[20:23], v[152:155], v[200:203], v[20:23]
	v_mfma_f32_16x16x32_bf16 v[16:19], v[160:163], v[200:203], v[16:19]
	v_mfma_f32_16x16x32_bf16 v[4:7], v[152:155], v[208:211], v[4:7]
	v_mfma_f32_16x16x32_bf16 v[0:3], v[160:163], v[208:211], v[0:3]
	v_mfma_f32_16x16x32_bf16 v[52:55], v[156:159], v[174:177], v[52:55]
	v_mfma_f32_16x16x32_bf16 v[48:51], v[164:167], v[174:177], v[48:51]
	v_mfma_f32_16x16x32_bf16 v[36:39], v[156:159], v[196:199], v[36:39]
	v_mfma_f32_16x16x32_bf16 v[32:35], v[164:167], v[196:199], v[32:35]
	v_mfma_f32_16x16x32_bf16 v[20:23], v[156:159], v[204:207], v[20:23]
	v_mfma_f32_16x16x32_bf16 v[16:19], v[164:167], v[204:207], v[16:19]
	v_mfma_f32_16x16x32_bf16 v[4:7], v[156:159], v[212:215], v[4:7]
	v_mfma_f32_16x16x32_bf16 v[0:3], v[164:167], v[212:215], v[0:3]
	s_barrier
	s_add_i32 s66, s66, 2
	s_add_u32 s38, s38, 0x100
	s_addc_u32 s39, s39, 0
	s_add_u32 s64, s64, 0x100
	s_addc_u32 s65, s65, 0
	s_cmp_gt_u32 s66, 13
	s_cbranch_scc0 .LBB0_1575
	s_and_b64 vcc, exec, s[22:23]
	s_cbranch_vccz .LBB0_1578
	s_barrier

;     __device__ __forceinline__ bool next(int i, Unit& u) const { const int L = i * G + c; if (L >= nsub) return false; u.pk = L >> 4; u.pm = MLAT / BM + (L & 3); u.pn = (L >> 2) & 3; return true; }
; #define PG8_STAGE(bufoff, gbase, voff) do { _Pragma("unroll") for (int _i = 0; _i < 2; ++_i) \
;         __builtin_amdgcn_global_load_lds((const unsigned*)((const char*)(gbase) + (voff)[_i]), (PG8_LAS unsigned*)(lds + (bufoff) + ldsw + _i * 8192), 16, 0, 0); } while (0)
; #define PG8_LDA(dst, b, h) do { _Pragma("unroll") for (int m = 0; m < 4; ++m) _Pragma("unroll") for (int k = 0; k < 2; ++k) dst[m][k] = *(const PG8_LAS bf16x8*)(lds + PG8_SA(b, h) + aoff + m * 2048 + k * 1024); } while (0)
; #define PG8_LDB(dst, b, h) do { _Pragma("unroll") for (int n = 0; n < 2; ++n) _Pragma("unroll") for (int k = 0; k < 2; ++k) dst[n][k] = *(const PG8_LAS bf16x8*)(lds + PG8_SB(b, h) + boff + n * 2048 + k * 1024); } while (0)
; #define PG8_WAIT_V(n) asm volatile("s_waitcnt vmcnt(" #n ")" ::: "memory")
; #define PG8_WAIT_L(n) asm volatile("s_waitcnt lgkmcnt(" #n ")" ::: "memory")
; template <class Epi, class Sched, bool ALIGN_EPI = false, bool SP2 = false>
; __device__ __forceinline__ void gemm_phase(PG8_LAS unsigned char* lds, const Gemm g, const Sched& S, const Epi& E) {
;     ...
;         const bool has_next = S.next(ui + 1, nxt);
;         const char* nA = has_next ? g.a_of(nxt) : cA; const char* nB = has_next ? g.b_of(nxt) : cB;
;         for (int t = 0; t < nt; t += 2) {
;             const bool last = (t == nt - 2);
;             const char* a1 = cA + (size_t)(t + 1) * kstep;
;             const char* a2 = last ? nA : cA + (size_t)(t + 2) * kstep; const char* b2 = last ? nB : cB + (size_t)(t + 2) * kstep;
;             const char* a3 = a2 + kstep; const char* b3 = b2 + kstep;
;             if (last && has_next) S.a_ready(nxt);
;             if constexpr (SP2) {
;             PG8_LDB(B0, 0, 0); PG8_LDB(B1, 0, 1); PG8_SCHED; PG8_LDA(At, 0, 0); PG8_STAGE(PG8_SA(1, 1), a1 + hstepA, voffA);
;             PG8_WAIT_V(8); PG8_WAIT_L(0); PG8_BAR; PG8_MMA(0, 0, At, B0); PG8_MMA(0, 1, At, B1); PG8_BAR; PG8_SCHED;
;             PG8_LDA(At, 0, 1); PG8_STAGE(PG8_SB(0, 0), b2, voffB); PG8_STAGE(PG8_SB(0, 1), b2 + hstepB, voffB); PG8_STAGE(PG8_SA(0, 0), a2, voffA);
;             PG8_WAIT_V(8); PG8_WAIT_L(0); PG8_BAR; PG8_MMA(1, 0, At, B0); PG8_MMA(1, 1, At, B1); PG8_BAR; PG8_SCHED;
.LBB0_1612:
	s_add_u32 s23, s26, s19
	s_addc_u32 s40, s27, 0
	s_add_u32 s36, s23, 0x100
	s_addc_u32 s37, s40, 0
	s_and_b64 s[34:35], s[30:31], exec
	s_cselect_b32 s37, s17, s37
	s_cselect_b32 s36, s16, s36
	s_add_u32 s19, s24, s19
	s_addc_u32 s34, s25, 0
	s_add_u32 s19, s19, 0x100
	s_addc_u32 s34, s34, 0
	s_add_i32 s66, 0, 0x10000
	s_and_b64 s[30:31], s[30:31], exec
	s_cselect_b32 s39, s21, s34
	s_cselect_b32 s38, s20, s19
	s_add_i32 s31, 0, 0x14000
	s_add_u32 s42, s23, 0x40080
	s_addc_u32 s43, s40, 0
	s_add_i32 s65, s66, s50
	s_add_i32 m0, s51, 0xc000
	s_add_i32 s68, s51, 0xe000
	s_add_i32 s62, s65, 0x2000
	s_add_u32 s40, s38, 0x40000
	v_add_u32_e32 v124, s66, v154
	v_add_u32_e32 v152, s31, v154
	s_addc_u32 s41, s39, 0
	s_add_i32 s64, s31, s50
	ds_read_b128 v[112:115], v124
	ds_read_b128 v[116:119], v124 offset:1024
	ds_read_b128 v[120:123], v124 offset:2048
	ds_read_b128 v[124:127], v124 offset:3072
	ds_read_b128 v[148:151], v152
	ds_read_b128 v[158:161], v152 offset:1024
	ds_read_b128 v[162:165], v152 offset:2048
	ds_read_b128 v[166:169], v152 offset:3072
	s_add_i32 s63, s64, 0x2000
	s_add_i32 s61, 0, 0x18000
	s_add_i32 s60, 0, 0x1c000
	s_add_u32 s34, s36, 0x40000
	s_addc_u32 s35, s37, 0
	s_add_i32 s23, s61, s50
	s_add_i32 s19, s23, 0x2000
	s_add_u32 s30, s38, 0x40080
	s_addc_u32 s31, s39, 0
	s_add_i32 s67, s60, s50
	s_add_i32 s66, s67, 0x2000
	v_lshl_add_u64 v[152:153], s[42:43], 0, v[146:147]
	ds_read_b128 v[174:177], v157
	ds_read_b128 v[178:181], v157 offset:1024
	ds_read_b128 v[182:185], v157 offset:2048
	ds_read_b128 v[192:195], v157 offset:3072
	ds_read_b128 v[196:199], v157 offset:4096
	ds_read_b128 v[200:203], v157 offset:5120
	ds_read_b128 v[204:207], v157 offset:6144
	ds_read_b128 v[208:211], v157 offset:7168
	global_load_lds_dwordx4 v[152:153], off
	v_lshl_add_u64 v[152:153], s[42:43], 0, v[144:145]
	s_mov_b32 m0, s68
	s_nop 0
	global_load_lds_dwordx4 v[152:153], off
	s_waitcnt vmcnt(8)
	s_waitcnt lgkmcnt(0)
	s_barrier
	s_waitcnt lgkmcnt(0)
	v_mfma_f32_16x16x32_bf16 v[140:143], v[112:115], v[174:177], v[140:143]
	v_mfma_f32_16x16x32_bf16 v[136:139], v[120:123], v[174:177], v[136:139]
	v_mfma_f32_16x16x32_bf16 v[108:111], v[112:115], v[182:185], v[108:111]
	v_mfma_f32_16x16x32_bf16 v[104:107], v[120:123], v[182:185], v[104:107]
	v_mfma_f32_16x16x32_bf16 v[92:95], v[112:115], v[196:199], v[92:95]
	v_mfma_f32_16x16x32_bf16 v[88:91], v[120:123], v[196:199], v[88:91]
	v_mfma_f32_16x16x32_bf16 v[76:79], v[112:115], v[204:207], v[76:79]
	v_mfma_f32_16x16x32_bf16 v[72:75], v[120:123], v[204:207], v[72:75]
	v_mfma_f32_16x16x32_bf16 v[140:143], v[116:119], v[178:181], v[140:143]
	v_mfma_f32_16x16x32_bf16 v[136:139], v[124:127], v[178:181], v[136:139]
	v_mfma_f32_16x16x32_bf16 v[108:111], v[116:119], v[192:195], v[108:111]
	v_mfma_f32_16x16x32_bf16 v[104:107], v[124:127], v[192:195], v[104:107]
	v_mfma_f32_16x16x32_bf16 v[92:95], v[116:119], v[200:203], v[92:95]
	v_mfma_f32_16x16x32_bf16 v[88:91], v[124:127], v[200:203], v[88:91]
	v_mfma_f32_16x16x32_bf16 v[76:79], v[116:119], v[208:211], v[76:79]
	v_mfma_f32_16x16x32_bf16 v[72:75], v[124:127], v[208:211], v[72:75]
	v_mfma_f32_16x16x32_bf16 v[132:135], v[148:151], v[174:177], v[132:135]
	v_mfma_f32_16x16x32_bf16 v[128:131], v[162:165], v[174:177], v[128:131]
	v_mfma_f32_16x16x32_bf16 v[100:103], v[148:151], v[182:185], v[100:103]
	v_mfma_f32_16x16x32_bf16 v[96:99], v[162:165], v[182:185], v[96:99]
	v_mfma_f32_16x16x32_bf16 v[84:87], v[148:151], v[196:199], v[84:87]
	v_mfma_f32_16x16x32_bf16 v[80:83], v[162:165], v[196:199], v[80:83]
	v_mfma_f32_16x16x32_bf16 v[68:71], v[148:151], v[204:207], v[68:71]
	v_mfma_f32_16x16x32_bf16 v[64:67], v[162:165], v[204:207], v[64:67]
	v_mfma_f32_16x16x32_bf16 v[132:135], v[158:161], v[178:181], v[132:135]
	v_mfma_f32_16x16x32_bf16 v[128:131], v[166:169], v[178:181], v[128:131]
	v_mfma_f32_16x16x32_bf16 v[100:103], v[158:161], v[192:195], v[100:103]
	v_mfma_f32_16x16x32_bf16 v[96:99], v[166:169], v[192:195], v[96:99]
	v_mfma_f32_16x16x32_bf16 v[84:87], v[158:161], v[200:203], v[84:87]
	v_mfma_f32_16x16x32_bf16 v[80:83], v[166:169], v[200:203], v[80:83]
	v_mfma_f32_16x16x32_bf16 v[68:71], v[158:161], v[208:211], v[68:71]
	v_mfma_f32_16x16x32_bf16 v[64:67], v[166:169], v[208:211], v[64:67]
	s_barrier
	s_mov_b32 m0, s65
	v_lshl_add_u64 v[152:153], s[38:39], 0, v[146:147]
	ds_read_b128 v[174:177], v157 offset:16384
	ds_read_b128 v[178:181], v157 offset:17408
	ds_read_b128 v[182:185], v157 offset:18432
	ds_read_b128 v[192:195], v157 offset:19456
	ds_read_b128 v[196:199], v157 offset:20480
	ds_read_b128 v[200:203], v157 offset:21504
	ds_read_b128 v[204:207], v157 offset:22528
	ds_read_b128 v[208:211], v157 offset:23552
	global_load_lds_dwordx4 v[152:153], off
	v_lshl_add_u64 v[170:171], s[38:39], 0, v[144:145]
	s_mov_b32 m0, s62
	v_lshl_add_u64 v[186:187], s[40:41], 0, v[146:147]
	global_load_lds_dwordx4 v[170:171], off
	s_mov_b32 m0, s64
	v_lshl_add_u64 v[212:213], s[36:37], 0, v[144:145]
	global_load_lds_dwordx4 v[186:187], off
	v_lshl_add_u64 v[186:187], s[40:41], 0, v[144:145]
	s_mov_b32 m0, s63
	s_nop 0
	global_load_lds_dwordx4 v[186:187], off
	v_lshl_add_u64 v[186:187], s[36:37], 0, v[146:147]
	s_mov_b32 m0, s51
	s_nop 0
	global_load_lds_dwordx4 v[186:187], off
	s_mov_b32 m0, s52
	s_nop 0
	global_load_lds_dwordx4 v[212:213], off
	s_waitcnt vmcnt(8)
	s_waitcnt lgkmcnt(0)
	s_barrier
; #define PG8_STAGE(bufoff, gbase, voff) do { _Pragma("unroll") for (int _i = 0; _i < 2; ++_i) \
;         __builtin_amdgcn_global_load_lds((const unsigned*)((const char*)(gbase) + (voff)[_i]), (PG8_LAS unsigned*)(lds + (bufoff) + ldsw + _i * 8192), 16, 0, 0); } while (0)
; #define PG8_LDA(dst, b, h) do { _Pragma("unroll") for (int m = 0; m < 4; ++m) _Pragma("unroll") for (int k = 0; k < 2; ++k) dst[m][k] = *(const PG8_LAS bf16x8*)(lds + PG8_SA(b, h) + aoff + m * 2048 + k * 1024); } while (0)
; #define PG8_LDB(dst, b, h) do { _Pragma("unroll") for (int n = 0; n < 2; ++n) _Pragma("unroll") for (int k = 0; k < 2; ++k) dst[n][k] = *(const PG8_LAS bf16x8*)(lds + PG8_SB(b, h) + boff + n * 2048 + k * 1024); } while (0)
; #define PG8_MMA(ai, bj, At, Bt) do { __builtin_amdgcn_s_setprio(1); _Pragma("unroll") for (int m = 0; m < 4; ++m) _Pragma("unroll") for (int n = 0; n < 2; ++n) _Pragma("unroll") for (int k = 0; k < 2; ++k) \
;         acc[ai][bj][m][n] = __builtin_amdgcn_mfma_f32_16x16x32_bf16(Bt[n][k], At[m][k], acc[ai][bj][m][n], 0, 0, 0); __builtin_amdgcn_s_setprio(0); } while (0)
; #define PG8_WAIT_V(n) asm volatile("s_waitcnt vmcnt(" #n ")" ::: "memory")
; #define PG8_WAIT_L(n) asm volatile("s_waitcnt lgkmcnt(" #n ")" ::: "memory")
; #define PG8_BAR __builtin_amdgcn_s_barrier()
; #define PG8_SCHED __builtin_amdgcn_sched_barrier(0)
; template <class Epi, class Sched, bool ALIGN_EPI = false, bool SP2 = false>
; __device__ __forceinline__ void gemm_phase(PG8_LAS unsigned char* lds, const Gemm g, const Sched& S, const Epi& E) {
;     ...
;             PG8_WAIT_V(8); PG8_WAIT_L(0); PG8_BAR; PG8_MMA(1, 0, At, B0); PG8_MMA(1, 1, At, B1); PG8_BAR; PG8_SCHED;
;             PG8_LDB(B0, 1, 0); PG8_LDB(B1, 1, 1); PG8_SCHED; PG8_LDA(At, 1, 0); PG8_STAGE(PG8_SA(0, 1), a2 + hstepA, voffA);
;             PG8_WAIT_V(8); PG8_WAIT_L(0); PG8_BAR; PG8_MMA(0, 0, At, B0); PG8_MMA(0, 1, At, B1); PG8_BAR; PG8_SCHED;
	s_waitcnt lgkmcnt(0)
	v_mfma_f32_16x16x32_bf16 v[60:63], v[112:115], v[174:177], v[60:63]
	v_mfma_f32_16x16x32_bf16 v[56:59], v[120:123], v[174:177], v[56:59]
	v_mfma_f32_16x16x32_bf16 v[52:55], v[112:115], v[182:185], v[52:55]
	v_mfma_f32_16x16x32_bf16 v[40:43], v[120:123], v[182:185], v[40:43]
	v_mfma_f32_16x16x32_bf16 v[36:39], v[112:115], v[196:199], v[36:39]
	v_mfma_f32_16x16x32_bf16 v[24:27], v[120:123], v[196:199], v[24:27]
	v_mfma_f32_16x16x32_bf16 v[20:23], v[112:115], v[204:207], v[20:23]
	v_mfma_f32_16x16x32_bf16 v[8:11], v[120:123], v[204:207], v[8:11]
	v_mfma_f32_16x16x32_bf16 v[60:63], v[116:119], v[178:181], v[60:63]
	v_mfma_f32_16x16x32_bf16 v[56:59], v[124:127], v[178:181], v[56:59]
	v_mfma_f32_16x16x32_bf16 v[52:55], v[116:119], v[192:195], v[52:55]
	v_mfma_f32_16x16x32_bf16 v[40:43], v[124:127], v[192:195], v[40:43]
	v_mfma_f32_16x16x32_bf16 v[36:39], v[116:119], v[200:203], v[36:39]
	v_mfma_f32_16x16x32_bf16 v[24:27], v[124:127], v[200:203], v[24:27]
	v_mfma_f32_16x16x32_bf16 v[20:23], v[116:119], v[208:211], v[20:23]
	v_mfma_f32_16x16x32_bf16 v[8:11], v[124:127], v[208:211], v[8:11]
	v_mfma_f32_16x16x32_bf16 v[48:51], v[148:151], v[174:177], v[48:51]
	v_mfma_f32_16x16x32_bf16 v[44:47], v[162:165], v[174:177], v[44:47]
	v_mfma_f32_16x16x32_bf16 v[32:35], v[148:151], v[182:185], v[32:35]
	v_mfma_f32_16x16x32_bf16 v[28:31], v[162:165], v[182:185], v[28:31]
	v_mfma_f32_16x16x32_bf16 v[16:19], v[148:151], v[196:199], v[16:19]
	v_mfma_f32_16x16x32_bf16 v[12:15], v[162:165], v[196:199], v[12:15]
	v_mfma_f32_16x16x32_bf16 v[4:7], v[148:151], v[204:207], v[4:7]
	v_mfma_f32_16x16x32_bf16 v[0:3], v[162:165], v[204:207], v[0:3]
	v_mfma_f32_16x16x32_bf16 v[48:51], v[158:161], v[178:181], v[48:51]
	v_mfma_f32_16x16x32_bf16 v[44:47], v[166:169], v[178:181], v[44:47]
	v_mfma_f32_16x16x32_bf16 v[32:35], v[158:161], v[192:195], v[32:35]
	v_mfma_f32_16x16x32_bf16 v[28:31], v[166:169], v[192:195], v[28:31]
	v_mfma_f32_16x16x32_bf16 v[16:19], v[158:161], v[200:203], v[16:19]
	v_mfma_f32_16x16x32_bf16 v[12:15], v[166:169], v[200:203], v[12:15]
	v_mfma_f32_16x16x32_bf16 v[4:7], v[158:161], v[208:211], v[4:7]
	v_mfma_f32_16x16x32_bf16 v[0:3], v[166:169], v[208:211], v[0:3]
	s_barrier
	v_add_u32_e32 v124, s61, v154
	v_add_u32_e32 v166, s60, v154
	ds_read_b128 v[112:115], v124
	ds_read_b128 v[116:119], v124 offset:1024
	ds_read_b128 v[120:123], v124 offset:2048
	ds_read_b128 v[124:127], v124 offset:3072
	ds_read_b128 v[148:151], v166
	ds_read_b128 v[158:161], v166 offset:1024
	ds_read_b128 v[162:165], v166 offset:2048
	ds_read_b128 v[166:169], v166 offset:3072
	s_mov_b32 m0, s53
	v_lshl_add_u64 v[214:215], s[34:35], 0, v[146:147]
	ds_read_b128 v[174:177], v157 offset:32768
	ds_read_b128 v[178:181], v157 offset:33792
	ds_read_b128 v[182:185], v157 offset:34816
	ds_read_b128 v[192:195], v157 offset:35840
	ds_read_b128 v[196:199], v157 offset:36864
	ds_read_b128 v[200:203], v157 offset:37888
	ds_read_b128 v[204:207], v157 offset:38912
	ds_read_b128 v[208:211], v157 offset:39936
	global_load_lds_dwordx4 v[214:215], off
	v_lshl_add_u64 v[214:215], s[34:35], 0, v[144:145]
	s_mov_b32 m0, s54
	s_nop 0
	global_load_lds_dwordx4 v[214:215], off
	s_waitcnt vmcnt(8)
	s_waitcnt lgkmcnt(0)
	s_barrier
	s_waitcnt lgkmcnt(0)
	v_mfma_f32_16x16x32_bf16 v[140:143], v[112:115], v[174:177], v[140:143]
	v_mfma_f32_16x16x32_bf16 v[136:139], v[120:123], v[174:177], v[136:139]
	v_mfma_f32_16x16x32_bf16 v[108:111], v[112:115], v[182:185], v[108:111]
	v_mfma_f32_16x16x32_bf16 v[104:107], v[120:123], v[182:185], v[104:107]
	v_mfma_f32_16x16x32_bf16 v[92:95], v[112:115], v[196:199], v[92:95]
	v_mfma_f32_16x16x32_bf16 v[88:91], v[120:123], v[196:199], v[88:91]
	v_mfma_f32_16x16x32_bf16 v[76:79], v[112:115], v[204:207], v[76:79]
	v_mfma_f32_16x16x32_bf16 v[72:75], v[120:123], v[204:207], v[72:75]
	v_mfma_f32_16x16x32_bf16 v[140:143], v[116:119], v[178:181], v[140:143]
	v_mfma_f32_16x16x32_bf16 v[136:139], v[124:127], v[178:181], v[136:139]
	v_mfma_f32_16x16x32_bf16 v[108:111], v[116:119], v[192:195], v[108:111]
	v_mfma_f32_16x16x32_bf16 v[104:107], v[124:127], v[192:195], v[104:107]
	v_mfma_f32_16x16x32_bf16 v[92:95], v[116:119], v[200:203], v[92:95]
	v_mfma_f32_16x16x32_bf16 v[88:91], v[124:127], v[200:203], v[88:91]
	v_mfma_f32_16x16x32_bf16 v[76:79], v[116:119], v[208:211], v[76:79]
	v_mfma_f32_16x16x32_bf16 v[72:75], v[124:127], v[208:211], v[72:75]
	v_mfma_f32_16x16x32_bf16 v[132:135], v[148:151], v[174:177], v[132:135]
	v_mfma_f32_16x16x32_bf16 v[128:131], v[162:165], v[174:177], v[128:131]
	v_mfma_f32_16x16x32_bf16 v[100:103], v[148:151], v[182:185], v[100:103]
	v_mfma_f32_16x16x32_bf16 v[96:99], v[162:165], v[182:185], v[96:99]
	v_mfma_f32_16x16x32_bf16 v[84:87], v[148:151], v[196:199], v[84:87]
	v_mfma_f32_16x16x32_bf16 v[80:83], v[162:165], v[196:199], v[80:83]
	v_mfma_f32_16x16x32_bf16 v[68:71], v[148:151], v[204:207], v[68:71]
	v_mfma_f32_16x16x32_bf16 v[64:67], v[162:165], v[204:207], v[64:67]
	v_mfma_f32_16x16x32_bf16 v[132:135], v[158:161], v[178:181], v[132:135]
	v_mfma_f32_16x16x32_bf16 v[128:131], v[166:169], v[178:181], v[128:131]
	v_mfma_f32_16x16x32_bf16 v[100:103], v[158:161], v[192:195], v[100:103]
	v_mfma_f32_16x16x32_bf16 v[96:99], v[166:169], v[192:195], v[96:99]
	v_mfma_f32_16x16x32_bf16 v[84:87], v[158:161], v[200:203], v[84:87]
	v_mfma_f32_16x16x32_bf16 v[80:83], v[166:169], v[200:203], v[80:83]
	v_mfma_f32_16x16x32_bf16 v[68:71], v[158:161], v[208:211], v[68:71]
	v_mfma_f32_16x16x32_bf16 v[64:67], v[166:169], v[208:211], v[64:67]
	s_barrier
; #define PG8_STAGE(bufoff, gbase, voff) do { _Pragma("unroll") for (int _i = 0; _i < 2; ++_i) \
;         __builtin_amdgcn_global_load_lds((const unsigned*)((const char*)(gbase) + (voff)[_i]), (PG8_LAS unsigned*)(lds + (bufoff) + ldsw + _i * 8192), 16, 0, 0); } while (0)
; #define PG8_LDA(dst, b, h) do { _Pragma("unroll") for (int m = 0; m < 4; ++m) _Pragma("unroll") for (int k = 0; k < 2; ++k) dst[m][k] = *(const PG8_LAS bf16x8*)(lds + PG8_SA(b, h) + aoff + m * 2048 + k * 1024); } while (0)
; #define PG8_MMA(ai, bj, At, Bt) do { __builtin_amdgcn_s_setprio(1); _Pragma("unroll") for (int m = 0; m < 4; ++m) _Pragma("unroll") for (int n = 0; n < 2; ++n) _Pragma("unroll") for (int k = 0; k < 2; ++k) \
;         acc[ai][bj][m][n] = __builtin_amdgcn_mfma_f32_16x16x32_bf16(Bt[n][k], At[m][k], acc[ai][bj][m][n], 0, 0, 0); __builtin_amdgcn_s_setprio(0); } while (0)
; #define PG8_WAIT_V(n) asm volatile("s_waitcnt vmcnt(" #n ")" ::: "memory")
; #define PG8_WAIT_L(n) asm volatile("s_waitcnt lgkmcnt(" #n ")" ::: "memory")
; #define PG8_BAR __builtin_amdgcn_s_barrier()
; #define PG8_SCHED __builtin_amdgcn_sched_barrier(0)
; template <class Epi, class Sched, bool ALIGN_EPI = false, bool SP2 = false>
; __device__ __forceinline__ void gemm_phase(PG8_LAS unsigned char* lds, const Gemm g, const Sched& S, const Epi& E) {
;     ...
;             PG8_LDA(At, 1, 1); PG8_STAGE(PG8_SB(1, 0), b3, voffB); PG8_STAGE(PG8_SB(1, 1), b3 + hstepB, voffB); PG8_STAGE(PG8_SA(1, 0), a3, voffA);
;             PG8_WAIT_V(8); PG8_WAIT_L(0); PG8_BAR; PG8_MMA(1, 0, At, B0); PG8_MMA(1, 1, At, B1); PG8_BAR; PG8_SCHED;
;     ...
;         if constexpr (ALIGN_EPI) { if (wr == 0) PG8_BAR; }
	s_mov_b32 m0, s23
	v_lshl_add_u64 v[152:153], v[152:153], 0, s[80:81]
	ds_read_b128 v[174:177], v157 offset:49152
	ds_read_b128 v[178:181], v157 offset:50176
	ds_read_b128 v[182:185], v157 offset:51200
	ds_read_b128 v[192:195], v157 offset:52224
	ds_read_b128 v[196:199], v157 offset:53248
	ds_read_b128 v[200:203], v157 offset:54272
	ds_read_b128 v[204:207], v157 offset:55296
	ds_read_b128 v[208:211], v157 offset:56320
	global_load_lds_dwordx4 v[152:153], off
	v_lshl_add_u64 v[152:153], v[170:171], 0, s[80:81]
	s_mov_b32 m0, s19
	s_nop 0
	global_load_lds_dwordx4 v[152:153], off
	v_lshl_add_u64 v[152:153], s[30:31], 0, v[146:147]
	s_mov_b32 m0, s67
	s_nop 0
	global_load_lds_dwordx4 v[152:153], off
	v_lshl_add_u64 v[152:153], s[30:31], 0, v[144:145]
	s_mov_b32 m0, s66
	s_nop 0
	global_load_lds_dwordx4 v[152:153], off
	v_lshl_add_u64 v[152:153], v[186:187], 0, s[80:81]
	s_mov_b32 m0, s55
	s_nop 0
	global_load_lds_dwordx4 v[152:153], off
	v_lshl_add_u64 v[152:153], v[212:213], 0, s[80:81]
	s_mov_b32 m0, s56
	s_nop 0
	global_load_lds_dwordx4 v[152:153], off
	s_waitcnt vmcnt(8)
	s_waitcnt lgkmcnt(0)
	s_barrier
	s_waitcnt lgkmcnt(0)
	v_mfma_f32_16x16x32_bf16 v[60:63], v[112:115], v[174:177], v[60:63]
	v_mfma_f32_16x16x32_bf16 v[56:59], v[120:123], v[174:177], v[56:59]
	v_mfma_f32_16x16x32_bf16 v[52:55], v[112:115], v[182:185], v[52:55]
	v_mfma_f32_16x16x32_bf16 v[40:43], v[120:123], v[182:185], v[40:43]
	v_mfma_f32_16x16x32_bf16 v[36:39], v[112:115], v[196:199], v[36:39]
	v_mfma_f32_16x16x32_bf16 v[24:27], v[120:123], v[196:199], v[24:27]
	v_mfma_f32_16x16x32_bf16 v[20:23], v[112:115], v[204:207], v[20:23]
	v_mfma_f32_16x16x32_bf16 v[8:11], v[120:123], v[204:207], v[8:11]
	v_mfma_f32_16x16x32_bf16 v[60:63], v[116:119], v[178:181], v[60:63]
	v_mfma_f32_16x16x32_bf16 v[56:59], v[124:127], v[178:181], v[56:59]
	v_mfma_f32_16x16x32_bf16 v[52:55], v[116:119], v[192:195], v[52:55]
	v_mfma_f32_16x16x32_bf16 v[40:43], v[124:127], v[192:195], v[40:43]
	v_mfma_f32_16x16x32_bf16 v[36:39], v[116:119], v[200:203], v[36:39]
	v_mfma_f32_16x16x32_bf16 v[24:27], v[124:127], v[200:203], v[24:27]
	v_mfma_f32_16x16x32_bf16 v[20:23], v[116:119], v[208:211], v[20:23]
	v_mfma_f32_16x16x32_bf16 v[8:11], v[124:127], v[208:211], v[8:11]
	v_mfma_f32_16x16x32_bf16 v[48:51], v[148:151], v[174:177], v[48:51]
	v_mfma_f32_16x16x32_bf16 v[44:47], v[162:165], v[174:177], v[44:47]
	v_mfma_f32_16x16x32_bf16 v[32:35], v[148:151], v[182:185], v[32:35]
	v_mfma_f32_16x16x32_bf16 v[28:31], v[162:165], v[182:185], v[28:31]
	v_mfma_f32_16x16x32_bf16 v[16:19], v[148:151], v[196:199], v[16:19]
	v_mfma_f32_16x16x32_bf16 v[12:15], v[162:165], v[196:199], v[12:15]
	v_mfma_f32_16x16x32_bf16 v[4:7], v[148:151], v[204:207], v[4:7]
	v_mfma_f32_16x16x32_bf16 v[0:3], v[162:165], v[204:207], v[0:3]
	v_mfma_f32_16x16x32_bf16 v[48:51], v[158:161], v[178:181], v[48:51]
	v_mfma_f32_16x16x32_bf16 v[44:47], v[166:169], v[178:181], v[44:47]
	v_mfma_f32_16x16x32_bf16 v[32:35], v[158:161], v[192:195], v[32:35]
	v_mfma_f32_16x16x32_bf16 v[28:31], v[166:169], v[192:195], v[28:31]
	v_mfma_f32_16x16x32_bf16 v[16:19], v[158:161], v[200:203], v[16:19]
	v_mfma_f32_16x16x32_bf16 v[12:15], v[166:169], v[200:203], v[12:15]
	v_mfma_f32_16x16x32_bf16 v[4:7], v[158:161], v[208:211], v[4:7]
	v_mfma_f32_16x16x32_bf16 v[0:3], v[166:169], v[208:211], v[0:3]
	s_barrier
	s_movk_i32 s19, 0x100
	s_andn2_b64 vcc, exec, s[28:29]
	s_mov_b64 s[30:31], -1
	s_mov_b64 s[28:29], 0
	s_cbranch_vccz .LBB0_1612
	s_and_b64 vcc, exec, s[10:11]
	s_cbranch_vccz .LBB0_1615
	s_barrier

;     __device__ __forceinline__ bool next(int i, Unit& u) const { const int L = i * G + c; if (L >= nsub) return false; u.pk = L >> 4; u.pm = MLAT / BM + (L & 3); u.pn = (L >> 2) & 3; return true; }
; #define PG8_STAGE(bufoff, gbase, voff) do { _Pragma("unroll") for (int _i = 0; _i < 2; ++_i) \
;         __builtin_amdgcn_global_load_lds((const unsigned*)((const char*)(gbase) + (voff)[_i]), (PG8_LAS unsigned*)(lds + (bufoff) + ldsw + _i * 8192), 16, 0, 0); } while (0)
; #define PG8_LDA(dst, b, h) do { _Pragma("unroll") for (int m = 0; m < 4; ++m) _Pragma("unroll") for (int k = 0; k < 2; ++k) dst[m][k] = *(const PG8_LAS bf16x8*)(lds + PG8_SA(b, h) + aoff + m * 2048 + k * 1024); } while (0)
; #define PG8_LDB(dst, b, h) do { _Pragma("unroll") for (int n = 0; n < 2; ++n) _Pragma("unroll") for (int k = 0; k < 2; ++k) dst[n][k] = *(const PG8_LAS bf16x8*)(lds + PG8_SB(b, h) + boff + n * 2048 + k * 1024); } while (0)
; #define PG8_WAIT_V(n) asm volatile("s_waitcnt vmcnt(" #n ")" ::: "memory")
; #define PG8_WAIT_L(n) asm volatile("s_waitcnt lgkmcnt(" #n ")" ::: "memory")
; template <class Epi, class Sched, bool ALIGN_EPI = false, bool SP2 = false>
; __device__ __forceinline__ void gemm_phase(PG8_LAS unsigned char* lds, const Gemm g, const Sched& S, const Epi& E) {
;     ...
;         const bool has_next = S.next(ui + 1, nxt);
;         const char* nA = has_next ? g.a_of(nxt) : cA; const char* nB = has_next ? g.b_of(nxt) : cB;
;         for (int t = 0; t < nt; t += 2) {
;             const bool last = (t == nt - 2);
;             const char* a1 = cA + (size_t)(t + 1) * kstep;
;             const char* a2 = last ? nA : cA + (size_t)(t + 2) * kstep; const char* b2 = last ? nB : cB + (size_t)(t + 2) * kstep;
;             const char* a3 = a2 + kstep; const char* b3 = b2 + kstep;
;             if (last && has_next) S.a_ready(nxt);
;             if constexpr (SP2) {
;             PG8_LDB(B0, 0, 0); PG8_LDB(B1, 0, 1); PG8_SCHED; PG8_LDA(At, 0, 0); PG8_STAGE(PG8_SA(1, 1), a1 + hstepA, voffA);
;             PG8_WAIT_V(8); PG8_WAIT_L(0); PG8_BAR; PG8_MMA(0, 0, At, B0); PG8_MMA(0, 1, At, B1); PG8_BAR; PG8_SCHED;
;             PG8_LDA(At, 0, 1); PG8_STAGE(PG8_SB(0, 0), b2, voffB); PG8_STAGE(PG8_SB(0, 1), b2 + hstepB, voffB); PG8_STAGE(PG8_SA(0, 0), a2, voffA);
;             PG8_WAIT_V(8); PG8_WAIT_L(0); PG8_BAR; PG8_MMA(1, 0, At, B0); PG8_MMA(1, 1, At, B1); PG8_BAR; PG8_SCHED;
.LBB0_1786:
	s_add_u32 s36, s34, 0xfffc0080
	s_addc_u32 s37, s35, -1
	s_add_i32 s64, 0, 0x10000
	s_cmp_eq_u32 s63, 12
	s_cselect_b32 s39, s11, s37
	s_cselect_b32 s38, s25, s36
	s_cselect_b32 s37, s23, s62
	s_cselect_b32 s36, s60, s61
	s_add_i32 s66, 0, 0x14000
	v_add_u32_e32 v140, s64, v163
	v_add_u32_e32 v158, s66, v163
	ds_read_b128 v[128:131], v140
	ds_read_b128 v[132:135], v140 offset:1024
	ds_read_b128 v[136:139], v140 offset:2048
	ds_read_b128 v[140:143], v140 offset:3072
	ds_read_b128 v[154:157], v158
	ds_read_b128 v[166:169], v158 offset:1024
	ds_read_b128 v[174:177], v158 offset:2048
	ds_read_b128 v[178:181], v158 offset:3072
	v_lshl_add_u64 v[158:159], s[34:35], 0, v[150:151]
	s_add_i32 m0, s31, 0xc000
	ds_read_b128 v[182:185], v165
	ds_read_b128 v[192:195], v165 offset:1024
	ds_read_b128 v[196:199], v165 offset:2048
	ds_read_b128 v[200:203], v165 offset:3072
	ds_read_b128 v[204:207], v165 offset:4096
	ds_read_b128 v[208:211], v165 offset:5120
	ds_read_b128 v[212:215], v165 offset:6144
	ds_read_b128 v[216:219], v165 offset:7168
	global_load_lds_dwordx4 v[158:159], off
	v_lshl_add_u64 v[158:159], s[34:35], 0, v[152:153]
	s_add_i32 m0, s31, 0xe000
	s_nop 0
	global_load_lds_dwordx4 v[158:159], off
	s_waitcnt vmcnt(8)
	s_waitcnt lgkmcnt(0)
	s_barrier
	s_waitcnt lgkmcnt(0)
	v_mfma_f32_16x16x32_bf16 v[124:127], v[128:131], v[182:185], v[124:127]
	v_mfma_f32_16x16x32_bf16 v[120:123], v[136:139], v[182:185], v[120:123]
	v_mfma_f32_16x16x32_bf16 v[108:111], v[128:131], v[196:199], v[108:111]
	v_mfma_f32_16x16x32_bf16 v[104:107], v[136:139], v[196:199], v[104:107]
	v_mfma_f32_16x16x32_bf16 v[92:95], v[128:131], v[204:207], v[92:95]
	v_mfma_f32_16x16x32_bf16 v[88:91], v[136:139], v[204:207], v[88:91]
	v_mfma_f32_16x16x32_bf16 v[76:79], v[128:131], v[212:215], v[76:79]
	v_mfma_f32_16x16x32_bf16 v[72:75], v[136:139], v[212:215], v[72:75]
	v_mfma_f32_16x16x32_bf16 v[124:127], v[132:135], v[192:195], v[124:127]
	v_mfma_f32_16x16x32_bf16 v[120:123], v[140:143], v[192:195], v[120:123]
	v_mfma_f32_16x16x32_bf16 v[108:111], v[132:135], v[200:203], v[108:111]
	v_mfma_f32_16x16x32_bf16 v[104:107], v[140:143], v[200:203], v[104:107]
	v_mfma_f32_16x16x32_bf16 v[92:95], v[132:135], v[208:211], v[92:95]
	v_mfma_f32_16x16x32_bf16 v[88:91], v[140:143], v[208:211], v[88:91]
	v_mfma_f32_16x16x32_bf16 v[76:79], v[132:135], v[216:219], v[76:79]
	v_mfma_f32_16x16x32_bf16 v[72:75], v[140:143], v[216:219], v[72:75]
	v_mfma_f32_16x16x32_bf16 v[116:119], v[154:157], v[182:185], v[116:119]
	v_mfma_f32_16x16x32_bf16 v[112:115], v[174:177], v[182:185], v[112:115]
	v_mfma_f32_16x16x32_bf16 v[100:103], v[154:157], v[196:199], v[100:103]
	v_mfma_f32_16x16x32_bf16 v[96:99], v[174:177], v[196:199], v[96:99]
	v_mfma_f32_16x16x32_bf16 v[84:87], v[154:157], v[204:207], v[84:87]
	v_mfma_f32_16x16x32_bf16 v[80:83], v[174:177], v[204:207], v[80:83]
	v_mfma_f32_16x16x32_bf16 v[68:71], v[154:157], v[212:215], v[68:71]
	v_mfma_f32_16x16x32_bf16 v[64:67], v[174:177], v[212:215], v[64:67]
	v_mfma_f32_16x16x32_bf16 v[116:119], v[166:169], v[192:195], v[116:119]
	v_mfma_f32_16x16x32_bf16 v[112:115], v[178:181], v[192:195], v[112:115]
	v_mfma_f32_16x16x32_bf16 v[100:103], v[166:169], v[200:203], v[100:103]
	v_mfma_f32_16x16x32_bf16 v[96:99], v[178:181], v[200:203], v[96:99]
	v_mfma_f32_16x16x32_bf16 v[84:87], v[166:169], v[208:211], v[84:87]
	v_mfma_f32_16x16x32_bf16 v[80:83], v[178:181], v[208:211], v[80:83]
	v_mfma_f32_16x16x32_bf16 v[68:71], v[166:169], v[216:219], v[68:71]
	v_mfma_f32_16x16x32_bf16 v[64:67], v[178:181], v[216:219], v[64:67]
	s_barrier
	s_add_i32 s64, s64, s46
	v_lshl_add_u64 v[158:159], s[36:37], 0, v[172:173]
	s_mov_b32 m0, s64
	ds_read_b128 v[182:185], v165 offset:16384
	ds_read_b128 v[192:195], v165 offset:17408
	ds_read_b128 v[196:199], v165 offset:18432
	ds_read_b128 v[200:203], v165 offset:19456
	ds_read_b128 v[204:207], v165 offset:20480
	ds_read_b128 v[208:211], v165 offset:21504
	ds_read_b128 v[212:215], v165 offset:22528
	ds_read_b128 v[216:219], v165 offset:23552
	global_load_lds_dwordx4 v[158:159], off
	s_add_i32 m0, s64, 0x2000
	s_add_u32 s64, s36, 0x10000
	v_lshl_add_u64 v[170:171], s[36:37], 0, v[148:149]
	s_addc_u32 s65, s37, 0
	s_add_i32 s66, s66, s46
	global_load_lds_dwordx4 v[170:171], off
	v_lshl_add_u64 v[186:187], s[64:65], 0, v[172:173]
	s_mov_b32 m0, s66
	v_lshl_add_u64 v[220:221], s[38:39], 0, v[146:147]
	global_load_lds_dwordx4 v[186:187], off
	v_lshl_add_u64 v[186:187], s[64:65], 0, v[148:149]
	s_add_i32 m0, s66, 0x2000
	s_nop 0
	global_load_lds_dwordx4 v[186:187], off
	v_lshl_add_u64 v[186:187], s[38:39], 0, v[144:145]
	s_mov_b32 m0, s31
	s_nop 0
	global_load_lds_dwordx4 v[186:187], off
	s_mov_b32 m0, s47
	s_nop 0
	global_load_lds_dwordx4 v[220:221], off
	s_waitcnt vmcnt(8)
	s_waitcnt lgkmcnt(0)
	s_barrier
; #define PG8_STAGE(bufoff, gbase, voff) do { _Pragma("unroll") for (int _i = 0; _i < 2; ++_i) \
;         __builtin_amdgcn_global_load_lds((const unsigned*)((const char*)(gbase) + (voff)[_i]), (PG8_LAS unsigned*)(lds + (bufoff) + ldsw + _i * 8192), 16, 0, 0); } while (0)
; #define PG8_LDA(dst, b, h) do { _Pragma("unroll") for (int m = 0; m < 4; ++m) _Pragma("unroll") for (int k = 0; k < 2; ++k) dst[m][k] = *(const PG8_LAS bf16x8*)(lds + PG8_SA(b, h) + aoff + m * 2048 + k * 1024); } while (0)
; #define PG8_LDB(dst, b, h) do { _Pragma("unroll") for (int n = 0; n < 2; ++n) _Pragma("unroll") for (int k = 0; k < 2; ++k) dst[n][k] = *(const PG8_LAS bf16x8*)(lds + PG8_SB(b, h) + boff + n * 2048 + k * 1024); } while (0)
; #define PG8_MMA(ai, bj, At, Bt) do { __builtin_amdgcn_s_setprio(1); _Pragma("unroll") for (int m = 0; m < 4; ++m) _Pragma("unroll") for (int n = 0; n < 2; ++n) _Pragma("unroll") for (int k = 0; k < 2; ++k) \
;         acc[ai][bj][m][n] = __builtin_amdgcn_mfma_f32_16x16x32_bf16(Bt[n][k], At[m][k], acc[ai][bj][m][n], 0, 0, 0); __builtin_amdgcn_s_setprio(0); } while (0)
; #define PG8_WAIT_V(n) asm volatile("s_waitcnt vmcnt(" #n ")" ::: "memory")
; #define PG8_WAIT_L(n) asm volatile("s_waitcnt lgkmcnt(" #n ")" ::: "memory")
; #define PG8_BAR __builtin_amdgcn_s_barrier()
; #define PG8_SCHED __builtin_amdgcn_sched_barrier(0)
; template <class Epi, class Sched, bool ALIGN_EPI = false, bool SP2 = false>
; __device__ __forceinline__ void gemm_phase(PG8_LAS unsigned char* lds, const Gemm g, const Sched& S, const Epi& E) {
;     ...
;             PG8_WAIT_V(8); PG8_WAIT_L(0); PG8_BAR; PG8_MMA(1, 0, At, B0); PG8_MMA(1, 1, At, B1); PG8_BAR; PG8_SCHED;
;             PG8_LDB(B0, 1, 0); PG8_LDB(B1, 1, 1); PG8_SCHED; PG8_LDA(At, 1, 0); PG8_STAGE(PG8_SA(0, 1), a2 + hstepA, voffA);
;             PG8_WAIT_V(8); PG8_WAIT_L(0); PG8_BAR; PG8_MMA(0, 0, At, B0); PG8_MMA(0, 1, At, B1); PG8_BAR; PG8_SCHED;
	s_waitcnt lgkmcnt(0)
	v_mfma_f32_16x16x32_bf16 v[60:63], v[128:131], v[182:185], v[60:63]
	v_mfma_f32_16x16x32_bf16 v[56:59], v[136:139], v[182:185], v[56:59]
	v_mfma_f32_16x16x32_bf16 v[44:47], v[128:131], v[196:199], v[44:47]
	v_mfma_f32_16x16x32_bf16 v[40:43], v[136:139], v[196:199], v[40:43]
	v_mfma_f32_16x16x32_bf16 v[28:31], v[128:131], v[204:207], v[28:31]
	v_mfma_f32_16x16x32_bf16 v[24:27], v[136:139], v[204:207], v[24:27]
	v_mfma_f32_16x16x32_bf16 v[12:15], v[128:131], v[212:215], v[12:15]
	v_mfma_f32_16x16x32_bf16 v[8:11], v[136:139], v[212:215], v[8:11]
	v_mfma_f32_16x16x32_bf16 v[60:63], v[132:135], v[192:195], v[60:63]
	v_mfma_f32_16x16x32_bf16 v[56:59], v[140:143], v[192:195], v[56:59]
	v_mfma_f32_16x16x32_bf16 v[44:47], v[132:135], v[200:203], v[44:47]
	v_mfma_f32_16x16x32_bf16 v[40:43], v[140:143], v[200:203], v[40:43]
	v_mfma_f32_16x16x32_bf16 v[28:31], v[132:135], v[208:211], v[28:31]
	v_mfma_f32_16x16x32_bf16 v[24:27], v[140:143], v[208:211], v[24:27]
	v_mfma_f32_16x16x32_bf16 v[12:15], v[132:135], v[216:219], v[12:15]
	v_mfma_f32_16x16x32_bf16 v[8:11], v[140:143], v[216:219], v[8:11]
	v_mfma_f32_16x16x32_bf16 v[52:55], v[154:157], v[182:185], v[52:55]
	v_mfma_f32_16x16x32_bf16 v[48:51], v[174:177], v[182:185], v[48:51]
	v_mfma_f32_16x16x32_bf16 v[36:39], v[154:157], v[196:199], v[36:39]
	v_mfma_f32_16x16x32_bf16 v[32:35], v[174:177], v[196:199], v[32:35]
	v_mfma_f32_16x16x32_bf16 v[20:23], v[154:157], v[204:207], v[20:23]
	v_mfma_f32_16x16x32_bf16 v[16:19], v[174:177], v[204:207], v[16:19]
	v_mfma_f32_16x16x32_bf16 v[4:7], v[154:157], v[212:215], v[4:7]
	v_mfma_f32_16x16x32_bf16 v[0:3], v[174:177], v[212:215], v[0:3]
	v_mfma_f32_16x16x32_bf16 v[52:55], v[166:169], v[192:195], v[52:55]
	v_mfma_f32_16x16x32_bf16 v[48:51], v[178:181], v[192:195], v[48:51]
	v_mfma_f32_16x16x32_bf16 v[36:39], v[166:169], v[200:203], v[36:39]
	v_mfma_f32_16x16x32_bf16 v[32:35], v[178:181], v[200:203], v[32:35]
	v_mfma_f32_16x16x32_bf16 v[20:23], v[166:169], v[208:211], v[20:23]
	v_mfma_f32_16x16x32_bf16 v[16:19], v[178:181], v[208:211], v[16:19]
	v_mfma_f32_16x16x32_bf16 v[4:7], v[166:169], v[216:219], v[4:7]
	v_mfma_f32_16x16x32_bf16 v[0:3], v[178:181], v[216:219], v[0:3]
	s_barrier
	s_add_i32 s64, 0, 0x18000
	s_add_i32 s65, 0, 0x1c000
	v_add_u32_e32 v140, s64, v163
	v_add_u32_e32 v160, s65, v163
	ds_read_b128 v[128:131], v140
	ds_read_b128 v[132:135], v140 offset:1024
	ds_read_b128 v[136:139], v140 offset:2048
	ds_read_b128 v[140:143], v140 offset:3072
	ds_read_b128 v[154:157], v160
	ds_read_b128 v[166:169], v160 offset:1024
	ds_read_b128 v[174:177], v160 offset:2048
	ds_read_b128 v[178:181], v160 offset:3072
	s_add_u32 s38, s38, 0x40000
	s_addc_u32 s39, s39, 0
	s_mov_b32 m0, s49
	v_lshl_add_u64 v[222:223], s[38:39], 0, v[144:145]
	ds_read_b128 v[182:185], v165 offset:32768
	ds_read_b128 v[192:195], v165 offset:33792
	ds_read_b128 v[196:199], v165 offset:34816
	ds_read_b128 v[200:203], v165 offset:35840
	ds_read_b128 v[204:207], v165 offset:36864
	ds_read_b128 v[208:211], v165 offset:37888
	ds_read_b128 v[212:215], v165 offset:38912
	ds_read_b128 v[216:219], v165 offset:39936
	global_load_lds_dwordx4 v[222:223], off
	v_lshl_add_u64 v[222:223], s[38:39], 0, v[146:147]
	s_mov_b32 m0, s50
	s_nop 0
	global_load_lds_dwordx4 v[222:223], off
	s_waitcnt vmcnt(8)
	s_waitcnt lgkmcnt(0)
	s_barrier
	s_waitcnt lgkmcnt(0)
	v_mfma_f32_16x16x32_bf16 v[124:127], v[128:131], v[182:185], v[124:127]
	v_mfma_f32_16x16x32_bf16 v[120:123], v[136:139], v[182:185], v[120:123]
	v_mfma_f32_16x16x32_bf16 v[108:111], v[128:131], v[196:199], v[108:111]
	v_mfma_f32_16x16x32_bf16 v[104:107], v[136:139], v[196:199], v[104:107]
	v_mfma_f32_16x16x32_bf16 v[92:95], v[128:131], v[204:207], v[92:95]
	v_mfma_f32_16x16x32_bf16 v[88:91], v[136:139], v[204:207], v[88:91]
	v_mfma_f32_16x16x32_bf16 v[76:79], v[128:131], v[212:215], v[76:79]
	v_mfma_f32_16x16x32_bf16 v[72:75], v[136:139], v[212:215], v[72:75]
	v_mfma_f32_16x16x32_bf16 v[124:127], v[132:135], v[192:195], v[124:127]
	v_mfma_f32_16x16x32_bf16 v[120:123], v[140:143], v[192:195], v[120:123]
	v_mfma_f32_16x16x32_bf16 v[108:111], v[132:135], v[200:203], v[108:111]
	v_mfma_f32_16x16x32_bf16 v[104:107], v[140:143], v[200:203], v[104:107]
	v_mfma_f32_16x16x32_bf16 v[92:95], v[132:135], v[208:211], v[92:95]
	v_mfma_f32_16x16x32_bf16 v[88:91], v[140:143], v[208:211], v[88:91]
	v_mfma_f32_16x16x32_bf16 v[76:79], v[132:135], v[216:219], v[76:79]
	v_mfma_f32_16x16x32_bf16 v[72:75], v[140:143], v[216:219], v[72:75]
	v_mfma_f32_16x16x32_bf16 v[116:119], v[154:157], v[182:185], v[116:119]
	v_mfma_f32_16x16x32_bf16 v[112:115], v[174:177], v[182:185], v[112:115]
	v_mfma_f32_16x16x32_bf16 v[100:103], v[154:157], v[196:199], v[100:103]
	v_mfma_f32_16x16x32_bf16 v[96:99], v[174:177], v[196:199], v[96:99]
	v_mfma_f32_16x16x32_bf16 v[84:87], v[154:157], v[204:207], v[84:87]
	v_mfma_f32_16x16x32_bf16 v[80:83], v[174:177], v[204:207], v[80:83]
	v_mfma_f32_16x16x32_bf16 v[68:71], v[154:157], v[212:215], v[68:71]
	v_mfma_f32_16x16x32_bf16 v[64:67], v[174:177], v[212:215], v[64:67]
	v_mfma_f32_16x16x32_bf16 v[116:119], v[166:169], v[192:195], v[116:119]
	v_mfma_f32_16x16x32_bf16 v[112:115], v[178:181], v[192:195], v[112:115]
	v_mfma_f32_16x16x32_bf16 v[100:103], v[166:169], v[200:203], v[100:103]
	v_mfma_f32_16x16x32_bf16 v[96:99], v[178:181], v[200:203], v[96:99]
	v_mfma_f32_16x16x32_bf16 v[84:87], v[166:169], v[208:211], v[84:87]
	v_mfma_f32_16x16x32_bf16 v[80:83], v[178:181], v[208:211], v[80:83]
	v_mfma_f32_16x16x32_bf16 v[68:71], v[166:169], v[216:219], v[68:71]
	v_mfma_f32_16x16x32_bf16 v[64:67], v[178:181], v[216:219], v[64:67]
	s_barrier
; #define PG8_STAGE(bufoff, gbase, voff) do { _Pragma("unroll") for (int _i = 0; _i < 2; ++_i) \
;         __builtin_amdgcn_global_load_lds((const unsigned*)((const char*)(gbase) + (voff)[_i]), (PG8_LAS unsigned*)(lds + (bufoff) + ldsw + _i * 8192), 16, 0, 0); } while (0)
; #define PG8_LDA(dst, b, h) do { _Pragma("unroll") for (int m = 0; m < 4; ++m) _Pragma("unroll") for (int k = 0; k < 2; ++k) dst[m][k] = *(const PG8_LAS bf16x8*)(lds + PG8_SA(b, h) + aoff + m * 2048 + k * 1024); } while (0)
; #define PG8_MMA(ai, bj, At, Bt) do { __builtin_amdgcn_s_setprio(1); _Pragma("unroll") for (int m = 0; m < 4; ++m) _Pragma("unroll") for (int n = 0; n < 2; ++n) _Pragma("unroll") for (int k = 0; k < 2; ++k) \
;         acc[ai][bj][m][n] = __builtin_amdgcn_mfma_f32_16x16x32_bf16(Bt[n][k], At[m][k], acc[ai][bj][m][n], 0, 0, 0); __builtin_amdgcn_s_setprio(0); } while (0)
; #define PG8_WAIT_V(n) asm volatile("s_waitcnt vmcnt(" #n ")" ::: "memory")
; #define PG8_WAIT_L(n) asm volatile("s_waitcnt lgkmcnt(" #n ")" ::: "memory")
; #define PG8_BAR __builtin_amdgcn_s_barrier()
; #define PG8_SCHED __builtin_amdgcn_sched_barrier(0)
; template <class Epi, class Sched, bool ALIGN_EPI = false, bool SP2 = false>
; __device__ __forceinline__ void gemm_phase(PG8_LAS unsigned char* lds, const Gemm g, const Sched& S, const Epi& E) {
;     ...
;             PG8_LDA(At, 1, 1); PG8_STAGE(PG8_SB(1, 0), b3, voffB); PG8_STAGE(PG8_SB(1, 1), b3 + hstepB, voffB); PG8_STAGE(PG8_SA(1, 0), a3, voffA);
;             PG8_WAIT_V(8); PG8_WAIT_L(0); PG8_BAR; PG8_MMA(1, 0, At, B0); PG8_MMA(1, 1, At, B1); PG8_BAR; PG8_SCHED;
;     ...
;         if constexpr (ALIGN_EPI) { if (wr == 0) PG8_BAR; }
	s_add_i32 s38, s64, s46
	v_lshl_add_u64 v[158:159], v[158:159], 0, s[80:81]
	s_mov_b32 m0, s38
	ds_read_b128 v[182:185], v165 offset:49152
	ds_read_b128 v[192:195], v165 offset:50176
	ds_read_b128 v[196:199], v165 offset:51200
	ds_read_b128 v[200:203], v165 offset:52224
	ds_read_b128 v[204:207], v165 offset:53248
	ds_read_b128 v[208:211], v165 offset:54272
	ds_read_b128 v[212:215], v165 offset:55296
	ds_read_b128 v[216:219], v165 offset:56320
	global_load_lds_dwordx4 v[158:159], off
	s_add_i32 m0, s38, 0x2000
	s_add_u32 s36, s36, 0x10080
	v_lshl_add_u64 v[158:159], v[170:171], 0, s[80:81]
	s_addc_u32 s37, s37, 0
	s_add_i32 s38, s65, s46
	global_load_lds_dwordx4 v[158:159], off
	v_lshl_add_u64 v[158:159], s[36:37], 0, v[172:173]
	s_mov_b32 m0, s38
	s_nop 0
	global_load_lds_dwordx4 v[158:159], off
	v_lshl_add_u64 v[158:159], s[36:37], 0, v[148:149]
	s_add_i32 m0, s38, 0x2000
	s_nop 0
	global_load_lds_dwordx4 v[158:159], off
	v_lshl_add_u64 v[158:159], v[186:187], 0, s[80:81]
	s_mov_b32 m0, s57
	s_nop 0
	global_load_lds_dwordx4 v[158:159], off
	v_lshl_add_u64 v[158:159], v[220:221], 0, s[80:81]
	s_mov_b32 m0, s58
	s_nop 0
	global_load_lds_dwordx4 v[158:159], off
	s_waitcnt vmcnt(8)
	s_waitcnt lgkmcnt(0)
	s_barrier
	s_waitcnt lgkmcnt(0)
	v_mfma_f32_16x16x32_bf16 v[60:63], v[128:131], v[182:185], v[60:63]
	v_mfma_f32_16x16x32_bf16 v[56:59], v[136:139], v[182:185], v[56:59]
	v_mfma_f32_16x16x32_bf16 v[44:47], v[128:131], v[196:199], v[44:47]
	v_mfma_f32_16x16x32_bf16 v[40:43], v[136:139], v[196:199], v[40:43]
	v_mfma_f32_16x16x32_bf16 v[28:31], v[128:131], v[204:207], v[28:31]
	v_mfma_f32_16x16x32_bf16 v[24:27], v[136:139], v[204:207], v[24:27]
	v_mfma_f32_16x16x32_bf16 v[12:15], v[128:131], v[212:215], v[12:15]
	v_mfma_f32_16x16x32_bf16 v[8:11], v[136:139], v[212:215], v[8:11]
	v_mfma_f32_16x16x32_bf16 v[60:63], v[132:135], v[192:195], v[60:63]
	v_mfma_f32_16x16x32_bf16 v[56:59], v[140:143], v[192:195], v[56:59]
	v_mfma_f32_16x16x32_bf16 v[44:47], v[132:135], v[200:203], v[44:47]
	v_mfma_f32_16x16x32_bf16 v[40:43], v[140:143], v[200:203], v[40:43]
	v_mfma_f32_16x16x32_bf16 v[28:31], v[132:135], v[208:211], v[28:31]
	v_mfma_f32_16x16x32_bf16 v[24:27], v[140:143], v[208:211], v[24:27]
	v_mfma_f32_16x16x32_bf16 v[12:15], v[132:135], v[216:219], v[12:15]
	v_mfma_f32_16x16x32_bf16 v[8:11], v[140:143], v[216:219], v[8:11]
	v_mfma_f32_16x16x32_bf16 v[52:55], v[154:157], v[182:185], v[52:55]
	v_mfma_f32_16x16x32_bf16 v[48:51], v[174:177], v[182:185], v[48:51]
	v_mfma_f32_16x16x32_bf16 v[36:39], v[154:157], v[196:199], v[36:39]
	v_mfma_f32_16x16x32_bf16 v[32:35], v[174:177], v[196:199], v[32:35]
	v_mfma_f32_16x16x32_bf16 v[20:23], v[154:157], v[204:207], v[20:23]
	v_mfma_f32_16x16x32_bf16 v[16:19], v[174:177], v[204:207], v[16:19]
	v_mfma_f32_16x16x32_bf16 v[4:7], v[154:157], v[212:215], v[4:7]
	v_mfma_f32_16x16x32_bf16 v[0:3], v[174:177], v[212:215], v[0:3]
	v_mfma_f32_16x16x32_bf16 v[52:55], v[166:169], v[192:195], v[52:55]
	v_mfma_f32_16x16x32_bf16 v[48:51], v[178:181], v[192:195], v[48:51]
	v_mfma_f32_16x16x32_bf16 v[36:39], v[166:169], v[200:203], v[36:39]
	v_mfma_f32_16x16x32_bf16 v[32:35], v[178:181], v[200:203], v[32:35]
	v_mfma_f32_16x16x32_bf16 v[20:23], v[166:169], v[208:211], v[20:23]
	v_mfma_f32_16x16x32_bf16 v[16:19], v[178:181], v[208:211], v[16:19]
	v_mfma_f32_16x16x32_bf16 v[4:7], v[166:169], v[216:219], v[4:7]
	v_mfma_f32_16x16x32_bf16 v[0:3], v[178:181], v[216:219], v[0:3]
	s_barrier
	s_add_i32 s63, s63, 2
	s_add_u32 s34, s34, 0x100
	s_addc_u32 s35, s35, 0
	s_add_u32 s61, s61, 0x100
	s_addc_u32 s62, s62, 0
	s_cmp_gt_u32 s63, 13
	s_cbranch_scc0 .LBB0_1786
	s_and_b64 vcc, exec, s[20:21]
	s_cbranch_vccz .LBB0_1789
	s_barrier

;     __device__ __forceinline__ bool next(int i, Unit& u) const { const int L = i * G + c; if (L >= nsub) return false; u.pk = L >> 4; u.pm = MLAT / BM + (L & 3); u.pn = (L >> 2) & 3; return true; }
; #define PG8_STAGE(bufoff, gbase, voff) do { _Pragma("unroll") for (int _i = 0; _i < 2; ++_i) \
;         __builtin_amdgcn_global_load_lds((const unsigned*)((const char*)(gbase) + (voff)[_i]), (PG8_LAS unsigned*)(lds + (bufoff) + ldsw + _i * 8192), 16, 0, 0); } while (0)
; #define PG8_LDA(dst, b, h) do { _Pragma("unroll") for (int m = 0; m < 4; ++m) _Pragma("unroll") for (int k = 0; k < 2; ++k) dst[m][k] = *(const PG8_LAS bf16x8*)(lds + PG8_SA(b, h) + aoff + m * 2048 + k * 1024); } while (0)
; #define PG8_LDB(dst, b, h) do { _Pragma("unroll") for (int n = 0; n < 2; ++n) _Pragma("unroll") for (int k = 0; k < 2; ++k) dst[n][k] = *(const PG8_LAS bf16x8*)(lds + PG8_SB(b, h) + boff + n * 2048 + k * 1024); } while (0)
; #define PG8_WAIT_V(n) asm volatile("s_waitcnt vmcnt(" #n ")" ::: "memory")
; #define PG8_WAIT_L(n) asm volatile("s_waitcnt lgkmcnt(" #n ")" ::: "memory")
; template <class Epi, class Sched, bool ALIGN_EPI = false, bool SP2 = false>
; __device__ __forceinline__ void gemm_phase(PG8_LAS unsigned char* lds, const Gemm g, const Sched& S, const Epi& E) {
;     ...
;         const bool has_next = S.next(ui + 1, nxt);
;         const char* nA = has_next ? g.a_of(nxt) : cA; const char* nB = has_next ? g.b_of(nxt) : cB;
;         for (int t = 0; t < nt; t += 2) {
;             const bool last = (t == nt - 2);
;             const char* a1 = cA + (size_t)(t + 1) * kstep;
;             const char* a2 = last ? nA : cA + (size_t)(t + 2) * kstep; const char* b2 = last ? nB : cB + (size_t)(t + 2) * kstep;
;             const char* a3 = a2 + kstep; const char* b3 = b2 + kstep;
;             if (last && has_next) S.a_ready(nxt);
;             if constexpr (SP2) {
;             PG8_LDB(B0, 0, 0); PG8_LDB(B1, 0, 1); PG8_SCHED; PG8_LDA(At, 0, 0); PG8_STAGE(PG8_SA(1, 1), a1 + hstepA, voffA);
;             PG8_WAIT_V(8); PG8_WAIT_L(0); PG8_BAR; PG8_MMA(0, 0, At, B0); PG8_MMA(0, 1, At, B1); PG8_BAR; PG8_SCHED;
;             PG8_LDA(At, 0, 1); PG8_STAGE(PG8_SB(0, 0), b2, voffB); PG8_STAGE(PG8_SB(0, 1), b2 + hstepB, voffB); PG8_STAGE(PG8_SA(0, 0), a2, voffA);
;             PG8_WAIT_V(8); PG8_WAIT_L(0); PG8_BAR; PG8_MMA(1, 0, At, B0); PG8_MMA(1, 1, At, B1); PG8_BAR; PG8_SCHED;
.LBB0_1906:
	s_add_u32 s40, s38, 0xfff00080
	s_addc_u32 s41, s39, -1
	s_add_i32 s71, 0, 0x10000
	s_cmp_eq_u32 s70, 60
	s_cselect_b32 s43, s27, s41
	s_cselect_b32 s42, s35, s40
	s_cselect_b32 s41, s25, s68
	s_cselect_b32 s40, s37, s67
	s_add_i32 s74, 0, 0x14000
	v_add_u32_e32 v92, s71, v181
	v_add_u32_e32 v164, s74, v181
	ds_read_b128 v[72:75], v92
	ds_read_b128 v[80:83], v92 offset:1024
	ds_read_b128 v[88:91], v92 offset:2048
	ds_read_b128 v[92:95], v92 offset:3072
	ds_read_b128 v[152:155], v164
	ds_read_b128 v[156:159], v164 offset:1024
	ds_read_b128 v[160:163], v164 offset:2048
	ds_read_b128 v[164:167], v164 offset:3072
	v_lshl_add_u64 v[178:179], s[38:39], 0, v[148:149]
	s_add_i32 m0, s51, 0xc000
	ds_read_b128 v[168:171], v186
	ds_read_b128 v[174:177], v186 offset:1024
	ds_read_b128 v[192:195], v186 offset:2048
	ds_read_b128 v[196:199], v186 offset:3072
	ds_read_b128 v[200:203], v186 offset:4096
	ds_read_b128 v[204:207], v186 offset:5120
	ds_read_b128 v[208:211], v186 offset:6144
	ds_read_b128 v[212:215], v186 offset:7168
	global_load_lds_dwordx4 v[178:179], off
	v_lshl_add_u64 v[178:179], s[38:39], 0, v[150:151]
	s_add_i32 m0, s51, 0xe000
	s_nop 0
	global_load_lds_dwordx4 v[178:179], off
	s_waitcnt vmcnt(8)
	s_waitcnt lgkmcnt(0)
	s_barrier
	s_waitcnt lgkmcnt(0)
	v_mfma_f32_16x16x32_bf16 v[140:143], v[72:75], v[168:171], v[140:143]
	v_mfma_f32_16x16x32_bf16 v[136:139], v[88:91], v[168:171], v[136:139]
	v_mfma_f32_16x16x32_bf16 v[124:127], v[72:75], v[192:195], v[124:127]
	v_mfma_f32_16x16x32_bf16 v[120:123], v[88:91], v[192:195], v[120:123]
	v_mfma_f32_16x16x32_bf16 v[108:111], v[72:75], v[200:203], v[108:111]
	v_mfma_f32_16x16x32_bf16 v[104:107], v[88:91], v[200:203], v[104:107]
	v_mfma_f32_16x16x32_bf16 v[84:87], v[72:75], v[208:211], v[84:87]
	v_mfma_f32_16x16x32_bf16 v[76:79], v[88:91], v[208:211], v[76:79]
	v_mfma_f32_16x16x32_bf16 v[140:143], v[80:83], v[174:177], v[140:143]
	v_mfma_f32_16x16x32_bf16 v[136:139], v[92:95], v[174:177], v[136:139]
	v_mfma_f32_16x16x32_bf16 v[124:127], v[80:83], v[196:199], v[124:127]
	v_mfma_f32_16x16x32_bf16 v[120:123], v[92:95], v[196:199], v[120:123]
	v_mfma_f32_16x16x32_bf16 v[108:111], v[80:83], v[204:207], v[108:111]
	v_mfma_f32_16x16x32_bf16 v[104:107], v[92:95], v[204:207], v[104:107]
	v_mfma_f32_16x16x32_bf16 v[84:87], v[80:83], v[212:215], v[84:87]
	v_mfma_f32_16x16x32_bf16 v[76:79], v[92:95], v[212:215], v[76:79]
	v_mfma_f32_16x16x32_bf16 v[132:135], v[152:155], v[168:171], v[132:135]
	v_mfma_f32_16x16x32_bf16 v[128:131], v[160:163], v[168:171], v[128:131]
	v_mfma_f32_16x16x32_bf16 v[116:119], v[152:155], v[192:195], v[116:119]
	v_mfma_f32_16x16x32_bf16 v[112:115], v[160:163], v[192:195], v[112:115]
	v_mfma_f32_16x16x32_bf16 v[100:103], v[152:155], v[200:203], v[100:103]
	v_mfma_f32_16x16x32_bf16 v[96:99], v[160:163], v[200:203], v[96:99]
	v_mfma_f32_16x16x32_bf16 v[68:71], v[152:155], v[208:211], v[68:71]
	v_mfma_f32_16x16x32_bf16 v[64:67], v[160:163], v[208:211], v[64:67]
	v_mfma_f32_16x16x32_bf16 v[132:135], v[156:159], v[174:177], v[132:135]
	v_mfma_f32_16x16x32_bf16 v[128:131], v[164:167], v[174:177], v[128:131]
	v_mfma_f32_16x16x32_bf16 v[116:119], v[156:159], v[196:199], v[116:119]
	v_mfma_f32_16x16x32_bf16 v[112:115], v[164:167], v[196:199], v[112:115]
	v_mfma_f32_16x16x32_bf16 v[100:103], v[156:159], v[204:207], v[100:103]
	v_mfma_f32_16x16x32_bf16 v[96:99], v[164:167], v[204:207], v[96:99]
	v_mfma_f32_16x16x32_bf16 v[68:71], v[156:159], v[212:215], v[68:71]
	v_mfma_f32_16x16x32_bf16 v[64:67], v[164:167], v[212:215], v[64:67]
	s_barrier
	s_add_i32 s71, s71, s50
	v_lshl_add_u64 v[178:179], s[40:41], 0, v[172:173]
	s_mov_b32 m0, s71
	ds_read_b128 v[168:171], v186 offset:16384
	ds_read_b128 v[174:177], v186 offset:17408
	ds_read_b128 v[192:195], v186 offset:18432
	ds_read_b128 v[196:199], v186 offset:19456
	ds_read_b128 v[200:203], v186 offset:20480
	ds_read_b128 v[204:207], v186 offset:21504
	ds_read_b128 v[208:211], v186 offset:22528
	ds_read_b128 v[212:215], v186 offset:23552
	global_load_lds_dwordx4 v[178:179], off
	s_add_i32 m0, s71, 0x2000
	s_add_u32 s72, s40, 0x100000
	v_lshl_add_u64 v[216:217], s[40:41], 0, v[144:145]
	s_addc_u32 s73, s41, 0
	s_add_i32 s71, s74, s50
	global_load_lds_dwordx4 v[216:217], off
	v_lshl_add_u64 v[218:219], s[72:73], 0, v[172:173]
	s_mov_b32 m0, s71
	v_lshl_add_u64 v[220:221], s[42:43], 0, v[144:145]
	global_load_lds_dwordx4 v[218:219], off
	v_lshl_add_u64 v[218:219], s[72:73], 0, v[144:145]
	s_add_i32 m0, s71, 0x2000
	s_nop 0
	global_load_lds_dwordx4 v[218:219], off
	v_lshl_add_u64 v[218:219], s[42:43], 0, v[172:173]
	s_mov_b32 m0, s51
	s_nop 0
	global_load_lds_dwordx4 v[218:219], off
	s_mov_b32 m0, s52
	s_nop 0
	global_load_lds_dwordx4 v[220:221], off
	s_waitcnt vmcnt(8)
	s_waitcnt lgkmcnt(0)
	s_barrier
; #define PG8_STAGE(bufoff, gbase, voff) do { _Pragma("unroll") for (int _i = 0; _i < 2; ++_i) \
;         __builtin_amdgcn_global_load_lds((const unsigned*)((const char*)(gbase) + (voff)[_i]), (PG8_LAS unsigned*)(lds + (bufoff) + ldsw + _i * 8192), 16, 0, 0); } while (0)
; #define PG8_LDA(dst, b, h) do { _Pragma("unroll") for (int m = 0; m < 4; ++m) _Pragma("unroll") for (int k = 0; k < 2; ++k) dst[m][k] = *(const PG8_LAS bf16x8*)(lds + PG8_SA(b, h) + aoff + m * 2048 + k * 1024); } while (0)
; #define PG8_LDB(dst, b, h) do { _Pragma("unroll") for (int n = 0; n < 2; ++n) _Pragma("unroll") for (int k = 0; k < 2; ++k) dst[n][k] = *(const PG8_LAS bf16x8*)(lds + PG8_SB(b, h) + boff + n * 2048 + k * 1024); } while (0)
; #define PG8_MMA(ai, bj, At, Bt) do { __builtin_amdgcn_s_setprio(1); _Pragma("unroll") for (int m = 0; m < 4; ++m) _Pragma("unroll") for (int n = 0; n < 2; ++n) _Pragma("unroll") for (int k = 0; k < 2; ++k) \
;         acc[ai][bj][m][n] = __builtin_amdgcn_mfma_f32_16x16x32_bf16(Bt[n][k], At[m][k], acc[ai][bj][m][n], 0, 0, 0); __builtin_amdgcn_s_setprio(0); } while (0)
; #define PG8_WAIT_V(n) asm volatile("s_waitcnt vmcnt(" #n ")" ::: "memory")
; #define PG8_WAIT_L(n) asm volatile("s_waitcnt lgkmcnt(" #n ")" ::: "memory")
; #define PG8_BAR __builtin_amdgcn_s_barrier()
; #define PG8_SCHED __builtin_amdgcn_sched_barrier(0)
; template <class Epi, class Sched, bool ALIGN_EPI = false, bool SP2 = false>
; __device__ __forceinline__ void gemm_phase(PG8_LAS unsigned char* lds, const Gemm g, const Sched& S, const Epi& E) {
;     ...
;             PG8_WAIT_V(8); PG8_WAIT_L(0); PG8_BAR; PG8_MMA(1, 0, At, B0); PG8_MMA(1, 1, At, B1); PG8_BAR; PG8_SCHED;
;             PG8_LDB(B0, 1, 0); PG8_LDB(B1, 1, 1); PG8_SCHED; PG8_LDA(At, 1, 0); PG8_STAGE(PG8_SA(0, 1), a2 + hstepA, voffA);
;             PG8_WAIT_V(8); PG8_WAIT_L(0); PG8_BAR; PG8_MMA(0, 0, At, B0); PG8_MMA(0, 1, At, B1); PG8_BAR; PG8_SCHED;
	s_waitcnt lgkmcnt(0)
	v_mfma_f32_16x16x32_bf16 v[60:63], v[72:75], v[168:171], v[60:63]
	v_mfma_f32_16x16x32_bf16 v[56:59], v[88:91], v[168:171], v[56:59]
	v_mfma_f32_16x16x32_bf16 v[44:47], v[72:75], v[192:195], v[44:47]
	v_mfma_f32_16x16x32_bf16 v[40:43], v[88:91], v[192:195], v[40:43]
	v_mfma_f32_16x16x32_bf16 v[28:31], v[72:75], v[200:203], v[28:31]
	v_mfma_f32_16x16x32_bf16 v[24:27], v[88:91], v[200:203], v[24:27]
	v_mfma_f32_16x16x32_bf16 v[12:15], v[72:75], v[208:211], v[12:15]
	v_mfma_f32_16x16x32_bf16 v[8:11], v[88:91], v[208:211], v[8:11]
	v_mfma_f32_16x16x32_bf16 v[60:63], v[80:83], v[174:177], v[60:63]
	v_mfma_f32_16x16x32_bf16 v[56:59], v[92:95], v[174:177], v[56:59]
	v_mfma_f32_16x16x32_bf16 v[44:47], v[80:83], v[196:199], v[44:47]
	v_mfma_f32_16x16x32_bf16 v[40:43], v[92:95], v[196:199], v[40:43]
	v_mfma_f32_16x16x32_bf16 v[28:31], v[80:83], v[204:207], v[28:31]
	v_mfma_f32_16x16x32_bf16 v[24:27], v[92:95], v[204:207], v[24:27]
	v_mfma_f32_16x16x32_bf16 v[12:15], v[80:83], v[212:215], v[12:15]
	v_mfma_f32_16x16x32_bf16 v[8:11], v[92:95], v[212:215], v[8:11]
	v_mfma_f32_16x16x32_bf16 v[52:55], v[152:155], v[168:171], v[52:55]
	v_mfma_f32_16x16x32_bf16 v[48:51], v[160:163], v[168:171], v[48:51]
	v_mfma_f32_16x16x32_bf16 v[36:39], v[152:155], v[192:195], v[36:39]
	v_mfma_f32_16x16x32_bf16 v[32:35], v[160:163], v[192:195], v[32:35]
	v_mfma_f32_16x16x32_bf16 v[20:23], v[152:155], v[200:203], v[20:23]
	v_mfma_f32_16x16x32_bf16 v[16:19], v[160:163], v[200:203], v[16:19]
	v_mfma_f32_16x16x32_bf16 v[4:7], v[152:155], v[208:211], v[4:7]
	v_mfma_f32_16x16x32_bf16 v[0:3], v[160:163], v[208:211], v[0:3]
	v_mfma_f32_16x16x32_bf16 v[52:55], v[156:159], v[174:177], v[52:55]
	v_mfma_f32_16x16x32_bf16 v[48:51], v[164:167], v[174:177], v[48:51]
	v_mfma_f32_16x16x32_bf16 v[36:39], v[156:159], v[196:199], v[36:39]
	v_mfma_f32_16x16x32_bf16 v[32:35], v[164:167], v[196:199], v[32:35]
	v_mfma_f32_16x16x32_bf16 v[20:23], v[156:159], v[204:207], v[20:23]
	v_mfma_f32_16x16x32_bf16 v[16:19], v[164:167], v[204:207], v[16:19]
	v_mfma_f32_16x16x32_bf16 v[4:7], v[156:159], v[212:215], v[4:7]
	v_mfma_f32_16x16x32_bf16 v[0:3], v[164:167], v[212:215], v[0:3]
	s_barrier
	s_add_i32 s71, 0, 0x18000
	s_add_i32 s72, 0, 0x1c000
	v_add_u32_e32 v92, s71, v181
	v_add_u32_e32 v164, s72, v181
	ds_read_b128 v[72:75], v92
	ds_read_b128 v[80:83], v92 offset:1024
	ds_read_b128 v[88:91], v92 offset:2048
	ds_read_b128 v[92:95], v92 offset:3072
	ds_read_b128 v[152:155], v164
	ds_read_b128 v[156:159], v164 offset:1024
	ds_read_b128 v[160:163], v164 offset:2048
	ds_read_b128 v[164:167], v164 offset:3072
	s_add_u32 s42, s42, 0x100000
	s_addc_u32 s43, s43, 0
	s_mov_b32 m0, s53
	v_lshl_add_u64 v[222:223], s[42:43], 0, v[172:173]
	ds_read_b128 v[168:171], v186 offset:32768
	ds_read_b128 v[174:177], v186 offset:33792
	ds_read_b128 v[192:195], v186 offset:34816
	ds_read_b128 v[196:199], v186 offset:35840
	ds_read_b128 v[200:203], v186 offset:36864
	ds_read_b128 v[204:207], v186 offset:37888
	ds_read_b128 v[208:211], v186 offset:38912
	ds_read_b128 v[212:215], v186 offset:39936
	global_load_lds_dwordx4 v[222:223], off
	v_lshl_add_u64 v[222:223], s[42:43], 0, v[144:145]
	s_mov_b32 m0, s57
	s_nop 0
	global_load_lds_dwordx4 v[222:223], off
	s_waitcnt vmcnt(8)
	s_waitcnt lgkmcnt(0)
	s_barrier
	s_waitcnt lgkmcnt(0)
	v_mfma_f32_16x16x32_bf16 v[140:143], v[72:75], v[168:171], v[140:143]
	v_mfma_f32_16x16x32_bf16 v[136:139], v[88:91], v[168:171], v[136:139]
	v_mfma_f32_16x16x32_bf16 v[124:127], v[72:75], v[192:195], v[124:127]
	v_mfma_f32_16x16x32_bf16 v[120:123], v[88:91], v[192:195], v[120:123]
	v_mfma_f32_16x16x32_bf16 v[108:111], v[72:75], v[200:203], v[108:111]
	v_mfma_f32_16x16x32_bf16 v[104:107], v[88:91], v[200:203], v[104:107]
	v_mfma_f32_16x16x32_bf16 v[84:87], v[72:75], v[208:211], v[84:87]
	v_mfma_f32_16x16x32_bf16 v[76:79], v[88:91], v[208:211], v[76:79]
	v_mfma_f32_16x16x32_bf16 v[140:143], v[80:83], v[174:177], v[140:143]
	v_mfma_f32_16x16x32_bf16 v[136:139], v[92:95], v[174:177], v[136:139]
	v_mfma_f32_16x16x32_bf16 v[124:127], v[80:83], v[196:199], v[124:127]
	v_mfma_f32_16x16x32_bf16 v[120:123], v[92:95], v[196:199], v[120:123]
	v_mfma_f32_16x16x32_bf16 v[108:111], v[80:83], v[204:207], v[108:111]
	v_mfma_f32_16x16x32_bf16 v[104:107], v[92:95], v[204:207], v[104:107]
	v_mfma_f32_16x16x32_bf16 v[84:87], v[80:83], v[212:215], v[84:87]
	v_mfma_f32_16x16x32_bf16 v[76:79], v[92:95], v[212:215], v[76:79]
	v_mfma_f32_16x16x32_bf16 v[132:135], v[152:155], v[168:171], v[132:135]
	v_mfma_f32_16x16x32_bf16 v[128:131], v[160:163], v[168:171], v[128:131]
	v_mfma_f32_16x16x32_bf16 v[116:119], v[152:155], v[192:195], v[116:119]
	v_mfma_f32_16x16x32_bf16 v[112:115], v[160:163], v[192:195], v[112:115]
	v_mfma_f32_16x16x32_bf16 v[100:103], v[152:155], v[200:203], v[100:103]
	v_mfma_f32_16x16x32_bf16 v[96:99], v[160:163], v[200:203], v[96:99]
	v_mfma_f32_16x16x32_bf16 v[68:71], v[152:155], v[208:211], v[68:71]
	v_mfma_f32_16x16x32_bf16 v[64:67], v[160:163], v[208:211], v[64:67]
	v_mfma_f32_16x16x32_bf16 v[132:135], v[156:159], v[174:177], v[132:135]
	v_mfma_f32_16x16x32_bf16 v[128:131], v[164:167], v[174:177], v[128:131]
	v_mfma_f32_16x16x32_bf16 v[116:119], v[156:159], v[196:199], v[116:119]
	v_mfma_f32_16x16x32_bf16 v[112:115], v[164:167], v[196:199], v[112:115]
	v_mfma_f32_16x16x32_bf16 v[100:103], v[156:159], v[204:207], v[100:103]
	v_mfma_f32_16x16x32_bf16 v[96:99], v[164:167], v[204:207], v[96:99]
	v_mfma_f32_16x16x32_bf16 v[68:71], v[156:159], v[212:215], v[68:71]
	v_mfma_f32_16x16x32_bf16 v[64:67], v[164:167], v[212:215], v[64:67]
	s_barrier
; #define PG8_STAGE(bufoff, gbase, voff) do { _Pragma("unroll") for (int _i = 0; _i < 2; ++_i) \
;         __builtin_amdgcn_global_load_lds((const unsigned*)((const char*)(gbase) + (voff)[_i]), (PG8_LAS unsigned*)(lds + (bufoff) + ldsw + _i * 8192), 16, 0, 0); } while (0)
; #define PG8_LDA(dst, b, h) do { _Pragma("unroll") for (int m = 0; m < 4; ++m) _Pragma("unroll") for (int k = 0; k < 2; ++k) dst[m][k] = *(const PG8_LAS bf16x8*)(lds + PG8_SA(b, h) + aoff + m * 2048 + k * 1024); } while (0)
; #define PG8_MMA(ai, bj, At, Bt) do { __builtin_amdgcn_s_setprio(1); _Pragma("unroll") for (int m = 0; m < 4; ++m) _Pragma("unroll") for (int n = 0; n < 2; ++n) _Pragma("unroll") for (int k = 0; k < 2; ++k) \
;         acc[ai][bj][m][n] = __builtin_amdgcn_mfma_f32_16x16x32_bf16(Bt[n][k], At[m][k], acc[ai][bj][m][n], 0, 0, 0); __builtin_amdgcn_s_setprio(0); } while (0)
; #define PG8_WAIT_V(n) asm volatile("s_waitcnt vmcnt(" #n ")" ::: "memory")
; #define PG8_WAIT_L(n) asm volatile("s_waitcnt lgkmcnt(" #n ")" ::: "memory")
; #define PG8_BAR __builtin_amdgcn_s_barrier()
; #define PG8_SCHED __builtin_amdgcn_sched_barrier(0)
; template <class Epi, class Sched, bool ALIGN_EPI = false, bool SP2 = false>
; __device__ __forceinline__ void gemm_phase(PG8_LAS unsigned char* lds, const Gemm g, const Sched& S, const Epi& E) {
;     ...
;             PG8_LDA(At, 1, 1); PG8_STAGE(PG8_SB(1, 0), b3, voffB); PG8_STAGE(PG8_SB(1, 1), b3 + hstepB, voffB); PG8_STAGE(PG8_SA(1, 0), a3, voffA);
;             PG8_WAIT_V(8); PG8_WAIT_L(0); PG8_BAR; PG8_MMA(1, 0, At, B0); PG8_MMA(1, 1, At, B1); PG8_BAR; PG8_SCHED;
;     ...
;         if constexpr (ALIGN_EPI) { if (wr == 0) PG8_BAR; }
	s_add_i32 s42, s71, s50
	v_lshl_add_u64 v[178:179], v[178:179], 0, s[80:81]
	s_mov_b32 m0, s42
	ds_read_b128 v[168:171], v186 offset:49152
	ds_read_b128 v[174:177], v186 offset:50176
	ds_read_b128 v[192:195], v186 offset:51200
	ds_read_b128 v[196:199], v186 offset:52224
	ds_read_b128 v[200:203], v186 offset:53248
	ds_read_b128 v[204:207], v186 offset:54272
	ds_read_b128 v[208:211], v186 offset:55296
	ds_read_b128 v[212:215], v186 offset:56320
	global_load_lds_dwordx4 v[178:179], off
	s_add_i32 m0, s42, 0x2000
	s_add_u32 s40, s40, 0x100080
	v_lshl_add_u64 v[178:179], v[216:217], 0, s[80:81]
	s_addc_u32 s41, s41, 0
	s_add_i32 s42, s72, s50
	global_load_lds_dwordx4 v[178:179], off
	v_lshl_add_u64 v[178:179], s[40:41], 0, v[172:173]
	s_mov_b32 m0, s42
	s_nop 0
	global_load_lds_dwordx4 v[178:179], off
	v_lshl_add_u64 v[178:179], s[40:41], 0, v[144:145]
	s_add_i32 m0, s42, 0x2000
	s_nop 0
	global_load_lds_dwordx4 v[178:179], off
	v_lshl_add_u64 v[178:179], v[218:219], 0, s[80:81]
	s_mov_b32 m0, s62
	s_nop 0
	global_load_lds_dwordx4 v[178:179], off
	v_lshl_add_u64 v[178:179], v[220:221], 0, s[80:81]
	s_mov_b32 m0, s63
	s_nop 0
	global_load_lds_dwordx4 v[178:179], off
	s_waitcnt vmcnt(8)
	s_waitcnt lgkmcnt(0)
	s_barrier
	s_waitcnt lgkmcnt(0)
	v_mfma_f32_16x16x32_bf16 v[60:63], v[72:75], v[168:171], v[60:63]
	v_mfma_f32_16x16x32_bf16 v[56:59], v[88:91], v[168:171], v[56:59]
	v_mfma_f32_16x16x32_bf16 v[44:47], v[72:75], v[192:195], v[44:47]
	v_mfma_f32_16x16x32_bf16 v[40:43], v[88:91], v[192:195], v[40:43]
	v_mfma_f32_16x16x32_bf16 v[28:31], v[72:75], v[200:203], v[28:31]
	v_mfma_f32_16x16x32_bf16 v[24:27], v[88:91], v[200:203], v[24:27]
	v_mfma_f32_16x16x32_bf16 v[12:15], v[72:75], v[208:211], v[12:15]
	v_mfma_f32_16x16x32_bf16 v[8:11], v[88:91], v[208:211], v[8:11]
	v_mfma_f32_16x16x32_bf16 v[60:63], v[80:83], v[174:177], v[60:63]
	v_mfma_f32_16x16x32_bf16 v[56:59], v[92:95], v[174:177], v[56:59]
	v_mfma_f32_16x16x32_bf16 v[44:47], v[80:83], v[196:199], v[44:47]
	v_mfma_f32_16x16x32_bf16 v[40:43], v[92:95], v[196:199], v[40:43]
	v_mfma_f32_16x16x32_bf16 v[28:31], v[80:83], v[204:207], v[28:31]
	v_mfma_f32_16x16x32_bf16 v[24:27], v[92:95], v[204:207], v[24:27]
	v_mfma_f32_16x16x32_bf16 v[12:15], v[80:83], v[212:215], v[12:15]
	v_mfma_f32_16x16x32_bf16 v[8:11], v[92:95], v[212:215], v[8:11]
	v_mfma_f32_16x16x32_bf16 v[52:55], v[152:155], v[168:171], v[52:55]
	v_mfma_f32_16x16x32_bf16 v[48:51], v[160:163], v[168:171], v[48:51]
	v_mfma_f32_16x16x32_bf16 v[36:39], v[152:155], v[192:195], v[36:39]
	v_mfma_f32_16x16x32_bf16 v[32:35], v[160:163], v[192:195], v[32:35]
	v_mfma_f32_16x16x32_bf16 v[20:23], v[152:155], v[200:203], v[20:23]
	v_mfma_f32_16x16x32_bf16 v[16:19], v[160:163], v[200:203], v[16:19]
	v_mfma_f32_16x16x32_bf16 v[4:7], v[152:155], v[208:211], v[4:7]
	v_mfma_f32_16x16x32_bf16 v[0:3], v[160:163], v[208:211], v[0:3]
	v_mfma_f32_16x16x32_bf16 v[52:55], v[156:159], v[174:177], v[52:55]
	v_mfma_f32_16x16x32_bf16 v[48:51], v[164:167], v[174:177], v[48:51]
	v_mfma_f32_16x16x32_bf16 v[36:39], v[156:159], v[196:199], v[36:39]
	v_mfma_f32_16x16x32_bf16 v[32:35], v[164:167], v[196:199], v[32:35]
	v_mfma_f32_16x16x32_bf16 v[20:23], v[156:159], v[204:207], v[20:23]
	v_mfma_f32_16x16x32_bf16 v[16:19], v[164:167], v[204:207], v[16:19]
	v_mfma_f32_16x16x32_bf16 v[4:7], v[156:159], v[212:215], v[4:7]
	v_mfma_f32_16x16x32_bf16 v[0:3], v[164:167], v[212:215], v[0:3]
	s_barrier
	s_add_i32 s70, s70, 2
	s_add_u32 s38, s38, 0x100
	s_addc_u32 s39, s39, 0
	s_add_u32 s67, s67, 0x100
	s_addc_u32 s68, s68, 0
	s_cmp_gt_u32 s70, 61
	s_cbranch_scc0 .LBB0_1906
	s_and_b64 vcc, exec, s[22:23]
	s_cbranch_vccz .LBB0_1909
	s_barrier

;     __device__ __forceinline__ bool next(int i, Unit& u) const { const int L = i * G + c; if (L >= nsub) return false; u.pk = L >> 4; u.pm = MLAT / BM + (L & 3); u.pn = (L >> 2) & 3; return true; }
; #define PG8_STAGE(bufoff, gbase, voff) do { _Pragma("unroll") for (int _i = 0; _i < 2; ++_i) \
;         __builtin_amdgcn_global_load_lds((const unsigned*)((const char*)(gbase) + (voff)[_i]), (PG8_LAS unsigned*)(lds + (bufoff) + ldsw + _i * 8192), 16, 0, 0); } while (0)
; #define PG8_LDA(dst, b, h) do { _Pragma("unroll") for (int m = 0; m < 4; ++m) _Pragma("unroll") for (int k = 0; k < 2; ++k) dst[m][k] = *(const PG8_LAS bf16x8*)(lds + PG8_SA(b, h) + aoff + m * 2048 + k * 1024); } while (0)
; #define PG8_LDB(dst, b, h) do { _Pragma("unroll") for (int n = 0; n < 2; ++n) _Pragma("unroll") for (int k = 0; k < 2; ++k) dst[n][k] = *(const PG8_LAS bf16x8*)(lds + PG8_SB(b, h) + boff + n * 2048 + k * 1024); } while (0)
; #define PG8_WAIT_V(n) asm volatile("s_waitcnt vmcnt(" #n ")" ::: "memory")
; #define PG8_WAIT_L(n) asm volatile("s_waitcnt lgkmcnt(" #n ")" ::: "memory")
; template <class Epi, class Sched, bool ALIGN_EPI = false, bool SP2 = false>
; __device__ __forceinline__ void gemm_phase(PG8_LAS unsigned char* lds, const Gemm g, const Sched& S, const Epi& E) {
;     ...
;         const bool has_next = S.next(ui + 1, nxt);
;         const char* nA = has_next ? g.a_of(nxt) : cA; const char* nB = has_next ? g.b_of(nxt) : cB;
;         for (int t = 0; t < nt; t += 2) {
;             const bool last = (t == nt - 2);
;             const char* a1 = cA + (size_t)(t + 1) * kstep;
;             const char* a2 = last ? nA : cA + (size_t)(t + 2) * kstep; const char* b2 = last ? nB : cB + (size_t)(t + 2) * kstep;
;             const char* a3 = a2 + kstep; const char* b3 = b2 + kstep;
;             if (last && has_next) S.a_ready(nxt);
;             if constexpr (SP2) {
;             PG8_LDB(B0, 0, 0); PG8_LDB(B1, 0, 1); PG8_SCHED; PG8_LDA(At, 0, 0); PG8_STAGE(PG8_SA(1, 1), a1 + hstepA, voffA);
;             PG8_WAIT_V(8); PG8_WAIT_L(0); PG8_BAR; PG8_MMA(0, 0, At, B0); PG8_MMA(0, 1, At, B1); PG8_BAR; PG8_SCHED;
;             PG8_LDA(At, 0, 1); PG8_STAGE(PG8_SB(0, 0), b2, voffB); PG8_STAGE(PG8_SB(0, 1), b2 + hstepB, voffB); PG8_STAGE(PG8_SA(0, 0), a2, voffA);
;             PG8_WAIT_V(8); PG8_WAIT_L(0); PG8_BAR; PG8_MMA(1, 0, At, B0); PG8_MMA(1, 1, At, B1); PG8_BAR; PG8_SCHED;
.LBB0_1950:
	s_add_u32 s30, s28, 0xfff00080
	s_addc_u32 s31, s29, -1
	s_add_i32 s62, 0, 0x10000
	s_cmp_eq_u32 s61, 60
	s_cselect_b32 s35, s21, s31
	s_cselect_b32 s34, s27, s30
	s_cselect_b32 s31, s15, s60
	s_cselect_b32 s30, s58, s59
	s_add_i32 s64, 0, 0x14000
	v_add_u32_e32 v108, s62, v153
	v_add_u32_e32 v150, s64, v153
	ds_read_b128 v[52:55], v108
	ds_read_b128 v[92:95], v108 offset:1024
	ds_read_b128 v[100:103], v108 offset:2048
	ds_read_b128 v[108:111], v108 offset:3072
	ds_read_b128 v[156:159], v150
	ds_read_b128 v[160:163], v150 offset:1024
	ds_read_b128 v[164:167], v150 offset:2048
	ds_read_b128 v[168:171], v150 offset:3072
	v_lshl_add_u64 v[150:151], s[28:29], 0, v[146:147]
	s_add_i32 m0, s38, 0xc000
	ds_read_b128 v[174:177], v155
	ds_read_b128 v[178:181], v155 offset:1024
	ds_read_b128 v[182:185], v155 offset:2048
	ds_read_b128 v[192:195], v155 offset:3072
	ds_read_b128 v[196:199], v155 offset:4096
	ds_read_b128 v[200:203], v155 offset:5120
	ds_read_b128 v[204:207], v155 offset:6144
	ds_read_b128 v[208:211], v155 offset:7168
	global_load_lds_dwordx4 v[150:151], off
	v_lshl_add_u64 v[150:151], s[28:29], 0, v[148:149]
	s_add_i32 m0, s38, 0xe000
	s_nop 0
	global_load_lds_dwordx4 v[150:151], off
	s_waitcnt vmcnt(8)
	s_waitcnt lgkmcnt(0)
	s_barrier
	s_waitcnt lgkmcnt(0)
	v_mfma_f32_16x16x32_bf16 v[140:143], v[52:55], v[174:177], v[140:143]
	v_mfma_f32_16x16x32_bf16 v[136:139], v[100:103], v[174:177], v[136:139]
	v_mfma_f32_16x16x32_bf16 v[124:127], v[52:55], v[182:185], v[124:127]
	v_mfma_f32_16x16x32_bf16 v[120:123], v[100:103], v[182:185], v[120:123]
	v_mfma_f32_16x16x32_bf16 v[104:107], v[52:55], v[196:199], v[104:107]
	v_mfma_f32_16x16x32_bf16 v[96:99], v[100:103], v[196:199], v[96:99]
	v_mfma_f32_16x16x32_bf16 v[80:83], v[52:55], v[204:207], v[80:83]
	v_mfma_f32_16x16x32_bf16 v[76:79], v[100:103], v[204:207], v[76:79]
	v_mfma_f32_16x16x32_bf16 v[140:143], v[92:95], v[178:181], v[140:143]
	v_mfma_f32_16x16x32_bf16 v[136:139], v[108:111], v[178:181], v[136:139]
	v_mfma_f32_16x16x32_bf16 v[124:127], v[92:95], v[192:195], v[124:127]
	v_mfma_f32_16x16x32_bf16 v[120:123], v[108:111], v[192:195], v[120:123]
	v_mfma_f32_16x16x32_bf16 v[104:107], v[92:95], v[200:203], v[104:107]
	v_mfma_f32_16x16x32_bf16 v[96:99], v[108:111], v[200:203], v[96:99]
	v_mfma_f32_16x16x32_bf16 v[80:83], v[92:95], v[208:211], v[80:83]
	v_mfma_f32_16x16x32_bf16 v[76:79], v[108:111], v[208:211], v[76:79]
	v_mfma_f32_16x16x32_bf16 v[132:135], v[156:159], v[174:177], v[132:135]
	v_mfma_f32_16x16x32_bf16 v[128:131], v[164:167], v[174:177], v[128:131]
	v_mfma_f32_16x16x32_bf16 v[116:119], v[156:159], v[182:185], v[116:119]
	v_mfma_f32_16x16x32_bf16 v[112:115], v[164:167], v[182:185], v[112:115]
	v_mfma_f32_16x16x32_bf16 v[88:91], v[156:159], v[196:199], v[88:91]
	v_mfma_f32_16x16x32_bf16 v[84:87], v[164:167], v[196:199], v[84:87]
	v_mfma_f32_16x16x32_bf16 v[72:75], v[156:159], v[204:207], v[72:75]
	v_mfma_f32_16x16x32_bf16 v[68:71], v[164:167], v[204:207], v[68:71]
	v_mfma_f32_16x16x32_bf16 v[132:135], v[160:163], v[178:181], v[132:135]
	v_mfma_f32_16x16x32_bf16 v[128:131], v[168:171], v[178:181], v[128:131]
	v_mfma_f32_16x16x32_bf16 v[116:119], v[160:163], v[192:195], v[116:119]
	v_mfma_f32_16x16x32_bf16 v[112:115], v[168:171], v[192:195], v[112:115]
	v_mfma_f32_16x16x32_bf16 v[88:91], v[160:163], v[200:203], v[88:91]
	v_mfma_f32_16x16x32_bf16 v[84:87], v[168:171], v[200:203], v[84:87]
	v_mfma_f32_16x16x32_bf16 v[72:75], v[160:163], v[208:211], v[72:75]
	v_mfma_f32_16x16x32_bf16 v[68:71], v[168:171], v[208:211], v[68:71]
	s_barrier
	s_add_i32 s62, s62, s37
	v_lshl_add_u64 v[150:151], s[30:31], 0, v[172:173]
	s_mov_b32 m0, s62
	ds_read_b128 v[174:177], v155 offset:16384
	ds_read_b128 v[178:181], v155 offset:17408
	ds_read_b128 v[182:185], v155 offset:18432
	ds_read_b128 v[192:195], v155 offset:19456
	ds_read_b128 v[196:199], v155 offset:20480
	ds_read_b128 v[200:203], v155 offset:21504
	ds_read_b128 v[204:207], v155 offset:22528
	ds_read_b128 v[208:211], v155 offset:23552
	global_load_lds_dwordx4 v[150:151], off
	s_add_i32 m0, s62, 0x2000
	s_add_u32 s62, s30, 0x100000
	v_lshl_add_u64 v[186:187], s[30:31], 0, v[144:145]
	s_addc_u32 s63, s31, 0
	s_add_i32 s64, s64, s37
	global_load_lds_dwordx4 v[186:187], off
	v_lshl_add_u64 v[212:213], s[62:63], 0, v[172:173]
	s_mov_b32 m0, s64
	v_lshl_add_u64 v[214:215], s[34:35], 0, v[144:145]
	global_load_lds_dwordx4 v[212:213], off
	v_lshl_add_u64 v[212:213], s[62:63], 0, v[144:145]
	s_add_i32 m0, s64, 0x2000
	s_nop 0
	global_load_lds_dwordx4 v[212:213], off
	v_lshl_add_u64 v[212:213], s[34:35], 0, v[172:173]
	s_mov_b32 m0, s38
	s_nop 0
	global_load_lds_dwordx4 v[212:213], off
	s_mov_b32 m0, s39
	s_nop 0
	global_load_lds_dwordx4 v[214:215], off
	s_waitcnt vmcnt(8)
	s_waitcnt lgkmcnt(0)
	s_barrier
; #define PG8_STAGE(bufoff, gbase, voff) do { _Pragma("unroll") for (int _i = 0; _i < 2; ++_i) \
;         __builtin_amdgcn_global_load_lds((const unsigned*)((const char*)(gbase) + (voff)[_i]), (PG8_LAS unsigned*)(lds + (bufoff) + ldsw + _i * 8192), 16, 0, 0); } while (0)
; #define PG8_LDA(dst, b, h) do { _Pragma("unroll") for (int m = 0; m < 4; ++m) _Pragma("unroll") for (int k = 0; k < 2; ++k) dst[m][k] = *(const PG8_LAS bf16x8*)(lds + PG8_SA(b, h) + aoff + m * 2048 + k * 1024); } while (0)
; #define PG8_LDB(dst, b, h) do { _Pragma("unroll") for (int n = 0; n < 2; ++n) _Pragma("unroll") for (int k = 0; k < 2; ++k) dst[n][k] = *(const PG8_LAS bf16x8*)(lds + PG8_SB(b, h) + boff + n * 2048 + k * 1024); } while (0)
; #define PG8_MMA(ai, bj, At, Bt) do { __builtin_amdgcn_s_setprio(1); _Pragma("unroll") for (int m = 0; m < 4; ++m) _Pragma("unroll") for (int n = 0; n < 2; ++n) _Pragma("unroll") for (int k = 0; k < 2; ++k) \
;         acc[ai][bj][m][n] = __builtin_amdgcn_mfma_f32_16x16x32_bf16(Bt[n][k], At[m][k], acc[ai][bj][m][n], 0, 0, 0); __builtin_amdgcn_s_setprio(0); } while (0)
; #define PG8_WAIT_V(n) asm volatile("s_waitcnt vmcnt(" #n ")" ::: "memory")
; #define PG8_WAIT_L(n) asm volatile("s_waitcnt lgkmcnt(" #n ")" ::: "memory")
; #define PG8_BAR __builtin_amdgcn_s_barrier()
; #define PG8_SCHED __builtin_amdgcn_sched_barrier(0)
; template <class Epi, class Sched, bool ALIGN_EPI = false, bool SP2 = false>
; __device__ __forceinline__ void gemm_phase(PG8_LAS unsigned char* lds, const Gemm g, const Sched& S, const Epi& E) {
;     ...
;             PG8_WAIT_V(8); PG8_WAIT_L(0); PG8_BAR; PG8_MMA(1, 0, At, B0); PG8_MMA(1, 1, At, B1); PG8_BAR; PG8_SCHED;
;             PG8_LDB(B0, 1, 0); PG8_LDB(B1, 1, 1); PG8_SCHED; PG8_LDA(At, 1, 0); PG8_STAGE(PG8_SA(0, 1), a2 + hstepA, voffA);
;             PG8_WAIT_V(8); PG8_WAIT_L(0); PG8_BAR; PG8_MMA(0, 0, At, B0); PG8_MMA(0, 1, At, B1); PG8_BAR; PG8_SCHED;
	s_waitcnt lgkmcnt(0)
	v_mfma_f32_16x16x32_bf16 v[64:67], v[52:55], v[174:177], v[64:67]
	v_mfma_f32_16x16x32_bf16 v[60:63], v[100:103], v[174:177], v[60:63]
	v_mfma_f32_16x16x32_bf16 v[44:47], v[52:55], v[182:185], v[44:47]
	v_mfma_f32_16x16x32_bf16 v[40:43], v[100:103], v[182:185], v[40:43]
	v_mfma_f32_16x16x32_bf16 v[28:31], v[52:55], v[196:199], v[28:31]
	v_mfma_f32_16x16x32_bf16 v[24:27], v[100:103], v[196:199], v[24:27]
	v_mfma_f32_16x16x32_bf16 v[12:15], v[52:55], v[204:207], v[12:15]
	v_mfma_f32_16x16x32_bf16 v[8:11], v[100:103], v[204:207], v[8:11]
	v_mfma_f32_16x16x32_bf16 v[64:67], v[92:95], v[178:181], v[64:67]
	v_mfma_f32_16x16x32_bf16 v[60:63], v[108:111], v[178:181], v[60:63]
	v_mfma_f32_16x16x32_bf16 v[44:47], v[92:95], v[192:195], v[44:47]
	v_mfma_f32_16x16x32_bf16 v[40:43], v[108:111], v[192:195], v[40:43]
	v_mfma_f32_16x16x32_bf16 v[28:31], v[92:95], v[200:203], v[28:31]
	v_mfma_f32_16x16x32_bf16 v[24:27], v[108:111], v[200:203], v[24:27]
	v_mfma_f32_16x16x32_bf16 v[12:15], v[92:95], v[208:211], v[12:15]
	v_mfma_f32_16x16x32_bf16 v[8:11], v[108:111], v[208:211], v[8:11]
	v_mfma_f32_16x16x32_bf16 v[48:51], v[164:167], v[174:177], v[48:51]
	v_mfma_f32_16x16x32_bf16 v[36:39], v[156:159], v[182:185], v[36:39]
	v_mfma_f32_16x16x32_bf16 v[32:35], v[164:167], v[182:185], v[32:35]
	v_mfma_f32_16x16x32_bf16 v[20:23], v[156:159], v[196:199], v[20:23]
	v_mfma_f32_16x16x32_bf16 v[16:19], v[164:167], v[196:199], v[16:19]
	v_mfma_f32_16x16x32_bf16 v[4:7], v[156:159], v[204:207], v[4:7]
	v_mfma_f32_16x16x32_bf16 v[0:3], v[164:167], v[204:207], v[0:3]
	v_mfma_f32_16x16x32_bf16 v[52:55], v[156:159], v[174:177], v[56:59]
	v_mfma_f32_16x16x32_bf16 v[48:51], v[168:171], v[178:181], v[48:51]
	v_mfma_f32_16x16x32_bf16 v[36:39], v[160:163], v[192:195], v[36:39]
	v_mfma_f32_16x16x32_bf16 v[32:35], v[168:171], v[192:195], v[32:35]
	v_mfma_f32_16x16x32_bf16 v[20:23], v[160:163], v[200:203], v[20:23]
	v_mfma_f32_16x16x32_bf16 v[16:19], v[168:171], v[200:203], v[16:19]
	v_mfma_f32_16x16x32_bf16 v[4:7], v[160:163], v[208:211], v[4:7]
	v_mfma_f32_16x16x32_bf16 v[0:3], v[168:171], v[208:211], v[0:3]
	v_mfma_f32_16x16x32_bf16 v[52:55], v[160:163], v[178:181], v[52:55]
	s_barrier
	s_add_i32 s62, 0, 0x18000
	s_add_i32 s63, 0, 0x1c000
	v_add_u32_e32 v108, s62, v153
	v_add_u32_e32 v168, s63, v153
	ds_read_b128 v[56:59], v108
	ds_read_b128 v[92:95], v108 offset:1024
	ds_read_b128 v[100:103], v108 offset:2048
	ds_read_b128 v[108:111], v108 offset:3072
	ds_read_b128 v[156:159], v168
	ds_read_b128 v[160:163], v168 offset:1024
	ds_read_b128 v[164:167], v168 offset:2048
	ds_read_b128 v[168:171], v168 offset:3072
	s_add_u32 s34, s34, 0x100000
	s_addc_u32 s35, s35, 0
	s_mov_b32 m0, s40
	v_lshl_add_u64 v[216:217], s[34:35], 0, v[172:173]
	ds_read_b128 v[174:177], v155 offset:32768
	ds_read_b128 v[178:181], v155 offset:33792
	ds_read_b128 v[182:185], v155 offset:34816
	ds_read_b128 v[192:195], v155 offset:35840
	ds_read_b128 v[196:199], v155 offset:36864
	ds_read_b128 v[200:203], v155 offset:37888
	ds_read_b128 v[204:207], v155 offset:38912
	ds_read_b128 v[208:211], v155 offset:39936
	global_load_lds_dwordx4 v[216:217], off
	v_lshl_add_u64 v[216:217], s[34:35], 0, v[144:145]
	s_mov_b32 m0, s41
	s_nop 0
	global_load_lds_dwordx4 v[216:217], off
	s_waitcnt vmcnt(8)
	s_waitcnt lgkmcnt(0)
	s_barrier
	s_waitcnt lgkmcnt(0)
	v_mfma_f32_16x16x32_bf16 v[140:143], v[56:59], v[174:177], v[140:143]
	v_mfma_f32_16x16x32_bf16 v[136:139], v[100:103], v[174:177], v[136:139]
	v_mfma_f32_16x16x32_bf16 v[124:127], v[56:59], v[182:185], v[124:127]
	v_mfma_f32_16x16x32_bf16 v[120:123], v[100:103], v[182:185], v[120:123]
	v_mfma_f32_16x16x32_bf16 v[104:107], v[56:59], v[196:199], v[104:107]
	v_mfma_f32_16x16x32_bf16 v[96:99], v[100:103], v[196:199], v[96:99]
	v_mfma_f32_16x16x32_bf16 v[80:83], v[56:59], v[204:207], v[80:83]
	v_mfma_f32_16x16x32_bf16 v[76:79], v[100:103], v[204:207], v[76:79]
	v_mfma_f32_16x16x32_bf16 v[140:143], v[92:95], v[178:181], v[140:143]
	v_mfma_f32_16x16x32_bf16 v[136:139], v[108:111], v[178:181], v[136:139]
	v_mfma_f32_16x16x32_bf16 v[124:127], v[92:95], v[192:195], v[124:127]
	v_mfma_f32_16x16x32_bf16 v[120:123], v[108:111], v[192:195], v[120:123]
	v_mfma_f32_16x16x32_bf16 v[104:107], v[92:95], v[200:203], v[104:107]
	v_mfma_f32_16x16x32_bf16 v[96:99], v[108:111], v[200:203], v[96:99]
	v_mfma_f32_16x16x32_bf16 v[80:83], v[92:95], v[208:211], v[80:83]
	v_mfma_f32_16x16x32_bf16 v[76:79], v[108:111], v[208:211], v[76:79]
	v_mfma_f32_16x16x32_bf16 v[132:135], v[156:159], v[174:177], v[132:135]
	v_mfma_f32_16x16x32_bf16 v[128:131], v[164:167], v[174:177], v[128:131]
	v_mfma_f32_16x16x32_bf16 v[116:119], v[156:159], v[182:185], v[116:119]
	v_mfma_f32_16x16x32_bf16 v[112:115], v[164:167], v[182:185], v[112:115]
	v_mfma_f32_16x16x32_bf16 v[88:91], v[156:159], v[196:199], v[88:91]
	v_mfma_f32_16x16x32_bf16 v[84:87], v[164:167], v[196:199], v[84:87]
	v_mfma_f32_16x16x32_bf16 v[72:75], v[156:159], v[204:207], v[72:75]
	v_mfma_f32_16x16x32_bf16 v[68:71], v[164:167], v[204:207], v[68:71]
	v_mfma_f32_16x16x32_bf16 v[132:135], v[160:163], v[178:181], v[132:135]
	v_mfma_f32_16x16x32_bf16 v[128:131], v[168:171], v[178:181], v[128:131]
	v_mfma_f32_16x16x32_bf16 v[116:119], v[160:163], v[192:195], v[116:119]
	v_mfma_f32_16x16x32_bf16 v[112:115], v[168:171], v[192:195], v[112:115]
	v_mfma_f32_16x16x32_bf16 v[88:91], v[160:163], v[200:203], v[88:91]
	v_mfma_f32_16x16x32_bf16 v[84:87], v[168:171], v[200:203], v[84:87]
	v_mfma_f32_16x16x32_bf16 v[72:75], v[160:163], v[208:211], v[72:75]
	v_mfma_f32_16x16x32_bf16 v[68:71], v[168:171], v[208:211], v[68:71]
	s_barrier
; #define PG8_STAGE(bufoff, gbase, voff) do { _Pragma("unroll") for (int _i = 0; _i < 2; ++_i) \
;         __builtin_amdgcn_global_load_lds((const unsigned*)((const char*)(gbase) + (voff)[_i]), (PG8_LAS unsigned*)(lds + (bufoff) + ldsw + _i * 8192), 16, 0, 0); } while (0)
; #define PG8_LDA(dst, b, h) do { _Pragma("unroll") for (int m = 0; m < 4; ++m) _Pragma("unroll") for (int k = 0; k < 2; ++k) dst[m][k] = *(const PG8_LAS bf16x8*)(lds + PG8_SA(b, h) + aoff + m * 2048 + k * 1024); } while (0)
; #define PG8_MMA(ai, bj, At, Bt) do { __builtin_amdgcn_s_setprio(1); _Pragma("unroll") for (int m = 0; m < 4; ++m) _Pragma("unroll") for (int n = 0; n < 2; ++n) _Pragma("unroll") for (int k = 0; k < 2; ++k) \
;         acc[ai][bj][m][n] = __builtin_amdgcn_mfma_f32_16x16x32_bf16(Bt[n][k], At[m][k], acc[ai][bj][m][n], 0, 0, 0); __builtin_amdgcn_s_setprio(0); } while (0)
; #define PG8_WAIT_V(n) asm volatile("s_waitcnt vmcnt(" #n ")" ::: "memory")
; #define PG8_WAIT_L(n) asm volatile("s_waitcnt lgkmcnt(" #n ")" ::: "memory")
; #define PG8_BAR __builtin_amdgcn_s_barrier()
; #define PG8_SCHED __builtin_amdgcn_sched_barrier(0)
; template <class Epi, class Sched, bool ALIGN_EPI = false, bool SP2 = false>
; __device__ __forceinline__ void gemm_phase(PG8_LAS unsigned char* lds, const Gemm g, const Sched& S, const Epi& E) {
;     ...
;             PG8_LDA(At, 1, 1); PG8_STAGE(PG8_SB(1, 0), b3, voffB); PG8_STAGE(PG8_SB(1, 1), b3 + hstepB, voffB); PG8_STAGE(PG8_SA(1, 0), a3, voffA);
;             PG8_WAIT_V(8); PG8_WAIT_L(0); PG8_BAR; PG8_MMA(1, 0, At, B0); PG8_MMA(1, 1, At, B1); PG8_BAR; PG8_SCHED;
;     ...
;         if constexpr (ALIGN_EPI) { if (wr == 0) PG8_BAR; }
	s_add_i32 s34, s62, s37
	v_lshl_add_u64 v[150:151], v[150:151], 0, s[80:81]
	s_mov_b32 m0, s34
	ds_read_b128 v[174:177], v155 offset:49152
	ds_read_b128 v[178:181], v155 offset:50176
	ds_read_b128 v[182:185], v155 offset:51200
	ds_read_b128 v[192:195], v155 offset:52224
	ds_read_b128 v[196:199], v155 offset:53248
	ds_read_b128 v[200:203], v155 offset:54272
	ds_read_b128 v[204:207], v155 offset:55296
	ds_read_b128 v[208:211], v155 offset:56320
	global_load_lds_dwordx4 v[150:151], off
	s_add_i32 m0, s34, 0x2000
	s_add_u32 s30, s30, 0x100080
	v_lshl_add_u64 v[150:151], v[186:187], 0, s[80:81]
	s_addc_u32 s31, s31, 0
	s_add_i32 s34, s63, s37
	global_load_lds_dwordx4 v[150:151], off
	v_lshl_add_u64 v[150:151], s[30:31], 0, v[172:173]
	s_mov_b32 m0, s34
	s_nop 0
	global_load_lds_dwordx4 v[150:151], off
	v_lshl_add_u64 v[150:151], s[30:31], 0, v[144:145]
	s_add_i32 m0, s34, 0x2000
	s_nop 0
	global_load_lds_dwordx4 v[150:151], off
	v_lshl_add_u64 v[150:151], v[212:213], 0, s[80:81]
	s_mov_b32 m0, s50
	s_nop 0
	global_load_lds_dwordx4 v[150:151], off
	v_lshl_add_u64 v[150:151], v[214:215], 0, s[80:81]
	s_mov_b32 m0, s51
	s_nop 0
	global_load_lds_dwordx4 v[150:151], off
	s_waitcnt vmcnt(8)
	s_waitcnt lgkmcnt(0)
	s_barrier
	s_waitcnt lgkmcnt(0)
	v_mfma_f32_16x16x32_bf16 v[64:67], v[56:59], v[174:177], v[64:67]
	v_mfma_f32_16x16x32_bf16 v[60:63], v[100:103], v[174:177], v[60:63]
	v_mfma_f32_16x16x32_bf16 v[44:47], v[56:59], v[182:185], v[44:47]
	v_mfma_f32_16x16x32_bf16 v[40:43], v[100:103], v[182:185], v[40:43]
	v_mfma_f32_16x16x32_bf16 v[28:31], v[56:59], v[196:199], v[28:31]
	v_mfma_f32_16x16x32_bf16 v[24:27], v[100:103], v[196:199], v[24:27]
	v_mfma_f32_16x16x32_bf16 v[12:15], v[56:59], v[204:207], v[12:15]
	v_mfma_f32_16x16x32_bf16 v[8:11], v[100:103], v[204:207], v[8:11]
	v_mfma_f32_16x16x32_bf16 v[64:67], v[92:95], v[178:181], v[64:67]
	v_mfma_f32_16x16x32_bf16 v[60:63], v[108:111], v[178:181], v[60:63]
	v_mfma_f32_16x16x32_bf16 v[44:47], v[92:95], v[192:195], v[44:47]
	v_mfma_f32_16x16x32_bf16 v[40:43], v[108:111], v[192:195], v[40:43]
	v_mfma_f32_16x16x32_bf16 v[28:31], v[92:95], v[200:203], v[28:31]
	v_mfma_f32_16x16x32_bf16 v[24:27], v[108:111], v[200:203], v[24:27]
	v_mfma_f32_16x16x32_bf16 v[12:15], v[92:95], v[208:211], v[12:15]
	v_mfma_f32_16x16x32_bf16 v[8:11], v[108:111], v[208:211], v[8:11]
	v_mfma_f32_16x16x32_bf16 v[52:55], v[156:159], v[174:177], v[52:55]
	v_mfma_f32_16x16x32_bf16 v[48:51], v[164:167], v[174:177], v[48:51]
	v_mfma_f32_16x16x32_bf16 v[36:39], v[156:159], v[182:185], v[36:39]
	v_mfma_f32_16x16x32_bf16 v[32:35], v[164:167], v[182:185], v[32:35]
	v_mfma_f32_16x16x32_bf16 v[20:23], v[156:159], v[196:199], v[20:23]
	v_mfma_f32_16x16x32_bf16 v[16:19], v[164:167], v[196:199], v[16:19]
	v_mfma_f32_16x16x32_bf16 v[4:7], v[156:159], v[204:207], v[4:7]
	v_mfma_f32_16x16x32_bf16 v[0:3], v[164:167], v[204:207], v[0:3]
	v_mfma_f32_16x16x32_bf16 v[56:59], v[160:163], v[178:181], v[52:55]
	v_mfma_f32_16x16x32_bf16 v[48:51], v[168:171], v[178:181], v[48:51]
	v_mfma_f32_16x16x32_bf16 v[36:39], v[160:163], v[192:195], v[36:39]
	v_mfma_f32_16x16x32_bf16 v[32:35], v[168:171], v[192:195], v[32:35]
	v_mfma_f32_16x16x32_bf16 v[20:23], v[160:163], v[200:203], v[20:23]
	v_mfma_f32_16x16x32_bf16 v[16:19], v[168:171], v[200:203], v[16:19]
	v_mfma_f32_16x16x32_bf16 v[4:7], v[160:163], v[208:211], v[4:7]
	v_mfma_f32_16x16x32_bf16 v[0:3], v[168:171], v[208:211], v[0:3]
	s_barrier
	s_add_i32 s61, s61, 2
	s_add_u32 s28, s28, 0x100
	s_addc_u32 s29, s29, 0
	s_add_u32 s59, s59, 0x100
	s_addc_u32 s60, s60, 0
	s_cmp_gt_u32 s61, 61
	s_cbranch_scc0 .LBB0_1950
	s_and_b64 vcc, exec, s[12:13]
	s_cbranch_vccz .LBB0_1953
	s_barrier

;     __device__ __forceinline__ bool next(int i, Unit& u) const { const int L = i * G + c; if (L >= nsub) return false; u.pk = L >> 4; u.pm = MLAT / BM + (L & 3); u.pn = (L >> 2) & 3; return true; }
; #define PG8_STAGE(bufoff, gbase, voff) do { _Pragma("unroll") for (int _i = 0; _i < 2; ++_i) \
;         __builtin_amdgcn_global_load_lds((const unsigned*)((const char*)(gbase) + (voff)[_i]), (PG8_LAS unsigned*)(lds + (bufoff) + ldsw + _i * 8192), 16, 0, 0); } while (0)
; #define PG8_LDA(dst, b, h) do { _Pragma("unroll") for (int m = 0; m < 4; ++m) _Pragma("unroll") for (int k = 0; k < 2; ++k) dst[m][k] = *(const PG8_LAS bf16x8*)(lds + PG8_SA(b, h) + aoff + m * 2048 + k * 1024); } while (0)
; #define PG8_LDB(dst, b, h) do { _Pragma("unroll") for (int n = 0; n < 2; ++n) _Pragma("unroll") for (int k = 0; k < 2; ++k) dst[n][k] = *(const PG8_LAS bf16x8*)(lds + PG8_SB(b, h) + boff + n * 2048 + k * 1024); } while (0)
; #define PG8_WAIT_V(n) asm volatile("s_waitcnt vmcnt(" #n ")" ::: "memory")
; #define PG8_WAIT_L(n) asm volatile("s_waitcnt lgkmcnt(" #n ")" ::: "memory")
; template <class Epi, class Sched, bool ALIGN_EPI = false, bool SP2 = false>
; __device__ __forceinline__ void gemm_phase(PG8_LAS unsigned char* lds, const Gemm g, const Sched& S, const Epi& E) {
;     ...
;         const bool has_next = S.next(ui + 1, nxt);
;         const char* nA = has_next ? g.a_of(nxt) : cA; const char* nB = has_next ? g.b_of(nxt) : cB;
;         for (int t = 0; t < nt; t += 2) {
;             const bool last = (t == nt - 2);
;             const char* a1 = cA + (size_t)(t + 1) * kstep;
;             const char* a2 = last ? nA : cA + (size_t)(t + 2) * kstep; const char* b2 = last ? nB : cB + (size_t)(t + 2) * kstep;
;             const char* a3 = a2 + kstep; const char* b3 = b2 + kstep;
;             if (last && has_next) S.a_ready(nxt);
;             if constexpr (SP2) {
;             PG8_LDB(B0, 0, 0); PG8_LDB(B1, 0, 1); PG8_SCHED; PG8_LDA(At, 0, 0); PG8_STAGE(PG8_SA(1, 1), a1 + hstepA, voffA);
;             PG8_WAIT_V(8); PG8_WAIT_L(0); PG8_BAR; PG8_MMA(0, 0, At, B0); PG8_MMA(0, 1, At, B1); PG8_BAR; PG8_SCHED;
;             PG8_LDA(At, 0, 1); PG8_STAGE(PG8_SB(0, 0), b2, voffB); PG8_STAGE(PG8_SB(0, 1), b2 + hstepB, voffB); PG8_STAGE(PG8_SA(0, 0), a2, voffA);
;             PG8_WAIT_V(8); PG8_WAIT_L(0); PG8_BAR; PG8_MMA(1, 0, At, B0); PG8_MMA(1, 1, At, B1); PG8_BAR; PG8_SCHED;
.LBB0_1972:
	s_add_u32 s26, s24, 0xfff00080
	s_addc_u32 s27, s25, -1
	s_add_i32 s49, 0, 0x10000
	s_cmp_eq_u32 s47, 4
	s_cselect_b32 s29, s15, s27
	s_cselect_b32 s28, s14, s26
	s_cselect_b32 s27, s21, s23
	s_cselect_b32 s26, s20, s17
	s_add_i32 s52, 0, 0x14000
	v_add_u32_e32 v124, s49, v158
	v_add_u32_e32 v156, s52, v158
	ds_read_b128 v[108:111], v124
	ds_read_b128 v[116:119], v124 offset:1024
	ds_read_b128 v[120:123], v124 offset:2048
	ds_read_b128 v[124:127], v124 offset:3072
	ds_read_b128 v[152:155], v156
	ds_read_b128 v[162:165], v156 offset:1024
	ds_read_b128 v[166:169], v156 offset:2048
	ds_read_b128 v[174:177], v156 offset:3072
	v_lshl_add_u64 v[156:157], s[24:25], 0, v[148:149]
	s_add_i32 m0, s34, 0xc000
	ds_read_b128 v[178:181], v161
	ds_read_b128 v[182:185], v161 offset:1024
	ds_read_b128 v[192:195], v161 offset:2048
	ds_read_b128 v[196:199], v161 offset:3072
	ds_read_b128 v[200:203], v161 offset:4096
	ds_read_b128 v[204:207], v161 offset:5120
	ds_read_b128 v[208:211], v161 offset:6144
	ds_read_b128 v[212:215], v161 offset:7168
	global_load_lds_dwordx4 v[156:157], off
	v_lshl_add_u64 v[156:157], s[24:25], 0, v[150:151]
	s_add_i32 m0, s34, 0xe000
	s_nop 0
	global_load_lds_dwordx4 v[156:157], off
	s_waitcnt vmcnt(8)
	s_waitcnt lgkmcnt(0)
	s_barrier
	s_waitcnt lgkmcnt(0)
	v_mfma_f32_16x16x32_bf16 v[140:143], v[108:111], v[178:181], v[140:143]
	v_mfma_f32_16x16x32_bf16 v[136:139], v[120:123], v[178:181], v[136:139]
	v_mfma_f32_16x16x32_bf16 v[112:115], v[108:111], v[192:195], v[112:115]
	v_mfma_f32_16x16x32_bf16 v[104:107], v[120:123], v[192:195], v[104:107]
	v_mfma_f32_16x16x32_bf16 v[92:95], v[108:111], v[200:203], v[92:95]
	v_mfma_f32_16x16x32_bf16 v[88:91], v[120:123], v[200:203], v[88:91]
	v_mfma_f32_16x16x32_bf16 v[76:79], v[108:111], v[208:211], v[76:79]
	v_mfma_f32_16x16x32_bf16 v[72:75], v[120:123], v[208:211], v[72:75]
	v_mfma_f32_16x16x32_bf16 v[140:143], v[116:119], v[182:185], v[140:143]
	v_mfma_f32_16x16x32_bf16 v[136:139], v[124:127], v[182:185], v[136:139]
	v_mfma_f32_16x16x32_bf16 v[112:115], v[116:119], v[196:199], v[112:115]
	v_mfma_f32_16x16x32_bf16 v[104:107], v[124:127], v[196:199], v[104:107]
	v_mfma_f32_16x16x32_bf16 v[92:95], v[116:119], v[204:207], v[92:95]
	v_mfma_f32_16x16x32_bf16 v[88:91], v[124:127], v[204:207], v[88:91]
	v_mfma_f32_16x16x32_bf16 v[76:79], v[116:119], v[212:215], v[76:79]
	v_mfma_f32_16x16x32_bf16 v[72:75], v[124:127], v[212:215], v[72:75]
	v_mfma_f32_16x16x32_bf16 v[132:135], v[152:155], v[178:181], v[132:135]
	v_mfma_f32_16x16x32_bf16 v[128:131], v[166:169], v[178:181], v[128:131]
	v_mfma_f32_16x16x32_bf16 v[100:103], v[152:155], v[192:195], v[100:103]
	v_mfma_f32_16x16x32_bf16 v[96:99], v[166:169], v[192:195], v[96:99]
	v_mfma_f32_16x16x32_bf16 v[84:87], v[152:155], v[200:203], v[84:87]
	v_mfma_f32_16x16x32_bf16 v[80:83], v[166:169], v[200:203], v[80:83]
	v_mfma_f32_16x16x32_bf16 v[68:71], v[152:155], v[208:211], v[68:71]
	v_mfma_f32_16x16x32_bf16 v[64:67], v[166:169], v[208:211], v[64:67]
	v_mfma_f32_16x16x32_bf16 v[132:135], v[162:165], v[182:185], v[132:135]
	v_mfma_f32_16x16x32_bf16 v[128:131], v[174:177], v[182:185], v[128:131]
	v_mfma_f32_16x16x32_bf16 v[100:103], v[162:165], v[196:199], v[100:103]
	v_mfma_f32_16x16x32_bf16 v[96:99], v[174:177], v[196:199], v[96:99]
	v_mfma_f32_16x16x32_bf16 v[84:87], v[162:165], v[204:207], v[84:87]
	v_mfma_f32_16x16x32_bf16 v[80:83], v[174:177], v[204:207], v[80:83]
	v_mfma_f32_16x16x32_bf16 v[68:71], v[162:165], v[212:215], v[68:71]
	v_mfma_f32_16x16x32_bf16 v[64:67], v[174:177], v[212:215], v[64:67]
	s_barrier
	s_add_i32 s49, s49, s31
	v_lshl_add_u64 v[156:157], s[26:27], 0, v[146:147]
	s_mov_b32 m0, s49
	ds_read_b128 v[178:181], v161 offset:16384
	ds_read_b128 v[182:185], v161 offset:17408
	ds_read_b128 v[192:195], v161 offset:18432
	ds_read_b128 v[196:199], v161 offset:19456
	ds_read_b128 v[200:203], v161 offset:20480
	ds_read_b128 v[204:207], v161 offset:21504
	ds_read_b128 v[208:211], v161 offset:22528
	ds_read_b128 v[212:215], v161 offset:23552
	global_load_lds_dwordx4 v[156:157], off
	s_add_i32 m0, s49, 0x2000
	s_add_u32 s50, s26, 0x100000
	v_lshl_add_u64 v[170:171], s[26:27], 0, v[144:145]
	s_addc_u32 s51, s27, 0
	s_add_i32 s49, s52, s31
	global_load_lds_dwordx4 v[170:171], off
	v_lshl_add_u64 v[186:187], s[50:51], 0, v[146:147]
	s_mov_b32 m0, s49
	v_lshl_add_u64 v[216:217], s[28:29], 0, v[144:145]
	global_load_lds_dwordx4 v[186:187], off
	v_lshl_add_u64 v[186:187], s[50:51], 0, v[144:145]
	s_add_i32 m0, s49, 0x2000
	s_nop 0
	global_load_lds_dwordx4 v[186:187], off
	v_lshl_add_u64 v[186:187], s[28:29], 0, v[146:147]
	s_mov_b32 m0, s34
	s_nop 0
	global_load_lds_dwordx4 v[186:187], off
	s_mov_b32 m0, s35
	s_nop 0
	global_load_lds_dwordx4 v[216:217], off
	s_waitcnt vmcnt(8)
	s_waitcnt lgkmcnt(0)
	s_barrier
; #define PG8_STAGE(bufoff, gbase, voff) do { _Pragma("unroll") for (int _i = 0; _i < 2; ++_i) \
;         __builtin_amdgcn_global_load_lds((const unsigned*)((const char*)(gbase) + (voff)[_i]), (PG8_LAS unsigned*)(lds + (bufoff) + ldsw + _i * 8192), 16, 0, 0); } while (0)
; #define PG8_LDA(dst, b, h) do { _Pragma("unroll") for (int m = 0; m < 4; ++m) _Pragma("unroll") for (int k = 0; k < 2; ++k) dst[m][k] = *(const PG8_LAS bf16x8*)(lds + PG8_SA(b, h) + aoff + m * 2048 + k * 1024); } while (0)
; #define PG8_LDB(dst, b, h) do { _Pragma("unroll") for (int n = 0; n < 2; ++n) _Pragma("unroll") for (int k = 0; k < 2; ++k) dst[n][k] = *(const PG8_LAS bf16x8*)(lds + PG8_SB(b, h) + boff + n * 2048 + k * 1024); } while (0)
; #define PG8_MMA(ai, bj, At, Bt) do { __builtin_amdgcn_s_setprio(1); _Pragma("unroll") for (int m = 0; m < 4; ++m) _Pragma("unroll") for (int n = 0; n < 2; ++n) _Pragma("unroll") for (int k = 0; k < 2; ++k) \
;         acc[ai][bj][m][n] = __builtin_amdgcn_mfma_f32_16x16x32_bf16(Bt[n][k], At[m][k], acc[ai][bj][m][n], 0, 0, 0); __builtin_amdgcn_s_setprio(0); } while (0)
; #define PG8_WAIT_V(n) asm volatile("s_waitcnt vmcnt(" #n ")" ::: "memory")
; #define PG8_WAIT_L(n) asm volatile("s_waitcnt lgkmcnt(" #n ")" ::: "memory")
; #define PG8_BAR __builtin_amdgcn_s_barrier()
; #define PG8_SCHED __builtin_amdgcn_sched_barrier(0)
; template <class Epi, class Sched, bool ALIGN_EPI = false, bool SP2 = false>
; __device__ __forceinline__ void gemm_phase(PG8_LAS unsigned char* lds, const Gemm g, const Sched& S, const Epi& E) {
;     ...
;             PG8_WAIT_V(8); PG8_WAIT_L(0); PG8_BAR; PG8_MMA(1, 0, At, B0); PG8_MMA(1, 1, At, B1); PG8_BAR; PG8_SCHED;
;             PG8_LDB(B0, 1, 0); PG8_LDB(B1, 1, 1); PG8_SCHED; PG8_LDA(At, 1, 0); PG8_STAGE(PG8_SA(0, 1), a2 + hstepA, voffA);
;             PG8_WAIT_V(8); PG8_WAIT_L(0); PG8_BAR; PG8_MMA(0, 0, At, B0); PG8_MMA(0, 1, At, B1); PG8_BAR; PG8_SCHED;
	s_waitcnt lgkmcnt(0)
	v_mfma_f32_16x16x32_bf16 v[60:63], v[108:111], v[178:181], v[60:63]
	v_mfma_f32_16x16x32_bf16 v[56:59], v[120:123], v[178:181], v[56:59]
	v_mfma_f32_16x16x32_bf16 v[52:55], v[108:111], v[192:195], v[52:55]
	v_mfma_f32_16x16x32_bf16 v[40:43], v[120:123], v[192:195], v[40:43]
	v_mfma_f32_16x16x32_bf16 v[36:39], v[108:111], v[200:203], v[36:39]
	v_mfma_f32_16x16x32_bf16 v[24:27], v[120:123], v[200:203], v[24:27]
	v_mfma_f32_16x16x32_bf16 v[20:23], v[108:111], v[208:211], v[20:23]
	v_mfma_f32_16x16x32_bf16 v[8:11], v[120:123], v[208:211], v[8:11]
	v_mfma_f32_16x16x32_bf16 v[60:63], v[116:119], v[182:185], v[60:63]
	v_mfma_f32_16x16x32_bf16 v[56:59], v[124:127], v[182:185], v[56:59]
	v_mfma_f32_16x16x32_bf16 v[52:55], v[116:119], v[196:199], v[52:55]
	v_mfma_f32_16x16x32_bf16 v[40:43], v[124:127], v[196:199], v[40:43]
	v_mfma_f32_16x16x32_bf16 v[36:39], v[116:119], v[204:207], v[36:39]
	v_mfma_f32_16x16x32_bf16 v[24:27], v[124:127], v[204:207], v[24:27]
	v_mfma_f32_16x16x32_bf16 v[20:23], v[116:119], v[212:215], v[20:23]
	v_mfma_f32_16x16x32_bf16 v[8:11], v[124:127], v[212:215], v[8:11]
	v_mfma_f32_16x16x32_bf16 v[48:51], v[152:155], v[178:181], v[48:51]
	v_mfma_f32_16x16x32_bf16 v[44:47], v[166:169], v[178:181], v[44:47]
	v_mfma_f32_16x16x32_bf16 v[32:35], v[152:155], v[192:195], v[32:35]
	v_mfma_f32_16x16x32_bf16 v[28:31], v[166:169], v[192:195], v[28:31]
	v_mfma_f32_16x16x32_bf16 v[16:19], v[152:155], v[200:203], v[16:19]
	v_mfma_f32_16x16x32_bf16 v[12:15], v[166:169], v[200:203], v[12:15]
	v_mfma_f32_16x16x32_bf16 v[4:7], v[152:155], v[208:211], v[4:7]
	v_mfma_f32_16x16x32_bf16 v[0:3], v[166:169], v[208:211], v[0:3]
	v_mfma_f32_16x16x32_bf16 v[48:51], v[162:165], v[182:185], v[48:51]
	v_mfma_f32_16x16x32_bf16 v[44:47], v[174:177], v[182:185], v[44:47]
	v_mfma_f32_16x16x32_bf16 v[32:35], v[162:165], v[196:199], v[32:35]
	v_mfma_f32_16x16x32_bf16 v[28:31], v[174:177], v[196:199], v[28:31]
	v_mfma_f32_16x16x32_bf16 v[16:19], v[162:165], v[204:207], v[16:19]
	v_mfma_f32_16x16x32_bf16 v[12:15], v[174:177], v[204:207], v[12:15]
	v_mfma_f32_16x16x32_bf16 v[4:7], v[162:165], v[212:215], v[4:7]
	v_mfma_f32_16x16x32_bf16 v[0:3], v[174:177], v[212:215], v[0:3]
	s_barrier
	s_add_i32 s49, 0, 0x18000
	s_add_i32 s50, 0, 0x1c000
	v_add_u32_e32 v124, s49, v158
	v_add_u32_e32 v172, s50, v158
	ds_read_b128 v[108:111], v124
	ds_read_b128 v[116:119], v124 offset:1024
	ds_read_b128 v[120:123], v124 offset:2048
	ds_read_b128 v[124:127], v124 offset:3072
	ds_read_b128 v[152:155], v172
	ds_read_b128 v[162:165], v172 offset:1024
	ds_read_b128 v[166:169], v172 offset:2048
	ds_read_b128 v[174:177], v172 offset:3072
	s_add_u32 s28, s28, 0x100000
	s_addc_u32 s29, s29, 0
	s_mov_b32 m0, s36
	v_lshl_add_u64 v[218:219], s[28:29], 0, v[146:147]
	ds_read_b128 v[178:181], v161 offset:32768
	ds_read_b128 v[182:185], v161 offset:33792
	ds_read_b128 v[192:195], v161 offset:34816
	ds_read_b128 v[196:199], v161 offset:35840
	ds_read_b128 v[200:203], v161 offset:36864
	ds_read_b128 v[204:207], v161 offset:37888
	ds_read_b128 v[208:211], v161 offset:38912
	ds_read_b128 v[212:215], v161 offset:39936
	global_load_lds_dwordx4 v[218:219], off
	v_lshl_add_u64 v[218:219], s[28:29], 0, v[144:145]
	s_mov_b32 m0, s37
	s_nop 0
	global_load_lds_dwordx4 v[218:219], off
	s_waitcnt vmcnt(8)
	s_waitcnt lgkmcnt(0)
	s_barrier
	s_waitcnt lgkmcnt(0)
	v_mfma_f32_16x16x32_bf16 v[140:143], v[108:111], v[178:181], v[140:143]
	v_mfma_f32_16x16x32_bf16 v[136:139], v[120:123], v[178:181], v[136:139]
	v_mfma_f32_16x16x32_bf16 v[112:115], v[108:111], v[192:195], v[112:115]
	v_mfma_f32_16x16x32_bf16 v[104:107], v[120:123], v[192:195], v[104:107]
	v_mfma_f32_16x16x32_bf16 v[92:95], v[108:111], v[200:203], v[92:95]
	v_mfma_f32_16x16x32_bf16 v[88:91], v[120:123], v[200:203], v[88:91]
	v_mfma_f32_16x16x32_bf16 v[76:79], v[108:111], v[208:211], v[76:79]
	v_mfma_f32_16x16x32_bf16 v[72:75], v[120:123], v[208:211], v[72:75]
	v_mfma_f32_16x16x32_bf16 v[140:143], v[116:119], v[182:185], v[140:143]
	v_mfma_f32_16x16x32_bf16 v[136:139], v[124:127], v[182:185], v[136:139]
	v_mfma_f32_16x16x32_bf16 v[112:115], v[116:119], v[196:199], v[112:115]
	v_mfma_f32_16x16x32_bf16 v[104:107], v[124:127], v[196:199], v[104:107]
	v_mfma_f32_16x16x32_bf16 v[92:95], v[116:119], v[204:207], v[92:95]
	v_mfma_f32_16x16x32_bf16 v[88:91], v[124:127], v[204:207], v[88:91]
	v_mfma_f32_16x16x32_bf16 v[76:79], v[116:119], v[212:215], v[76:79]
	v_mfma_f32_16x16x32_bf16 v[72:75], v[124:127], v[212:215], v[72:75]
	v_mfma_f32_16x16x32_bf16 v[132:135], v[152:155], v[178:181], v[132:135]
	v_mfma_f32_16x16x32_bf16 v[128:131], v[166:169], v[178:181], v[128:131]
	v_mfma_f32_16x16x32_bf16 v[100:103], v[152:155], v[192:195], v[100:103]
	v_mfma_f32_16x16x32_bf16 v[96:99], v[166:169], v[192:195], v[96:99]
	v_mfma_f32_16x16x32_bf16 v[84:87], v[152:155], v[200:203], v[84:87]
	v_mfma_f32_16x16x32_bf16 v[80:83], v[166:169], v[200:203], v[80:83]
	v_mfma_f32_16x16x32_bf16 v[68:71], v[152:155], v[208:211], v[68:71]
	v_mfma_f32_16x16x32_bf16 v[64:67], v[166:169], v[208:211], v[64:67]
	v_mfma_f32_16x16x32_bf16 v[132:135], v[162:165], v[182:185], v[132:135]
	v_mfma_f32_16x16x32_bf16 v[128:131], v[174:177], v[182:185], v[128:131]
	v_mfma_f32_16x16x32_bf16 v[100:103], v[162:165], v[196:199], v[100:103]
	v_mfma_f32_16x16x32_bf16 v[96:99], v[174:177], v[196:199], v[96:99]
	v_mfma_f32_16x16x32_bf16 v[84:87], v[162:165], v[204:207], v[84:87]
	v_mfma_f32_16x16x32_bf16 v[80:83], v[174:177], v[204:207], v[80:83]
	v_mfma_f32_16x16x32_bf16 v[68:71], v[162:165], v[212:215], v[68:71]
	v_mfma_f32_16x16x32_bf16 v[64:67], v[174:177], v[212:215], v[64:67]
	s_barrier
; #define PG8_STAGE(bufoff, gbase, voff) do { _Pragma("unroll") for (int _i = 0; _i < 2; ++_i) \
;         __builtin_amdgcn_global_load_lds((const unsigned*)((const char*)(gbase) + (voff)[_i]), (PG8_LAS unsigned*)(lds + (bufoff) + ldsw + _i * 8192), 16, 0, 0); } while (0)
; #define PG8_LDA(dst, b, h) do { _Pragma("unroll") for (int m = 0; m < 4; ++m) _Pragma("unroll") for (int k = 0; k < 2; ++k) dst[m][k] = *(const PG8_LAS bf16x8*)(lds + PG8_SA(b, h) + aoff + m * 2048 + k * 1024); } while (0)
; #define PG8_LDB(dst, b, h) do { _Pragma("unroll") for (int n = 0; n < 2; ++n) _Pragma("unroll") for (int k = 0; k < 2; ++k) dst[n][k] = *(const PG8_LAS bf16x8*)(lds + PG8_SB(b, h) + boff + n * 2048 + k * 1024); } while (0)
; template <class Epi, class Sched, bool ALIGN_EPI = false, bool SP2 = false>
; __device__ __forceinline__ void gemm_phase(PG8_LAS unsigned char* lds, const Gemm g, const Sched& S, const Epi& E) {
;     ...
;         for (int t = 0; t < nt; t += 2) {
;             const bool last = (t == nt - 2);
;             const char* a1 = cA + (size_t)(t + 1) * kstep;
;             const char* a2 = last ? nA : cA + (size_t)(t + 2) * kstep; const char* b2 = last ? nB : cB + (size_t)(t + 2) * kstep;
;             const char* a3 = a2 + kstep; const char* b3 = b2 + kstep;
;             if (last && has_next) S.a_ready(nxt);
;             if constexpr (SP2) {
;             PG8_LDB(B0, 0, 0); PG8_LDB(B1, 0, 1); PG8_SCHED; PG8_LDA(At, 0, 0); PG8_STAGE(PG8_SA(1, 1), a1 + hstepA, voffA);
;             PG8_WAIT_V(8); PG8_WAIT_L(0); PG8_BAR; PG8_MMA(0, 0, At, B0); PG8_MMA(0, 1, At, B1); PG8_BAR; PG8_SCHED;
;             PG8_LDA(At, 0, 1); PG8_STAGE(PG8_SB(0, 0), b2, voffB); PG8_STAGE(PG8_SB(0, 1), b2 + hstepB, voffB); PG8_STAGE(PG8_SA(0, 0), a2, voffA);
;             PG8_WAIT_V(8); PG8_WAIT_L(0); PG8_BAR; PG8_MMA(1, 0, At, B0); PG8_MMA(1, 1, At, B1); PG8_BAR; PG8_SCHED;
;             PG8_LDB(B0, 1, 0); PG8_LDB(B1, 1, 1); PG8_SCHED; PG8_LDA(At, 1, 0); PG8_STAGE(PG8_SA(0, 1), a2 + hstepA, voffA);
;             PG8_WAIT_V(8); PG8_WAIT_L(0); PG8_BAR; PG8_MMA(0, 0, At, B0); PG8_MMA(0, 1, At, B1); PG8_BAR; PG8_SCHED;
;             PG8_LDA(At, 1, 1); PG8_STAGE(PG8_SB(1, 0), b3, voffB); PG8_STAGE(PG8_SB(1, 1), b3 + hstepB, voffB); PG8_STAGE(PG8_SA(1, 0), a3, voffA);
;             PG8_WAIT_V(8); PG8_WAIT_L(0); PG8_BAR; PG8_MMA(1, 0, At, B0); PG8_MMA(1, 1, At, B1); PG8_BAR; PG8_SCHED;
	s_add_i32 s28, s49, s31
	v_lshl_add_u64 v[156:157], v[156:157], 0, s[80:81]
	s_mov_b32 m0, s28
	ds_read_b128 v[178:181], v161 offset:49152
	ds_read_b128 v[182:185], v161 offset:50176
	ds_read_b128 v[192:195], v161 offset:51200
	ds_read_b128 v[196:199], v161 offset:52224
	ds_read_b128 v[200:203], v161 offset:53248
	ds_read_b128 v[204:207], v161 offset:54272
	ds_read_b128 v[208:211], v161 offset:55296
	ds_read_b128 v[212:215], v161 offset:56320
	global_load_lds_dwordx4 v[156:157], off
	s_add_i32 m0, s28, 0x2000
	s_add_u32 s26, s26, 0x100080
	v_lshl_add_u64 v[156:157], v[170:171], 0, s[80:81]
	s_addc_u32 s27, s27, 0
	s_add_i32 s28, s50, s31
	global_load_lds_dwordx4 v[156:157], off
	v_lshl_add_u64 v[156:157], s[26:27], 0, v[146:147]
	s_mov_b32 m0, s28
	s_nop 0
	global_load_lds_dwordx4 v[156:157], off
	v_lshl_add_u64 v[156:157], s[26:27], 0, v[144:145]
	s_add_i32 m0, s28, 0x2000
	s_nop 0
	global_load_lds_dwordx4 v[156:157], off
	v_lshl_add_u64 v[156:157], v[186:187], 0, s[80:81]
	s_mov_b32 m0, s2
	s_nop 0
	global_load_lds_dwordx4 v[156:157], off
	v_lshl_add_u64 v[156:157], v[216:217], 0, s[80:81]
	s_mov_b32 m0, s38
	s_nop 0
	global_load_lds_dwordx4 v[156:157], off
	s_waitcnt vmcnt(8)
	s_waitcnt lgkmcnt(0)
	s_barrier
	s_waitcnt lgkmcnt(0)
	v_mfma_f32_16x16x32_bf16 v[60:63], v[108:111], v[178:181], v[60:63]
	v_mfma_f32_16x16x32_bf16 v[56:59], v[120:123], v[178:181], v[56:59]
	v_mfma_f32_16x16x32_bf16 v[52:55], v[108:111], v[192:195], v[52:55]
	v_mfma_f32_16x16x32_bf16 v[40:43], v[120:123], v[192:195], v[40:43]
	v_mfma_f32_16x16x32_bf16 v[36:39], v[108:111], v[200:203], v[36:39]
	v_mfma_f32_16x16x32_bf16 v[24:27], v[120:123], v[200:203], v[24:27]
	v_mfma_f32_16x16x32_bf16 v[20:23], v[108:111], v[208:211], v[20:23]
	v_mfma_f32_16x16x32_bf16 v[8:11], v[120:123], v[208:211], v[8:11]
	v_mfma_f32_16x16x32_bf16 v[60:63], v[116:119], v[182:185], v[60:63]
	v_mfma_f32_16x16x32_bf16 v[56:59], v[124:127], v[182:185], v[56:59]
	v_mfma_f32_16x16x32_bf16 v[52:55], v[116:119], v[196:199], v[52:55]
	v_mfma_f32_16x16x32_bf16 v[40:43], v[124:127], v[196:199], v[40:43]
	v_mfma_f32_16x16x32_bf16 v[36:39], v[116:119], v[204:207], v[36:39]
	v_mfma_f32_16x16x32_bf16 v[24:27], v[124:127], v[204:207], v[24:27]
	v_mfma_f32_16x16x32_bf16 v[20:23], v[116:119], v[212:215], v[20:23]
	v_mfma_f32_16x16x32_bf16 v[8:11], v[124:127], v[212:215], v[8:11]
	v_mfma_f32_16x16x32_bf16 v[48:51], v[152:155], v[178:181], v[48:51]
	v_mfma_f32_16x16x32_bf16 v[44:47], v[166:169], v[178:181], v[44:47]
	v_mfma_f32_16x16x32_bf16 v[32:35], v[152:155], v[192:195], v[32:35]
	v_mfma_f32_16x16x32_bf16 v[28:31], v[166:169], v[192:195], v[28:31]
	v_mfma_f32_16x16x32_bf16 v[16:19], v[152:155], v[200:203], v[16:19]
	v_mfma_f32_16x16x32_bf16 v[12:15], v[166:169], v[200:203], v[12:15]
	v_mfma_f32_16x16x32_bf16 v[4:7], v[152:155], v[208:211], v[4:7]
	v_mfma_f32_16x16x32_bf16 v[0:3], v[166:169], v[208:211], v[0:3]
	v_mfma_f32_16x16x32_bf16 v[48:51], v[162:165], v[182:185], v[48:51]
	v_mfma_f32_16x16x32_bf16 v[44:47], v[174:177], v[182:185], v[44:47]
	v_mfma_f32_16x16x32_bf16 v[32:35], v[162:165], v[196:199], v[32:35]
	v_mfma_f32_16x16x32_bf16 v[28:31], v[174:177], v[196:199], v[28:31]
	v_mfma_f32_16x16x32_bf16 v[16:19], v[162:165], v[204:207], v[16:19]
	v_mfma_f32_16x16x32_bf16 v[12:15], v[174:177], v[204:207], v[12:15]
	v_mfma_f32_16x16x32_bf16 v[4:7], v[162:165], v[212:215], v[4:7]
	v_mfma_f32_16x16x32_bf16 v[0:3], v[174:177], v[212:215], v[0:3]
	s_barrier
	s_add_i32 s47, s47, 2
	s_add_u32 s24, s24, 0x100
	s_addc_u32 s25, s25, 0
	s_add_u32 s17, s17, 0x100
	s_addc_u32 s23, s23, 0
	s_cmp_gt_u32 s47, 5
	s_cbranch_scc0 .LBB0_1972
	s_and_b64 vcc, exec, s[10:11]
	s_cbranch_vccz .LBB0_1975
	s_barrier
